# v013
# speedup vs baseline: 1.0553x; 1.0553x over previous
; __device__ __forceinline__ void convert_wt(const float* __restrict__ W, int K, int N, u16* __restrict__ Wt, int Npad, int mode, char* smem,
;                                            const float* __restrict__ gain = nullptr) {
;     ...
;   for (int t = blockIdx.x; t < nkt * nnt; t += gridDim.x) {
;     const int n0 = (t / nkt) * 32, k0 = (t % nkt) * 64;
;     int sn0 = n0;
;     if (mode == 1) { int pair = n0 >> 6; sn0 = ((n0 & 63) == 0) ? pair * 32 : FF + pair * 32; }
;     const bool valid = (n0 < N);
;     {
;       const int kk = tid >> 3, n4 = tid & 7;
; #pragma unroll
;       for (int p = 0; p < 2; ++p) {
;         const int k = p * 32 + kk;
;         float4 v = make_float4(0.f, 0.f, 0.f, 0.f);
;         if (valid && (sn0 + n4 * 4 + 3) < N) v = *(const float4*)(W + (size_t)(k0 + k) * N + sn0 + n4 * 4);
;         if (gain) { const float gk = gain[k0 + k]; v.x *= gk; v.y *= gk; v.z *= gk; v.w *= gk; }
;         tile[(n4 * 4 + 0) * 65 + k] = v.x; tile[(n4 * 4 + 1) * 65 + k] = v.y;
;         tile[(n4 * 4 + 2) * 65 + k] = v.z; tile[(n4 * 4 + 3) * 65 + k] = v.w;
;       }
;     }
;     __syncthreads();
;     {
;       const int nn = tid >> 3, kc = tid & 7;
;       bf16x8 o;
; #pragma unroll
;       for (int e = 0; e < 8; ++e) o[e] = (short)f2bf(tile[nn * 65 + kc * 8 + e]);
;       *(bf16x8*)(Wt + (size_t)(n0 + nn) * K + k0 + kc * 8) = o;
;     }
;     __syncthreads();
; __global__ void __launch_bounds__(256, 2) fwd_megakernel(Params p) {
;     ...
;     convert_wt(p.ffn1_w_out + (size_t)l * FF * DM, FF, DM, p.wt_ffn_out[l * 2 + 0], DM, 0, smem);
;     convert_wt(p.ffn2_w_out + (size_t)l * FF * DM, FF, DM, p.wt_ffn_out[l * 2 + 1], DM, 0, smem);
.LBB0_37:
	s_load_dwordx2 s[6:7], s[96:97], 0x48
	s_cmpk_lt_i32 s64, 0x580
	s_waitcnt lgkmcnt(0)
	s_cselect_b64 s[10:11], -1, 0
	v_mov_b32_e32 v2, v140
	s_and_b64 vcc, exec, s[10:11]
	s_cbranch_vccz .LBB0_42
	s_load_dwordx2 s[4:5], s[96:97], 0x100
	v_ashrrev_i32_e32 v1, 3, v2
	s_movk_i32 s8, 0x104
	v_and_b32_e32 v3, 7, v2
	v_mul_lo_u32 v2, v1, s8
	v_mul_u32_u24_e32 v4, 0x410, v3
	v_lshlrev_b32_e32 v10, 4, v3
	v_mov_b32_e32 v11, 0
	v_add_u32_e32 v5, 0, v2
	v_lshlrev_b32_e32 v6, 5, v3
	v_lshlrev_b32_e32 v2, 3, v3
	v_lshlrev_b32_e32 v7, 2, v1
	v_lshl_add_u64 v[12:13], s[6:7], 0, v[10:11]
	v_add3_u32 v16, 0, v4, v7
	v_lshl_or_b32 v17, v3, 2, 3
	s_lshl_b32 s12, s64, 6
	s_lshl_b32 s13, s68, 6
	s_movk_i32 s14, 0x400
	v_add_u32_e32 v18, v5, v6
	s_mov_b32 s15, 0x5040100
	s_movk_i32 s16, 0x1600
	s_waitcnt lgkmcnt(0)
	v_mov_b64_e32 v[14:15], s[4:5]
	v_lshlrev_b32_e32 v10, 1, v2
	v_bfe_u32 v11, v140, 2, 1
	v_lshl_add_u32 v10, v11, 6, v10
	v_bfe_u32 v11, v140, 3, 1
	v_mul_u32_u24_e32 v11, 0x15c0, v11
	v_sub_u32_e32 v10, v10, v11
	v_ashrrev_i32_e32 v11, 31, v10
	s_mov_b32 s17, s64
	s_branch .LBB0_40
.LBB0_39:
	s_or_b64 exec, exec, s[8:9]
	s_waitcnt vmcnt(0)
	ds_write2_b32 v16, v2, v6 offset1:32
	ds_write2_b32 v16, v3, v7 offset0:65 offset1:97
	ds_write2_b32 v16, v4, v8 offset0:130 offset1:162
	ds_write2_b32 v16, v5, v9 offset0:195 offset1:227
	s_waitcnt lgkmcnt(0)
	s_barrier
	ds_read2_b32 v[4:5], v18 offset1:7
	ds_read2_b32 v[2:3], v18 offset0:1 offset1:2
	ds_read2_b32 v[6:7], v18 offset0:3 offset1:4
	ds_read2_b32 v[8:9], v18 offset0:5 offset1:6
	s_add_i32 s8, s12, s18
	s_waitcnt lgkmcnt(3)
	v_cvt_pk_bf16_f32 v4, v4, s0
	s_waitcnt lgkmcnt(2)
	v_cvt_pk_bf16_f32 v3, v2, v3
	v_perm_b32 v2, v3, v4, s15
	s_waitcnt lgkmcnt(1)
	v_cvt_pk_bf16_f32 v4, v6, v7
	s_waitcnt lgkmcnt(0)
	v_cvt_pk_bf16_f32 v6, v8, v9
	v_cvt_pk_bf16_f32 v5, v5, s0
	v_alignbit_b32 v3, v4, v3, 16
	v_alignbit_b32 v4, v6, v4, 16
	v_alignbit_b32 v5, v5, v6, 16
	v_add_u32_e32 v6, s4, v1
	v_mad_i64_i32 v[6:7], s[4:5], v6, s16, v[14:15]
	s_ashr_i32 s9, s8, 31
	v_lshl_add_u64 v[6:7], s[8:9], 2, v[6:7]
	s_add_i32 s17, s17, s68
	s_add_i32 s12, s12, s13
	v_lshl_add_u64 v[6:7], v[6:7], 0, v[10:11]
	s_cmpk_lt_i32 s17, 0x580
	global_store_dwordx4 v[6:7], v[2:5], off
	s_barrier
	s_cbranch_scc0 .LBB0_42

; __device__ __forceinline__ void convert_wt(const float* __restrict__ W, int K, int N, u16* __restrict__ Wt, int Npad, int mode, char* smem,
;                                            const float* __restrict__ gain = nullptr) {
;     ...
;   for (int t = blockIdx.x; t < nkt * nnt; t += gridDim.x) {
;     const int n0 = (t / nkt) * 32, k0 = (t % nkt) * 64;
;     int sn0 = n0;
;     if (mode == 1) { int pair = n0 >> 6; sn0 = ((n0 & 63) == 0) ? pair * 32 : FF + pair * 32; }
;     const bool valid = (n0 < N);
;     {
;       const int kk = tid >> 3, n4 = tid & 7;
; #pragma unroll
;       for (int p = 0; p < 2; ++p) {
;         const int k = p * 32 + kk;
;         float4 v = make_float4(0.f, 0.f, 0.f, 0.f);
;         if (valid && (sn0 + n4 * 4 + 3) < N) v = *(const float4*)(W + (size_t)(k0 + k) * N + sn0 + n4 * 4);
;         if (gain) { const float gk = gain[k0 + k]; v.x *= gk; v.y *= gk; v.z *= gk; v.w *= gk; }
;         tile[(n4 * 4 + 0) * 65 + k] = v.x; tile[(n4 * 4 + 1) * 65 + k] = v.y;
;         tile[(n4 * 4 + 2) * 65 + k] = v.z; tile[(n4 * 4 + 3) * 65 + k] = v.w;
;       }
;     }
;     __syncthreads();
;     {
;       const int nn = tid >> 3, kc = tid & 7;
;       bf16x8 o;
; #pragma unroll
;       for (int e = 0; e < 8; ++e) o[e] = (short)f2bf(tile[nn * 65 + kc * 8 + e]);
;       *(bf16x8*)(Wt + (size_t)(n0 + nn) * K + k0 + kc * 8) = o;
;     }
;     __syncthreads();
; __global__ void __launch_bounds__(256, 2) fwd_megakernel(Params p) {
;     ...
;     convert_wt(p.ffn1_w_out + (size_t)l * FF * DM, FF, DM, p.wt_ffn_out[l * 2 + 0], DM, 0, smem);
;     convert_wt(p.ffn2_w_out + (size_t)l * FF * DM, FF, DM, p.wt_ffn_out[l * 2 + 1], DM, 0, smem);
.LBB0_42:
	s_load_dwordx2 s[8:9], s[96:97], 0x68
	v_cndmask_b32_e64 v1, 0, 1, s[10:11]
	v_mov_b32_e32 v2, v140
	v_cmp_ne_u32_e64 s[4:5], 1, v1
	s_andn2_b64 vcc, exec, s[10:11]
	s_cbranch_vccnz .LBB0_47
	s_load_dwordx2 s[10:11], s[96:97], 0x108
	v_ashrrev_i32_e32 v1, 3, v2
	s_movk_i32 s12, 0x104
	v_and_b32_e32 v3, 7, v2
	v_mul_lo_u32 v2, v1, s12
	v_mul_u32_u24_e32 v4, 0x410, v3
	v_lshlrev_b32_e32 v10, 4, v3
	v_mov_b32_e32 v11, 0
	v_add_u32_e32 v5, 0, v2
	v_lshlrev_b32_e32 v6, 5, v3
	v_lshlrev_b32_e32 v2, 3, v3
	v_lshlrev_b32_e32 v7, 2, v1
	s_waitcnt lgkmcnt(0)
	v_lshl_add_u64 v[12:13], s[8:9], 0, v[10:11]
	v_add3_u32 v16, 0, v4, v7
	v_lshl_or_b32 v17, v3, 2, 3
	s_lshl_b32 s14, s64, 6
	s_lshl_b32 s15, s68, 6
	s_movk_i32 s16, 0x400
	v_add_u32_e32 v18, v5, v6
	s_mov_b32 s17, 0x5040100
	s_movk_i32 s18, 0x1600
	v_mov_b64_e32 v[14:15], s[10:11]
	v_lshlrev_b32_e32 v10, 1, v2
	v_bfe_u32 v11, v140, 2, 1
	v_lshl_add_u32 v10, v11, 6, v10
	v_bfe_u32 v11, v140, 3, 1
	v_mul_u32_u24_e32 v11, 0x15c0, v11
	v_sub_u32_e32 v10, v10, v11
	v_ashrrev_i32_e32 v11, 31, v10
	s_mov_b32 s19, s64
	s_branch .LBB0_45
.LBB0_44:
	s_or_b64 exec, exec, s[12:13]
	s_waitcnt vmcnt(0)
	ds_write2_b32 v16, v2, v6 offset1:32
	ds_write2_b32 v16, v3, v7 offset0:65 offset1:97
	ds_write2_b32 v16, v4, v8 offset0:130 offset1:162
	ds_write2_b32 v16, v5, v9 offset0:195 offset1:227
	s_waitcnt lgkmcnt(0)
	s_barrier
	ds_read2_b32 v[4:5], v18 offset1:7
	ds_read2_b32 v[2:3], v18 offset0:1 offset1:2
	ds_read2_b32 v[6:7], v18 offset0:3 offset1:4
	ds_read2_b32 v[8:9], v18 offset0:5 offset1:6
	s_add_i32 s12, s14, s20
	s_waitcnt lgkmcnt(3)
	v_cvt_pk_bf16_f32 v4, v4, s0
	s_waitcnt lgkmcnt(2)
	v_cvt_pk_bf16_f32 v3, v2, v3
	v_perm_b32 v2, v3, v4, s17
	s_waitcnt lgkmcnt(1)
	v_cvt_pk_bf16_f32 v4, v6, v7
	s_waitcnt lgkmcnt(0)
	v_cvt_pk_bf16_f32 v6, v8, v9
	v_cvt_pk_bf16_f32 v5, v5, s0
	v_alignbit_b32 v3, v4, v3, 16
	v_alignbit_b32 v4, v6, v4, 16
	v_alignbit_b32 v5, v5, v6, 16
	v_add_u32_e32 v6, s10, v1
	v_mad_i64_i32 v[6:7], s[10:11], v6, s18, v[14:15]
	s_ashr_i32 s13, s12, 31
	v_lshl_add_u64 v[6:7], s[12:13], 2, v[6:7]
	s_add_i32 s19, s19, s68
	s_add_i32 s14, s14, s15
	v_lshl_add_u64 v[6:7], v[6:7], 0, v[10:11]
	s_cmpk_lt_i32 s19, 0x580
	global_store_dwordx4 v[6:7], v[2:5], off
	s_barrier
	s_cbranch_scc0 .LBB0_47

; __device__ __forceinline__ void convert_wt(const float* __restrict__ W, int K, int N, u16* __restrict__ Wt, int Npad, int mode, char* smem,
;                                            const float* __restrict__ gain = nullptr) {
;     ...
;   for (int t = blockIdx.x; t < nkt * nnt; t += gridDim.x) {
;     const int n0 = (t / nkt) * 32, k0 = (t % nkt) * 64;
;     int sn0 = n0;
;     if (mode == 1) { int pair = n0 >> 6; sn0 = ((n0 & 63) == 0) ? pair * 32 : FF + pair * 32; }
;     const bool valid = (n0 < N);
;     {
;       const int kk = tid >> 3, n4 = tid & 7;
; #pragma unroll
;       for (int p = 0; p < 2; ++p) {
;         const int k = p * 32 + kk;
;         float4 v = make_float4(0.f, 0.f, 0.f, 0.f);
;         if (valid && (sn0 + n4 * 4 + 3) < N) v = *(const float4*)(W + (size_t)(k0 + k) * N + sn0 + n4 * 4);
;         if (gain) { const float gk = gain[k0 + k]; v.x *= gk; v.y *= gk; v.z *= gk; v.w *= gk; }
;         tile[(n4 * 4 + 0) * 65 + k] = v.x; tile[(n4 * 4 + 1) * 65 + k] = v.y;
;         tile[(n4 * 4 + 2) * 65 + k] = v.z; tile[(n4 * 4 + 3) * 65 + k] = v.w;
;       }
;     }
;     __syncthreads();
;     {
;       const int nn = tid >> 3, kc = tid & 7;
;       bf16x8 o;
; #pragma unroll
;       for (int e = 0; e < 8; ++e) o[e] = (short)f2bf(tile[nn * 65 + kc * 8 + e]);
;       *(bf16x8*)(Wt + (size_t)(n0 + nn) * K + k0 + kc * 8) = o;
;     }
;     __syncthreads();
; __global__ void __launch_bounds__(256, 2) fwd_megakernel(Params p) {
;     ...
;     convert_wt(p.ffn1_w_out + (size_t)l * FF * DM, FF, DM, p.wt_ffn_out[l * 2 + 0], DM, 0, smem);
;     convert_wt(p.ffn2_w_out + (size_t)l * FF * DM, FF, DM, p.wt_ffn_out[l * 2 + 1], DM, 0, smem);
.LBB0_47:
	v_mov_b32_e32 v2, v140
	s_and_b64 vcc, exec, s[4:5]
	s_cbranch_vccnz .LBB0_52
	v_and_b32_e32 v4, 7, v2
	s_load_dwordx2 s[10:11], s[96:97], 0x110
	v_lshlrev_b32_e32 v10, 4, v4
	v_mov_b32_e32 v11, 0
	v_ashrrev_i32_e32 v1, 3, v2
	v_lshl_add_u64 v[2:3], s[6:7], 0, v[10:11]
	s_mov_b64 s[6:7], 0xb00000
	v_lshl_add_u64 v[12:13], v[2:3], 0, s[6:7]
	s_movk_i32 s6, 0x104
	v_mul_lo_u32 v2, v1, s6
	v_mul_u32_u24_e32 v5, 0x410, v4
	v_add_u32_e32 v3, 0, v2
	v_lshlrev_b32_e32 v6, 5, v4
	v_lshlrev_b32_e32 v2, 3, v4
	v_lshlrev_b32_e32 v7, 2, v1
	v_add3_u32 v16, 0, v5, v7
	v_lshl_or_b32 v17, v4, 2, 3
	s_lshl_b32 s12, s64, 6
	s_lshl_b32 s13, s68, 6
	s_movk_i32 s14, 0x400
	v_add_u32_e32 v18, v3, v6
	s_mov_b32 s15, 0x5040100
	s_movk_i32 s16, 0x1600
	s_waitcnt lgkmcnt(0)
	v_mov_b64_e32 v[14:15], s[10:11]
	v_lshlrev_b32_e32 v10, 1, v2
	v_bfe_u32 v11, v140, 2, 1
	v_lshl_add_u32 v10, v11, 6, v10
	v_bfe_u32 v11, v140, 3, 1
	v_mul_u32_u24_e32 v11, 0x15c0, v11
	v_sub_u32_e32 v10, v10, v11
	v_ashrrev_i32_e32 v11, 31, v10
	s_mov_b32 s17, s64
	s_branch .LBB0_50
.LBB0_49:
	s_or_b64 exec, exec, s[10:11]
	s_waitcnt vmcnt(0)
	ds_write2_b32 v16, v2, v6 offset1:32
	ds_write2_b32 v16, v3, v7 offset0:65 offset1:97
	ds_write2_b32 v16, v4, v8 offset0:130 offset1:162
	ds_write2_b32 v16, v5, v9 offset0:195 offset1:227
	s_waitcnt lgkmcnt(0)
	s_barrier
	ds_read2_b32 v[4:5], v18 offset1:7
	ds_read2_b32 v[2:3], v18 offset0:1 offset1:2
	ds_read2_b32 v[6:7], v18 offset0:3 offset1:4
	ds_read2_b32 v[8:9], v18 offset0:5 offset1:6
	s_add_i32 s10, s12, s18
	s_waitcnt lgkmcnt(3)
	v_cvt_pk_bf16_f32 v4, v4, s0
	s_waitcnt lgkmcnt(2)
	v_cvt_pk_bf16_f32 v3, v2, v3
	v_perm_b32 v2, v3, v4, s15
	s_waitcnt lgkmcnt(1)
	v_cvt_pk_bf16_f32 v4, v6, v7
	s_waitcnt lgkmcnt(0)
	v_cvt_pk_bf16_f32 v6, v8, v9
	v_cvt_pk_bf16_f32 v5, v5, s0
	v_alignbit_b32 v3, v4, v3, 16
	v_alignbit_b32 v4, v6, v4, 16
	v_alignbit_b32 v5, v5, v6, 16
	v_add_u32_e32 v6, s6, v1
	v_mad_i64_i32 v[6:7], s[6:7], v6, s16, v[14:15]
	s_ashr_i32 s11, s10, 31
	v_lshl_add_u64 v[6:7], s[10:11], 2, v[6:7]
	s_add_i32 s17, s17, s68
	s_add_i32 s12, s12, s13
	v_lshl_add_u64 v[6:7], v[6:7], 0, v[10:11]
	s_cmpk_lt_i32 s17, 0x580
	global_store_dwordx4 v[6:7], v[2:5], off
	s_barrier
	s_cbranch_scc0 .LBB0_52

; __device__ __forceinline__ void convert_wt(const float* __restrict__ W, int K, int N, u16* __restrict__ Wt, int Npad, int mode, char* smem,
;                                            const float* __restrict__ gain = nullptr) {
;     ...
;   for (int t = blockIdx.x; t < nkt * nnt; t += gridDim.x) {
;     const int n0 = (t / nkt) * 32, k0 = (t % nkt) * 64;
;     int sn0 = n0;
;     if (mode == 1) { int pair = n0 >> 6; sn0 = ((n0 & 63) == 0) ? pair * 32 : FF + pair * 32; }
;     const bool valid = (n0 < N);
;     {
;       const int kk = tid >> 3, n4 = tid & 7;
; #pragma unroll
;       for (int p = 0; p < 2; ++p) {
;         const int k = p * 32 + kk;
;         float4 v = make_float4(0.f, 0.f, 0.f, 0.f);
;         if (valid && (sn0 + n4 * 4 + 3) < N) v = *(const float4*)(W + (size_t)(k0 + k) * N + sn0 + n4 * 4);
;         if (gain) { const float gk = gain[k0 + k]; v.x *= gk; v.y *= gk; v.z *= gk; v.w *= gk; }
;         tile[(n4 * 4 + 0) * 65 + k] = v.x; tile[(n4 * 4 + 1) * 65 + k] = v.y;
;         tile[(n4 * 4 + 2) * 65 + k] = v.z; tile[(n4 * 4 + 3) * 65 + k] = v.w;
;       }
;     }
;     __syncthreads();
;     {
;       const int nn = tid >> 3, kc = tid & 7;
;       bf16x8 o;
; #pragma unroll
;       for (int e = 0; e < 8; ++e) o[e] = (short)f2bf(tile[nn * 65 + kc * 8 + e]);
;       *(bf16x8*)(Wt + (size_t)(n0 + nn) * K + k0 + kc * 8) = o;
;     }
;     __syncthreads();
; __global__ void __launch_bounds__(256, 2) fwd_megakernel(Params p) {
;     ...
;     convert_wt(p.ffn1_w_out + (size_t)l * FF * DM, FF, DM, p.wt_ffn_out[l * 2 + 0], DM, 0, smem);
;     convert_wt(p.ffn2_w_out + (size_t)l * FF * DM, FF, DM, p.wt_ffn_out[l * 2 + 1], DM, 0, smem);
.LBB0_52:
	v_mov_b32_e32 v2, v140
	s_and_b64 vcc, exec, s[4:5]
	s_cbranch_vccnz .LBB0_57
	v_and_b32_e32 v4, 7, v2
	s_load_dwordx2 s[4:5], s[96:97], 0x118
	v_lshlrev_b32_e32 v10, 4, v4
	v_mov_b32_e32 v11, 0
	v_ashrrev_i32_e32 v1, 3, v2
	s_waitcnt lgkmcnt(0)
	v_lshl_add_u64 v[2:3], s[8:9], 0, v[10:11]
	s_mov_b64 s[6:7], 0xb00000
	v_lshl_add_u64 v[12:13], v[2:3], 0, s[6:7]
	s_movk_i32 s6, 0x104
	v_mul_lo_u32 v2, v1, s6
	v_mul_u32_u24_e32 v5, 0x410, v4
	v_add_u32_e32 v3, 0, v2
	v_lshlrev_b32_e32 v6, 5, v4
	v_lshlrev_b32_e32 v2, 3, v4
	v_lshlrev_b32_e32 v7, 2, v1
	v_add3_u32 v16, 0, v5, v7
	v_lshl_or_b32 v17, v4, 2, 3
	s_lshl_b32 s8, s64, 6
	s_lshl_b32 s9, s68, 6
	s_movk_i32 s10, 0x400
	v_add_u32_e32 v18, v3, v6
	s_mov_b32 s11, 0x5040100
	s_movk_i32 s12, 0x1600
	v_mov_b64_e32 v[14:15], s[4:5]
	v_lshlrev_b32_e32 v10, 1, v2
	v_bfe_u32 v11, v140, 2, 1
	v_lshl_add_u32 v10, v11, 6, v10
	v_bfe_u32 v11, v140, 3, 1
	v_mul_u32_u24_e32 v11, 0x15c0, v11
	v_sub_u32_e32 v10, v10, v11
	v_ashrrev_i32_e32 v11, 31, v10
	s_mov_b32 s13, s64
	s_branch .LBB0_55
.LBB0_54:
	s_or_b64 exec, exec, s[6:7]
	s_waitcnt vmcnt(0)
	ds_write2_b32 v16, v2, v6 offset1:32
	ds_write2_b32 v16, v3, v7 offset0:65 offset1:97
	ds_write2_b32 v16, v4, v8 offset0:130 offset1:162
	ds_write2_b32 v16, v5, v9 offset0:195 offset1:227
	s_waitcnt lgkmcnt(0)
	s_barrier
	ds_read2_b32 v[4:5], v18 offset1:7
	ds_read2_b32 v[2:3], v18 offset0:1 offset1:2
	ds_read2_b32 v[6:7], v18 offset0:3 offset1:4
	ds_read2_b32 v[8:9], v18 offset0:5 offset1:6
	s_add_i32 s6, s8, s14
	s_waitcnt lgkmcnt(3)
	v_cvt_pk_bf16_f32 v4, v4, s0
	s_waitcnt lgkmcnt(2)
	v_cvt_pk_bf16_f32 v3, v2, v3
	v_perm_b32 v2, v3, v4, s11
	s_waitcnt lgkmcnt(1)
	v_cvt_pk_bf16_f32 v4, v6, v7
	s_waitcnt lgkmcnt(0)
	v_cvt_pk_bf16_f32 v6, v8, v9
	v_cvt_pk_bf16_f32 v5, v5, s0
	v_alignbit_b32 v3, v4, v3, 16
	v_alignbit_b32 v4, v6, v4, 16
	v_alignbit_b32 v5, v5, v6, 16
	v_add_u32_e32 v6, s4, v1
	v_mad_i64_i32 v[6:7], s[4:5], v6, s12, v[14:15]
	s_ashr_i32 s7, s6, 31
	v_lshl_add_u64 v[6:7], s[6:7], 2, v[6:7]
	s_add_i32 s13, s13, s68
	s_add_i32 s8, s8, s9
	v_lshl_add_u64 v[6:7], v[6:7], 0, v[10:11]
	s_cmpk_lt_i32 s13, 0x580
	global_store_dwordx4 v[6:7], v[2:5], off
	s_barrier
	s_cbranch_scc0 .LBB0_57

; template <bool FINAL>
; __device__ __forceinline__ void norm_phase(const float* __restrict__ src0, const float* __restrict__ src1, const float* __restrict__ gain,
;                            u16* __restrict__ dst, float* __restrict__ dstf) {
;     ...
;   for (int row = blockIdx.x * 4 + wid; row < MT; row += nw) {
;     const float* p = (row < MP) ? src0 + (size_t)row * DM : src1 + (size_t)(row - MP) * DM;
;     float4 v[4];
;     float ss = 0.f;
; #pragma unroll
;     for (int c = 0; c < 4; ++c) {
;       v[c] = ((const float4*)p)[c * 64 + lane];
;       ss += v[c].x * v[c].x + v[c].y * v[c].y + v[c].z * v[c].z + v[c].w * v[c].w;
;     }
; #pragma unroll
;     for (int o = 32; o >= 1; o >>= 1) ss += __shfl_xor(ss, o);
;     const float r = rsqrtf(ss * (1.f / DM) + 1e-6f);
; #pragma unroll
;     for (int c = 0; c < 4; ++c) {
;       float4 g = ((const float4*)gain)[c * 64 + lane];
;       float a = v[c].x * r * g.x, b = v[c].y * r * g.y, cc = v[c].z * r * g.z, d = v[c].w * r * g.w;
;       if (FINAL) {
;         ((float4*)(dstf + (size_t)row * DM))[c * 64 + lane] = make_float4(a, b, cc, d);
;       } else {
;         bf16x4 o;
;         o[0] = (short)f2bf(a); o[1] = (short)f2bf(b); o[2] = (short)f2bf(cc); o[3] = (short)f2bf(d);
;         *(bf16x4*)(dst + (size_t)row * DM + c * 256 + lane * 4) = o;
;       }
;     }
.LBB0_93:
	s_or_b64 exec, exec, s[6:7]
	v_lshl_add_u64 v[28:29], v[28:29], 0, v[20:21]
	global_load_dwordx4 v[38:41], v[28:29], off
	global_load_dwordx4 v[42:45], v[28:29], off offset:1024
	global_load_dwordx4 v[46:49], v[28:29], off offset:2048
	global_load_dwordx4 v[50:53], v[28:29], off offset:3072
	v_lshl_add_u64 v[18:19], v[18:19], 0, s[28:29]
	v_lshlrev_b64 v[26:27], 11, v[26:27]
	v_cmp_lt_i32_e64 s[6:7], s14, v18
	v_lshl_add_u64 v[26:27], v[22:23], 0, v[26:27]
	s_or_b64 s[8:9], s[6:7], s[8:9]
	v_lshl_add_u64 v[24:25], v[24:25], 0, s[2:3]
	s_waitcnt vmcnt(3)
	v_mov_b32_e32 v54, v39
	s_waitcnt vmcnt(2)
	v_mov_b32_e32 v55, v43
	v_mov_b32_e32 v28, v38
	v_mov_b32_e32 v29, v42
	s_waitcnt vmcnt(1)
	v_mov_b32_e32 v62, v47
	s_waitcnt vmcnt(0)
	v_mov_b32_e32 v63, v51
	v_pk_mul_f32 v[54:55], v[54:55], v[54:55]
	v_mov_b32_e32 v56, v40
	v_mov_b32_e32 v57, v44
	v_mov_b32_e32 v60, v46
	v_mov_b32_e32 v61, v50
	v_pk_mul_f32 v[62:63], v[62:63], v[62:63]
	v_pk_fma_f32 v[28:29], v[28:29], v[28:29], v[54:55]
	v_mov_b32_e32 v58, v41
	v_mov_b32_e32 v59, v45
	v_mov_b32_e32 v64, v48
	v_mov_b32_e32 v65, v52
	v_pk_fma_f32 v[54:55], v[60:61], v[60:61], v[62:63]
	v_pk_fma_f32 v[28:29], v[56:57], v[56:57], v[28:29]
	v_mov_b32_e32 v66, v49
	v_mov_b32_e32 v67, v53
	v_pk_fma_f32 v[54:55], v[64:65], v[64:65], v[54:55]
	v_pk_fma_f32 v[28:29], v[58:59], v[58:59], v[28:29]
	v_pk_fma_f32 v[54:55], v[66:67], v[66:67], v[54:55]
	v_add_f32_e32 v28, v28, v29
	v_add_f32_e32 v28, v28, v54
	v_add_f32_e32 v28, v28, v55
	ds_bpermute_b32 v29, v1, v28
	s_waitcnt lgkmcnt(0)
	v_add_f32_e32 v28, v28, v29
	ds_bpermute_b32 v29, v31, v28
	s_waitcnt lgkmcnt(0)
	v_add_f32_e32 v28, v28, v29
	ds_bpermute_b32 v29, v32, v28
	s_waitcnt lgkmcnt(0)
	v_add_f32_e32 v28, v28, v29
	ds_bpermute_b32 v29, v33, v28
	s_waitcnt lgkmcnt(0)
	v_add_f32_e32 v28, v28, v29
	ds_bpermute_b32 v29, v34, v28
	s_waitcnt lgkmcnt(0)
	v_add_f32_e32 v28, v28, v29
	ds_bpermute_b32 v29, v35, v28
	s_waitcnt lgkmcnt(0)
	v_add_f32_e32 v28, v28, v29
	v_fmamk_f32 v28, v28, 0x3a800000, v36
	v_mul_f32_e32 v29, 0x4b800000, v28
	v_cmp_gt_f32_e32 vcc, s13, v28
	s_nop 1
	v_cndmask_b32_e32 v28, v28, v29, vcc
	v_rsq_f32_e32 v28, v28
	s_nop 0
	v_mul_f32_e32 v29, 0x45800000, v28
	v_cndmask_b32_e32 v28, v28, v29, vcc
	v_pk_mul_f32 v[38:39], v[38:39], v[28:29] op_sel_hi:[1,0]
	v_pk_mul_f32 v[40:41], v[40:41], v[28:29] op_sel_hi:[1,0]
	v_pk_mul_f32 v[42:43], v[42:43], v[28:29] op_sel_hi:[1,0]
	v_pk_mul_f32 v[44:45], v[44:45], v[28:29] op_sel_hi:[1,0]
	v_pk_mul_f32 v[46:47], v[46:47], v[28:29] op_sel_hi:[1,0]
	v_pk_mul_f32 v[48:49], v[48:49], v[28:29] op_sel_hi:[1,0]
	v_pk_mul_f32 v[50:51], v[50:51], v[28:29] op_sel_hi:[1,0]
	v_pk_mul_f32 v[28:29], v[52:53], v[28:29] op_sel_hi:[1,0]
	v_pk_mul_f32 v[38:39], v[2:3], v[38:39]
	v_pk_mul_f32 v[40:41], v[4:5], v[40:41]
	v_pk_mul_f32 v[42:43], v[6:7], v[42:43]
	v_pk_mul_f32 v[44:45], v[8:9], v[44:45]
	v_pk_mul_f32 v[46:47], v[10:11], v[46:47]
	v_pk_mul_f32 v[48:49], v[12:13], v[48:49]
	v_pk_mul_f32 v[50:51], v[14:15], v[50:51]
	v_pk_mul_f32 v[28:29], v[16:17], v[28:29]
	v_cvt_pk_bf16_f32 v38, v38, v39
	v_cvt_pk_bf16_f32 v39, v40, v41
	v_cvt_pk_bf16_f32 v40, v42, v43
	v_cvt_pk_bf16_f32 v41, v44, v45
	v_cvt_pk_bf16_f32 v42, v46, v47
	v_cvt_pk_bf16_f32 v43, v48, v49
	v_cvt_pk_bf16_f32 v44, v50, v51
	v_cvt_pk_bf16_f32 v45, v28, v29
	v_lshlrev_b32_e32 v255, 1, v26
	v_bfi_b32 v255, s100, v255, v26
	v_lshrrev_b32_e32 v26, 5, v26
	v_bfi_b32 v26, 64, v26, v255
	global_store_dwordx2 v[26:27], v[38:39], off
	global_store_dwordx2 v[26:27], v[40:41], off offset:1024
	global_store_dwordx2 v[26:27], v[42:43], off offset:2048
	global_store_dwordx2 v[26:27], v[44:45], off offset:3072
	s_andn2_b64 exec, exec, s[8:9]
	s_cbranch_execz .LBB0_96

; __device__ __forceinline__ int opaque_tid() { int t = threadIdx.x; asm volatile("" : "+v"(t)); return t; }
; template <int EPI, int MF>
; __device__ __forceinline__ void gemm_part(const u16* __restrict__ A, int lda, const u16* __restrict__ Bt, int K, int ntn, GemmEpi ep, char* smem,
;                                           int mbase, int mrows) {
;   const int tid = opaque_tid(), lane = tid & 63, wid = tid >> 6, wr = wid >> 1, wc = wid & 1, fr = lane & 15, fq = lane >> 4;
;   constexpr int BM = 32 * MF;
;   constexpr int STG = BM * 32 + 4096;
;   constexpr int NA = MF / 2;
;   u16* const sbase = (u16*)smem;
;   const int ntm = mrows / BM;
;   const int total = ntm * ntn;
;   const int nk = K / 32;
;   const int nbx = (MF == 2) ? (int)gridDim.x : (int)(gridDim.x >> 3);
;   const int xcd = (MF == 2) ? 0 : (int)(blockIdx.x & 7), li = (MF == 2) ? (int)blockIdx.x : (int)(blockIdx.x >> 3);
;   for (int q = xcd; q * nbx < total; q += (MF == 2) ? 1 : 8) {
;     const int L = q * nbx + li;
;     if (L >= total) continue;
;     const int g = L / (8 * ntn), rr = L % (8 * ntn);
;     const int rows = min(8, ntm - 8 * g);
;     const int tm = 8 * g + rr % rows, tn = rr / rows;
;     const int row0 = mbase + tm * BM, col0 = tn * 128;
;     f32x4 acc[MF][4];
; #pragma unroll
;     for (int m = 0; m < MF; ++m)
; #pragma unroll
;       for (int n = 0; n < 4; ++n) acc[m][n] = (f32x4){0.f, 0.f, 0.f, 0.f};
;     const u16* gA = A + (size_t)(row0 + (tid >> 2)) * lda + (tid & 3) * 8;
;     const u16* gB = Bt + (size_t)(col0 + (tid >> 2)) * K + (tid & 3) * 8;
.LBB0_129:
	v_writelane_b32 v254, s4, 63
	s_xor_b64 s[2:3], s[4:5], -1
	v_mov_b32_e32 v2, v140
	v_writelane_b32 v252, s5, 0
	v_writelane_b32 v252, s2, 1
	v_cmp_ne_u32_e64 s[4:5], 1, v203
	s_nop 0
	v_writelane_b32 v252, s3, 2
	s_lshl_b64 s[2:3], s[90:91], 3
	s_add_u32 s2, s96, s2
	s_addc_u32 s3, s97, s3
	v_writelane_b32 v252, s2, 3
	s_nop 1
	v_writelane_b32 v252, s3, 4
	s_load_dwordx2 s[2:3], s[2:3], 0xe0
	v_writelane_b32 v252, s4, 5
	s_nop 1
	v_writelane_b32 v252, s5, 6
	v_readlane_b32 s4, v253, 10
	v_readlane_b32 s5, v253, 11
	s_andn2_b64 vcc, exec, s[4:5]
	s_cbranch_vccnz .LBB0_152
	v_lshlrev_b32_e32 v7, 4, v2
	v_and_b32_e32 v4, 48, v7
	v_mov_b32_e32 v5, v0
	v_bfe_u32 v6, v2, 6, 1
	v_lshl_add_u64 v[130:131], s[44:45], 0, v[4:5]
	s_waitcnt lgkmcnt(0)
	v_lshl_add_u64 v[132:133], s[2:3], 0, v[4:5]
	v_lshlrev_b32_e32 v4, 5, v2
	v_bfe_u32 v3, v2, 4, 2
	v_and_b32_e32 v153, 0xfffff1e0, v4
	v_lshlrev_b32_e32 v4, 6, v6
	v_lshlrev_b32_e32 v134, 3, v3
	v_lshl_add_u64 v[4:5], s[46:47], 0, v[4:5]
	v_mov_b32_e32 v135, v0
	v_ashrrev_i32_e32 v1, 2, v2
	v_and_b32_e32 v154, 0xffffff8f, v2
	v_lshl_add_u64 v[136:137], v[4:5], 0, v[134:135]
	v_and_b32_e32 v8, 1, v140
	v_mul_u32_u24_e32 v8, 0x15c0, v8
	v_bfe_u32 v9, v140, 6, 1
	v_lshlrev_b32_e32 v9, 6, v9
	v_sub_u32_e32 v8, v9, v8
	v_ashrrev_i32_e32 v9, 31, v8
	v_lshl_add_u64 v[136:137], v[136:137], 0, v[8:9]
	v_lshlrev_b32_e32 v135, 12, v6
	v_lshlrev_b32_e32 v4, 6, v2
	v_lshl_add_u32 v3, v3, 4, 0
	v_and_b32_e32 v2, 3, v2
	v_add_u32_e32 v151, 0, v7
	v_and_b32_e32 v155, 0x3c0, v4
	v_lshl_add_u32 v156, v153, 1, v3
	v_add_u32_e32 v4, v3, v135
	v_lshlrev_b32_e32 v2, 4, v2
	v_mov_b32_e32 v3, v0
	v_lshl_add_u64 v[138:139], s[44:45], 0, v[2:3]
	v_add_u32_e32 v157, 0x1000, v151
	v_add_u32_e32 v158, 0x2000, v151
	v_add_u32_e32 v159, 0x3000, v151
	v_add_u32_e32 v160, 0x4000, v151
	v_add_u32_e32 v161, 0x5000, v151
	v_add_u32_e32 v162, 0x6000, v151
	v_add_u32_e32 v163, 0x7000, v151
	v_add_u32_e32 v164, 0x8000, v151
	v_add_u32_e32 v165, 0x9000, v151
	v_add_u32_e32 v166, 0xa000, v151
	v_add_u32_e32 v167, 0xb000, v151
	v_add_u32_e32 v168, v4, v155
	v_readlane_b32 s4, v253, 56
	v_readlane_b32 s10, v253, 9
	s_branch .LBB0_133

; template <int EPI, int MF>
; __device__ __forceinline__ void gemm_part(const u16* __restrict__ A, int lda, const u16* __restrict__ Bt, int K, int ntn, GemmEpi ep, char* smem,
;                                           int mbase, int mrows) {
;     ...
;   for (int q = xcd; q * nbx < total; q += (MF == 2) ? 1 : 8) {
;     const int L = q * nbx + li;
;     if (L >= total) continue;
;     const int g = L / (8 * ntn), rr = L % (8 * ntn);
;     const int rows = min(8, ntm - 8 * g);
;     const int tm = 8 * g + rr % rows, tn = rr / rows;
;     const int row0 = mbase + tm * BM, col0 = tn * 128;
;     f32x4 acc[MF][4];
; #pragma unroll
;     for (int m = 0; m < MF; ++m)
; #pragma unroll
;       for (int n = 0; n < 4; ++n) acc[m][n] = (f32x4){0.f, 0.f, 0.f, 0.f};
;     const u16* gA = A + (size_t)(row0 + (tid >> 2)) * lda + (tid & 3) * 8;
;     const u16* gB = Bt + (size_t)(col0 + (tid >> 2)) * K + (tid & 3) * 8;
;     ...
;     GEMM_ISSUE(0);
;     GEMM_ISSUE(1);
.LBB0_133:
	s_add_i32 s4, s4, s63
	s_cmpk_gt_u32 s4, 0x2bff
	s_cbranch_scc1 .LBB0_132
	s_and_b32 s5, s4, 0xffff
	s_mul_i32 s5, s5, 0xba2f
	s_lshr_b32 s5, s5, 24
	s_mul_i32 s8, s5, 0x160
	s_sub_i32 s4, s4, s8
	s_lshl_b32 s5, s5, 3
	s_and_b32 s8, s4, 7
	s_or_b32 s5, s5, s8
	s_and_b32 s5, s5, 0x7ff
	s_lshl_b32 s9, s5, 8
	v_add_u32_e32 v2, s9, v1
	v_ashrrev_i32_e32 v3, 31, v2
	s_bfe_u32 s8, s4, 0xd0003
	v_lshlrev_b64 v[2:3], 11, v[2:3]
	v_readfirstlane_b32 s4, v151
	v_lshl_add_u64 v[4:5], v[130:131], 0, v[2:3]
	v_lshlrev_b32_e32 v255, 1, v4
	v_bfi_b32 v255, s100, v255, v4
	v_lshrrev_b32_e32 v4, 5, v4
	v_bfi_b32 v4, 64, v4, v255
	s_mov_b32 m0, s4
	s_mov_b64 s[12:13], 0x20000
	v_readfirstlane_b32 s4, v157
	global_load_lds_dwordx4 v[4:5], off
	v_lshl_add_u64 v[8:9], v[4:5], 0, s[12:13]
	s_mov_b32 m0, s4
	s_mov_b64 s[4:5], 0x40000
	global_load_lds_dwordx4 v[8:9], off
	v_lshl_add_u64 v[8:9], v[4:5], 0, s[4:5]
	v_readfirstlane_b32 s4, v158
	v_lshl_add_u32 v6, s8, 7, v1
	s_mov_b32 m0, s4
	s_mov_b64 s[4:5], 0x60000
	v_ashrrev_i32_e32 v7, 31, v6
	global_load_lds_dwordx4 v[8:9], off
	v_lshl_add_u64 v[8:9], v[4:5], 0, s[4:5]
	v_readfirstlane_b32 s4, v159
	v_lshlrev_b64 v[6:7], 11, v[6:7]
	s_mov_b32 m0, s4
	v_readfirstlane_b32 s4, v160
	global_load_lds_dwordx4 v[8:9], off
	v_lshl_add_u64 v[146:147], v[132:133], 0, v[6:7]
	v_lshlrev_b32_e32 v255, 1, v146
	v_bfi_b32 v255, s100, v255, v146
	v_lshrrev_b32_e32 v146, 5, v146
	v_bfi_b32 v146, 64, v146, v255
	s_mov_b32 m0, s4
	v_readfirstlane_b32 s4, v161
	global_load_lds_dwordx4 v[146:147], off
	v_lshl_add_u64 v[6:7], v[146:147], 0, s[12:13]
	s_mov_b32 m0, s4
	v_readfirstlane_b32 s4, v162
	global_load_lds_dwordx4 v[6:7], off
	v_lshl_add_u64 v[6:7], v[4:5], 0, 64
	v_lshl_add_u64 v[6:7], v[6:7], 0, 64
	s_mov_b32 m0, s4
	s_mov_b64 s[12:13], 0x20040
	v_readfirstlane_b32 s4, v163
	global_load_lds_dwordx4 v[6:7], off
	v_lshl_add_u64 v[6:7], v[4:5], 0, s[12:13]
	v_lshl_add_u64 v[6:7], v[6:7], 0, 64
	s_mov_b32 m0, s4
	s_mov_b64 s[4:5], 0x40040
	global_load_lds_dwordx4 v[6:7], off
	v_lshl_add_u64 v[6:7], v[4:5], 0, s[4:5]
	v_lshl_add_u64 v[6:7], v[6:7], 0, 64
	v_readfirstlane_b32 s4, v164
	s_mov_b32 m0, s4
	s_mov_b64 s[4:5], 0x60040
	v_lshl_add_u64 v[4:5], v[4:5], 0, s[4:5]
	v_lshl_add_u64 v[4:5], v[4:5], 0, 64
	v_readfirstlane_b32 s4, v165
	global_load_lds_dwordx4 v[6:7], off
	s_mov_b32 m0, s4
	v_readfirstlane_b32 s4, v166
	global_load_lds_dwordx4 v[4:5], off
	v_lshl_add_u64 v[4:5], v[146:147], 0, 64
	v_lshl_add_u64 v[4:5], v[4:5], 0, 64
	s_mov_b32 m0, s4
	v_readfirstlane_b32 s4, v167
	global_load_lds_dwordx4 v[4:5], off
	v_lshl_add_u64 v[4:5], v[146:147], 0, s[12:13]
	v_lshl_add_u64 v[4:5], v[4:5], 0, 64
	s_mov_b32 m0, s4
	v_lshl_add_u64 v[148:149], v[138:139], 0, v[2:3]
	v_lshlrev_b32_e32 v255, 1, v148
	v_bfi_b32 v255, s100, v255, v148
	v_lshrrev_b32_e32 v148, 5, v148
	v_bfi_b32 v148, 64, v148, v255
	v_lshl_add_u64 v[148:149], v[148:149], 0, 64
	v_lshl_add_u64 v[148:149], v[148:149], 0, 64
	global_load_lds_dwordx4 v[4:5], off
	v_lshl_add_u64 v[146:147], v[146:147], 0, 64
	v_lshl_add_u64 v[146:147], v[146:147], 0, 64
	v_mov_b32_e32 v2, 0
	s_mov_b64 s[4:5], 0
	s_mov_b32 s11, 2
	v_mov_b32_e32 v3, v2
	v_mov_b32_e32 v4, v2
	v_mov_b32_e32 v5, v2
	v_mov_b32_e32 v6, v2
	v_mov_b32_e32 v7, v2
	v_mov_b32_e32 v8, v2
	v_mov_b32_e32 v9, v2
	v_mov_b32_e32 v10, v2
	v_mov_b32_e32 v11, v2
	v_mov_b32_e32 v12, v2
	v_mov_b32_e32 v13, v2
	v_mov_b32_e32 v14, v2
	v_mov_b32_e32 v15, v2
	v_mov_b32_e32 v16, v2
	v_mov_b32_e32 v17, v2
	v_mov_b32_e32 v18, v2
	v_mov_b32_e32 v19, v2
	v_mov_b32_e32 v20, v2
	v_mov_b32_e32 v21, v2
	v_mov_b32_e32 v22, v2
	v_mov_b32_e32 v23, v2
	v_mov_b32_e32 v24, v2
	v_mov_b32_e32 v25, v2
	v_mov_b32_e32 v26, v2
	v_mov_b32_e32 v27, v2
	v_mov_b32_e32 v28, v2
	v_mov_b32_e32 v29, v2
	v_mov_b32_e32 v30, v2
	v_mov_b32_e32 v31, v2
	v_mov_b32_e32 v32, v2
	v_mov_b32_e32 v33, v2
	v_mov_b32_e32 v34, v2
	v_mov_b32_e32 v35, v2
	v_mov_b32_e32 v36, v2
	v_mov_b32_e32 v37, v2
	v_mov_b32_e32 v38, v2
	v_mov_b32_e32 v39, v2
	v_mov_b32_e32 v40, v2
	v_mov_b32_e32 v41, v2
	v_mov_b32_e32 v42, v2
	v_mov_b32_e32 v43, v2
	v_mov_b32_e32 v44, v2
	v_mov_b32_e32 v45, v2
	v_mov_b32_e32 v46, v2
	v_mov_b32_e32 v47, v2
	v_mov_b32_e32 v48, v2
	v_mov_b32_e32 v49, v2
	v_mov_b32_e32 v50, v2
	v_mov_b32_e32 v51, v2
	v_mov_b32_e32 v52, v2
	v_mov_b32_e32 v53, v2
	v_mov_b32_e32 v54, v2
	v_mov_b32_e32 v55, v2
	v_mov_b32_e32 v56, v2
	v_mov_b32_e32 v57, v2
	v_mov_b32_e32 v58, v2
	v_mov_b32_e32 v59, v2
	v_mov_b32_e32 v60, v2
	v_mov_b32_e32 v61, v2
	v_mov_b32_e32 v62, v2
	v_mov_b32_e32 v63, v2
	v_mov_b32_e32 v64, v2
	v_mov_b32_e32 v65, v2
	v_mov_b32_e32 v66, v2
	v_mov_b32_e32 v67, v2
	v_mov_b32_e32 v68, v2
	v_mov_b32_e32 v69, v2
	v_mov_b32_e32 v70, v2
	v_mov_b32_e32 v71, v2
	v_mov_b32_e32 v72, v2
	v_mov_b32_e32 v73, v2
	v_mov_b32_e32 v74, v2
	v_mov_b32_e32 v75, v2
	v_mov_b32_e32 v76, v2
	v_mov_b32_e32 v77, v2
	v_mov_b32_e32 v78, v2
	v_mov_b32_e32 v79, v2
	v_mov_b32_e32 v80, v2
	v_mov_b32_e32 v81, v2
	v_mov_b32_e32 v82, v2
	v_mov_b32_e32 v83, v2
	v_mov_b32_e32 v84, v2
	v_mov_b32_e32 v85, v2
	v_mov_b32_e32 v86, v2
	v_mov_b32_e32 v87, v2
	s_waitcnt vmcnt(0)
	v_mov_b32_e32 v88, v2
	v_mov_b32_e32 v89, v2
	v_mov_b32_e32 v90, v2
	v_mov_b32_e32 v91, v2
	v_mov_b32_e32 v92, v2
	v_mov_b32_e32 v93, v2
	v_mov_b32_e32 v94, v2
	v_mov_b32_e32 v95, v2
	v_mov_b32_e32 v96, v2
	v_mov_b32_e32 v97, v2
	v_mov_b32_e32 v98, v2
	v_mov_b32_e32 v99, v2
	v_mov_b32_e32 v100, v2
	v_mov_b32_e32 v101, v2
	v_mov_b32_e32 v102, v2
	v_mov_b32_e32 v103, v2
	v_mov_b32_e32 v104, v2
	v_mov_b32_e32 v105, v2
	v_mov_b32_e32 v106, v2
	v_mov_b32_e32 v107, v2
	v_mov_b32_e32 v108, v2
	v_mov_b32_e32 v109, v2
	v_mov_b32_e32 v110, v2
	v_mov_b32_e32 v111, v2
	v_mov_b32_e32 v112, v2
	v_mov_b32_e32 v113, v2
	v_mov_b32_e32 v114, v2
	v_mov_b32_e32 v115, v2
	v_mov_b32_e32 v116, v2
	v_mov_b32_e32 v117, v2
	v_mov_b32_e32 v118, v2
	v_mov_b32_e32 v119, v2
	v_mov_b32_e32 v120, v2
	v_mov_b32_e32 v121, v2
	v_mov_b32_e32 v122, v2
	v_mov_b32_e32 v123, v2
	v_mov_b32_e32 v124, v2
	v_mov_b32_e32 v125, v2
	v_mov_b32_e32 v126, v2
	v_mov_b32_e32 v127, v2
	v_mov_b32_e32 v128, v2
	v_mov_b32_e32 v129, v2
; #define MFMA(a, b, c) __builtin_amdgcn_mfma_f32_16x16x32_bf16((a), (b), (c), 0, 0, 0)
; template <int EPI, int MF>
; __device__ __forceinline__ void gemm_part(const u16* __restrict__ A, int lda, const u16* __restrict__ Bt, int K, int ntn, GemmEpi ep, char* smem,
;                                           int mbase, int mrows) {
;     ...
;     for (int kt = 0; kt < nk; ++kt) {
;       if (kt + 1 < nk) {
;         if (MF == 8) asm volatile("s_waitcnt vmcnt(6)" ::: "memory");
;         else asm volatile("s_waitcnt vmcnt(3)" ::: "memory");
;       } else asm volatile("s_waitcnt vmcnt(0)" ::: "memory");
;       asm volatile("s_waitcnt lgkmcnt(0)" ::: "memory");
;       __builtin_amdgcn_s_barrier();
;       const u16* a_ = sbase + (kt % 3) * STG;
;       const u16* b_ = a_ + BM * 32;
;       bf16x8 bfr[4], afc[2], afn[2];
;       const u16* ap_ = a_ + (wr * (16 * MF) + fr) * 32 + fq * 8;
; #pragma unroll
;       for (int n = 0; n < 4; ++n) bfr[n] = rd_std(b_ + (wc * 64 + n * 16 + fr) * 32 + fq * 8);
;       afc[0] = rd_std(ap_); afc[1] = rd_std(ap_ + 16 * 32);
;       __builtin_amdgcn_sched_barrier(0);
;       if (kt + 2 < nk) GEMM_ISSUE(kt + 2);
;       __builtin_amdgcn_sched_barrier(0);
; #pragma unroll
;       for (int mh = 0; mh < MF / 2; ++mh) {
;         if (mh + 1 < MF / 2) {
;           afn[0] = rd_std(ap_ + ((mh + 1) * 2) * 16 * 32);
;           afn[1] = rd_std(ap_ + ((mh + 1) * 2 + 1) * 16 * 32);
;         }
;         __builtin_amdgcn_sched_barrier(0);
; #pragma unroll
;         for (int m = 0; m < 2; ++m)
; #pragma unroll
;           for (int n = 0; n < 4; ++n) acc[mh * 2 + m][n] = MFMA(bfr[n], afc[m], acc[mh * 2 + m][n]);
;         __builtin_amdgcn_sched_barrier(0);
;         afc[0] = afn[0]; afc[1] = afn[1];
;       }
;     }
.LBB0_135:
	s_mul_i32 s12, s11, 0xab
	s_add_i32 s13, s12, 0xfeaa
	s_bfe_u32 s13, s13, 0x70009
	s_mul_i32 s13, s13, 3
	s_sub_i32 s13, s11, s13
	s_add_i32 s13, s13, 0xfffe
	s_and_b32 s13, s13, 0xff
	s_mulk_i32 s13, 0x6000
	s_add_i32 s13, s13, 0
	v_lshl_add_u32 v150, v134, 1, s13
	s_waitcnt vmcnt(6)
	v_add3_u32 v152, v150, v135, v155
	s_waitcnt lgkmcnt(0)
	s_barrier
	ds_read_b128 v[170:173], v152 offset:16384
	ds_read_b128 v[174:177], v152 offset:17408
	ds_read_b128 v[178:181], v152 offset:18432
	ds_read_b128 v[182:185], v152 offset:19456
	v_lshl_add_u32 v150, v153, 1, v150
	ds_read_b128 v[186:189], v150
	ds_read_b128 v[190:193], v150 offset:1024
	s_bfe_u32 s12, s12, 0x70009
	s_mul_i32 s12, s12, 3
	s_sub_i32 s12, s11, s12
	s_and_b32 s12, s12, 0xff
	s_mulk_i32 s12, 0x6000
	v_add_u32_e32 v152, s12, v151
	v_lshl_add_u64 v[194:195], s[4:5], 1, v[148:149]
	v_readfirstlane_b32 s12, v152
	v_add_u32_e32 v169, 0x1000, v152
	v_lshl_add_u64 v[196:197], v[194:195], 0, s[74:75]
	s_mov_b32 m0, s12
	v_readfirstlane_b32 s12, v169
	v_add_u32_e32 v169, 0x2000, v152
	global_load_lds_dwordx4 v[196:197], off
	v_lshl_add_u64 v[196:197], v[194:195], 0, s[92:93]
	s_mov_b32 m0, s12
	v_readfirstlane_b32 s12, v169
	v_add_u32_e32 v169, 0x3000, v152
	global_load_lds_dwordx4 v[196:197], off
	v_lshl_add_u64 v[196:197], v[194:195], 0, s[88:89]
	s_mov_b32 m0, s12
	v_readfirstlane_b32 s12, v169
	global_load_lds_dwordx4 v[196:197], off
	v_lshl_add_u64 v[194:195], v[194:195], 0, s[6:7]
	s_mov_b32 m0, s12
	v_add_u32_e32 v169, 0x4000, v152
	global_load_lds_dwordx4 v[194:195], off
	v_lshl_add_u64 v[194:195], s[4:5], 1, v[146:147]
	v_readfirstlane_b32 s12, v169
	v_add_u32_e32 v152, 0x5000, v152
	v_lshl_add_u64 v[196:197], v[194:195], 0, s[74:75]
	s_mov_b32 m0, s12
	v_readfirstlane_b32 s12, v152
	global_load_lds_dwordx4 v[196:197], off
	v_lshl_add_u64 v[194:195], v[194:195], 0, s[92:93]
	s_mov_b32 m0, s12
	s_nop 0
	global_load_lds_dwordx4 v[194:195], off
	ds_read_b128 v[194:197], v150 offset:2048
	ds_read_b128 v[210:213], v150 offset:3072
	s_waitcnt lgkmcnt(0)
	v_mfma_f32_16x16x32_bf16 v[126:129], v[170:173], v[186:189], v[126:129]
	v_mfma_f32_16x16x32_bf16 v[122:125], v[174:177], v[186:189], v[122:125]
	v_mfma_f32_16x16x32_bf16 v[118:121], v[178:181], v[186:189], v[118:121]
	v_mfma_f32_16x16x32_bf16 v[114:117], v[182:185], v[186:189], v[114:117]
	v_mfma_f32_16x16x32_bf16 v[110:113], v[170:173], v[190:193], v[110:113]
	v_mfma_f32_16x16x32_bf16 v[106:109], v[174:177], v[190:193], v[106:109]
	v_mfma_f32_16x16x32_bf16 v[102:105], v[178:181], v[190:193], v[102:105]
	v_mfma_f32_16x16x32_bf16 v[98:101], v[182:185], v[190:193], v[98:101]
	ds_read_b128 v[186:189], v150 offset:4096
	ds_read_b128 v[190:193], v150 offset:5120
	v_mfma_f32_16x16x32_bf16 v[94:97], v[170:173], v[194:197], v[94:97]
	v_mfma_f32_16x16x32_bf16 v[90:93], v[174:177], v[194:197], v[90:93]
	v_mfma_f32_16x16x32_bf16 v[86:89], v[178:181], v[194:197], v[86:89]
	v_mfma_f32_16x16x32_bf16 v[82:85], v[182:185], v[194:197], v[82:85]
	v_mfma_f32_16x16x32_bf16 v[78:81], v[170:173], v[210:213], v[78:81]
	v_mfma_f32_16x16x32_bf16 v[74:77], v[174:177], v[210:213], v[74:77]
	v_mfma_f32_16x16x32_bf16 v[70:73], v[178:181], v[210:213], v[70:73]
	v_mfma_f32_16x16x32_bf16 v[66:69], v[182:185], v[210:213], v[66:69]
	ds_read_b128 v[194:197], v150 offset:6144
	ds_read_b128 v[210:213], v150 offset:7168
	s_waitcnt lgkmcnt(0)
	v_mfma_f32_16x16x32_bf16 v[62:65], v[170:173], v[186:189], v[62:65]
	v_mfma_f32_16x16x32_bf16 v[58:61], v[174:177], v[186:189], v[58:61]
	v_mfma_f32_16x16x32_bf16 v[54:57], v[178:181], v[186:189], v[54:57]
	v_mfma_f32_16x16x32_bf16 v[50:53], v[182:185], v[186:189], v[50:53]
	v_mfma_f32_16x16x32_bf16 v[46:49], v[170:173], v[190:193], v[46:49]
	v_mfma_f32_16x16x32_bf16 v[42:45], v[174:177], v[190:193], v[42:45]
	v_mfma_f32_16x16x32_bf16 v[38:41], v[178:181], v[190:193], v[38:41]
	v_mfma_f32_16x16x32_bf16 v[34:37], v[182:185], v[190:193], v[34:37]
	v_mfma_f32_16x16x32_bf16 v[30:33], v[170:173], v[194:197], v[30:33]
	v_mfma_f32_16x16x32_bf16 v[26:29], v[174:177], v[194:197], v[26:29]
	v_mfma_f32_16x16x32_bf16 v[22:25], v[178:181], v[194:197], v[22:25]
	v_mfma_f32_16x16x32_bf16 v[18:21], v[182:185], v[194:197], v[18:21]
	v_mfma_f32_16x16x32_bf16 v[14:17], v[170:173], v[210:213], v[14:17]
	v_mfma_f32_16x16x32_bf16 v[10:13], v[174:177], v[210:213], v[10:13]
	v_mfma_f32_16x16x32_bf16 v[6:9], v[178:181], v[210:213], v[6:9]
	v_mfma_f32_16x16x32_bf16 v[2:5], v[182:185], v[210:213], v[2:5]
	s_add_u32 s4, s4, 64
	s_addc_u32 s5, s5, 0
	s_add_i32 s11, s11, 1
	s_cmpk_eq_i32 s4, 0x780
	s_cbranch_scc0 .LBB0_135
	s_waitcnt vmcnt(6)
	s_waitcnt lgkmcnt(0)
	s_barrier
; #define MFMA(a, b, c) __builtin_amdgcn_mfma_f32_16x16x32_bf16((a), (b), (c), 0, 0, 0)
; template <int EPI, int MF>
; __device__ __forceinline__ void gemm_part(const u16* __restrict__ A, int lda, const u16* __restrict__ Bt, int K, int ntn, GemmEpi ep, char* smem,
;                                           int mbase, int mrows) {
;     ...
;     for (int kt = 0; kt < nk; ++kt) {
;       if (kt + 1 < nk) {
;         if (MF == 8) asm volatile("s_waitcnt vmcnt(6)" ::: "memory");
;         else asm volatile("s_waitcnt vmcnt(3)" ::: "memory");
;       } else asm volatile("s_waitcnt vmcnt(0)" ::: "memory");
;       asm volatile("s_waitcnt lgkmcnt(0)" ::: "memory");
;       __builtin_amdgcn_s_barrier();
;       const u16* a_ = sbase + (kt % 3) * STG;
;       const u16* b_ = a_ + BM * 32;
;       bf16x8 bfr[4], afc[2], afn[2];
;       const u16* ap_ = a_ + (wr * (16 * MF) + fr) * 32 + fq * 8;
; #pragma unroll
;       for (int n = 0; n < 4; ++n) bfr[n] = rd_std(b_ + (wc * 64 + n * 16 + fr) * 32 + fq * 8);
;       afc[0] = rd_std(ap_); afc[1] = rd_std(ap_ + 16 * 32);
;       __builtin_amdgcn_sched_barrier(0);
;       if (kt + 2 < nk) GEMM_ISSUE(kt + 2);
;       __builtin_amdgcn_sched_barrier(0);
; #pragma unroll
;       for (int mh = 0; mh < MF / 2; ++mh) {
;         if (mh + 1 < MF / 2) {
;           afn[0] = rd_std(ap_ + ((mh + 1) * 2) * 16 * 32);
;           afn[1] = rd_std(ap_ + ((mh + 1) * 2 + 1) * 16 * 32);
;         }
;         __builtin_amdgcn_sched_barrier(0);
; #pragma unroll
;         for (int m = 0; m < 2; ++m)
; #pragma unroll
;           for (int n = 0; n < 4; ++n) acc[mh * 2 + m][n] = MFMA(bfr[n], afc[m], acc[mh * 2 + m][n]);
;         __builtin_amdgcn_sched_barrier(0);
;         afc[0] = afn[0]; afc[1] = afn[1];
;       }
;     }
;     ...
;     __syncthreads();
; #pragma unroll
;     for (int m = 0; m < MF; ++m) {
;       if (EPI == EPI_SWIGLU || (m & 1) == 0) __builtin_amdgcn_sched_barrier(0);
;       const int row = row0 + wr * (16 * MF) + m * 16 + fr;
;       const int cb = col0 + wc * 64 + 4 * fq;
;       float rstd = 1.f;
;       if (EPI != EPI_RESID) { if (ep.rss_in) rstd = rsqrtf(ep.rss_in[row] * (1.f / DM) + 1e-6f); }
	ds_read_b128 v[146:149], v168 offset:16384
	ds_read_b128 v[170:173], v168 offset:17408
	ds_read_b128 v[174:177], v168 offset:18432
	ds_read_b128 v[178:181], v168 offset:19456
	ds_read_b128 v[182:185], v156
	ds_read_b128 v[186:189], v156 offset:1024
	ds_read_b128 v[190:193], v156 offset:2048
	ds_read_b128 v[194:197], v156 offset:3072
	s_waitcnt lgkmcnt(0)
	v_mfma_f32_16x16x32_bf16 v[126:129], v[146:149], v[182:185], v[126:129]
	v_mfma_f32_16x16x32_bf16 v[122:125], v[170:173], v[182:185], v[122:125]
	v_mfma_f32_16x16x32_bf16 v[114:117], v[178:181], v[182:185], v[114:117]
	v_mfma_f32_16x16x32_bf16 v[110:113], v[146:149], v[186:189], v[110:113]
	v_mfma_f32_16x16x32_bf16 v[106:109], v[170:173], v[186:189], v[106:109]
	v_mfma_f32_16x16x32_bf16 v[98:101], v[178:181], v[186:189], v[98:101]
	v_mfma_f32_16x16x32_bf16 v[210:213], v[174:177], v[182:185], v[118:121]
	v_mfma_f32_16x16x32_bf16 v[182:185], v[174:177], v[186:189], v[102:105]
	s_nop 2
	ds_read_b128 v[102:105], v156 offset:4096
	ds_read_b128 v[118:121], v156 offset:5120
	v_mfma_f32_16x16x32_bf16 v[94:97], v[146:149], v[190:193], v[94:97]
	v_mfma_f32_16x16x32_bf16 v[90:93], v[170:173], v[190:193], v[90:93]
	v_mfma_f32_16x16x32_bf16 v[82:85], v[178:181], v[190:193], v[82:85]
	v_mfma_f32_16x16x32_bf16 v[78:81], v[146:149], v[194:197], v[78:81]
	v_mfma_f32_16x16x32_bf16 v[74:77], v[170:173], v[194:197], v[74:77]
	v_mfma_f32_16x16x32_bf16 v[66:69], v[178:181], v[194:197], v[66:69]
	v_mfma_f32_16x16x32_bf16 v[186:189], v[174:177], v[190:193], v[86:89]
	v_mfma_f32_16x16x32_bf16 v[190:193], v[174:177], v[194:197], v[70:73]
	s_nop 2
	ds_read_b128 v[70:73], v156 offset:6144
	ds_read_b128 v[86:89], v156 offset:7168
	s_waitcnt lgkmcnt(0)
	v_mfma_f32_16x16x32_bf16 v[62:65], v[146:149], v[102:105], v[62:65]
	v_mfma_f32_16x16x32_bf16 v[58:61], v[170:173], v[102:105], v[58:61]
	v_mfma_f32_16x16x32_bf16 v[50:53], v[178:181], v[102:105], v[50:53]
	v_mfma_f32_16x16x32_bf16 v[46:49], v[146:149], v[118:121], v[46:49]
	v_mfma_f32_16x16x32_bf16 v[42:45], v[170:173], v[118:121], v[42:45]
	v_mfma_f32_16x16x32_bf16 v[34:37], v[178:181], v[118:121], v[34:37]
	v_mfma_f32_16x16x32_bf16 v[194:197], v[174:177], v[102:105], v[54:57]
	v_mfma_f32_16x16x32_bf16 v[214:217], v[174:177], v[118:121], v[38:41]
	v_mfma_f32_16x16x32_bf16 v[30:33], v[146:149], v[70:73], v[30:33]
	v_mfma_f32_16x16x32_bf16 v[26:29], v[170:173], v[70:73], v[26:29]
	v_mfma_f32_16x16x32_bf16 v[18:21], v[178:181], v[70:73], v[18:21]
	v_mfma_f32_16x16x32_bf16 v[14:17], v[146:149], v[86:89], v[14:17]
	v_mfma_f32_16x16x32_bf16 v[10:13], v[170:173], v[86:89], v[10:13]
	v_mfma_f32_16x16x32_bf16 v[146:149], v[174:177], v[86:89], v[6:9]
	v_mfma_f32_16x16x32_bf16 v[2:5], v[178:181], v[86:89], v[2:5]
	v_mfma_f32_16x16x32_bf16 v[218:221], v[174:177], v[70:73], v[22:25]
	s_waitcnt vmcnt(0)
	s_waitcnt lgkmcnt(0)
	s_barrier
	ds_read_b128 v[6:9], v168 offset:40960
	ds_read_b128 v[170:173], v168 offset:41984
	ds_read_b128 v[174:177], v168 offset:43008
	ds_read_b128 v[178:181], v168 offset:44032
	ds_read_b128 v[22:25], v156 offset:24576
	ds_read_b128 v[38:41], v156 offset:25600
	ds_read_b128 v[54:57], v156 offset:26624
	ds_read_b128 v[222:225], v156 offset:27648
	s_waitcnt lgkmcnt(0)
	v_mfma_f32_16x16x32_bf16 v[126:129], v[6:9], v[22:25], v[126:129]
	v_mfma_f32_16x16x32_bf16 v[118:121], v[170:173], v[22:25], v[122:125]
	v_mfma_f32_16x16x32_bf16 v[122:125], v[174:177], v[22:25], v[210:213]
	v_mfma_f32_16x16x32_bf16 v[114:117], v[178:181], v[22:25], v[114:117]
	v_mfma_f32_16x16x32_bf16 v[110:113], v[6:9], v[38:41], v[110:113]
	v_mfma_f32_16x16x32_bf16 v[102:105], v[170:173], v[38:41], v[106:109]
	v_mfma_f32_16x16x32_bf16 v[106:109], v[174:177], v[38:41], v[182:185]
	v_mfma_f32_16x16x32_bf16 v[98:101], v[178:181], v[38:41], v[98:101]
	ds_read_b128 v[22:25], v156 offset:28672
	s_nop 0
	ds_read_b128 v[182:185], v156 offset:29696
	v_mfma_f32_16x16x32_bf16 v[94:97], v[6:9], v[54:57], v[94:97]
	v_mfma_f32_16x16x32_bf16 v[86:89], v[170:173], v[54:57], v[90:93]
	v_mfma_f32_16x16x32_bf16 v[90:93], v[174:177], v[54:57], v[186:189]
	v_mfma_f32_16x16x32_bf16 v[82:85], v[178:181], v[54:57], v[82:85]
	v_mfma_f32_16x16x32_bf16 v[78:81], v[6:9], v[222:225], v[78:81]
	v_mfma_f32_16x16x32_bf16 v[70:73], v[170:173], v[222:225], v[74:77]
	v_mfma_f32_16x16x32_bf16 v[74:77], v[174:177], v[222:225], v[190:193]
	v_mfma_f32_16x16x32_bf16 v[66:69], v[178:181], v[222:225], v[66:69]
	ds_read_b128 v[186:189], v156 offset:30720
	s_nop 0
	ds_read_b128 v[190:193], v156 offset:31744
	s_waitcnt lgkmcnt(0)
	v_mfma_f32_16x16x32_bf16 v[62:65], v[6:9], v[22:25], v[62:65]
	v_mfma_f32_16x16x32_bf16 v[54:57], v[170:173], v[22:25], v[58:61]
	v_mfma_f32_16x16x32_bf16 v[58:61], v[174:177], v[22:25], v[194:197]
	v_mfma_f32_16x16x32_bf16 v[50:53], v[178:181], v[22:25], v[50:53]
	v_mfma_f32_16x16x32_bf16 v[46:49], v[6:9], v[182:185], v[46:49]
	v_mfma_f32_16x16x32_bf16 v[38:41], v[170:173], v[182:185], v[42:45]
	v_mfma_f32_16x16x32_bf16 v[42:45], v[174:177], v[182:185], v[214:217]
	v_mfma_f32_16x16x32_bf16 v[34:37], v[178:181], v[182:185], v[34:37]
	v_mfma_f32_16x16x32_bf16 v[30:33], v[6:9], v[186:189], v[30:33]
	v_mfma_f32_16x16x32_bf16 v[22:25], v[170:173], v[186:189], v[26:29]
	v_mfma_f32_16x16x32_bf16 v[26:29], v[174:177], v[186:189], v[218:221]
	v_mfma_f32_16x16x32_bf16 v[18:21], v[178:181], v[186:189], v[18:21]
	v_mfma_f32_16x16x32_bf16 v[14:17], v[6:9], v[190:193], v[14:17]
	v_mfma_f32_16x16x32_bf16 v[6:9], v[170:173], v[190:193], v[10:13]
	v_mfma_f32_16x16x32_bf16 v[10:13], v[174:177], v[190:193], v[146:149]
	v_mfma_f32_16x16x32_bf16 v[2:5], v[178:181], v[190:193], v[2:5]
	s_nop 1
	v_add_u32_e32 v146, s9, v154
	s_waitcnt vmcnt(0)
	s_barrier
	v_readlane_b32 s4, v252, 1
	v_readlane_b32 s5, v252, 2
	v_ashrrev_i32_e32 v147, 31, v146
	v_mov_b32_e32 v150, 1.0
	s_and_b64 vcc, exec, s[4:5]
	v_mov_b32_e32 v152, 1.0
	s_cbranch_vccz .LBB0_138
	v_lshl_add_u64 v[148:149], v[146:147], 2, s[14:15]
	global_load_dword v147, v[148:149], off
	s_waitcnt vmcnt(0)
	v_fmamk_f32 v147, v147, 0x3a800000, v142
	v_mul_f32_e32 v148, 0x4b800000, v147
	v_cmp_gt_f32_e32 vcc, s69, v147
	s_nop 1
	v_cndmask_b32_e32 v147, v147, v148, vcc
	v_rsq_f32_e32 v147, v147
	s_nop 0
	v_mul_f32_e32 v148, 0x45800000, v147
	v_cndmask_b32_e32 v152, v147, v148, vcc
; __device__ __forceinline__ float siluf_(float x) { return x * __builtin_amdgcn_rcpf(1.f + __expf(-x)); }
; template <int EPI, int MF>
; __device__ __forceinline__ void gemm_part(const u16* __restrict__ A, int lda, const u16* __restrict__ Bt, int K, int ntn, GemmEpi ep, char* smem,
;                                           int mbase, int mrows) {
;     ...
;       if (EPI == EPI_SWIGLU || (m & 1) == 0) __builtin_amdgcn_sched_barrier(0);
;       const int row = row0 + wr * (16 * MF) + m * 16 + fr;
;       const int cb = col0 + wc * 64 + 4 * fq;
;       float rstd = 1.f;
;       if (EPI != EPI_RESID) { if (ep.rss_in) rstd = rsqrtf(ep.rss_in[row] * (1.f / DM) + 1e-6f); }
;       if (EPI == EPI_SWIGLU) {
; #pragma unroll
;         for (int n = 0; n < 2; ++n) {
;           bf16x4 o;
; #pragma unroll
;           for (int jj = 0; jj < 4; ++jj) o[jj] = (short)f2bf(siluf_(acc[m][n][jj] * rstd) * (acc[m][n + 2][jj] * rstd));
;           *(bf16x4*)(ep.outb + (size_t)row * FF + (col0 >> 1) + wc * 32 + n * 16 + 4 * fq) = o;
;         }
.LBB0_138:
	v_pk_mul_f32 v[126:127], v[126:127], v[152:153] op_sel_hi:[1,0]
	v_pk_mul_f32 v[122:123], v[122:123], v[152:153] op_sel_hi:[1,0]
	v_mul_f32_e32 v147, 0xbfb8aa3b, v126
	v_exp_f32_e32 v147, v147
	s_lshl_b32 s90, s8, 8
	v_pk_mul_f32 v[124:125], v[124:125], v[152:153] op_sel_hi:[1,0]
	v_lshl_add_u64 v[148:149], v[136:137], 0, s[90:91]
	v_add_f32_e32 v147, 1.0, v147
	v_rcp_f32_e32 v172, v147
	v_mul_f32_e32 v147, 0xbfb8aa3b, v127
	v_exp_f32_e32 v147, v147
	v_mad_i64_i32 v[170:171], s[4:5], v146, s33, v[148:149]
	v_pk_mul_f32 v[118:119], v[118:119], v[152:153] op_sel_hi:[1,0]
	v_add_f32_e32 v147, 1.0, v147
	v_rcp_f32_e32 v173, v147
	v_pk_mul_f32 v[114:115], v[114:115], v[152:153] op_sel_hi:[1,0]
	v_pk_mul_f32 v[116:117], v[116:117], v[152:153] op_sel_hi:[1,0]
	v_pk_mul_f32 v[126:127], v[126:127], v[172:173]
	s_nop 0
	v_pk_mul_f32 v[122:123], v[122:123], v[126:127]
	v_pk_mul_f32 v[126:127], v[128:129], v[152:153] op_sel_hi:[1,0]
	v_cvt_pk_bf16_f32 v122, v122, v123
	v_mul_f32_e32 v123, 0xbfb8aa3b, v126
	v_exp_f32_e32 v123, v123
	s_nop 0
	v_add_f32_e32 v123, 1.0, v123
	v_rcp_f32_e32 v128, v123
	v_mul_f32_e32 v123, 0xbfb8aa3b, v127
	v_exp_f32_e32 v123, v123
	s_nop 0
	v_add_f32_e32 v123, 1.0, v123
	v_rcp_f32_e32 v129, v123
	s_nop 0
	v_pk_mul_f32 v[126:127], v[126:127], v[128:129]
	s_nop 0
	v_pk_mul_f32 v[124:125], v[124:125], v[126:127]
	s_nop 0
	v_cvt_pk_bf16_f32 v123, v124, v125
	global_store_dwordx2 v[170:171], v[122:123], off
	v_mul_f32_e32 v122, 0xbfb8aa3b, v118
	v_mul_f32_e32 v123, 0xbfb8aa3b, v119
	v_exp_f32_e32 v122, v122
	v_exp_f32_e32 v123, v123
	v_add_f32_e32 v122, 1.0, v122
	v_add_f32_e32 v123, 1.0, v123
	v_rcp_f32_e32 v122, v122
	v_rcp_f32_e32 v123, v123
	s_nop 0
	v_pk_mul_f32 v[118:119], v[118:119], v[122:123]
	s_nop 0
	v_pk_mul_f32 v[114:115], v[114:115], v[118:119]
	v_pk_mul_f32 v[118:119], v[120:121], v[152:153] op_sel_hi:[1,0]
	v_cvt_pk_bf16_f32 v114, v114, v115
	v_mul_f32_e32 v115, 0xbfb8aa3b, v118
	v_exp_f32_e32 v115, v115
	s_nop 0
	v_add_f32_e32 v115, 1.0, v115
	v_rcp_f32_e32 v120, v115
	v_mul_f32_e32 v115, 0xbfb8aa3b, v119
	v_exp_f32_e32 v115, v115
	s_nop 0
	v_add_f32_e32 v115, 1.0, v115
	v_rcp_f32_e32 v121, v115
	s_nop 0
	v_pk_mul_f32 v[118:119], v[118:119], v[120:121]
	s_nop 0
	v_pk_mul_f32 v[116:117], v[116:117], v[118:119]
	s_nop 0
	v_cvt_pk_bf16_f32 v115, v116, v117
	global_store_dwordx2 v[170:171], v[114:115], off offset:32
	v_readlane_b32 s4, v252, 1
	v_readlane_b32 s5, v252, 2
	v_or_b32_e32 v114, 16, v146
	s_andn2_b64 vcc, exec, s[4:5]
	v_cndmask_b32_e64 v115, 0, 1, s[4:5]
	v_cmp_ne_u32_e64 s[8:9], 1, v115
	v_ashrrev_i32_e32 v115, 31, v114
	s_cbranch_vccnz .LBB0_140
	v_lshl_add_u64 v[116:117], v[114:115], 2, s[14:15]
	global_load_dword v115, v[116:117], off
	s_waitcnt vmcnt(0)
	v_fmamk_f32 v115, v115, 0x3a800000, v142
	v_mul_f32_e32 v116, 0x4b800000, v115
	v_cmp_gt_f32_e32 vcc, s69, v115
	s_nop 1
	v_cndmask_b32_e32 v115, v115, v116, vcc
	v_rsq_f32_e32 v115, v115
	s_nop 0
	v_mul_f32_e32 v116, 0x45800000, v115
	v_cndmask_b32_e32 v150, v115, v116, vcc

; __device__ __forceinline__ int opaque_tid() { int t = threadIdx.x; asm volatile("" : "+v"(t)); return t; }
; template <int EPI, int MF>
; __device__ __forceinline__ void gemm_part(const u16* __restrict__ A, int lda, const u16* __restrict__ Bt, int K, int ntn, GemmEpi ep, char* smem,
;                                           int mbase, int mrows) {
;   const int tid = opaque_tid(), lane = tid & 63, wid = tid >> 6, wr = wid >> 1, wc = wid & 1, fr = lane & 15, fq = lane >> 4;
;   constexpr int BM = 32 * MF;
;   constexpr int STG = BM * 32 + 4096;
;   constexpr int NA = MF / 2;
;   u16* const sbase = (u16*)smem;
;   const int ntm = mrows / BM;
;   const int total = ntm * ntn;
;   const int nk = K / 32;
;   const int nbx = (MF == 2) ? (int)gridDim.x : (int)(gridDim.x >> 3);
;   const int xcd = (MF == 2) ? 0 : (int)(blockIdx.x & 7), li = (MF == 2) ? (int)blockIdx.x : (int)(blockIdx.x >> 3);
;   for (int q = xcd; q * nbx < total; q += (MF == 2) ? 1 : 8) {
;     const int L = q * nbx + li;
;     if (L >= total) continue;
;     const int g = L / (8 * ntn), rr = L % (8 * ntn);
;     const int rows = min(8, ntm - 8 * g);
;     const int tm = 8 * g + rr % rows, tn = rr / rows;
;     const int row0 = mbase + tm * BM, col0 = tn * 128;
;     f32x4 acc[MF][4];
; #pragma unroll
;     for (int m = 0; m < MF; ++m)
; #pragma unroll
;       for (int n = 0; n < 4; ++n) acc[m][n] = (f32x4){0.f, 0.f, 0.f, 0.f};
;     const u16* gA = A + (size_t)(row0 + (tid >> 2)) * lda + (tid & 3) * 8;
;     const u16* gB = Bt + (size_t)(col0 + (tid >> 2)) * K + (tid & 3) * 8;
.LBB0_152:
	v_mov_b32_e32 v4, v140
	v_mov_b32_e32 v3, v0
	v_lshlrev_b32_e32 v9, 4, v4
	v_bfe_u32 v6, v4, 6, 1
	v_and_b32_e32 v2, 48, v9
	v_ashrrev_i32_e32 v5, 7, v4
	v_bfe_u32 v8, v4, 4, 2
	v_lshl_add_u64 v[34:35], s[44:45], 0, v[2:3]
	s_waitcnt lgkmcnt(0)
	v_lshl_add_u64 v[36:37], s[2:3], 0, v[2:3]
	v_lshlrev_b32_e32 v2, 6, v6
	v_and_b32_e32 v7, 15, v4
	v_lshlrev_b32_e32 v52, 11, v5
	v_lshlrev_b32_e32 v38, 3, v8
	v_lshl_add_u64 v[2:3], s[46:47], 0, v[2:3]
	v_mov_b32_e32 v39, v0
	v_lshlrev_b32_e32 v53, 6, v7
	v_lshl_add_u64 v[40:41], v[2:3], 0, v[38:39]
	v_and_b32_e32 v10, 1, v140
	v_mul_u32_u24_e32 v10, 0x15c0, v10
	v_bfe_u32 v11, v140, 6, 1
	v_lshlrev_b32_e32 v11, 6, v11
	v_sub_u32_e32 v10, v11, v10
	v_ashrrev_i32_e32 v11, 31, v10
	v_lshl_add_u64 v[40:41], v[40:41], 0, v[10:11]
	v_add_u32_e32 v2, 0, v52
	v_lshlrev_b32_e32 v3, 4, v8
	v_lshl_or_b32 v54, v5, 5, v7
	v_lshlrev_b32_e32 v39, 12, v6
	v_add_u32_e32 v5, 0, v3
	v_add3_u32 v55, v2, v53, v3
	v_and_b32_e32 v2, 3, v4
	v_add_u32_e32 v6, v5, v53
	v_add_u32_e32 v5, v5, v39
	v_lshlrev_b32_e32 v2, 4, v2
	v_mov_b32_e32 v3, v0
	v_ashrrev_i32_e32 v1, 2, v4
	v_add_u32_e32 v51, 0, v9
	v_lshl_add_u64 v[42:43], s[44:45], 0, v[2:3]
	s_mov_b32 s2, 0
	v_add_u32_e32 v56, v5, v53
	v_add_u32_e32 v57, v6, v39
	s_mov_b32 s4, 0
	s_branch .LBB0_155

; template <int EPI, int MF>
; __device__ __forceinline__ void gemm_part(const u16* __restrict__ A, int lda, const u16* __restrict__ Bt, int K, int ntn, GemmEpi ep, char* smem,
;                                           int mbase, int mrows) {
;     ...
;   for (int q = xcd; q * nbx < total; q += (MF == 2) ? 1 : 8) {
;     const int L = q * nbx + li;
;     if (L >= total) continue;
;     const int g = L / (8 * ntn), rr = L % (8 * ntn);
;     const int rows = min(8, ntm - 8 * g);
;     const int tm = 8 * g + rr % rows, tn = rr / rows;
;     const int row0 = mbase + tm * BM, col0 = tn * 128;
;     f32x4 acc[MF][4];
; #pragma unroll
;     for (int m = 0; m < MF; ++m)
; #pragma unroll
;       for (int n = 0; n < 4; ++n) acc[m][n] = (f32x4){0.f, 0.f, 0.f, 0.f};
;     const u16* gA = A + (size_t)(row0 + (tid >> 2)) * lda + (tid & 3) * 8;
;     const u16* gB = Bt + (size_t)(col0 + (tid >> 2)) * K + (tid & 3) * 8;
;     ...
;     GEMM_ISSUE(0);
;     GEMM_ISSUE(1);
;     for (int kt = 0; kt < nk; ++kt) {
;       if (kt + 1 < nk) {
;         if (MF == 8) asm volatile("s_waitcnt vmcnt(6)" ::: "memory");
;         else asm volatile("s_waitcnt vmcnt(3)" ::: "memory");
;       } else asm volatile("s_waitcnt vmcnt(0)" ::: "memory");
;       asm volatile("s_waitcnt lgkmcnt(0)" ::: "memory");
;       __builtin_amdgcn_s_barrier();
;       const u16* a_ = sbase + (kt % 3) * STG;
;       const u16* b_ = a_ + BM * 32;
;       bf16x8 bfr[4], afc[2], afn[2];
;       const u16* ap_ = a_ + (wr * (16 * MF) + fr) * 32 + fq * 8;
; #pragma unroll
;       for (int n = 0; n < 4; ++n) bfr[n] = rd_std(b_ + (wc * 64 + n * 16 + fr) * 32 + fq * 8);
;       afc[0] = rd_std(ap_); afc[1] = rd_std(ap_ + 16 * 32);
;       __builtin_amdgcn_sched_barrier(0);
;       if (kt + 2 < nk) GEMM_ISSUE(kt + 2);
;       __builtin_amdgcn_sched_barrier(0);
; #pragma unroll
;       for (int mh = 0; mh < MF / 2; ++mh) {
;         if (mh + 1 < MF / 2) {
;           afn[0] = rd_std(ap_ + ((mh + 1) * 2) * 16 * 32);
;           afn[1] = rd_std(ap_ + ((mh + 1) * 2 + 1) * 16 * 32);
;         }
;         __builtin_amdgcn_sched_barrier(0);
; #pragma unroll
;         for (int m = 0; m < 2; ++m)
; #pragma unroll
;           for (int n = 0; n < 4; ++n) acc[mh * 2 + m][n] = MFMA(bfr[n], afc[m], acc[mh * 2 + m][n]);
;         __builtin_amdgcn_sched_barrier(0);
;         afc[0] = afn[0]; afc[1] = afn[1];
;       }
;     }
.LBB0_155:
	s_add_i32 s2, s2, s64
	s_cmpk_gt_i32 s2, 0x15f
	s_cbranch_scc1 .LBB0_154
	s_mul_hi_i32 s3, s2, 0x2e8ba2e9
	s_lshr_b32 s5, s3, 31
	s_ashr_i32 s3, s3, 6
	s_add_i32 s3, s3, s5
	s_mul_i32 s5, s3, 0x160
	s_sub_i32 s2, s2, s5
	s_sext_i32_i16 s5, s2
	s_bfe_u32 s5, s5, 0x3001c
	s_add_i32 s5, s2, s5
	s_sext_i32_i16 s9, s5
	s_and_b32 s5, s5, 0xfff8
	s_sub_i32 s2, s2, s5
	s_sext_i32_i16 s2, s2
	s_lshl_b32 s3, s3, 9
	s_lshl_b32 s2, s2, 6
	s_add_i32 s8, s3, s2
	s_ashr_i32 s5, s9, 3
	s_add_i32 s8, s8, 0x10000
	v_lshl_add_u32 v6, s5, 7, v1
	v_add_u32_e32 v2, s8, v1
	v_ashrrev_i32_e32 v7, 31, v6
	v_ashrrev_i32_e32 v3, 31, v2
	v_lshlrev_b64 v[6:7], 11, v[6:7]
	v_lshlrev_b64 v[2:3], 11, v[2:3]
	v_lshl_add_u64 v[44:45], v[36:37], 0, v[6:7]
	v_lshlrev_b32_e32 v255, 1, v44
	v_bfi_b32 v255, s100, v255, v44
	v_lshrrev_b32_e32 v44, 5, v44
	v_bfi_b32 v44, 64, v44, v255
	v_readfirstlane_b32 s2, v51
	v_add_u32_e32 v6, 0x1000, v51
	v_lshl_add_u64 v[4:5], v[34:35], 0, v[2:3]
	v_lshlrev_b32_e32 v255, 1, v4
	v_bfi_b32 v255, s100, v255, v4
	v_lshrrev_b32_e32 v4, 5, v4
	v_bfi_b32 v4, 64, v4, v255
	s_mov_b32 m0, s2
	v_readfirstlane_b32 s2, v6
	global_load_lds_dwordx4 v[4:5], off
	s_mov_b32 m0, s2
	s_mov_b64 s[2:3], 0x20000
	v_add_u32_e32 v8, 0x2000, v51
	v_lshl_add_u64 v[6:7], v[44:45], 0, s[2:3]
	v_readfirstlane_b32 s2, v8
	global_load_lds_dwordx4 v[44:45], off
	s_mov_b32 m0, s2
	v_lshl_add_u64 v[4:5], v[4:5], 0, 64
	v_lshl_add_u64 v[4:5], v[4:5], 0, 64
	global_load_lds_dwordx4 v[6:7], off
	v_add_u32_e32 v6, 0x3000, v51
	v_lshl_add_u64 v[46:47], v[42:43], 0, v[2:3]
	v_lshlrev_b32_e32 v255, 1, v46
	v_bfi_b32 v255, s100, v255, v46
	v_lshrrev_b32_e32 v46, 5, v46
	v_bfi_b32 v46, 64, v46, v255
	v_lshl_add_u64 v[46:47], v[46:47], 0, 64
	v_lshl_add_u64 v[46:47], v[46:47], 0, 64
	v_readfirstlane_b32 s2, v6
	v_add_u32_e32 v6, 0x4000, v51
	s_mov_b32 m0, s2
	v_readfirstlane_b32 s2, v6
	global_load_lds_dwordx4 v[4:5], off
	v_lshl_add_u64 v[4:5], v[44:45], 0, 64
	v_lshl_add_u64 v[4:5], v[4:5], 0, 64
	s_mov_b32 m0, s2
	s_mov_b64 s[2:3], 0x20080
	v_add_u32_e32 v6, 0x5000, v51
	global_load_lds_dwordx4 v[4:5], off
	v_lshl_add_u64 v[4:5], v[44:45], 0, s[2:3]
	v_readfirstlane_b32 s2, v6
	s_mov_b32 m0, s2
	v_mov_b32_e32 v2, 0
	global_load_lds_dwordx4 v[4:5], off
	v_lshl_add_u64 v[44:45], v[44:45], 0, 64
	v_lshl_add_u64 v[44:45], v[44:45], 0, 64
	s_mov_b32 s9, 3
	s_mov_b64 s[2:3], 0
	v_mov_b32_e32 v3, v2
	v_mov_b32_e32 v4, v2
	v_mov_b32_e32 v5, v2
	v_mov_b32_e32 v6, v2
	v_mov_b32_e32 v7, v2
	v_mov_b32_e32 v8, v2
	v_mov_b32_e32 v9, v2
	v_mov_b32_e32 v10, v2
	v_mov_b32_e32 v11, v2
	v_mov_b32_e32 v12, v2
	v_mov_b32_e32 v13, v2
	v_mov_b32_e32 v14, v2
	v_mov_b32_e32 v15, v2
	v_mov_b32_e32 v16, v2
	v_mov_b32_e32 v17, v2
	v_mov_b32_e32 v18, v2
	v_mov_b32_e32 v19, v2
	v_mov_b32_e32 v20, v2
	v_mov_b32_e32 v21, v2
	v_mov_b32_e32 v22, v2
	v_mov_b32_e32 v23, v2
	v_mov_b32_e32 v24, v2
	v_mov_b32_e32 v25, v2
	v_mov_b32_e32 v26, v2
	v_mov_b32_e32 v27, v2
	v_mov_b32_e32 v28, v2
	v_mov_b32_e32 v29, v2
	v_mov_b32_e32 v30, v2
	v_mov_b32_e32 v31, v2
	v_mov_b32_e32 v32, v2
	v_mov_b32_e32 v33, v2
.LBB0_157:
	s_add_i32 s10, s9, 0xfffd
	s_and_b32 s11, s10, 0xff
	s_mulk_i32 s11, 0xab
	s_bfe_u32 s11, s11, 0x70009
	s_mul_i32 s11, s11, 3
	s_sub_i32 s11, s10, s11
	s_and_b32 s11, s11, 0xff
	s_mulk_i32 s11, 0x3000
	s_add_i32 s11, s11, 0
	v_lshlrev_b32_e32 v50, 1, v38
	v_add_u32_e32 v49, s11, v50
	s_waitcnt vmcnt(3)
	v_add3_u32 v49, v49, v39, v53
	s_waitcnt lgkmcnt(0)
	s_barrier
	v_add_u32_e32 v48, s11, v52
	ds_read_b128 v[58:61], v49 offset:4096
	ds_read_b128 v[62:65], v49 offset:5120
	ds_read_b128 v[66:69], v49 offset:6144
	ds_read_b128 v[70:73], v49 offset:7168
	v_add3_u32 v48, v48, v53, v50
	ds_read_b128 v[74:77], v48
	ds_read_b128 v[78:81], v48 offset:1024
	s_mul_i32 s11, s9, 0xab
	s_add_i32 s12, s11, 0xff55
	s_bfe_u32 s12, s12, 0x70009
	s_mul_i32 s12, s12, 3
	s_not_b32 s12, s12
	s_add_i32 s12, s12, s9
	s_and_b32 s12, s12, 0xff
	s_mulk_i32 s12, 0x3000
	v_add_u32_e32 v86, s12, v51
	v_lshl_add_u64 v[48:49], s[2:3], 1, v[46:47]
	v_readfirstlane_b32 s12, v86
	v_lshl_add_u64 v[82:83], v[48:49], 0, s[74:75]
	s_mov_b32 m0, s12
	v_add_u32_e32 v87, 0x1000, v86
	global_load_lds_dwordx4 v[82:83], off
	v_lshl_add_u64 v[82:83], s[2:3], 1, v[44:45]
	v_readfirstlane_b32 s12, v87
	v_add_u32_e32 v86, 0x2000, v86
	v_lshl_add_u64 v[84:85], v[82:83], 0, s[74:75]
	s_mov_b32 m0, s12
	v_readfirstlane_b32 s12, v86
	global_load_lds_dwordx4 v[84:85], off
	v_lshl_add_u64 v[84:85], v[82:83], 0, s[92:93]
	s_mov_b32 m0, s12
	s_nop 0
	global_load_lds_dwordx4 v[84:85], off
	s_waitcnt lgkmcnt(0)
	v_mfma_f32_16x16x32_bf16 v[30:33], v[58:61], v[74:77], v[30:33]
	v_mfma_f32_16x16x32_bf16 v[26:29], v[62:65], v[74:77], v[26:29]
	v_mfma_f32_16x16x32_bf16 v[22:25], v[66:69], v[74:77], v[22:25]
	v_mfma_f32_16x16x32_bf16 v[18:21], v[70:73], v[74:77], v[18:21]
	v_mfma_f32_16x16x32_bf16 v[14:17], v[58:61], v[78:81], v[14:17]
	v_mfma_f32_16x16x32_bf16 v[10:13], v[62:65], v[78:81], v[10:13]
	v_mfma_f32_16x16x32_bf16 v[6:9], v[66:69], v[78:81], v[6:9]
	v_mfma_f32_16x16x32_bf16 v[2:5], v[70:73], v[78:81], v[2:5]
	s_or_b32 s10, s10, 1
	s_and_b32 s12, s10, 0xff
	s_mulk_i32 s12, 0xab
	s_bfe_u32 s12, s12, 0x70009
	s_mul_i32 s12, s12, 3
	s_sub_i32 s10, s10, s12
	s_and_b32 s10, s10, 0xff
	s_mulk_i32 s10, 0x3000
	s_add_i32 s10, s10, 0
	v_add_u32_e32 v58, s10, v50
	s_waitcnt vmcnt(3)
	v_add3_u32 v70, v58, v39, v53
	s_waitcnt lgkmcnt(0)
	s_barrier
; template <int EPI, int MF>
; __device__ __forceinline__ void gemm_part(const u16* __restrict__ A, int lda, const u16* __restrict__ Bt, int K, int ntn, GemmEpi ep, char* smem,
;                                           int mbase, int mrows) {
;     ...
;     for (int kt = 0; kt < nk; ++kt) {
;       if (kt + 1 < nk) {
;         if (MF == 8) asm volatile("s_waitcnt vmcnt(6)" ::: "memory");
;         else asm volatile("s_waitcnt vmcnt(3)" ::: "memory");
;       } else asm volatile("s_waitcnt vmcnt(0)" ::: "memory");
;       asm volatile("s_waitcnt lgkmcnt(0)" ::: "memory");
;       __builtin_amdgcn_s_barrier();
;       const u16* a_ = sbase + (kt % 3) * STG;
;       const u16* b_ = a_ + BM * 32;
;       bf16x8 bfr[4], afc[2], afn[2];
;       const u16* ap_ = a_ + (wr * (16 * MF) + fr) * 32 + fq * 8;
; #pragma unroll
;       for (int n = 0; n < 4; ++n) bfr[n] = rd_std(b_ + (wc * 64 + n * 16 + fr) * 32 + fq * 8);
;       afc[0] = rd_std(ap_); afc[1] = rd_std(ap_ + 16 * 32);
;       __builtin_amdgcn_sched_barrier(0);
;       if (kt + 2 < nk) GEMM_ISSUE(kt + 2);
;       __builtin_amdgcn_sched_barrier(0);
; #pragma unroll
;       for (int mh = 0; mh < MF / 2; ++mh) {
;         if (mh + 1 < MF / 2) {
;           afn[0] = rd_std(ap_ + ((mh + 1) * 2) * 16 * 32);
;           afn[1] = rd_std(ap_ + ((mh + 1) * 2 + 1) * 16 * 32);
;         }
;         __builtin_amdgcn_sched_barrier(0);
; #pragma unroll
;         for (int m = 0; m < 2; ++m)
; #pragma unroll
;           for (int n = 0; n < 4; ++n) acc[mh * 2 + m][n] = MFMA(bfr[n], afc[m], acc[mh * 2 + m][n]);
;         __builtin_amdgcn_sched_barrier(0);
;         afc[0] = afn[0]; afc[1] = afn[1];
;       }
;     }
;     ...
;     __syncthreads();
; #pragma unroll
;     for (int m = 0; m < MF; ++m) {
;       if (EPI == EPI_SWIGLU || (m & 1) == 0) __builtin_amdgcn_sched_barrier(0);
;       const int row = row0 + wr * (16 * MF) + m * 16 + fr;
;       const int cb = col0 + wc * 64 + 4 * fq;
;       float rstd = 1.f;
;       if (EPI != EPI_RESID) { if (ep.rss_in) rstd = rsqrtf(ep.rss_in[row] * (1.f / DM) + 1e-6f); }
;       if (EPI == EPI_SWIGLU) {
; #pragma unroll
;         for (int n = 0; n < 2; ++n) {
;           bf16x4 o;
; #pragma unroll
;           for (int jj = 0; jj < 4; ++jj) o[jj] = (short)f2bf(siluf_(acc[m][n][jj] * rstd) * (acc[m][n + 2][jj] * rstd));
	v_add_u32_e32 v74, s10, v52
	ds_read_b128 v[58:61], v70 offset:4096
	ds_read_b128 v[62:65], v70 offset:5120
	ds_read_b128 v[66:69], v70 offset:6144
	ds_read_b128 v[70:73], v70 offset:7168
	v_add3_u32 v50, v74, v53, v50
	ds_read_b128 v[74:77], v50
	ds_read_b128 v[78:81], v50 offset:1024
	s_bfe_u32 s10, s11, 0x70009
	s_mul_i32 s10, s10, 3
	s_sub_i32 s10, s9, s10
	s_and_b32 s10, s10, 0xff
	s_mulk_i32 s10, 0x3000
	v_add_u32_e32 v50, s10, v51
	v_add_u32_e32 v84, 0x1000, v50
	v_readfirstlane_b32 s10, v50
	v_lshl_add_u64 v[48:49], v[48:49], 0, s[52:53]
	v_lshl_add_u64 v[48:49], v[48:49], 0, 64
	s_mov_b32 m0, s10
	v_readfirstlane_b32 s10, v84
	v_add_u32_e32 v50, 0x2000, v50
	global_load_lds_dwordx4 v[48:49], off
	v_lshl_add_u64 v[48:49], v[82:83], 0, s[52:53]
	v_lshl_add_u64 v[48:49], v[48:49], 0, 64
	s_mov_b32 m0, s10
	v_readfirstlane_b32 s10, v50
	global_load_lds_dwordx4 v[48:49], off
	v_lshl_add_u64 v[48:49], v[82:83], 0, s[54:55]
	v_lshl_add_u64 v[48:49], v[48:49], 0, 64
	s_mov_b32 m0, s10
	s_nop 0
	global_load_lds_dwordx4 v[48:49], off
	s_waitcnt lgkmcnt(0)
	v_mfma_f32_16x16x32_bf16 v[30:33], v[58:61], v[74:77], v[30:33]
	v_mfma_f32_16x16x32_bf16 v[26:29], v[62:65], v[74:77], v[26:29]
	v_mfma_f32_16x16x32_bf16 v[22:25], v[66:69], v[74:77], v[22:25]
	v_mfma_f32_16x16x32_bf16 v[18:21], v[70:73], v[74:77], v[18:21]
	v_mfma_f32_16x16x32_bf16 v[14:17], v[58:61], v[78:81], v[14:17]
	v_mfma_f32_16x16x32_bf16 v[10:13], v[62:65], v[78:81], v[10:13]
	v_mfma_f32_16x16x32_bf16 v[6:9], v[66:69], v[78:81], v[6:9]
	v_mfma_f32_16x16x32_bf16 v[2:5], v[70:73], v[78:81], v[2:5]
	s_add_u32 s2, s2, 0x80
	s_addc_u32 s3, s3, 0
	s_add_i32 s9, s9, 2
	s_cmpk_eq_i32 s2, 0x780
	s_cbranch_scc0 .LBB0_157
	s_waitcnt vmcnt(3)
	s_waitcnt lgkmcnt(0)
	s_barrier
	ds_read_b128 v[44:47], v56 offset:4096
	ds_read_b128 v[58:61], v56 offset:5120
	ds_read_b128 v[62:65], v56 offset:6144
	ds_read_b128 v[66:69], v56 offset:7168
	ds_read_b128 v[70:73], v55
	ds_read_b128 v[74:77], v55 offset:1024
	s_waitcnt lgkmcnt(0)
	v_mfma_f32_16x16x32_bf16 v[30:33], v[44:47], v[70:73], v[30:33]
	v_mfma_f32_16x16x32_bf16 v[26:29], v[58:61], v[70:73], v[26:29]
	v_mfma_f32_16x16x32_bf16 v[18:21], v[66:69], v[70:73], v[18:21]
	v_mfma_f32_16x16x32_bf16 v[14:17], v[44:47], v[74:77], v[14:17]
	v_mfma_f32_16x16x32_bf16 v[10:13], v[58:61], v[74:77], v[10:13]
	v_mfma_f32_16x16x32_bf16 v[44:47], v[62:65], v[74:77], v[6:9]
	v_mfma_f32_16x16x32_bf16 v[2:5], v[66:69], v[74:77], v[2:5]
	v_mfma_f32_16x16x32_bf16 v[78:81], v[62:65], v[70:73], v[22:25]
	s_waitcnt vmcnt(0)
	s_waitcnt lgkmcnt(0)
	s_barrier
	ds_read_b128 v[6:9], v57 offset:16384
	ds_read_b128 v[58:61], v57 offset:17408
	ds_read_b128 v[62:65], v57 offset:18432
	ds_read_b128 v[66:69], v57 offset:19456
	ds_read_b128 v[70:73], v55 offset:12288
	ds_read_b128 v[74:77], v55 offset:13312
	s_waitcnt lgkmcnt(0)
	v_mfma_f32_16x16x32_bf16 v[30:33], v[6:9], v[70:73], v[30:33]
	v_mfma_f32_16x16x32_bf16 v[22:25], v[58:61], v[70:73], v[26:29]
	v_mfma_f32_16x16x32_bf16 v[26:29], v[62:65], v[70:73], v[78:81]
	v_mfma_f32_16x16x32_bf16 v[18:21], v[66:69], v[70:73], v[18:21]
	v_mfma_f32_16x16x32_bf16 v[14:17], v[6:9], v[74:77], v[14:17]
	v_mfma_f32_16x16x32_bf16 v[6:9], v[58:61], v[74:77], v[10:13]
	v_mfma_f32_16x16x32_bf16 v[10:13], v[62:65], v[74:77], v[44:47]
	v_mfma_f32_16x16x32_bf16 v[2:5], v[66:69], v[74:77], v[2:5]
	v_add_u32_e32 v48, s8, v54
	s_waitcnt vmcnt(0)
	s_barrier
	v_readlane_b32 s2, v252, 1
	v_readlane_b32 s3, v252, 2
	v_ashrrev_i32_e32 v49, 31, v48
	v_mov_b32_e32 v44, 1.0
	s_and_b64 vcc, exec, s[2:3]
	v_mov_b32_e32 v50, 1.0
	s_cbranch_vccz .LBB0_160
	v_lshl_add_u64 v[46:47], v[48:49], 2, s[14:15]
	global_load_dword v45, v[46:47], off
	s_waitcnt vmcnt(0)
	v_fmamk_f32 v45, v45, 0x3a800000, v142
	v_mul_f32_e32 v46, 0x4b800000, v45
	v_cmp_gt_f32_e32 vcc, s69, v45
	s_nop 1
	v_cndmask_b32_e32 v45, v45, v46, vcc
	v_rsq_f32_e32 v45, v45
	s_nop 0
	v_mul_f32_e32 v46, 0x45800000, v45
	v_cndmask_b32_e32 v50, v45, v46, vcc
.LBB0_160:
	v_pk_mul_f32 v[30:31], v[30:31], v[50:51] op_sel_hi:[1,0]
	v_pk_mul_f32 v[26:27], v[26:27], v[50:51] op_sel_hi:[1,0]
	v_mul_f32_e32 v45, 0xbfb8aa3b, v30
	v_exp_f32_e32 v45, v45
	s_lshl_b32 s2, s5, 6
	s_ashr_i32 s3, s2, 31
	v_pk_mul_f32 v[28:29], v[28:29], v[50:51] op_sel_hi:[1,0]
	v_add_f32_e32 v45, 1.0, v45
	v_rcp_f32_e32 v60, v45
	v_mul_f32_e32 v45, 0xbfb8aa3b, v31
	v_exp_f32_e32 v45, v45
	v_lshl_add_u64 v[46:47], s[2:3], 2, v[40:41]
	v_mad_i64_i32 v[58:59], s[2:3], v48, s33, v[46:47]
	v_add_f32_e32 v45, 1.0, v45
	v_rcp_f32_e32 v61, v45
	v_pk_mul_f32 v[22:23], v[22:23], v[50:51] op_sel_hi:[1,0]
	v_pk_mul_f32 v[18:19], v[18:19], v[50:51] op_sel_hi:[1,0]
	v_pk_mul_f32 v[20:21], v[20:21], v[50:51] op_sel_hi:[1,0]
	v_pk_mul_f32 v[30:31], v[30:31], v[60:61]
	s_nop 0
	v_pk_mul_f32 v[26:27], v[26:27], v[30:31]
	v_pk_mul_f32 v[30:31], v[32:33], v[50:51] op_sel_hi:[1,0]
	v_cvt_pk_bf16_f32 v26, v26, v27
	v_mul_f32_e32 v27, 0xbfb8aa3b, v30
	v_exp_f32_e32 v27, v27
	s_nop 0
	v_add_f32_e32 v27, 1.0, v27
	v_rcp_f32_e32 v32, v27
	v_mul_f32_e32 v27, 0xbfb8aa3b, v31
	v_exp_f32_e32 v27, v27
	s_nop 0
	v_add_f32_e32 v27, 1.0, v27
	v_rcp_f32_e32 v33, v27
	s_nop 0
	v_pk_mul_f32 v[30:31], v[30:31], v[32:33]
	s_nop 0
	v_pk_mul_f32 v[28:29], v[28:29], v[30:31]
	s_nop 0
	v_cvt_pk_bf16_f32 v27, v28, v29
	global_store_dwordx2 v[58:59], v[26:27], off
	v_mul_f32_e32 v26, 0xbfb8aa3b, v22
	v_mul_f32_e32 v27, 0xbfb8aa3b, v23
	v_exp_f32_e32 v26, v26
	v_exp_f32_e32 v27, v27
	v_add_f32_e32 v26, 1.0, v26
	v_add_f32_e32 v27, 1.0, v27
	v_rcp_f32_e32 v26, v26
	v_rcp_f32_e32 v27, v27
	s_nop 0
	v_pk_mul_f32 v[22:23], v[22:23], v[26:27]
	s_nop 0
	v_pk_mul_f32 v[18:19], v[18:19], v[22:23]
	v_pk_mul_f32 v[22:23], v[24:25], v[50:51] op_sel_hi:[1,0]
	v_cvt_pk_bf16_f32 v18, v18, v19
	v_mul_f32_e32 v19, 0xbfb8aa3b, v22
	v_exp_f32_e32 v19, v19
	s_nop 0
	v_add_f32_e32 v19, 1.0, v19
	v_rcp_f32_e32 v24, v19
	v_mul_f32_e32 v19, 0xbfb8aa3b, v23
	v_exp_f32_e32 v19, v19
	s_nop 0
	v_add_f32_e32 v19, 1.0, v19
	v_rcp_f32_e32 v25, v19
	s_nop 0
	v_pk_mul_f32 v[22:23], v[22:23], v[24:25]
	s_nop 0
	v_pk_mul_f32 v[20:21], v[20:21], v[22:23]
	s_nop 0
	v_cvt_pk_bf16_f32 v19, v20, v21
	global_store_dwordx2 v[58:59], v[18:19], off offset:32
	v_readlane_b32 s2, v252, 1
	v_or_b32_e32 v18, 16, v48
	v_readlane_b32 s3, v252, 2
	v_ashrrev_i32_e32 v19, 31, v18
	s_andn2_b64 vcc, exec, s[2:3]
	s_cbranch_vccnz .LBB0_153
	v_lshl_add_u64 v[20:21], v[18:19], 2, s[14:15]
	global_load_dword v19, v[20:21], off
	s_waitcnt vmcnt(0)
	v_fmamk_f32 v19, v19, 0x3a800000, v142
	v_mul_f32_e32 v20, 0x4b800000, v19
	v_cmp_gt_f32_e32 vcc, s69, v19
	s_nop 1
	v_cndmask_b32_e32 v19, v19, v20, vcc
	v_rsq_f32_e32 v19, v19
	s_nop 0
	v_mul_f32_e32 v20, 0x45800000, v19
	v_cndmask_b32_e32 v44, v19, v20, vcc
	s_branch .LBB0_153

; template <int EPI, int MF>
; __device__ __forceinline__ void gemm_part(const u16* __restrict__ A, int lda, const u16* __restrict__ Bt, int K, int ntn, GemmEpi ep, char* smem,
;                                           int mbase, int mrows) {
;     ...
;   for (int q = xcd; q * nbx < total; q += (MF == 2) ? 1 : 8) {
;     const int L = q * nbx + li;
;     if (L >= total) continue;
;     const int g = L / (8 * ntn), rr = L % (8 * ntn);
;     const int rows = min(8, ntm - 8 * g);
;     const int tm = 8 * g + rr % rows, tn = rr / rows;
;     const int row0 = mbase + tm * BM, col0 = tn * 128;
;     f32x4 acc[MF][4];
; #pragma unroll
;     for (int m = 0; m < MF; ++m)
; #pragma unroll
;       for (int n = 0; n < 4; ++n) acc[m][n] = (f32x4){0.f, 0.f, 0.f, 0.f};
;     const u16* gA = A + (size_t)(row0 + (tid >> 2)) * lda + (tid & 3) * 8;
;     const u16* gB = Bt + (size_t)(col0 + (tid >> 2)) * K + (tid & 3) * 8;
;     ...
;     GEMM_ISSUE(0);
;     GEMM_ISSUE(1);
.LBB0_203:
	s_add_i32 s2, s2, s63
	s_cmpk_gt_u32 s2, 0x7ff
	s_cbranch_scc1 .LBB0_202
	s_lshl_b32 s3, s5, 5
	s_and_b32 s3, s3, 0xf800
	v_add_u32_e32 v4, s3, v163
	s_waitcnt lgkmcnt(0)
	v_mov_b64_e32 v[2:3], s[46:47]
	s_and_b32 s3, s4, 0x380
	v_mad_i64_i32 v[136:137], s[14:15], v4, s33, v[2:3]
	v_bfe_u32 v12, v140, 2, 1
	v_mul_u32_u24_e32 v12, 0x15c0, v12
	v_sub_u32_e32 v12, 0, v12
	v_ashrrev_i32_e32 v13, 31, v12
	v_lshl_add_u64 v[136:137], v[136:137], 0, v[12:13]
	v_lshl_add_u64 v[136:137], v[136:137], 0, 64
	v_lshl_add_u64 v[136:137], v[136:137], 0, 64
	v_add_u32_e32 v4, s3, v1
	s_lshr_b32 s3, s2, 3
	s_and_b32 s3, s3, 0xf8
	s_and_b32 s11, s2, 7
	s_or_b32 s3, s3, s11
	v_mov_b64_e32 v[2:3], s[20:21]
	s_lshl_b32 s11, s2, 4
	s_lshl_b32 s2, s3, 8
	v_mad_i64_i32 v[138:139], s[14:15], v4, s33, v[2:3]
	v_lshl_add_u64 v[138:139], v[138:139], 0, v[12:13]
	v_lshl_add_u64 v[138:139], v[138:139], 0, 64
	v_lshl_add_u64 v[138:139], v[138:139], 0, 64
	v_add_u32_e32 v2, s2, v1
	v_readfirstlane_b32 s3, v154
	v_add_u32_e32 v7, 0x1000, v154
	v_mad_i64_i32 v[2:3], s[14:15], v2, s33, v[130:131]
	v_lshl_add_u64 v[2:3], v[2:3], 0, v[12:13]
	s_mov_b32 m0, s3
	s_mov_b64 s[16:17], 0x58000
	v_readfirstlane_b32 s3, v7
	v_add_u32_e32 v7, 0x2000, v154
	global_load_lds_dwordx4 v[2:3], off
	v_lshl_add_u64 v[4:5], v[2:3], 0, s[16:17]
	s_mov_b32 m0, s3
	s_mov_b64 s[14:15], 0xb0000
	v_readfirstlane_b32 s3, v7
	v_add_u32_e32 v7, 0x3000, v154
	s_and_b32 s11, s11, 0x380
	global_load_lds_dwordx4 v[4:5], off
	v_lshl_add_u64 v[4:5], v[2:3], 0, s[14:15]
	s_mov_b32 m0, s3
	s_mov_b64 s[14:15], 0x108000
	v_readfirstlane_b32 s3, v7
	v_add_u32_e32 v6, s11, v1
	global_load_lds_dwordx4 v[4:5], off
	v_lshl_add_u64 v[4:5], v[2:3], 0, s[14:15]
	s_mov_b32 m0, s3
	v_add_u32_e32 v8, 0x5000, v154
	global_load_lds_dwordx4 v[4:5], off
	v_mad_i64_i32 v[4:5], s[14:15], v6, s33, v[132:133]
	v_lshl_add_u64 v[4:5], v[4:5], 0, v[12:13]
	v_add_u32_e32 v6, 0x4000, v154
	s_mov_b64 s[14:15], 0x58040
	v_readfirstlane_b32 s3, v6
	s_mov_b32 m0, s3
	v_readfirstlane_b32 s3, v8
	v_add_u32_e32 v8, 0x6000, v154
	global_load_lds_dwordx4 v[4:5], off
	v_lshl_add_u64 v[6:7], v[4:5], 0, s[16:17]
	s_mov_b32 m0, s3
	v_readfirstlane_b32 s3, v8
	v_add_u32_e32 v8, 0x7000, v154
	global_load_lds_dwordx4 v[6:7], off
	v_lshl_add_u64 v[6:7], v[2:3], 0, 64
	v_lshl_add_u64 v[6:7], v[6:7], 0, 64
	s_mov_b32 m0, s3
	v_readfirstlane_b32 s3, v8
	v_add_u32_e32 v8, 0x8000, v154
	global_load_lds_dwordx4 v[6:7], off
	v_lshl_add_u64 v[6:7], v[2:3], 0, s[14:15]
	v_lshl_add_u64 v[6:7], v[6:7], 0, 64
	s_mov_b32 m0, s3
	s_mov_b64 s[16:17], 0xb0040
	v_readfirstlane_b32 s3, v8
	global_load_lds_dwordx4 v[6:7], off
	v_lshl_add_u64 v[6:7], v[2:3], 0, s[16:17]
	v_lshl_add_u64 v[6:7], v[6:7], 0, 64
	s_mov_b32 m0, s3
	s_mov_b64 s[16:17], 0x108040
	global_load_lds_dwordx4 v[6:7], off
	v_add_u32_e32 v6, 0x9000, v154
	v_lshl_add_u64 v[2:3], v[2:3], 0, s[16:17]
	v_lshl_add_u64 v[2:3], v[2:3], 0, 64
	v_readfirstlane_b32 s3, v6
	v_add_u32_e32 v6, 0xa000, v154
	s_mov_b32 m0, s3
	v_readfirstlane_b32 s3, v6
	global_load_lds_dwordx4 v[2:3], off
	v_lshl_add_u64 v[2:3], v[4:5], 0, 64
	v_lshl_add_u64 v[2:3], v[2:3], 0, 64
	s_mov_b32 m0, s3
	s_mov_b32 s16, 0
	global_load_lds_dwordx4 v[2:3], off
	v_lshl_add_u64 v[2:3], v[4:5], 0, s[14:15]
	v_lshl_add_u64 v[2:3], v[2:3], 0, 64
	v_add_u32_e32 v4, 0xb000, v154
	s_mov_b32 s14, 1
	v_readfirstlane_b32 s3, v4
	s_mov_b32 m0, s3
	s_mov_b32 s3, 0
	global_load_lds_dwordx4 v[2:3], off
	v_mov_b32_e32 v2, 0
	s_mov_b32 s15, 2
	v_mov_b32_e32 v3, v2
	v_mov_b32_e32 v4, v2
	v_mov_b32_e32 v5, v2
	v_mov_b32_e32 v6, v2
	v_mov_b32_e32 v7, v2
	v_mov_b32_e32 v8, v2
	v_mov_b32_e32 v9, v2
	v_mov_b32_e32 v10, v2
	v_mov_b32_e32 v11, v2
	v_mov_b32_e32 v12, v2
	v_mov_b32_e32 v13, v2
	v_mov_b32_e32 v14, v2
	v_mov_b32_e32 v15, v2
	v_mov_b32_e32 v16, v2
	v_mov_b32_e32 v17, v2
	v_mov_b32_e32 v18, v2
	v_mov_b32_e32 v19, v2
	v_mov_b32_e32 v20, v2
	v_mov_b32_e32 v21, v2
	v_mov_b32_e32 v22, v2
	v_mov_b32_e32 v23, v2
	v_mov_b32_e32 v24, v2
	v_mov_b32_e32 v25, v2
	v_mov_b32_e32 v26, v2
	v_mov_b32_e32 v27, v2
	v_mov_b32_e32 v28, v2
	v_mov_b32_e32 v29, v2
	v_mov_b32_e32 v30, v2
	v_mov_b32_e32 v31, v2
	v_mov_b32_e32 v32, v2
	v_mov_b32_e32 v33, v2
	v_mov_b32_e32 v34, v2
	v_mov_b32_e32 v35, v2
	v_mov_b32_e32 v36, v2
	v_mov_b32_e32 v37, v2
	v_mov_b32_e32 v38, v2
	v_mov_b32_e32 v39, v2
	v_mov_b32_e32 v40, v2
	v_mov_b32_e32 v41, v2
	v_mov_b32_e32 v42, v2
	v_mov_b32_e32 v43, v2
	v_mov_b32_e32 v44, v2
	v_mov_b32_e32 v45, v2
	v_mov_b32_e32 v46, v2
	v_mov_b32_e32 v47, v2
	v_mov_b32_e32 v48, v2
	v_mov_b32_e32 v49, v2
	v_mov_b32_e32 v50, v2
	v_mov_b32_e32 v51, v2
	v_mov_b32_e32 v52, v2
	v_mov_b32_e32 v53, v2
	v_mov_b32_e32 v54, v2
	v_mov_b32_e32 v55, v2
	v_mov_b32_e32 v56, v2
	v_mov_b32_e32 v57, v2
	v_mov_b32_e32 v58, v2
	v_mov_b32_e32 v59, v2
	v_mov_b32_e32 v60, v2
	v_mov_b32_e32 v61, v2
	v_mov_b32_e32 v62, v2
	v_mov_b32_e32 v63, v2
	v_mov_b32_e32 v64, v2
	v_mov_b32_e32 v65, v2
	v_mov_b32_e32 v66, v2
	v_mov_b32_e32 v67, v2
	v_mov_b32_e32 v68, v2
	v_mov_b32_e32 v69, v2
	v_mov_b32_e32 v70, v2
	v_mov_b32_e32 v71, v2
	v_mov_b32_e32 v72, v2
	v_mov_b32_e32 v73, v2
	v_mov_b32_e32 v74, v2
	v_mov_b32_e32 v75, v2
	v_mov_b32_e32 v76, v2
	v_mov_b32_e32 v77, v2
	v_mov_b32_e32 v78, v2
	v_mov_b32_e32 v79, v2
	v_mov_b32_e32 v80, v2
	v_mov_b32_e32 v81, v2
	v_mov_b32_e32 v82, v2
	v_mov_b32_e32 v83, v2
	v_mov_b32_e32 v84, v2
	v_mov_b32_e32 v85, v2
	v_mov_b32_e32 v86, v2
	v_mov_b32_e32 v87, v2
	s_waitcnt vmcnt(0)
	v_mov_b32_e32 v88, v2
	v_mov_b32_e32 v89, v2
	v_mov_b32_e32 v90, v2
	v_mov_b32_e32 v91, v2
	v_mov_b32_e32 v92, v2
	v_mov_b32_e32 v93, v2
	v_mov_b32_e32 v94, v2
	v_mov_b32_e32 v95, v2
	v_mov_b32_e32 v96, v2
	v_mov_b32_e32 v97, v2
	v_mov_b32_e32 v98, v2
	v_mov_b32_e32 v99, v2
	v_mov_b32_e32 v100, v2
	v_mov_b32_e32 v101, v2
	v_mov_b32_e32 v102, v2
	v_mov_b32_e32 v103, v2
	v_mov_b32_e32 v104, v2
	v_mov_b32_e32 v105, v2
	v_mov_b32_e32 v106, v2
	v_mov_b32_e32 v107, v2
	v_mov_b32_e32 v108, v2
	v_mov_b32_e32 v109, v2
	v_mov_b32_e32 v110, v2
	v_mov_b32_e32 v111, v2
	v_mov_b32_e32 v112, v2
	v_mov_b32_e32 v113, v2
	v_mov_b32_e32 v114, v2
	v_mov_b32_e32 v115, v2
	v_mov_b32_e32 v116, v2
	v_mov_b32_e32 v117, v2
	v_mov_b32_e32 v118, v2
	v_mov_b32_e32 v119, v2
	v_mov_b32_e32 v120, v2
	v_mov_b32_e32 v121, v2
	v_mov_b32_e32 v122, v2
	v_mov_b32_e32 v123, v2
	v_mov_b32_e32 v124, v2
	v_mov_b32_e32 v125, v2
	v_mov_b32_e32 v126, v2
	v_mov_b32_e32 v127, v2
	v_mov_b32_e32 v128, v2
	v_mov_b32_e32 v129, v2
; #define MFMA(a, b, c) __builtin_amdgcn_mfma_f32_16x16x32_bf16((a), (b), (c), 0, 0, 0)
; template <int EPI, int MF>
; __device__ __forceinline__ void gemm_part(const u16* __restrict__ A, int lda, const u16* __restrict__ Bt, int K, int ntn, GemmEpi ep, char* smem,
;                                           int mbase, int mrows) {
;     ...
;     for (int kt = 0; kt < nk; ++kt) {
;       if (kt + 1 < nk) {
;         if (MF == 8) asm volatile("s_waitcnt vmcnt(6)" ::: "memory");
;         else asm volatile("s_waitcnt vmcnt(3)" ::: "memory");
;       } else asm volatile("s_waitcnt vmcnt(0)" ::: "memory");
;       asm volatile("s_waitcnt lgkmcnt(0)" ::: "memory");
;       __builtin_amdgcn_s_barrier();
;       const u16* a_ = sbase + (kt % 3) * STG;
;       const u16* b_ = a_ + BM * 32;
;       bf16x8 bfr[4], afc[2], afn[2];
;       const u16* ap_ = a_ + (wr * (16 * MF) + fr) * 32 + fq * 8;
; #pragma unroll
;       for (int n = 0; n < 4; ++n) bfr[n] = rd_std(b_ + (wc * 64 + n * 16 + fr) * 32 + fq * 8);
;       afc[0] = rd_std(ap_); afc[1] = rd_std(ap_ + 16 * 32);
;       __builtin_amdgcn_sched_barrier(0);
;       if (kt + 2 < nk) GEMM_ISSUE(kt + 2);
;       __builtin_amdgcn_sched_barrier(0);
; #pragma unroll
;       for (int mh = 0; mh < MF / 2; ++mh) {
;         if (mh + 1 < MF / 2) {
;           afn[0] = rd_std(ap_ + ((mh + 1) * 2) * 16 * 32);
;           afn[1] = rd_std(ap_ + ((mh + 1) * 2 + 1) * 16 * 32);
;         }
;         __builtin_amdgcn_sched_barrier(0);
; #pragma unroll
;         for (int m = 0; m < 2; ++m)
; #pragma unroll
;           for (int n = 0; n < 4; ++n) acc[mh * 2 + m][n] = MFMA(bfr[n], afc[m], acc[mh * 2 + m][n]);
;         __builtin_amdgcn_sched_barrier(0);
;         afc[0] = afn[0]; afc[1] = afn[1];
;       }
;     }
.LBB0_205:
	s_mul_hi_u32 s17, s16, 0xaaaaaaab
	s_lshr_b32 s17, s17, 1
	s_mul_i32 s17, s17, 0x12000
	v_add_u32_e32 v146, s3, v161
	v_subrev_u32_e32 v147, s17, v164
	s_waitcnt vmcnt(6)
	v_subrev_u32_e32 v148, s17, v160
	v_add_u32_e32 v170, v146, v147
	s_waitcnt lgkmcnt(0)
	s_barrier
	v_add_u32_e32 v190, v146, v148
	ds_read_b128 v[146:149], v170 offset:16384
	ds_read_b128 v[150:153], v170 offset:17408
	ds_read_b128 v[166:169], v170 offset:18432
	ds_read_b128 v[170:173], v170 offset:19456
	ds_read_b128 v[174:177], v190
	ds_read_b128 v[178:181], v190 offset:1024
	s_mul_hi_u32 s17, s15, 0xaaaaaaab
	s_add_i32 s16, s16, 1
	s_lshr_b32 s17, s17, 1
	s_mul_i32 s17, s17, 0x12000
	s_sub_i32 s17, s3, s17
	s_add_i32 s22, s17, 0xc000
	v_add_u32_e32 v186, s22, v154
	v_lshl_add_u64 v[182:183], v[136:137], 0, v[134:135]
	v_readfirstlane_b32 s22, v186
	s_mov_b32 m0, s22
	s_add_i32 s22, s17, 0xd000
	v_add_u32_e32 v186, s22, v154
	v_lshl_add_u64 v[184:185], v[182:183], 0, s[74:75]
	v_readfirstlane_b32 s22, v186
	global_load_lds_dwordx4 v[184:185], off
	s_mov_b32 m0, s22
	s_add_i32 s22, s17, 0xe000
	v_add_u32_e32 v186, s22, v154
	v_lshl_add_u64 v[184:185], v[182:183], 0, s[56:57]
	v_readfirstlane_b32 s22, v186
	global_load_lds_dwordx4 v[184:185], off
	v_lshl_add_u64 v[184:185], v[182:183], 0, s[58:59]
	s_mov_b32 m0, s22
	s_add_i32 s22, s17, 0xf000
	global_load_lds_dwordx4 v[184:185], off
	v_add_u32_e32 v184, s22, v154
	v_lshl_add_u64 v[182:183], v[182:183], 0, s[86:87]
	v_readfirstlane_b32 s22, v184
	s_mov_b32 m0, s22
	s_add_i32 s22, s17, 0x10000
	v_add_u32_e32 v186, s22, v154
	global_load_lds_dwordx4 v[182:183], off
	v_lshl_add_u64 v[182:183], v[138:139], 0, v[134:135]
	v_readfirstlane_b32 s22, v186
	v_lshl_add_u64 v[184:185], v[182:183], 0, s[74:75]
	s_mov_b32 m0, s22
	s_add_i32 s17, s17, 0x11000
	global_load_lds_dwordx4 v[184:185], off
	v_add_u32_e32 v184, s17, v154
	v_lshl_add_u64 v[182:183], v[182:183], 0, s[56:57]
	v_readfirstlane_b32 s17, v184
	s_mov_b32 m0, s17
	s_nop 0
	global_load_lds_dwordx4 v[182:183], off
	ds_read_b128 v[182:185], v190 offset:3072
	ds_read_b128 v[186:189], v190 offset:2048
	s_waitcnt lgkmcnt(0)
	v_mfma_f32_16x16x32_bf16 v[126:129], v[146:149], v[174:177], v[126:129]
	v_mfma_f32_16x16x32_bf16 v[122:125], v[150:153], v[174:177], v[122:125]
	v_mfma_f32_16x16x32_bf16 v[118:121], v[166:169], v[174:177], v[118:121]
	v_mfma_f32_16x16x32_bf16 v[114:117], v[170:173], v[174:177], v[114:117]
	v_mfma_f32_16x16x32_bf16 v[110:113], v[146:149], v[178:181], v[110:113]
	v_mfma_f32_16x16x32_bf16 v[106:109], v[150:153], v[178:181], v[106:109]
	v_mfma_f32_16x16x32_bf16 v[102:105], v[166:169], v[178:181], v[102:105]
	v_mfma_f32_16x16x32_bf16 v[98:101], v[170:173], v[178:181], v[98:101]
	ds_read_b128 v[174:177], v190 offset:5120
	ds_read_b128 v[178:181], v190 offset:4096
	v_mfma_f32_16x16x32_bf16 v[94:97], v[146:149], v[186:189], v[94:97]
	v_mfma_f32_16x16x32_bf16 v[90:93], v[150:153], v[186:189], v[90:93]
	v_mfma_f32_16x16x32_bf16 v[86:89], v[166:169], v[186:189], v[86:89]
	v_mfma_f32_16x16x32_bf16 v[82:85], v[170:173], v[186:189], v[82:85]
	v_mfma_f32_16x16x32_bf16 v[78:81], v[146:149], v[182:185], v[78:81]
	v_mfma_f32_16x16x32_bf16 v[74:77], v[150:153], v[182:185], v[74:77]
	v_mfma_f32_16x16x32_bf16 v[70:73], v[166:169], v[182:185], v[70:73]
	v_mfma_f32_16x16x32_bf16 v[66:69], v[170:173], v[182:185], v[66:69]
	ds_read_b128 v[182:185], v190 offset:7168
	ds_read_b128 v[186:189], v190 offset:6144
	s_waitcnt lgkmcnt(0)
	v_mfma_f32_16x16x32_bf16 v[62:65], v[146:149], v[178:181], v[62:65]
	v_mfma_f32_16x16x32_bf16 v[58:61], v[150:153], v[178:181], v[58:61]
	v_mfma_f32_16x16x32_bf16 v[54:57], v[166:169], v[178:181], v[54:57]
	v_mfma_f32_16x16x32_bf16 v[50:53], v[170:173], v[178:181], v[50:53]
	v_mfma_f32_16x16x32_bf16 v[46:49], v[146:149], v[174:177], v[46:49]
	v_mfma_f32_16x16x32_bf16 v[42:45], v[150:153], v[174:177], v[42:45]
	v_mfma_f32_16x16x32_bf16 v[38:41], v[166:169], v[174:177], v[38:41]
	v_mfma_f32_16x16x32_bf16 v[34:37], v[170:173], v[174:177], v[34:37]
	v_mfma_f32_16x16x32_bf16 v[30:33], v[146:149], v[186:189], v[30:33]
	v_mfma_f32_16x16x32_bf16 v[26:29], v[150:153], v[186:189], v[26:29]
	v_mfma_f32_16x16x32_bf16 v[22:25], v[166:169], v[186:189], v[22:25]
	v_mfma_f32_16x16x32_bf16 v[18:21], v[170:173], v[186:189], v[18:21]
	v_mfma_f32_16x16x32_bf16 v[14:17], v[146:149], v[182:185], v[14:17]
	v_mfma_f32_16x16x32_bf16 v[10:13], v[150:153], v[182:185], v[10:13]
	v_mfma_f32_16x16x32_bf16 v[6:9], v[166:169], v[182:185], v[6:9]
	v_mfma_f32_16x16x32_bf16 v[2:5], v[170:173], v[182:185], v[2:5]
	s_addk_i32 s3, 0x6000
	s_add_i32 s14, s14, 1
	s_add_i32 s15, s15, 1
	v_lshl_add_u64 v[136:137], v[136:137], 0, 64
	v_lshl_add_u64 v[136:137], v[136:137], 0, 64
	s_cmp_eq_u32 s3, 0x204000
	v_lshl_add_u64 v[138:139], v[138:139], 0, 64
	v_lshl_add_u64 v[138:139], v[138:139], 0, 64
	s_cbranch_scc0 .LBB0_205
	s_waitcnt vmcnt(6)
	s_waitcnt lgkmcnt(0)
	s_barrier
; #define MFMA(a, b, c) __builtin_amdgcn_mfma_f32_16x16x32_bf16((a), (b), (c), 0, 0, 0)
; template <int EPI, int MF>
; __device__ __forceinline__ void gemm_part(const u16* __restrict__ A, int lda, const u16* __restrict__ Bt, int K, int ntn, GemmEpi ep, char* smem,
;                                           int mbase, int mrows) {
;     ...
;     for (int kt = 0; kt < nk; ++kt) {
;       if (kt + 1 < nk) {
;         if (MF == 8) asm volatile("s_waitcnt vmcnt(6)" ::: "memory");
;         else asm volatile("s_waitcnt vmcnt(3)" ::: "memory");
;       } else asm volatile("s_waitcnt vmcnt(0)" ::: "memory");
;       asm volatile("s_waitcnt lgkmcnt(0)" ::: "memory");
;       __builtin_amdgcn_s_barrier();
;       const u16* a_ = sbase + (kt % 3) * STG;
;       const u16* b_ = a_ + BM * 32;
;       bf16x8 bfr[4], afc[2], afn[2];
;       const u16* ap_ = a_ + (wr * (16 * MF) + fr) * 32 + fq * 8;
; #pragma unroll
;       for (int n = 0; n < 4; ++n) bfr[n] = rd_std(b_ + (wc * 64 + n * 16 + fr) * 32 + fq * 8);
;       afc[0] = rd_std(ap_); afc[1] = rd_std(ap_ + 16 * 32);
;       __builtin_amdgcn_sched_barrier(0);
;       if (kt + 2 < nk) GEMM_ISSUE(kt + 2);
;       __builtin_amdgcn_sched_barrier(0);
; #pragma unroll
;       for (int mh = 0; mh < MF / 2; ++mh) {
;         if (mh + 1 < MF / 2) {
;           afn[0] = rd_std(ap_ + ((mh + 1) * 2) * 16 * 32);
;           afn[1] = rd_std(ap_ + ((mh + 1) * 2 + 1) * 16 * 32);
;         }
;         __builtin_amdgcn_sched_barrier(0);
; #pragma unroll
;         for (int m = 0; m < 2; ++m)
; #pragma unroll
;           for (int n = 0; n < 4; ++n) acc[mh * 2 + m][n] = MFMA(bfr[n], afc[m], acc[mh * 2 + m][n]);
;         __builtin_amdgcn_sched_barrier(0);
;         afc[0] = afn[0]; afc[1] = afn[1];
;       }
;     }
	ds_read_b128 v[136:139], v165
	ds_read_b128 v[146:149], v165 offset:1024
	ds_read_b128 v[150:153], v165 offset:2048
	ds_read_b128 v[166:169], v165 offset:3072
	ds_read_b128 v[170:173], v162 offset:49152
	ds_read_b128 v[174:177], v162 offset:50176
	s_mul_hi_u32 s14, s14, 0xaaaaaaab
	s_lshr_b32 s14, s14, 1
	s_mul_i32 s14, s14, 0x12000
	s_sub_i32 s3, s3, s14
	s_add_i32 s3, s3, 0
	s_addk_i32 s3, 0x6000
	ds_read_b128 v[178:181], v162 offset:52224
	ds_read_b128 v[182:185], v162 offset:51200
	s_waitcnt lgkmcnt(0)
	v_mfma_f32_16x16x32_bf16 v[126:129], v[136:139], v[170:173], v[126:129]
	v_mfma_f32_16x16x32_bf16 v[122:125], v[146:149], v[170:173], v[122:125]
	v_mfma_f32_16x16x32_bf16 v[118:121], v[150:153], v[170:173], v[118:121]
	v_mfma_f32_16x16x32_bf16 v[114:117], v[166:169], v[170:173], v[114:117]
	v_mfma_f32_16x16x32_bf16 v[110:113], v[136:139], v[174:177], v[110:113]
	v_mfma_f32_16x16x32_bf16 v[106:109], v[146:149], v[174:177], v[106:109]
	v_mfma_f32_16x16x32_bf16 v[102:105], v[150:153], v[174:177], v[102:105]
	v_mfma_f32_16x16x32_bf16 v[98:101], v[166:169], v[174:177], v[98:101]
	ds_read_b128 v[170:173], v162 offset:54272
	ds_read_b128 v[174:177], v162 offset:53248
	v_mfma_f32_16x16x32_bf16 v[94:97], v[136:139], v[182:185], v[94:97]
	v_mfma_f32_16x16x32_bf16 v[90:93], v[146:149], v[182:185], v[90:93]
	v_mfma_f32_16x16x32_bf16 v[86:89], v[150:153], v[182:185], v[86:89]
	v_mfma_f32_16x16x32_bf16 v[82:85], v[166:169], v[182:185], v[82:85]
	v_mfma_f32_16x16x32_bf16 v[78:81], v[136:139], v[178:181], v[78:81]
	v_mfma_f32_16x16x32_bf16 v[74:77], v[146:149], v[178:181], v[74:77]
	v_mfma_f32_16x16x32_bf16 v[70:73], v[150:153], v[178:181], v[70:73]
	v_mfma_f32_16x16x32_bf16 v[66:69], v[166:169], v[178:181], v[66:69]
	ds_read_b128 v[178:181], v162 offset:56320
	ds_read_b128 v[182:185], v162 offset:55296
	s_waitcnt lgkmcnt(0)
	v_mfma_f32_16x16x32_bf16 v[62:65], v[136:139], v[174:177], v[62:65]
	v_mfma_f32_16x16x32_bf16 v[58:61], v[146:149], v[174:177], v[58:61]
	v_mfma_f32_16x16x32_bf16 v[54:57], v[150:153], v[174:177], v[54:57]
	v_mfma_f32_16x16x32_bf16 v[50:53], v[166:169], v[174:177], v[50:53]
	v_mfma_f32_16x16x32_bf16 v[46:49], v[136:139], v[170:173], v[46:49]
	v_mfma_f32_16x16x32_bf16 v[42:45], v[146:149], v[170:173], v[42:45]
	v_mfma_f32_16x16x32_bf16 v[38:41], v[150:153], v[170:173], v[38:41]
	v_mfma_f32_16x16x32_bf16 v[34:37], v[166:169], v[170:173], v[34:37]
	v_mfma_f32_16x16x32_bf16 v[30:33], v[136:139], v[182:185], v[30:33]
	v_mfma_f32_16x16x32_bf16 v[26:29], v[146:149], v[182:185], v[26:29]
	v_mfma_f32_16x16x32_bf16 v[22:25], v[150:153], v[182:185], v[22:25]
	v_mfma_f32_16x16x32_bf16 v[18:21], v[166:169], v[182:185], v[18:21]
	v_mfma_f32_16x16x32_bf16 v[14:17], v[136:139], v[178:181], v[14:17]
	v_mfma_f32_16x16x32_bf16 v[10:13], v[146:149], v[178:181], v[10:13]
	v_mfma_f32_16x16x32_bf16 v[6:9], v[150:153], v[178:181], v[6:9]
	v_mfma_f32_16x16x32_bf16 v[2:5], v[166:169], v[178:181], v[2:5]
	v_lshl_add_u32 v136, v155, 1, s3
	s_waitcnt vmcnt(0)
	v_add3_u32 v166, v136, v158, v159
	s_waitcnt lgkmcnt(0)
	s_barrier
; #define MFMA(a, b, c) __builtin_amdgcn_mfma_f32_16x16x32_bf16((a), (b), (c), 0, 0, 0)
; template <int EPI, int MF>
; __device__ __forceinline__ void gemm_part(const u16* __restrict__ A, int lda, const u16* __restrict__ Bt, int K, int ntn, GemmEpi ep, char* smem,
;                                           int mbase, int mrows) {
;     ...
; #pragma unroll
;       for (int n = 0; n < 4; ++n) bfr[n] = rd_std(b_ + (wc * 64 + n * 16 + fr) * 32 + fq * 8);
;       afc[0] = rd_std(ap_); afc[1] = rd_std(ap_ + 16 * 32);
;       __builtin_amdgcn_sched_barrier(0);
;       if (kt + 2 < nk) GEMM_ISSUE(kt + 2);
;       __builtin_amdgcn_sched_barrier(0);
; #pragma unroll
;       for (int mh = 0; mh < MF / 2; ++mh) {
;         if (mh + 1 < MF / 2) {
;           afn[0] = rd_std(ap_ + ((mh + 1) * 2) * 16 * 32);
;           afn[1] = rd_std(ap_ + ((mh + 1) * 2 + 1) * 16 * 32);
;         }
;         __builtin_amdgcn_sched_barrier(0);
; #pragma unroll
;         for (int m = 0; m < 2; ++m)
; #pragma unroll
;           for (int n = 0; n < 4; ++n) acc[mh * 2 + m][n] = MFMA(bfr[n], afc[m], acc[mh * 2 + m][n]);
;         __builtin_amdgcn_sched_barrier(0);
;         afc[0] = afn[0]; afc[1] = afn[1];
;       }
;     }
;     ...
;       } else if (EPI == EPI_RESID) {
;         const float* rp = (row < MP) ? ep.res0 + (size_t)row * DM : ep.res1 + (size_t)(row - MP) * DM;
;         float ssq = 0.f;
; #pragma unroll
;         for (int n = 0; n < 4; ++n) {
;           const int col = cb + n * 16;
;           const float4 r = *(const float4*)(rp + col);
;           float4 v;
;           v.x = r.x + ep.scale * acc[m][n][0]; v.y = r.y + ep.scale * acc[m][n][1];
;           v.z = r.z + ep.scale * acc[m][n][2]; v.w = r.w + ep.scale * acc[m][n][3];
;           *(float4*)(ep.outf + (size_t)row * DM + col) = v;
;           if (ep.xcopy) {
;             bf16x4 o;
;             o[0] = (short)f2bf(v.x); o[1] = (short)f2bf(v.y); o[2] = (short)f2bf(v.z); o[3] = (short)f2bf(v.w);
;             *(bf16x4*)(ep.xcopy + (size_t)row * DM + col) = o;
;           }
	ds_read_b128 v[136:139], v166 offset:16384
	ds_read_b128 v[146:149], v166 offset:17408
	ds_read_b128 v[150:153], v166 offset:18432
	ds_read_b128 v[166:169], v166 offset:19456
	ds_read_b128 v[170:173], v162
	ds_read_b128 v[174:177], v162 offset:1024
	ds_read_b128 v[178:181], v162 offset:3072
	ds_read_b128 v[182:185], v162 offset:2048
	s_waitcnt lgkmcnt(0)
	v_mfma_f32_16x16x32_bf16 v[126:129], v[136:139], v[170:173], v[126:129]
	v_mfma_f32_16x16x32_bf16 v[122:125], v[146:149], v[170:173], v[122:125]
	v_mfma_f32_16x16x32_bf16 v[118:121], v[150:153], v[170:173], v[118:121]
	v_mfma_f32_16x16x32_bf16 v[114:117], v[166:169], v[170:173], v[114:117]
	v_mfma_f32_16x16x32_bf16 v[110:113], v[136:139], v[174:177], v[110:113]
	v_mfma_f32_16x16x32_bf16 v[106:109], v[146:149], v[174:177], v[106:109]
	v_mfma_f32_16x16x32_bf16 v[102:105], v[150:153], v[174:177], v[102:105]
	v_mfma_f32_16x16x32_bf16 v[98:101], v[166:169], v[174:177], v[98:101]
	ds_read_b128 v[170:173], v162 offset:5120
	ds_read_b128 v[174:177], v162 offset:4096
	v_mfma_f32_16x16x32_bf16 v[94:97], v[136:139], v[182:185], v[94:97]
	v_mfma_f32_16x16x32_bf16 v[90:93], v[146:149], v[182:185], v[90:93]
	v_mfma_f32_16x16x32_bf16 v[86:89], v[150:153], v[182:185], v[86:89]
	v_mfma_f32_16x16x32_bf16 v[82:85], v[166:169], v[182:185], v[82:85]
	v_mfma_f32_16x16x32_bf16 v[78:81], v[136:139], v[178:181], v[78:81]
	v_mfma_f32_16x16x32_bf16 v[74:77], v[146:149], v[178:181], v[74:77]
	v_mfma_f32_16x16x32_bf16 v[70:73], v[150:153], v[178:181], v[70:73]
	v_mfma_f32_16x16x32_bf16 v[66:69], v[166:169], v[178:181], v[66:69]
	ds_read_b128 v[178:181], v162 offset:7168
	ds_read_b128 v[182:185], v162 offset:6144
	s_waitcnt lgkmcnt(0)
	v_mfma_f32_16x16x32_bf16 v[62:65], v[136:139], v[174:177], v[62:65]
	v_mfma_f32_16x16x32_bf16 v[58:61], v[146:149], v[174:177], v[58:61]
	v_mfma_f32_16x16x32_bf16 v[54:57], v[150:153], v[174:177], v[54:57]
	v_mfma_f32_16x16x32_bf16 v[50:53], v[166:169], v[174:177], v[50:53]
	v_mfma_f32_16x16x32_bf16 v[46:49], v[136:139], v[170:173], v[46:49]
	v_mfma_f32_16x16x32_bf16 v[42:45], v[146:149], v[170:173], v[42:45]
	v_mfma_f32_16x16x32_bf16 v[38:41], v[150:153], v[170:173], v[38:41]
	v_mfma_f32_16x16x32_bf16 v[34:37], v[166:169], v[170:173], v[34:37]
	v_mfma_f32_16x16x32_bf16 v[30:33], v[136:139], v[182:185], v[30:33]
	v_mfma_f32_16x16x32_bf16 v[26:29], v[146:149], v[182:185], v[26:29]
	v_mfma_f32_16x16x32_bf16 v[22:25], v[150:153], v[182:185], v[22:25]
	v_mfma_f32_16x16x32_bf16 v[18:21], v[166:169], v[182:185], v[18:21]
	v_mfma_f32_16x16x32_bf16 v[14:17], v[136:139], v[178:181], v[14:17]
	v_mfma_f32_16x16x32_bf16 v[10:13], v[146:149], v[178:181], v[10:13]
	v_mfma_f32_16x16x32_bf16 v[6:9], v[150:153], v[178:181], v[6:9]
	v_mfma_f32_16x16x32_bf16 v[2:5], v[166:169], v[178:181], v[2:5]
	v_add_u32_e32 v138, s2, v156
	s_waitcnt vmcnt(0)
	s_barrier
	s_mov_b32 s2, 0xffff
	v_cmp_lt_i32_e32 vcc, s2, v138
	s_and_saveexec_b64 s[2:3], vcc
	s_xor_b64 s[2:3], exec, s[2:3]
	v_add_u32_e32 v136, 0xffff0000, v138
	v_mov_b32_e32 v137, v0
	v_lshlrev_b64 v[136:137], 12, v[136:137]
	v_lshl_add_u64 v[136:137], s[18:19], 0, v[136:137]
	v_mov_b32_e32 v139, v0
	s_andn2_saveexec_b64 s[2:3], s[2:3]
	v_ashrrev_i32_e32 v139, 31, v138
	v_lshlrev_b64 v[136:137], 12, v[138:139]
	v_lshl_add_u64 v[136:137], s[8:9], 0, v[136:137]
	s_or_b64 exec, exec, s[2:3]
	v_lshlrev_b64 v[146:147], 12, v[138:139]
	v_or_b32_e32 v170, s11, v157
	v_lshl_add_u64 v[150:151], s[26:27], 0, v[146:147]
	v_lshlrev_b64 v[146:147], 11, v[138:139]
	v_lshl_add_u64 v[148:149], s[44:45], 0, v[146:147]
	v_lshlrev_b32_e32 v146, 2, v170
	v_mov_b32_e32 v147, v0
	v_lshl_add_u64 v[152:153], v[136:137], 0, v[146:147]
	global_load_dwordx4 v[166:169], v[152:153], off
	global_load_dwordx4 v[172:175], v[152:153], off offset:64
	global_load_dwordx4 v[176:179], v[152:153], off offset:128
	global_load_dwordx4 v[180:183], v[152:153], off offset:192
	v_readlane_b32 s2, v253, 24
	v_readlane_b32 s3, v253, 25
	v_lshl_add_u64 v[150:151], v[150:151], 0, v[146:147]
	s_andn2_b64 vcc, exec, s[2:3]
	v_cndmask_b32_e64 v136, 0, 1, s[2:3]
	v_cmp_ne_u32_e64 s[14:15], 1, v136
	v_lshlrev_b32_e32 v136, 1, v170
	s_waitcnt vmcnt(0)
	v_pk_fma_f32 v[126:127], v[126:127], 0.5, v[166:167] op_sel_hi:[1,0,1]
	v_pk_fma_f32 v[128:129], v[128:129], 0.5, v[168:169] op_sel_hi:[1,0,1]
	global_store_dwordx4 v[150:151], v[126:129], off
	s_cbranch_vccnz .LBB0_212
	v_mov_b32_e32 v137, v0
	v_cvt_pk_bf16_f32 v166, v126, v127
	v_cvt_pk_bf16_f32 v167, v128, v129
	v_lshl_add_u64 v[168:169], v[148:149], 0, v[136:137]
	global_store_dwordx2 v[168:169], v[166:167], off

; template <int EPI, int MF>
; __device__ __forceinline__ void gemm_part(const u16* __restrict__ A, int lda, const u16* __restrict__ Bt, int K, int ntn, GemmEpi ep, char* smem,
;                                           int mbase, int mrows) {
;     ...
;   for (int q = xcd; q * nbx < total; q += (MF == 2) ? 1 : 8) {
;     const int L = q * nbx + li;
;     if (L >= total) continue;
;     const int g = L / (8 * ntn), rr = L % (8 * ntn);
;     const int rows = min(8, ntm - 8 * g);
;     const int tm = 8 * g + rr % rows, tn = rr / rows;
;     const int row0 = mbase + tm * BM, col0 = tn * 128;
;     f32x4 acc[MF][4];
; #pragma unroll
;     for (int m = 0; m < MF; ++m)
; #pragma unroll
;       for (int n = 0; n < 4; ++n) acc[m][n] = (f32x4){0.f, 0.f, 0.f, 0.f};
;     const u16* gA = A + (size_t)(row0 + (tid >> 2)) * lda + (tid & 3) * 8;
;     const u16* gB = Bt + (size_t)(col0 + (tid >> 2)) * K + (tid & 3) * 8;
;     ...
;     GEMM_ISSUE(0);
;     GEMM_ISSUE(1);
;     for (int kt = 0; kt < nk; ++kt) {
;       if (kt + 1 < nk) {
;         if (MF == 8) asm volatile("s_waitcnt vmcnt(6)" ::: "memory");
;         else asm volatile("s_waitcnt vmcnt(3)" ::: "memory");
;       } else asm volatile("s_waitcnt vmcnt(0)" ::: "memory");
;       asm volatile("s_waitcnt lgkmcnt(0)" ::: "memory");
;       __builtin_amdgcn_s_barrier();
;       const u16* a_ = sbase + (kt % 3) * STG;
;       const u16* b_ = a_ + BM * 32;
;       bf16x8 bfr[4], afc[2], afn[2];
;       const u16* ap_ = a_ + (wr * (16 * MF) + fr) * 32 + fq * 8;
; #pragma unroll
;       for (int n = 0; n < 4; ++n) bfr[n] = rd_std(b_ + (wc * 64 + n * 16 + fr) * 32 + fq * 8);
;       afc[0] = rd_std(ap_); afc[1] = rd_std(ap_ + 16 * 32);
;       __builtin_amdgcn_sched_barrier(0);
;       if (kt + 2 < nk) GEMM_ISSUE(kt + 2);
;       __builtin_amdgcn_sched_barrier(0);
; #pragma unroll
;       for (int mh = 0; mh < MF / 2; ++mh) {
;         if (mh + 1 < MF / 2) {
;           afn[0] = rd_std(ap_ + ((mh + 1) * 2) * 16 * 32);
;           afn[1] = rd_std(ap_ + ((mh + 1) * 2 + 1) * 16 * 32);
;         }
;         __builtin_amdgcn_sched_barrier(0);
; #pragma unroll
;         for (int m = 0; m < 2; ++m)
; #pragma unroll
;           for (int n = 0; n < 4; ++n) acc[mh * 2 + m][n] = MFMA(bfr[n], afc[m], acc[mh * 2 + m][n]);
;         __builtin_amdgcn_sched_barrier(0);
;         afc[0] = afn[0]; afc[1] = afn[1];
;       }
;     }
.LBB0_336:
	s_add_i32 s2, s2, s64
	s_cmp_gt_i32 s2, 63
	s_cbranch_scc1 .LBB0_335
	s_ashr_i32 s3, s2, 31
	s_lshr_b32 s3, s3, 26
	s_add_i32 s3, s2, s3
	s_and_b32 s5, s3, 0xffc0
	s_sub_i32 s2, s2, s5
	s_bfe_i32 s5, s2, 0x80000
	s_bfe_u32 s5, s5, 0x3000c
	s_add_i32 s5, s2, s5
	s_bfe_i32 s10, s5, 0x80000
	s_and_b32 s5, s5, 0xf8
	s_sub_i32 s2, s2, s5
	s_sext_i32_i8 s2, s2
	s_lshl_b32 s3, s3, 3
	s_sext_i32_i16 s10, s10
	s_and_b32 s3, s3, 0xfffffe00
	s_lshl_b32 s2, s2, 6
	s_add_i32 s2, s3, s2
	s_lshl_b32 s3, s10, 4
	s_add_i32 s2, s2, 0x10000
	s_and_b32 s5, s3, 0xffffff80
	v_add_u32_e32 v8, s2, v1
	v_add_u32_e32 v9, s5, v1
	v_readfirstlane_b32 s3, v52
	v_add_u32_e32 v6, 0x1000, v52
	s_waitcnt lgkmcnt(0)
	v_mad_i64_i32 v[2:3], s[10:11], v8, s33, v[34:35]
	v_bfe_u32 v12, v140, 2, 1
	v_mul_u32_u24_e32 v12, 0x15c0, v12
	v_sub_u32_e32 v12, 0, v12
	v_ashrrev_i32_e32 v13, 31, v12
	v_lshl_add_u64 v[2:3], v[2:3], 0, v[12:13]
	v_mad_i64_i32 v[4:5], s[10:11], v9, s33, v[36:37]
	v_lshl_add_u64 v[4:5], v[4:5], 0, v[12:13]
	s_mov_b32 m0, s3
	v_readfirstlane_b32 s3, v6
	v_add_u32_e32 v10, 0x2000, v52
	global_load_lds_dwordx4 v[2:3], off
	s_mov_b32 m0, s3
	s_mov_b64 s[10:11], 0x58000
	v_readfirstlane_b32 s3, v10
	global_load_lds_dwordx4 v[4:5], off
	v_lshl_add_u64 v[6:7], v[4:5], 0, s[10:11]
	s_mov_b32 m0, s3
	v_lshl_add_u64 v[2:3], v[2:3], 0, 64
	v_lshl_add_u64 v[2:3], v[2:3], 0, 64
	global_load_lds_dwordx4 v[6:7], off
	v_add_u32_e32 v6, 0x3000, v52
	s_mov_b64 s[10:11], 0x58040
	v_readfirstlane_b32 s3, v6
	v_add_u32_e32 v6, 0x4000, v52
	s_mov_b32 m0, s3
	v_readfirstlane_b32 s3, v6
	global_load_lds_dwordx4 v[2:3], off
	v_lshl_add_u64 v[2:3], v[4:5], 0, 64
	v_lshl_add_u64 v[2:3], v[2:3], 0, 64
	s_mov_b32 m0, s3
	s_nop 0
	global_load_lds_dwordx4 v[2:3], off
	v_lshl_add_u64 v[2:3], v[4:5], 0, s[10:11]
	v_lshl_add_u64 v[2:3], v[2:3], 0, 64
	v_add_u32_e32 v4, 0x5000, v52
	s_mov_b32 s10, 3
	v_readfirstlane_b32 s3, v4
	s_mov_b32 m0, s3
	s_mov_b32 s3, 0
	global_load_lds_dwordx4 v[2:3], off
	v_mov_b64_e32 v[2:3], s[20:21]
	v_mad_i64_i32 v[40:41], s[14:15], v9, s33, v[2:3]
	v_lshl_add_u64 v[40:41], v[40:41], 0, v[12:13]
	v_lshl_add_u64 v[40:41], v[40:41], 0, 64
	v_lshl_add_u64 v[40:41], v[40:41], 0, 64
	v_mov_b64_e32 v[2:3], s[46:47]
	v_mad_i64_i32 v[42:43], s[14:15], v8, s33, v[2:3]
	v_lshl_add_u64 v[42:43], v[42:43], 0, v[12:13]
	v_lshl_add_u64 v[42:43], v[42:43], 0, 64
	v_lshl_add_u64 v[42:43], v[42:43], 0, 64
	v_mov_b32_e32 v2, 0
	s_mov_b32 s11, 1
	s_mov_b32 s14, 2
	s_mov_b32 s15, 0
	v_mov_b32_e32 v3, v2
	v_mov_b32_e32 v4, v2
	v_mov_b32_e32 v5, v2
	v_mov_b32_e32 v6, v2
	v_mov_b32_e32 v7, v2
	v_mov_b32_e32 v8, v2
	v_mov_b32_e32 v9, v2
	v_mov_b32_e32 v10, v2
	v_mov_b32_e32 v11, v2
	v_mov_b32_e32 v12, v2
	v_mov_b32_e32 v13, v2
	v_mov_b32_e32 v14, v2
	v_mov_b32_e32 v15, v2
	v_mov_b32_e32 v16, v2
	v_mov_b32_e32 v17, v2
	v_mov_b32_e32 v18, v2
	v_mov_b32_e32 v19, v2
	v_mov_b32_e32 v20, v2
	v_mov_b32_e32 v21, v2
	v_mov_b32_e32 v22, v2
	v_mov_b32_e32 v23, v2
	v_mov_b32_e32 v24, v2
	v_mov_b32_e32 v25, v2
	v_mov_b32_e32 v26, v2
	v_mov_b32_e32 v27, v2
	v_mov_b32_e32 v28, v2
	v_mov_b32_e32 v29, v2
	v_mov_b32_e32 v30, v2
	v_mov_b32_e32 v31, v2
	v_mov_b32_e32 v32, v2
	v_mov_b32_e32 v33, v2
.LBB0_338:
	s_mul_hi_u32 s17, s15, 0xaaaaaaab
	s_lshr_b32 s17, s17, 1
	s_mul_i32 s17, s17, 0x9000
	s_mul_hi_u32 s16, s11, 0xaaaaaaab
	v_subrev_u32_e32 v44, s17, v60
	v_add_u32_e32 v97, s3, v58
	s_lshr_b32 s16, s16, 1
	s_waitcnt vmcnt(3)
	v_add_u32_e32 v74, v97, v44
	s_mul_i32 s16, s16, 0x9000
	v_subrev_u32_e32 v78, s17, v61
	s_waitcnt lgkmcnt(0)
	s_barrier
	ds_read_b128 v[44:47], v74 offset:4096
	ds_read_b128 v[48:51], v74 offset:5120
	ds_read_b128 v[70:73], v74 offset:6144
	ds_read_b128 v[74:77], v74 offset:7168
	v_subrev_u32_e32 v92, s16, v60
	v_subrev_u32_e32 v93, s16, v62
	s_mul_hi_u32 s16, s10, 0xaaaaaaab
	v_add_u32_e32 v82, v97, v78
	s_lshr_b32 s16, s16, 1
	ds_read_b128 v[78:81], v82
	ds_read_b128 v[82:85], v82 offset:1024
	s_mul_i32 s16, s16, 0x9000
	v_subrev_u32_e32 v94, s16, v63
	v_subrev_u32_e32 v95, s16, v64
	v_subrev_u32_e32 v96, s16, v65
	s_mul_hi_u32 s16, s14, 0xaaaaaaab
	s_lshr_b32 s16, s16, 1
	s_mul_i32 s16, s16, 0x9000
	s_waitcnt vmcnt(0)
	v_subrev_u32_e32 v90, s16, v66
	v_subrev_u32_e32 v98, s16, v67
	v_subrev_u32_e32 v99, s16, v68
	s_add_i32 s16, s3, 0
	v_add_u32_e32 v90, s16, v90
	v_lshl_add_u64 v[86:87], v[42:43], 0, v[38:39]
	v_readfirstlane_b32 s17, v90
	v_lshl_add_u64 v[88:89], v[86:87], 0, s[74:75]
	s_mov_b32 m0, s17
	v_add_u32_e32 v98, s16, v98
	global_load_lds_dwordx4 v[88:89], off
	v_lshl_add_u64 v[88:89], v[40:41], 0, v[38:39]
	v_readfirstlane_b32 s17, v98
	v_add_u32_e32 v98, s16, v99
	v_lshl_add_u64 v[90:91], v[88:89], 0, s[74:75]
	s_mov_b32 m0, s17
	v_readfirstlane_b32 s17, v98
	global_load_lds_dwordx4 v[90:91], off
	v_lshl_add_u64 v[90:91], v[88:89], 0, s[56:57]
	s_mov_b32 m0, s17
	s_add_i32 s15, s15, 2
	global_load_lds_dwordx4 v[90:91], off
	s_waitcnt lgkmcnt(0)
	v_mfma_f32_16x16x32_bf16 v[30:33], v[44:47], v[78:81], v[30:33]
	v_mfma_f32_16x16x32_bf16 v[26:29], v[48:51], v[78:81], v[26:29]
	v_mfma_f32_16x16x32_bf16 v[22:25], v[70:73], v[78:81], v[22:25]
	v_mfma_f32_16x16x32_bf16 v[18:21], v[74:77], v[78:81], v[18:21]
	v_mfma_f32_16x16x32_bf16 v[14:17], v[44:47], v[82:85], v[14:17]
	v_mfma_f32_16x16x32_bf16 v[10:13], v[48:51], v[82:85], v[10:13]
	v_mfma_f32_16x16x32_bf16 v[6:9], v[70:73], v[82:85], v[6:9]
	v_mfma_f32_16x16x32_bf16 v[2:5], v[74:77], v[82:85], v[2:5]
	s_waitcnt vmcnt(3)
	v_add_u32_e32 v74, v97, v92
	s_waitcnt lgkmcnt(0)
	s_barrier
; #define MFMA(a, b, c) __builtin_amdgcn_mfma_f32_16x16x32_bf16((a), (b), (c), 0, 0, 0)
; template <int EPI, int MF>
; __device__ __forceinline__ void gemm_part(const u16* __restrict__ A, int lda, const u16* __restrict__ Bt, int K, int ntn, GemmEpi ep, char* smem,
;                                           int mbase, int mrows) {
;     ...
;     for (int kt = 0; kt < nk; ++kt) {
;       if (kt + 1 < nk) {
;         if (MF == 8) asm volatile("s_waitcnt vmcnt(6)" ::: "memory");
;         else asm volatile("s_waitcnt vmcnt(3)" ::: "memory");
;       } else asm volatile("s_waitcnt vmcnt(0)" ::: "memory");
;       asm volatile("s_waitcnt lgkmcnt(0)" ::: "memory");
;       __builtin_amdgcn_s_barrier();
;       const u16* a_ = sbase + (kt % 3) * STG;
;       const u16* b_ = a_ + BM * 32;
;       bf16x8 bfr[4], afc[2], afn[2];
;       const u16* ap_ = a_ + (wr * (16 * MF) + fr) * 32 + fq * 8;
; #pragma unroll
;       for (int n = 0; n < 4; ++n) bfr[n] = rd_std(b_ + (wc * 64 + n * 16 + fr) * 32 + fq * 8);
;       afc[0] = rd_std(ap_); afc[1] = rd_std(ap_ + 16 * 32);
;       __builtin_amdgcn_sched_barrier(0);
;       if (kt + 2 < nk) GEMM_ISSUE(kt + 2);
;       __builtin_amdgcn_sched_barrier(0);
; #pragma unroll
;       for (int mh = 0; mh < MF / 2; ++mh) {
;         if (mh + 1 < MF / 2) {
;           afn[0] = rd_std(ap_ + ((mh + 1) * 2) * 16 * 32);
;           afn[1] = rd_std(ap_ + ((mh + 1) * 2 + 1) * 16 * 32);
;         }
;         __builtin_amdgcn_sched_barrier(0);
; #pragma unroll
;         for (int m = 0; m < 2; ++m)
; #pragma unroll
;           for (int n = 0; n < 4; ++n) acc[mh * 2 + m][n] = MFMA(bfr[n], afc[m], acc[mh * 2 + m][n]);
;         __builtin_amdgcn_sched_barrier(0);
;         afc[0] = afn[0]; afc[1] = afn[1];
;       }
;     }
;     ...
;       } else if (EPI == EPI_RESID) {
;         const float* rp = (row < MP) ? ep.res0 + (size_t)row * DM : ep.res1 + (size_t)(row - MP) * DM;
;         float ssq = 0.f;
; #pragma unroll
;         for (int n = 0; n < 4; ++n) {
;           const int col = cb + n * 16;
;           const float4 r = *(const float4*)(rp + col);
;           float4 v;
;           v.x = r.x + ep.scale * acc[m][n][0]; v.y = r.y + ep.scale * acc[m][n][1];
;           v.z = r.z + ep.scale * acc[m][n][2]; v.w = r.w + ep.scale * acc[m][n][3];
;           *(float4*)(ep.outf + (size_t)row * DM + col) = v;
;           if (ep.xcopy) {
;             bf16x4 o;
	ds_read_b128 v[44:47], v74 offset:16384
	ds_read_b128 v[48:51], v74 offset:17408
	ds_read_b128 v[70:73], v74 offset:18432
	ds_read_b128 v[74:77], v74 offset:19456
	v_add_u32_e32 v82, v97, v93
	ds_read_b128 v[78:81], v82
	ds_read_b128 v[82:85], v82 offset:1024
	v_add_u32_e32 v90, s16, v96
	v_lshl_add_u64 v[86:87], v[86:87], 0, s[52:53]
	v_lshl_add_u64 v[86:87], v[86:87], 0, 64
	v_readfirstlane_b32 s17, v90
	v_add_u32_e32 v90, s16, v95
	s_mov_b32 m0, s17
	v_readfirstlane_b32 s17, v90
	global_load_lds_dwordx4 v[86:87], off
	v_lshl_add_u64 v[86:87], v[88:89], 0, s[52:53]
	v_lshl_add_u64 v[86:87], v[86:87], 0, 64
	s_mov_b32 m0, s17
	s_nop 0
	global_load_lds_dwordx4 v[86:87], off
	v_lshl_add_u64 v[86:87], v[88:89], 0, s[0:1]
	v_lshl_add_u64 v[86:87], v[86:87], 0, 64
	v_add_u32_e32 v88, s16, v94
	s_nop 0
	v_readfirstlane_b32 s16, v88
	s_mov_b32 m0, s16
	s_nop 0
	global_load_lds_dwordx4 v[86:87], off
	s_waitcnt lgkmcnt(0)
	v_mfma_f32_16x16x32_bf16 v[30:33], v[44:47], v[78:81], v[30:33]
	v_mfma_f32_16x16x32_bf16 v[26:29], v[48:51], v[78:81], v[26:29]
	v_mfma_f32_16x16x32_bf16 v[22:25], v[70:73], v[78:81], v[22:25]
	v_mfma_f32_16x16x32_bf16 v[18:21], v[74:77], v[78:81], v[18:21]
	v_mfma_f32_16x16x32_bf16 v[14:17], v[44:47], v[82:85], v[14:17]
	v_mfma_f32_16x16x32_bf16 v[10:13], v[48:51], v[82:85], v[10:13]
	v_mfma_f32_16x16x32_bf16 v[6:9], v[70:73], v[82:85], v[6:9]
	v_mfma_f32_16x16x32_bf16 v[2:5], v[74:77], v[82:85], v[2:5]
	s_addk_i32 s3, 0x6000
	s_add_i32 s11, s11, 2
	s_add_i32 s10, s10, 2
	s_add_i32 s14, s14, 2
	v_lshl_add_u64 v[40:41], v[40:41], 0, s[74:75]
	v_lshl_add_u64 v[40:41], v[40:41], 0, s[74:75]
	s_cmp_eq_u32 s3, 0x102000
	v_lshl_add_u64 v[42:43], v[42:43], 0, s[74:75]
	v_lshl_add_u64 v[42:43], v[42:43], 0, s[74:75]
	s_cbranch_scc0 .LBB0_338
	s_waitcnt vmcnt(3)
	s_waitcnt lgkmcnt(0)
	s_barrier
	ds_read_b128 v[40:43], v69 offset:28672
	ds_read_b128 v[44:47], v69 offset:29696
	ds_read_b128 v[48:51], v69 offset:30720
	ds_read_b128 v[70:73], v69 offset:31744
	ds_read_b128 v[74:77], v59 offset:24576
	ds_read_b128 v[78:81], v59 offset:25600
	s_mul_hi_u32 s10, s11, 0xaaaaaaab
	s_lshr_b32 s10, s10, 1
	s_mul_i32 s10, s10, 0x9000
	s_sub_i32 s3, s3, s10
	s_add_i32 s3, s3, 0
	s_addk_i32 s3, 0x3000
	s_waitcnt lgkmcnt(0)
	v_mfma_f32_16x16x32_bf16 v[30:33], v[40:43], v[74:77], v[30:33]
	v_mfma_f32_16x16x32_bf16 v[26:29], v[44:47], v[74:77], v[26:29]
	v_mfma_f32_16x16x32_bf16 v[22:25], v[48:51], v[74:77], v[22:25]
	v_mfma_f32_16x16x32_bf16 v[18:21], v[70:73], v[74:77], v[18:21]
	v_mfma_f32_16x16x32_bf16 v[14:17], v[40:43], v[78:81], v[14:17]
	v_mfma_f32_16x16x32_bf16 v[10:13], v[44:47], v[78:81], v[10:13]
	v_mfma_f32_16x16x32_bf16 v[6:9], v[48:51], v[78:81], v[6:9]
	v_mfma_f32_16x16x32_bf16 v[2:5], v[70:73], v[78:81], v[2:5]
	v_lshl_add_u32 v40, v54, 1, s3
	s_waitcnt vmcnt(0)
	v_add3_u32 v70, v40, v57, v53
	s_waitcnt lgkmcnt(0)
	s_barrier
	ds_read_b128 v[40:43], v70 offset:4096
	ds_read_b128 v[44:47], v70 offset:5120
	ds_read_b128 v[48:51], v70 offset:6144
	ds_read_b128 v[70:73], v70 offset:7168
	ds_read_b128 v[74:77], v59
	ds_read_b128 v[78:81], v59 offset:1024
	s_waitcnt lgkmcnt(0)
	v_mfma_f32_16x16x32_bf16 v[30:33], v[40:43], v[74:77], v[30:33]
	v_mfma_f32_16x16x32_bf16 v[26:29], v[44:47], v[74:77], v[26:29]
	v_mfma_f32_16x16x32_bf16 v[22:25], v[48:51], v[74:77], v[22:25]
	v_mfma_f32_16x16x32_bf16 v[18:21], v[70:73], v[74:77], v[18:21]
	v_mfma_f32_16x16x32_bf16 v[14:17], v[40:43], v[78:81], v[14:17]
	v_mfma_f32_16x16x32_bf16 v[10:13], v[44:47], v[78:81], v[10:13]
	v_mfma_f32_16x16x32_bf16 v[6:9], v[48:51], v[78:81], v[6:9]
	v_mfma_f32_16x16x32_bf16 v[2:5], v[70:73], v[78:81], v[2:5]
	v_add_u32_e32 v42, s2, v55
	s_waitcnt vmcnt(0)
	s_barrier
	s_mov_b32 s2, 0xffff
	v_cmp_lt_i32_e32 vcc, s2, v42
	s_and_saveexec_b64 s[2:3], vcc
	s_xor_b64 s[2:3], exec, s[2:3]
	v_add_u32_e32 v40, 0xffff0000, v42
	v_mov_b32_e32 v41, v0
	v_lshlrev_b64 v[40:41], 12, v[40:41]
	v_lshl_add_u64 v[46:47], s[18:19], 0, v[40:41]
	v_mov_b32_e32 v43, v0
	s_andn2_saveexec_b64 s[2:3], s[2:3]
	v_ashrrev_i32_e32 v43, 31, v42
	v_lshlrev_b64 v[40:41], 12, v[42:43]
	v_lshl_add_u64 v[46:47], s[8:9], 0, v[40:41]
	s_or_b64 exec, exec, s[2:3]
	v_or_b32_e32 v40, s5, v56
	v_lshlrev_b64 v[44:45], 12, v[42:43]
	v_lshl_add_u64 v[50:51], s[26:27], 0, v[44:45]
	v_lshlrev_b64 v[44:45], 11, v[42:43]
	v_ashrrev_i32_e32 v41, 31, v40
	v_lshl_add_u64 v[74:75], s[44:45], 0, v[44:45]
	v_lshlrev_b64 v[44:45], 2, v[40:41]
	v_lshl_add_u64 v[48:49], v[46:47], 0, v[44:45]
	global_load_dwordx4 v[70:73], v[48:49], off
	v_readlane_b32 s2, v253, 24
	v_readlane_b32 s3, v253, 25
	v_lshl_add_u64 v[46:47], v[50:51], 0, v[44:45]
	s_andn2_b64 vcc, exec, s[2:3]
	v_cndmask_b32_e64 v50, 0, 1, s[2:3]
	v_cmp_ne_u32_e64 s[14:15], 1, v50
	v_lshl_add_u64 v[50:51], v[40:41], 1, v[74:75]
	s_waitcnt vmcnt(0)
	v_pk_fma_f32 v[30:31], v[30:31], 0.5, v[70:71] op_sel_hi:[1,0,1]
	v_pk_fma_f32 v[32:33], v[32:33], 0.5, v[72:73] op_sel_hi:[1,0,1]
	global_store_dwordx4 v[46:47], v[30:33], off
	s_cbranch_vccnz .LBB0_345
	v_cvt_pk_bf16_f32 v70, v30, v31
	v_cvt_pk_bf16_f32 v71, v32, v33
	global_store_dwordx2 v[50:51], v[70:71], off

; #define MFMA(a, b, c) __builtin_amdgcn_mfma_f32_16x16x32_bf16((a), (b), (c), 0, 0, 0)
; template <int EPI, int MF>
; __device__ __forceinline__ void gemm_part(const u16* __restrict__ A, int lda, const u16* __restrict__ Bt, int K, int ntn, GemmEpi ep, char* smem,
;                                           int mbase, int mrows) {
;     ...
;     for (int kt = 0; kt < nk; ++kt) {
;       if (kt + 1 < nk) {
;         if (MF == 8) asm volatile("s_waitcnt vmcnt(6)" ::: "memory");
;         else asm volatile("s_waitcnt vmcnt(3)" ::: "memory");
;       } else asm volatile("s_waitcnt vmcnt(0)" ::: "memory");
;       asm volatile("s_waitcnt lgkmcnt(0)" ::: "memory");
;       __builtin_amdgcn_s_barrier();
;       const u16* a_ = sbase + (kt % 3) * STG;
;       const u16* b_ = a_ + BM * 32;
;       bf16x8 bfr[4], afc[2], afn[2];
;       const u16* ap_ = a_ + (wr * (16 * MF) + fr) * 32 + fq * 8;
; #pragma unroll
;       for (int n = 0; n < 4; ++n) bfr[n] = rd_std(b_ + (wc * 64 + n * 16 + fr) * 32 + fq * 8);
;       afc[0] = rd_std(ap_); afc[1] = rd_std(ap_ + 16 * 32);
;       __builtin_amdgcn_sched_barrier(0);
;       if (kt + 2 < nk) GEMM_ISSUE(kt + 2);
;       __builtin_amdgcn_sched_barrier(0);
; #pragma unroll
;       for (int mh = 0; mh < MF / 2; ++mh) {
;         if (mh + 1 < MF / 2) {
;           afn[0] = rd_std(ap_ + ((mh + 1) * 2) * 16 * 32);
;           afn[1] = rd_std(ap_ + ((mh + 1) * 2 + 1) * 16 * 32);
;         }
;         __builtin_amdgcn_sched_barrier(0);
; #pragma unroll
;         for (int m = 0; m < 2; ++m)
; #pragma unroll
;           for (int n = 0; n < 4; ++n) acc[mh * 2 + m][n] = MFMA(bfr[n], afc[m], acc[mh * 2 + m][n]);
;         __builtin_amdgcn_sched_barrier(0);
;         afc[0] = afn[0]; afc[1] = afn[1];
;       }
;     }
.LBB0_1128:
	s_mul_hi_u32 s13, s12, 0xaaaaaaab
	s_lshr_b32 s13, s13, 1
	s_mul_i32 s13, s13, 0x12000
	v_add_u32_e32 v146, s3, v156
	v_subrev_u32_e32 v147, s13, v159
	s_waitcnt vmcnt(6)
	v_subrev_u32_e32 v161, s13, v155
	v_add_u32_e32 v147, v146, v147
	s_waitcnt lgkmcnt(0)
	s_barrier
	v_add_u32_e32 v161, v146, v161
	ds_read_b128 v[162:165], v147 offset:16384
	ds_read_b128 v[166:169], v147 offset:17408
	ds_read_b128 v[170:173], v147 offset:18432
	ds_read_b128 v[174:177], v147 offset:19456
	ds_read_b128 v[178:181], v161
	ds_read_b128 v[182:185], v161 offset:1024
	s_mul_hi_u32 s13, s11, 0xaaaaaaab
	s_add_i32 s12, s12, 1
	s_lshr_b32 s13, s13, 1
	s_mul_i32 s13, s13, 0x12000
	s_sub_i32 s13, s3, s13
	s_add_i32 s14, s13, 0xc000
	v_add_u32_e32 v188, s14, v148
	v_lshl_add_u64 v[146:147], v[136:137], 0, v[134:135]
	v_readfirstlane_b32 s14, v188
	s_mov_b32 m0, s14
	s_add_i32 s14, s13, 0xd000
	v_add_u32_e32 v188, s14, v148
	v_lshl_add_u64 v[186:187], v[146:147], 0, s[74:75]
	v_readfirstlane_b32 s14, v188
	global_load_lds_dwordx4 v[186:187], off
	s_mov_b32 m0, s14
	s_add_i32 s14, s13, 0xe000
	v_add_u32_e32 v188, s14, v148
	v_lshl_add_u64 v[186:187], v[146:147], 0, s[92:93]
	v_readfirstlane_b32 s14, v188
	global_load_lds_dwordx4 v[186:187], off
	v_lshl_add_u64 v[186:187], v[146:147], 0, s[88:89]
	s_mov_b32 m0, s14
	s_add_i32 s14, s13, 0xf000
	global_load_lds_dwordx4 v[186:187], off
	v_add_u32_e32 v186, s14, v148
	v_lshl_add_u64 v[146:147], v[146:147], 0, s[6:7]
	v_readfirstlane_b32 s14, v186
	s_mov_b32 m0, s14
	s_add_i32 s14, s13, 0x10000
	v_add_u32_e32 v188, s14, v148
	global_load_lds_dwordx4 v[146:147], off
	v_lshl_add_u64 v[146:147], v[138:139], 0, v[134:135]
	v_readfirstlane_b32 s14, v188
	v_lshl_add_u64 v[186:187], v[146:147], 0, s[74:75]
	s_mov_b32 m0, s14
	s_add_i32 s13, s13, 0x11000
	global_load_lds_dwordx4 v[186:187], off
	v_add_u32_e32 v186, s13, v148
	v_lshl_add_u64 v[146:147], v[146:147], 0, s[92:93]
	v_readfirstlane_b32 s13, v186
	s_mov_b32 m0, s13
	s_nop 0
	global_load_lds_dwordx4 v[146:147], off
	ds_read_b128 v[186:189], v161 offset:3072
	ds_read_b128 v[190:193], v161 offset:2048
	s_waitcnt lgkmcnt(0)
	v_mfma_f32_16x16x32_bf16 v[126:129], v[162:165], v[178:181], v[126:129]
	v_mfma_f32_16x16x32_bf16 v[122:125], v[166:169], v[178:181], v[122:125]
	v_mfma_f32_16x16x32_bf16 v[118:121], v[170:173], v[178:181], v[118:121]
	v_mfma_f32_16x16x32_bf16 v[114:117], v[174:177], v[178:181], v[114:117]
	v_mfma_f32_16x16x32_bf16 v[110:113], v[162:165], v[182:185], v[110:113]
	v_mfma_f32_16x16x32_bf16 v[106:109], v[166:169], v[182:185], v[106:109]
	v_mfma_f32_16x16x32_bf16 v[102:105], v[170:173], v[182:185], v[102:105]
	v_mfma_f32_16x16x32_bf16 v[98:101], v[174:177], v[182:185], v[98:101]
	ds_read_b128 v[178:181], v161 offset:5120
	ds_read_b128 v[182:185], v161 offset:4096
	v_mfma_f32_16x16x32_bf16 v[94:97], v[162:165], v[190:193], v[94:97]
	v_mfma_f32_16x16x32_bf16 v[90:93], v[166:169], v[190:193], v[90:93]
	v_mfma_f32_16x16x32_bf16 v[86:89], v[170:173], v[190:193], v[86:89]
	v_mfma_f32_16x16x32_bf16 v[82:85], v[174:177], v[190:193], v[82:85]
	v_mfma_f32_16x16x32_bf16 v[78:81], v[162:165], v[186:189], v[78:81]
	v_mfma_f32_16x16x32_bf16 v[74:77], v[166:169], v[186:189], v[74:77]
	v_mfma_f32_16x16x32_bf16 v[70:73], v[170:173], v[186:189], v[70:73]
	v_mfma_f32_16x16x32_bf16 v[66:69], v[174:177], v[186:189], v[66:69]
	ds_read_b128 v[186:189], v161 offset:7168
	ds_read_b128 v[190:193], v161 offset:6144
	s_waitcnt lgkmcnt(0)
	v_mfma_f32_16x16x32_bf16 v[62:65], v[162:165], v[182:185], v[62:65]
	v_mfma_f32_16x16x32_bf16 v[58:61], v[166:169], v[182:185], v[58:61]
	v_mfma_f32_16x16x32_bf16 v[54:57], v[170:173], v[182:185], v[54:57]
	v_mfma_f32_16x16x32_bf16 v[50:53], v[174:177], v[182:185], v[50:53]
	v_mfma_f32_16x16x32_bf16 v[46:49], v[162:165], v[178:181], v[46:49]
	v_mfma_f32_16x16x32_bf16 v[42:45], v[166:169], v[178:181], v[42:45]
	v_mfma_f32_16x16x32_bf16 v[38:41], v[170:173], v[178:181], v[38:41]
	v_mfma_f32_16x16x32_bf16 v[34:37], v[174:177], v[178:181], v[34:37]
	v_mfma_f32_16x16x32_bf16 v[30:33], v[162:165], v[190:193], v[30:33]
	v_mfma_f32_16x16x32_bf16 v[26:29], v[166:169], v[190:193], v[26:29]
	v_mfma_f32_16x16x32_bf16 v[22:25], v[170:173], v[190:193], v[22:25]
	v_mfma_f32_16x16x32_bf16 v[18:21], v[174:177], v[190:193], v[18:21]
	v_mfma_f32_16x16x32_bf16 v[14:17], v[162:165], v[186:189], v[14:17]
	v_mfma_f32_16x16x32_bf16 v[10:13], v[166:169], v[186:189], v[10:13]
	v_mfma_f32_16x16x32_bf16 v[6:9], v[170:173], v[186:189], v[6:9]
	v_mfma_f32_16x16x32_bf16 v[2:5], v[174:177], v[186:189], v[2:5]
	s_addk_i32 s3, 0x6000
	s_add_i32 s10, s10, 1
	s_add_i32 s11, s11, 1
	v_lshl_add_u64 v[136:137], v[136:137], 0, 64
	s_cmp_eq_u32 s3, 0xb4000
	v_lshl_add_u64 v[138:139], v[138:139], 0, 64
	s_cbranch_scc0 .LBB0_1128
	s_waitcnt vmcnt(6)
	s_waitcnt lgkmcnt(0)
	s_barrier
; #define MFMA(a, b, c) __builtin_amdgcn_mfma_f32_16x16x32_bf16((a), (b), (c), 0, 0, 0)
; template <int EPI, int MF>
; __device__ __forceinline__ void gemm_part(const u16* __restrict__ A, int lda, const u16* __restrict__ Bt, int K, int ntn, GemmEpi ep, char* smem,
;                                           int mbase, int mrows) {
;     ...
;     for (int kt = 0; kt < nk; ++kt) {
;       if (kt + 1 < nk) {
;         if (MF == 8) asm volatile("s_waitcnt vmcnt(6)" ::: "memory");
;         else asm volatile("s_waitcnt vmcnt(3)" ::: "memory");
;       } else asm volatile("s_waitcnt vmcnt(0)" ::: "memory");
;       asm volatile("s_waitcnt lgkmcnt(0)" ::: "memory");
;       __builtin_amdgcn_s_barrier();
;       const u16* a_ = sbase + (kt % 3) * STG;
;       const u16* b_ = a_ + BM * 32;
;       bf16x8 bfr[4], afc[2], afn[2];
;       const u16* ap_ = a_ + (wr * (16 * MF) + fr) * 32 + fq * 8;
; #pragma unroll
;       for (int n = 0; n < 4; ++n) bfr[n] = rd_std(b_ + (wc * 64 + n * 16 + fr) * 32 + fq * 8);
;       afc[0] = rd_std(ap_); afc[1] = rd_std(ap_ + 16 * 32);
;       __builtin_amdgcn_sched_barrier(0);
;       if (kt + 2 < nk) GEMM_ISSUE(kt + 2);
;       __builtin_amdgcn_sched_barrier(0);
; #pragma unroll
;       for (int mh = 0; mh < MF / 2; ++mh) {
;         if (mh + 1 < MF / 2) {
;           afn[0] = rd_std(ap_ + ((mh + 1) * 2) * 16 * 32);
;           afn[1] = rd_std(ap_ + ((mh + 1) * 2 + 1) * 16 * 32);
;         }
;         __builtin_amdgcn_sched_barrier(0);
; #pragma unroll
;         for (int m = 0; m < 2; ++m)
; #pragma unroll
;           for (int n = 0; n < 4; ++n) acc[mh * 2 + m][n] = MFMA(bfr[n], afc[m], acc[mh * 2 + m][n]);
;         __builtin_amdgcn_sched_barrier(0);
;         afc[0] = afn[0]; afc[1] = afn[1];
;       }
;     }
	ds_read_b128 v[136:139], v160 offset:16384
	ds_read_b128 v[162:165], v160 offset:17408
	ds_read_b128 v[166:169], v160 offset:18432
	ds_read_b128 v[170:173], v160 offset:19456
	ds_read_b128 v[174:177], v157
	ds_read_b128 v[178:181], v157 offset:1024
	s_mul_hi_u32 s10, s10, 0xaaaaaaab
	s_lshr_b32 s10, s10, 1
	s_mul_i32 s10, s10, 0x12000
	s_sub_i32 s3, s3, s10
	s_add_i32 s3, s3, 0
	s_addk_i32 s3, 0x6000
	ds_read_b128 v[182:185], v157 offset:3072
	ds_read_b128 v[186:189], v157 offset:2048
	s_waitcnt lgkmcnt(0)
	v_mfma_f32_16x16x32_bf16 v[126:129], v[136:139], v[174:177], v[126:129]
	v_mfma_f32_16x16x32_bf16 v[122:125], v[162:165], v[174:177], v[122:125]
	v_mfma_f32_16x16x32_bf16 v[118:121], v[166:169], v[174:177], v[118:121]
	v_mfma_f32_16x16x32_bf16 v[114:117], v[170:173], v[174:177], v[114:117]
	v_mfma_f32_16x16x32_bf16 v[110:113], v[136:139], v[178:181], v[110:113]
	v_mfma_f32_16x16x32_bf16 v[106:109], v[162:165], v[178:181], v[106:109]
	v_mfma_f32_16x16x32_bf16 v[102:105], v[166:169], v[178:181], v[102:105]
	v_mfma_f32_16x16x32_bf16 v[98:101], v[170:173], v[178:181], v[98:101]
	ds_read_b128 v[174:177], v157 offset:5120
	ds_read_b128 v[178:181], v157 offset:4096
	v_mfma_f32_16x16x32_bf16 v[94:97], v[136:139], v[186:189], v[94:97]
	v_mfma_f32_16x16x32_bf16 v[90:93], v[162:165], v[186:189], v[90:93]
	v_mfma_f32_16x16x32_bf16 v[86:89], v[166:169], v[186:189], v[86:89]
	v_mfma_f32_16x16x32_bf16 v[82:85], v[170:173], v[186:189], v[82:85]
	v_mfma_f32_16x16x32_bf16 v[78:81], v[136:139], v[182:185], v[78:81]
	v_mfma_f32_16x16x32_bf16 v[74:77], v[162:165], v[182:185], v[74:77]
	v_mfma_f32_16x16x32_bf16 v[70:73], v[166:169], v[182:185], v[70:73]
	v_mfma_f32_16x16x32_bf16 v[66:69], v[170:173], v[182:185], v[66:69]
	ds_read_b128 v[182:185], v157 offset:7168
	ds_read_b128 v[186:189], v157 offset:6144
	s_waitcnt lgkmcnt(0)
	v_mfma_f32_16x16x32_bf16 v[62:65], v[136:139], v[178:181], v[62:65]
	v_mfma_f32_16x16x32_bf16 v[58:61], v[162:165], v[178:181], v[58:61]
	v_mfma_f32_16x16x32_bf16 v[54:57], v[166:169], v[178:181], v[54:57]
	v_mfma_f32_16x16x32_bf16 v[50:53], v[170:173], v[178:181], v[50:53]
	v_mfma_f32_16x16x32_bf16 v[46:49], v[136:139], v[174:177], v[46:49]
	v_mfma_f32_16x16x32_bf16 v[42:45], v[162:165], v[174:177], v[42:45]
	v_mfma_f32_16x16x32_bf16 v[38:41], v[166:169], v[174:177], v[38:41]
	v_mfma_f32_16x16x32_bf16 v[34:37], v[170:173], v[174:177], v[34:37]
	v_mfma_f32_16x16x32_bf16 v[30:33], v[136:139], v[186:189], v[30:33]
	v_mfma_f32_16x16x32_bf16 v[26:29], v[162:165], v[186:189], v[26:29]
	v_mfma_f32_16x16x32_bf16 v[22:25], v[166:169], v[186:189], v[22:25]
	v_mfma_f32_16x16x32_bf16 v[18:21], v[170:173], v[186:189], v[18:21]
	v_mfma_f32_16x16x32_bf16 v[14:17], v[136:139], v[182:185], v[14:17]
	v_mfma_f32_16x16x32_bf16 v[10:13], v[162:165], v[182:185], v[10:13]
	v_mfma_f32_16x16x32_bf16 v[6:9], v[166:169], v[182:185], v[6:9]
	v_mfma_f32_16x16x32_bf16 v[2:5], v[170:173], v[182:185], v[2:5]
	v_lshl_add_u32 v146, v150, 1, s3
	s_waitcnt vmcnt(0)
	v_add3_u32 v147, v146, v153, v154
	s_waitcnt lgkmcnt(0)
	s_barrier
	ds_read_b128 v[136:139], v147 offset:16384
	ds_read_b128 v[162:165], v147 offset:17408
	ds_read_b128 v[166:169], v147 offset:18432
	ds_read_b128 v[170:173], v147 offset:19456
	v_lshl_add_u32 v146, v149, 1, v146
	ds_read_b128 v[174:177], v146
	ds_read_b128 v[178:181], v146 offset:1024
	ds_read_b128 v[182:185], v146 offset:3072
	ds_read_b128 v[186:189], v146 offset:2048
	s_waitcnt lgkmcnt(0)
	v_mfma_f32_16x16x32_bf16 v[126:129], v[136:139], v[174:177], v[126:129]
	v_mfma_f32_16x16x32_bf16 v[122:125], v[162:165], v[174:177], v[122:125]
	v_mfma_f32_16x16x32_bf16 v[118:121], v[166:169], v[174:177], v[118:121]
	v_mfma_f32_16x16x32_bf16 v[114:117], v[170:173], v[174:177], v[114:117]
	v_mfma_f32_16x16x32_bf16 v[110:113], v[136:139], v[178:181], v[110:113]
	v_mfma_f32_16x16x32_bf16 v[106:109], v[162:165], v[178:181], v[106:109]
	v_mfma_f32_16x16x32_bf16 v[102:105], v[166:169], v[178:181], v[102:105]
	v_mfma_f32_16x16x32_bf16 v[98:101], v[170:173], v[178:181], v[98:101]
	ds_read_b128 v[174:177], v146 offset:5120
	ds_read_b128 v[178:181], v146 offset:4096
	v_mfma_f32_16x16x32_bf16 v[94:97], v[136:139], v[186:189], v[94:97]
	v_mfma_f32_16x16x32_bf16 v[90:93], v[162:165], v[186:189], v[90:93]
	v_mfma_f32_16x16x32_bf16 v[86:89], v[166:169], v[186:189], v[86:89]
	v_mfma_f32_16x16x32_bf16 v[82:85], v[170:173], v[186:189], v[82:85]
	v_mfma_f32_16x16x32_bf16 v[78:81], v[136:139], v[182:185], v[78:81]
	v_mfma_f32_16x16x32_bf16 v[74:77], v[162:165], v[182:185], v[74:77]
	v_mfma_f32_16x16x32_bf16 v[70:73], v[166:169], v[182:185], v[70:73]
	v_mfma_f32_16x16x32_bf16 v[66:69], v[170:173], v[182:185], v[66:69]
	ds_read_b128 v[182:185], v146 offset:7168
	ds_read_b128 v[186:189], v146 offset:6144
	s_waitcnt lgkmcnt(0)
	v_mfma_f32_16x16x32_bf16 v[62:65], v[136:139], v[178:181], v[62:65]
	v_mfma_f32_16x16x32_bf16 v[58:61], v[162:165], v[178:181], v[58:61]
	v_mfma_f32_16x16x32_bf16 v[54:57], v[166:169], v[178:181], v[54:57]
	v_mfma_f32_16x16x32_bf16 v[50:53], v[170:173], v[178:181], v[50:53]
	v_mfma_f32_16x16x32_bf16 v[46:49], v[136:139], v[174:177], v[46:49]
	v_mfma_f32_16x16x32_bf16 v[42:45], v[162:165], v[174:177], v[42:45]
	v_mfma_f32_16x16x32_bf16 v[38:41], v[166:169], v[174:177], v[38:41]
	v_mfma_f32_16x16x32_bf16 v[34:37], v[170:173], v[174:177], v[34:37]
	v_mfma_f32_16x16x32_bf16 v[30:33], v[136:139], v[186:189], v[30:33]
	v_mfma_f32_16x16x32_bf16 v[26:29], v[162:165], v[186:189], v[26:29]
	v_mfma_f32_16x16x32_bf16 v[22:25], v[166:169], v[186:189], v[22:25]
	v_mfma_f32_16x16x32_bf16 v[18:21], v[170:173], v[186:189], v[18:21]
	v_mfma_f32_16x16x32_bf16 v[14:17], v[136:139], v[182:185], v[14:17]
	v_mfma_f32_16x16x32_bf16 v[10:13], v[162:165], v[182:185], v[10:13]
	v_mfma_f32_16x16x32_bf16 v[6:9], v[166:169], v[182:185], v[6:9]
	v_mfma_f32_16x16x32_bf16 v[2:5], v[170:173], v[182:185], v[2:5]
	v_add_u32_e32 v136, s2, v151
	s_waitcnt vmcnt(0)
	s_barrier
; template <int EPI, int MF>
; __device__ __forceinline__ void gemm_part(const u16* __restrict__ A, int lda, const u16* __restrict__ Bt, int K, int ntn, GemmEpi ep, char* smem,
;                                           int mbase, int mrows) {
;     ...
;       } else if (EPI == EPI_RESID) {
;         const float* rp = (row < MP) ? ep.res0 + (size_t)row * DM : ep.res1 + (size_t)(row - MP) * DM;
;         float ssq = 0.f;
; #pragma unroll
;         for (int n = 0; n < 4; ++n) {
;           const int col = cb + n * 16;
;           const float4 r = *(const float4*)(rp + col);
;           float4 v;
;           v.x = r.x + ep.scale * acc[m][n][0]; v.y = r.y + ep.scale * acc[m][n][1];
;           v.z = r.z + ep.scale * acc[m][n][2]; v.w = r.w + ep.scale * acc[m][n][3];
;           *(float4*)(ep.outf + (size_t)row * DM + col) = v;
;           if (ep.xcopy) {
;             bf16x4 o;
;             o[0] = (short)f2bf(v.x); o[1] = (short)f2bf(v.y); o[2] = (short)f2bf(v.z); o[3] = (short)f2bf(v.w);
;             *(bf16x4*)(ep.xcopy + (size_t)row * DM + col) = o;
;           }
;           ssq += v.x * v.x + v.y * v.y + v.z * v.z + v.w * v.w;
;         }
;         if (ep.rss_out) {
;           ssq += __shfl_xor(ssq, 16);
;           ssq += __shfl_xor(ssq, 32);
;           if (fq == 0) atomicAdd(ep.rss_out + row, ssq);
;         }
	s_mov_b32 s2, 0xffff
	v_cmp_lt_i32_e64 s[12:13], s2, v136
	s_and_saveexec_b64 s[2:3], s[12:13]
	s_xor_b64 s[2:3], exec, s[2:3]
	v_add_u32_e32 v138, 0xffff0000, v136
	v_mov_b32_e32 v139, v0
	v_lshlrev_b64 v[138:139], 12, v[138:139]
	v_lshl_add_u64 v[146:147], s[72:73], 0, v[138:139]
	v_mov_b32_e32 v137, v0
	s_andn2_saveexec_b64 s[2:3], s[2:3]
	v_ashrrev_i32_e32 v137, 31, v136
	v_lshlrev_b64 v[138:139], 12, v[136:137]
	v_lshl_add_u64 v[146:147], s[26:27], 0, v[138:139]
	s_or_b64 exec, exec, s[2:3]
	v_lshlrev_b64 v[138:139], 12, v[136:137]
	v_or_b32_e32 v161, s9, v152
	v_lshl_add_u64 v[162:163], s[26:27], 0, v[138:139]
	v_lshlrev_b64 v[138:139], 11, v[136:137]
	v_lshl_add_u64 v[166:167], s[28:29], 0, v[138:139]
	v_lshlrev_b32_e32 v138, 2, v161
	v_mov_b32_e32 v139, v0
	v_lshl_add_u64 v[146:147], v[146:147], 0, v[138:139]
	v_lshl_add_u64 v[168:169], v[162:163], 0, v[138:139]
	global_load_dwordx4 v[162:165], v[146:147], off
	global_load_dwordx4 v[172:175], v[146:147], off offset:64
	global_load_dwordx4 v[176:179], v[146:147], off offset:128
	global_load_dwordx4 v[180:183], v[146:147], off offset:192
	s_waitcnt vmcnt(0)
	v_pk_add_f32 v[162:163], v[126:127], v[162:163]
	v_pk_add_f32 v[164:165], v[128:129], v[164:165]
	v_lshlrev_b32_e32 v126, 1, v161
	v_mov_b32_e32 v127, v0
	v_cvt_pk_bf16_f32 v129, v164, v165
	v_cvt_pk_bf16_f32 v128, v162, v163
	v_lshl_add_u64 v[166:167], v[166:167], 0, v[126:127]
	global_store_dwordx4 v[168:169], v[162:165], off
	v_lshlrev_b32_e32 v184, 1, v166
	v_bfi_b32 v184, s100, v184, v166
	v_lshrrev_b32_e32 v185, 5, v166
	v_bfi_b32 v184, 64, v185, v184
	v_mov_b32_e32 v185, v167
	global_store_dwordx2 v[184:185], v[128:129], off
	v_pk_mul_f32 v[128:129], v[162:163], v[162:163]
	v_pk_mul_f32 v[170:171], v[164:165], v[164:165]
	s_nop 0
	s_nop 0
	v_pk_add_f32 v[122:123], v[122:123], v[172:173]
	v_pk_add_f32 v[124:125], v[124:125], v[174:175]
	v_cvt_pk_bf16_f32 v162, v122, v123
	v_cvt_pk_bf16_f32 v163, v124, v125
	global_store_dwordx4 v[168:169], v[122:125], off offset:64
	v_lshlrev_b32_e32 v184, 1, v166
	v_bfi_b32 v184, s100, v184, v166
	v_lshrrev_b32_e32 v185, 5, v166
	v_bfi_b32 v184, 64, v185, v184
	v_mov_b32_e32 v185, v167
	global_store_dwordx2 v[184:185], v[162:163], off offset:32
	v_pk_mul_f32 v[162:163], v[122:123], v[122:123]
	v_pk_mul_f32 v[164:165], v[124:125], v[124:125]
	s_nop 0
	s_nop 0
	v_pk_add_f32 v[118:119], v[118:119], v[176:177]
	v_pk_add_f32 v[120:121], v[120:121], v[178:179]
	v_cvt_pk_bf16_f32 v122, v118, v119
	v_cvt_pk_bf16_f32 v123, v120, v121
	global_store_dwordx4 v[168:169], v[118:121], off offset:128
	v_lshlrev_b32_e32 v184, 1, v166
	v_bfi_b32 v184, s100, v184, v166
	v_lshrrev_b32_e32 v185, 5, v166
	v_bfi_b32 v184, 64, v185, v184
	v_mov_b32_e32 v185, v167
	global_store_dwordx2 v[184:185], v[122:123], off offset:128
	v_pk_mul_f32 v[122:123], v[118:119], v[118:119]
	v_pk_mul_f32 v[124:125], v[120:121], v[120:121]
	s_nop 0
	s_nop 0
	v_pk_add_f32 v[114:115], v[114:115], v[180:181]
	v_pk_add_f32 v[116:117], v[116:117], v[182:183]
	v_cvt_pk_bf16_f32 v118, v114, v115
	v_cvt_pk_bf16_f32 v119, v116, v117
	global_store_dwordx4 v[168:169], v[114:117], off offset:192
	v_lshlrev_b32_e32 v184, 1, v166
	v_bfi_b32 v184, s100, v184, v166
	v_lshrrev_b32_e32 v185, 5, v166
	v_bfi_b32 v184, 64, v185, v184
	v_mov_b32_e32 v185, v167
	global_store_dwordx2 v[184:185], v[118:119], off offset:160
	v_add_f32_e32 v118, v128, v129
	v_add_f32_e32 v119, v162, v163
	v_pk_mul_f32 v[114:115], v[114:115], v[114:115]
	v_add_f32_e32 v118, v170, v118
	v_add_f32_e32 v119, v164, v119
	v_pk_mul_f32 v[116:117], v[116:117], v[116:117]
	v_add_f32_e32 v118, v171, v118
	v_add_f32_e32 v119, v165, v119
	v_add_f32_e32 v114, v114, v115
	v_add_f32_e32 v118, v118, v119
	v_add_f32_e32 v119, v122, v123
	v_add_f32_e32 v114, v116, v114
	v_and_b32_e32 v116, 64, v141
	v_add_f32_e32 v119, v124, v119
	v_xor_b32_e32 v115, 16, v141
	v_add_u32_e32 v116, 64, v116
	v_add_f32_e32 v119, v125, v119
	v_cmp_lt_i32_e64 s[12:13], v115, v116
	v_add_f32_e32 v118, v118, v119
	v_add_f32_e32 v114, v117, v114
	v_cndmask_b32_e64 v115, v141, v115, s[12:13]
	v_add_f32_e32 v114, v118, v114
	v_lshlrev_b32_e32 v118, 2, v115
	ds_bpermute_b32 v115, v118, v114
	s_waitcnt lgkmcnt(0)
	v_add_f32_e32 v114, v114, v115
	v_xor_b32_e32 v115, 32, v141
	v_cmp_lt_i32_e64 s[12:13], v115, v116
	s_nop 1
	v_cndmask_b32_e64 v115, v141, v115, s[12:13]
	v_lshlrev_b32_e32 v119, 2, v115
	ds_bpermute_b32 v115, v119, v114
	s_and_saveexec_b64 s[2:3], vcc
	s_cbranch_execz .LBB0_1135
	v_readlane_b32 s10, v252, 9
	v_readlane_b32 s11, v252, 10
	s_waitcnt lgkmcnt(0)
	v_add_f32_e32 v114, v114, v115
	v_lshl_add_u64 v[116:117], v[136:137], 2, s[10:11]
	global_atomic_add_f32 v[116:117], v114, off
; template <int EPI, int MF>
; __device__ __forceinline__ void gemm_part(const u16* __restrict__ A, int lda, const u16* __restrict__ Bt, int K, int ntn, GemmEpi ep, char* smem,
;                                           int mbase, int mrows) {
;     ...
;       } else if (EPI == EPI_RESID) {
;         const float* rp = (row < MP) ? ep.res0 + (size_t)row * DM : ep.res1 + (size_t)(row - MP) * DM;
;         float ssq = 0.f;
; #pragma unroll
;         for (int n = 0; n < 4; ++n) {
;           const int col = cb + n * 16;
;           const float4 r = *(const float4*)(rp + col);
;           float4 v;
;           v.x = r.x + ep.scale * acc[m][n][0]; v.y = r.y + ep.scale * acc[m][n][1];
;           v.z = r.z + ep.scale * acc[m][n][2]; v.w = r.w + ep.scale * acc[m][n][3];
;           *(float4*)(ep.outf + (size_t)row * DM + col) = v;
;           if (ep.xcopy) {
;             bf16x4 o;
;             o[0] = (short)f2bf(v.x); o[1] = (short)f2bf(v.y); o[2] = (short)f2bf(v.z); o[3] = (short)f2bf(v.w);
;             *(bf16x4*)(ep.xcopy + (size_t)row * DM + col) = o;
;           }
;           ssq += v.x * v.x + v.y * v.y + v.z * v.z + v.w * v.w;
;         }
;         if (ep.rss_out) {
;           ssq += __shfl_xor(ssq, 16);
;           ssq += __shfl_xor(ssq, 32);
;           if (fq == 0) atomicAdd(ep.rss_out + row, ssq);
;         }
.LBB0_1135:
	s_or_b64 exec, exec, s[2:3]
	s_waitcnt lgkmcnt(0)
	v_or_b32_e32 v114, 16, v136
	s_mov_b32 s2, 0xffff
	v_cmp_lt_i32_e64 s[12:13], s2, v114
	s_and_saveexec_b64 s[2:3], s[12:13]
	s_xor_b64 s[2:3], exec, s[2:3]
	v_add_u32_e32 v116, 0xffff0010, v136
	v_mov_b32_e32 v117, v0
	v_lshlrev_b64 v[116:117], 12, v[116:117]
	v_lshl_add_u64 v[116:117], s[72:73], 0, v[116:117]
	v_mov_b32_e32 v115, v0
	s_andn2_saveexec_b64 s[2:3], s[2:3]
	v_ashrrev_i32_e32 v115, 31, v114
	v_lshlrev_b64 v[116:117], 12, v[114:115]
	v_lshl_add_u64 v[116:117], s[26:27], 0, v[116:117]
	s_or_b64 exec, exec, s[2:3]
	v_lshlrev_b64 v[120:121], 12, v[114:115]
	v_mov_b32_e32 v139, v0
	v_lshl_add_u64 v[120:121], s[26:27], 0, v[120:121]
	v_lshlrev_b64 v[122:123], 11, v[114:115]
	v_lshl_add_u64 v[116:117], v[116:117], 0, v[138:139]
	v_lshl_add_u64 v[124:125], s[28:29], 0, v[122:123]
	v_lshl_add_u64 v[128:129], v[120:121], 0, v[138:139]
	global_load_dwordx4 v[120:123], v[116:117], off
	global_load_dwordx4 v[172:175], v[116:117], off offset:64
	global_load_dwordx4 v[176:179], v[116:117], off offset:128
	global_load_dwordx4 v[180:183], v[116:117], off offset:192
	v_mov_b32_e32 v127, v0
	s_waitcnt vmcnt(0)
	v_pk_add_f32 v[110:111], v[110:111], v[120:121]
	v_pk_add_f32 v[112:113], v[112:113], v[122:123]
	v_cvt_pk_bf16_f32 v120, v110, v111
	v_cvt_pk_bf16_f32 v121, v112, v113
	v_lshl_add_u64 v[122:123], v[124:125], 0, v[126:127]
	global_store_dwordx4 v[128:129], v[110:113], off
	v_lshlrev_b32_e32 v184, 1, v122
	v_bfi_b32 v184, s100, v184, v122
	v_lshrrev_b32_e32 v185, 5, v122
	v_bfi_b32 v184, 64, v185, v184
	v_mov_b32_e32 v185, v123
	global_store_dwordx2 v[184:185], v[120:121], off
	v_pk_mul_f32 v[120:121], v[110:111], v[110:111]
	v_pk_mul_f32 v[124:125], v[112:113], v[112:113]
	s_nop 0
	s_nop 0
	v_pk_add_f32 v[106:107], v[106:107], v[172:173]
	v_pk_add_f32 v[108:109], v[108:109], v[174:175]
	v_cvt_pk_bf16_f32 v110, v106, v107
	v_cvt_pk_bf16_f32 v111, v108, v109
	global_store_dwordx4 v[128:129], v[106:109], off offset:64
	v_lshlrev_b32_e32 v184, 1, v122
	v_bfi_b32 v184, s100, v184, v122
	v_lshrrev_b32_e32 v185, 5, v122
	v_bfi_b32 v184, 64, v185, v184
	v_mov_b32_e32 v185, v123
	global_store_dwordx2 v[184:185], v[110:111], off offset:32
	v_pk_mul_f32 v[110:111], v[106:107], v[106:107]
	v_pk_mul_f32 v[112:113], v[108:109], v[108:109]
	s_nop 0
	s_nop 0
	v_pk_add_f32 v[102:103], v[102:103], v[176:177]
	v_pk_add_f32 v[104:105], v[104:105], v[178:179]
	v_cvt_pk_bf16_f32 v106, v102, v103
	v_cvt_pk_bf16_f32 v107, v104, v105
	global_store_dwordx4 v[128:129], v[102:105], off offset:128
	v_lshlrev_b32_e32 v184, 1, v122
	v_bfi_b32 v184, s100, v184, v122
	v_lshrrev_b32_e32 v185, 5, v122
	v_bfi_b32 v184, 64, v185, v184
	v_mov_b32_e32 v185, v123
	global_store_dwordx2 v[184:185], v[106:107], off offset:128
	v_pk_mul_f32 v[106:107], v[102:103], v[102:103]
	v_pk_mul_f32 v[108:109], v[104:105], v[104:105]
	s_nop 0
	s_nop 0
	v_pk_add_f32 v[98:99], v[98:99], v[180:181]
	v_pk_add_f32 v[100:101], v[100:101], v[182:183]
	v_cvt_pk_bf16_f32 v102, v98, v99
	v_cvt_pk_bf16_f32 v103, v100, v101
	global_store_dwordx4 v[128:129], v[98:101], off offset:192
	v_lshlrev_b32_e32 v184, 1, v122
	v_bfi_b32 v184, s100, v184, v122
	v_lshrrev_b32_e32 v185, 5, v122
	v_bfi_b32 v184, 64, v185, v184
	v_mov_b32_e32 v185, v123
	global_store_dwordx2 v[184:185], v[102:103], off offset:160
	v_add_f32_e32 v102, v120, v121
	v_add_f32_e32 v103, v110, v111
	v_add_f32_e32 v102, v124, v102
	v_add_f32_e32 v103, v112, v103
	v_add_f32_e32 v102, v125, v102
	v_add_f32_e32 v103, v113, v103
	v_pk_mul_f32 v[98:99], v[98:99], v[98:99]
	v_add_f32_e32 v102, v102, v103
	v_add_f32_e32 v103, v106, v107
	v_pk_mul_f32 v[100:101], v[100:101], v[100:101]
	v_add_f32_e32 v103, v108, v103
	v_add_f32_e32 v98, v98, v99
	v_add_f32_e32 v103, v109, v103
	v_add_f32_e32 v98, v100, v98
	v_add_f32_e32 v102, v102, v103
	v_add_f32_e32 v98, v101, v98
	v_add_f32_e32 v98, v102, v98
	ds_bpermute_b32 v99, v118, v98
	s_waitcnt lgkmcnt(0)
	v_add_f32_e32 v98, v98, v99
	ds_bpermute_b32 v99, v119, v98
	s_and_saveexec_b64 s[2:3], vcc
	s_cbranch_execz .LBB0_1141
	v_readlane_b32 s10, v252, 9
	v_readlane_b32 s11, v252, 10
	s_waitcnt lgkmcnt(0)
	v_add_f32_e32 v98, v98, v99
	v_lshl_add_u64 v[100:101], v[114:115], 2, s[10:11]
	global_atomic_add_f32 v[100:101], v98, off
; template <int EPI, int MF>
; __device__ __forceinline__ void gemm_part(const u16* __restrict__ A, int lda, const u16* __restrict__ Bt, int K, int ntn, GemmEpi ep, char* smem,
;                                           int mbase, int mrows) {
;     ...
;       } else if (EPI == EPI_RESID) {
;         const float* rp = (row < MP) ? ep.res0 + (size_t)row * DM : ep.res1 + (size_t)(row - MP) * DM;
;         float ssq = 0.f;
; #pragma unroll
;         for (int n = 0; n < 4; ++n) {
;           const int col = cb + n * 16;
;           const float4 r = *(const float4*)(rp + col);
;           float4 v;
;           v.x = r.x + ep.scale * acc[m][n][0]; v.y = r.y + ep.scale * acc[m][n][1];
;           v.z = r.z + ep.scale * acc[m][n][2]; v.w = r.w + ep.scale * acc[m][n][3];
;           *(float4*)(ep.outf + (size_t)row * DM + col) = v;
;           if (ep.xcopy) {
;             bf16x4 o;
;             o[0] = (short)f2bf(v.x); o[1] = (short)f2bf(v.y); o[2] = (short)f2bf(v.z); o[3] = (short)f2bf(v.w);
;             *(bf16x4*)(ep.xcopy + (size_t)row * DM + col) = o;
;           }
;           ssq += v.x * v.x + v.y * v.y + v.z * v.z + v.w * v.w;
;         }
;         if (ep.rss_out) {
;           ssq += __shfl_xor(ssq, 16);
;           ssq += __shfl_xor(ssq, 32);
;           if (fq == 0) atomicAdd(ep.rss_out + row, ssq);
;         }
.LBB0_1141:
	s_or_b64 exec, exec, s[2:3]
	s_waitcnt lgkmcnt(0)
	v_or_b32_e32 v98, 32, v136
	s_mov_b32 s2, 0xffff
	v_cmp_lt_i32_e64 s[12:13], s2, v98
	s_and_saveexec_b64 s[2:3], s[12:13]
	s_xor_b64 s[2:3], exec, s[2:3]
	v_add_u32_e32 v100, 0xffff0020, v136
	v_mov_b32_e32 v101, v0
	v_lshlrev_b64 v[100:101], 12, v[100:101]
	v_lshl_add_u64 v[100:101], s[72:73], 0, v[100:101]
	v_mov_b32_e32 v99, v0
	s_andn2_saveexec_b64 s[2:3], s[2:3]
	v_ashrrev_i32_e32 v99, 31, v98
	v_lshlrev_b64 v[100:101], 12, v[98:99]
	v_lshl_add_u64 v[100:101], s[26:27], 0, v[100:101]
	s_or_b64 exec, exec, s[2:3]
	v_lshlrev_b64 v[102:103], 12, v[98:99]
	v_mov_b32_e32 v139, v0
	v_lshl_add_u64 v[102:103], s[26:27], 0, v[102:103]
	v_lshl_add_u64 v[106:107], v[100:101], 0, v[138:139]
	v_lshl_add_u64 v[108:109], v[102:103], 0, v[138:139]
	global_load_dwordx4 v[100:103], v[106:107], off
	global_load_dwordx4 v[172:175], v[106:107], off offset:64
	global_load_dwordx4 v[176:179], v[106:107], off offset:128
	global_load_dwordx4 v[180:183], v[106:107], off offset:192
	v_lshlrev_b64 v[104:105], 11, v[98:99]
	v_lshl_add_u64 v[104:105], s[28:29], 0, v[104:105]
	v_mov_b32_e32 v127, v0
	s_waitcnt vmcnt(0)
	v_pk_add_f32 v[94:95], v[94:95], v[100:101]
	v_pk_add_f32 v[96:97], v[96:97], v[102:103]
	v_cvt_pk_bf16_f32 v100, v94, v95
	v_cvt_pk_bf16_f32 v101, v96, v97
	v_lshl_add_u64 v[102:103], v[104:105], 0, v[126:127]
	global_store_dwordx4 v[108:109], v[94:97], off
	v_lshlrev_b32_e32 v184, 1, v102
	v_bfi_b32 v184, s100, v184, v102
	v_lshrrev_b32_e32 v185, 5, v102
	v_bfi_b32 v184, 64, v185, v184
	v_mov_b32_e32 v185, v103
	global_store_dwordx2 v[184:185], v[100:101], off
	v_pk_mul_f32 v[100:101], v[94:95], v[94:95]
	v_pk_mul_f32 v[104:105], v[96:97], v[96:97]
	s_nop 0
	s_nop 0
	v_pk_add_f32 v[90:91], v[90:91], v[172:173]
	v_pk_add_f32 v[92:93], v[92:93], v[174:175]
	v_cvt_pk_bf16_f32 v94, v90, v91
	v_cvt_pk_bf16_f32 v95, v92, v93
	global_store_dwordx4 v[108:109], v[90:93], off offset:64
	v_lshlrev_b32_e32 v184, 1, v102
	v_bfi_b32 v184, s100, v184, v102
	v_lshrrev_b32_e32 v185, 5, v102
	v_bfi_b32 v184, 64, v185, v184
	v_mov_b32_e32 v185, v103
	global_store_dwordx2 v[184:185], v[94:95], off offset:32
	v_pk_mul_f32 v[94:95], v[90:91], v[90:91]
	v_pk_mul_f32 v[96:97], v[92:93], v[92:93]
	s_nop 0
	s_nop 0
	v_pk_add_f32 v[86:87], v[86:87], v[176:177]
	v_pk_add_f32 v[88:89], v[88:89], v[178:179]
	v_cvt_pk_bf16_f32 v90, v86, v87
	v_cvt_pk_bf16_f32 v91, v88, v89
	global_store_dwordx4 v[108:109], v[86:89], off offset:128
	v_lshlrev_b32_e32 v184, 1, v102
	v_bfi_b32 v184, s100, v184, v102
	v_lshrrev_b32_e32 v185, 5, v102
	v_bfi_b32 v184, 64, v185, v184
	v_mov_b32_e32 v185, v103
	global_store_dwordx2 v[184:185], v[90:91], off offset:128
	v_pk_mul_f32 v[90:91], v[86:87], v[86:87]
	v_pk_mul_f32 v[92:93], v[88:89], v[88:89]
	s_nop 0
	s_nop 0
	v_pk_add_f32 v[82:83], v[82:83], v[180:181]
	v_pk_add_f32 v[84:85], v[84:85], v[182:183]
	v_cvt_pk_bf16_f32 v86, v82, v83
	v_cvt_pk_bf16_f32 v87, v84, v85
	global_store_dwordx4 v[108:109], v[82:85], off offset:192
	v_lshlrev_b32_e32 v184, 1, v102
	v_bfi_b32 v184, s100, v184, v102
	v_lshrrev_b32_e32 v185, 5, v102
	v_bfi_b32 v184, 64, v185, v184
	v_mov_b32_e32 v185, v103
	global_store_dwordx2 v[184:185], v[86:87], off offset:160
	v_add_f32_e32 v86, v100, v101
	v_add_f32_e32 v87, v94, v95
	v_add_f32_e32 v86, v104, v86
	v_add_f32_e32 v87, v96, v87
	v_add_f32_e32 v86, v105, v86
	v_add_f32_e32 v87, v97, v87
	v_pk_mul_f32 v[82:83], v[82:83], v[82:83]
	v_add_f32_e32 v86, v86, v87
	v_add_f32_e32 v87, v90, v91
	v_pk_mul_f32 v[84:85], v[84:85], v[84:85]
	v_add_f32_e32 v87, v92, v87
	v_add_f32_e32 v82, v82, v83
	v_add_f32_e32 v87, v93, v87
	v_add_f32_e32 v82, v84, v82
	v_add_f32_e32 v86, v86, v87
	v_add_f32_e32 v82, v85, v82
	v_add_f32_e32 v82, v86, v82
	ds_bpermute_b32 v83, v118, v82
	s_waitcnt lgkmcnt(0)
	v_add_f32_e32 v82, v82, v83
	ds_bpermute_b32 v83, v119, v82
	s_and_saveexec_b64 s[2:3], vcc
	s_cbranch_execz .LBB0_1147
	v_readlane_b32 s10, v252, 9
	v_readlane_b32 s11, v252, 10
	s_waitcnt lgkmcnt(0)
	v_add_f32_e32 v82, v82, v83
	v_lshl_add_u64 v[84:85], v[98:99], 2, s[10:11]
	global_atomic_add_f32 v[84:85], v82, off
.LBB0_1147:
	s_or_b64 exec, exec, s[2:3]
	s_waitcnt lgkmcnt(0)
	v_or_b32_e32 v82, 48, v136
	s_mov_b32 s2, 0xffff
	v_cmp_lt_i32_e64 s[12:13], s2, v82
	s_and_saveexec_b64 s[2:3], s[12:13]
	s_xor_b64 s[2:3], exec, s[2:3]
	v_add_u32_e32 v84, 0xffff0030, v136
	v_mov_b32_e32 v85, v0
	v_lshlrev_b64 v[84:85], 12, v[84:85]
	v_lshl_add_u64 v[84:85], s[72:73], 0, v[84:85]
	v_mov_b32_e32 v83, v0
	s_andn2_saveexec_b64 s[2:3], s[2:3]
	v_ashrrev_i32_e32 v83, 31, v82
	v_lshlrev_b64 v[84:85], 12, v[82:83]
	v_lshl_add_u64 v[84:85], s[26:27], 0, v[84:85]
	s_or_b64 exec, exec, s[2:3]
	v_lshlrev_b64 v[86:87], 12, v[82:83]
	v_mov_b32_e32 v139, v0
	v_lshl_add_u64 v[86:87], s[26:27], 0, v[86:87]
	v_lshl_add_u64 v[90:91], v[84:85], 0, v[138:139]
	v_lshl_add_u64 v[92:93], v[86:87], 0, v[138:139]
	global_load_dwordx4 v[84:87], v[90:91], off
	global_load_dwordx4 v[172:175], v[90:91], off offset:64
	global_load_dwordx4 v[176:179], v[90:91], off offset:128
	global_load_dwordx4 v[180:183], v[90:91], off offset:192
	v_lshlrev_b64 v[88:89], 11, v[82:83]
	v_lshl_add_u64 v[88:89], s[28:29], 0, v[88:89]
	v_mov_b32_e32 v127, v0
	s_waitcnt vmcnt(0)
; template <int EPI, int MF>
; __device__ __forceinline__ void gemm_part(const u16* __restrict__ A, int lda, const u16* __restrict__ Bt, int K, int ntn, GemmEpi ep, char* smem,
;                                           int mbase, int mrows) {
;     ...
;       } else if (EPI == EPI_RESID) {
;         const float* rp = (row < MP) ? ep.res0 + (size_t)row * DM : ep.res1 + (size_t)(row - MP) * DM;
;         float ssq = 0.f;
; #pragma unroll
;         for (int n = 0; n < 4; ++n) {
;           const int col = cb + n * 16;
;           const float4 r = *(const float4*)(rp + col);
;           float4 v;
;           v.x = r.x + ep.scale * acc[m][n][0]; v.y = r.y + ep.scale * acc[m][n][1];
;           v.z = r.z + ep.scale * acc[m][n][2]; v.w = r.w + ep.scale * acc[m][n][3];
;           *(float4*)(ep.outf + (size_t)row * DM + col) = v;
;           if (ep.xcopy) {
;             bf16x4 o;
;             o[0] = (short)f2bf(v.x); o[1] = (short)f2bf(v.y); o[2] = (short)f2bf(v.z); o[3] = (short)f2bf(v.w);
;             *(bf16x4*)(ep.xcopy + (size_t)row * DM + col) = o;
;           }
;           ssq += v.x * v.x + v.y * v.y + v.z * v.z + v.w * v.w;
;         }
;         if (ep.rss_out) {
;           ssq += __shfl_xor(ssq, 16);
;           ssq += __shfl_xor(ssq, 32);
;           if (fq == 0) atomicAdd(ep.rss_out + row, ssq);
;         }
	v_pk_add_f32 v[78:79], v[78:79], v[84:85]
	v_pk_add_f32 v[80:81], v[80:81], v[86:87]
	v_cvt_pk_bf16_f32 v84, v78, v79
	v_cvt_pk_bf16_f32 v85, v80, v81
	v_lshl_add_u64 v[86:87], v[88:89], 0, v[126:127]
	global_store_dwordx4 v[92:93], v[78:81], off
	v_lshlrev_b32_e32 v184, 1, v86
	v_bfi_b32 v184, s100, v184, v86
	v_lshrrev_b32_e32 v185, 5, v86
	v_bfi_b32 v184, 64, v185, v184
	v_mov_b32_e32 v185, v87
	global_store_dwordx2 v[184:185], v[84:85], off
	v_pk_mul_f32 v[84:85], v[78:79], v[78:79]
	v_pk_mul_f32 v[88:89], v[80:81], v[80:81]
	s_nop 0
	s_nop 0
	v_pk_add_f32 v[74:75], v[74:75], v[172:173]
	v_pk_add_f32 v[76:77], v[76:77], v[174:175]
	v_cvt_pk_bf16_f32 v78, v74, v75
	v_cvt_pk_bf16_f32 v79, v76, v77
	global_store_dwordx4 v[92:93], v[74:77], off offset:64
	v_lshlrev_b32_e32 v184, 1, v86
	v_bfi_b32 v184, s100, v184, v86
	v_lshrrev_b32_e32 v185, 5, v86
	v_bfi_b32 v184, 64, v185, v184
	v_mov_b32_e32 v185, v87
	global_store_dwordx2 v[184:185], v[78:79], off offset:32
	v_pk_mul_f32 v[78:79], v[74:75], v[74:75]
	v_pk_mul_f32 v[80:81], v[76:77], v[76:77]
	s_nop 0
	s_nop 0
	v_pk_add_f32 v[70:71], v[70:71], v[176:177]
	v_pk_add_f32 v[72:73], v[72:73], v[178:179]
	v_cvt_pk_bf16_f32 v74, v70, v71
	v_cvt_pk_bf16_f32 v75, v72, v73
	global_store_dwordx4 v[92:93], v[70:73], off offset:128
	v_lshlrev_b32_e32 v184, 1, v86
	v_bfi_b32 v184, s100, v184, v86
	v_lshrrev_b32_e32 v185, 5, v86
	v_bfi_b32 v184, 64, v185, v184
	v_mov_b32_e32 v185, v87
	global_store_dwordx2 v[184:185], v[74:75], off offset:128
	v_pk_mul_f32 v[74:75], v[70:71], v[70:71]
	v_pk_mul_f32 v[76:77], v[72:73], v[72:73]
	s_nop 0
	s_nop 0
	v_pk_add_f32 v[66:67], v[66:67], v[180:181]
	v_pk_add_f32 v[68:69], v[68:69], v[182:183]
	v_cvt_pk_bf16_f32 v70, v66, v67
	v_cvt_pk_bf16_f32 v71, v68, v69
	global_store_dwordx4 v[92:93], v[66:69], off offset:192
	v_lshlrev_b32_e32 v184, 1, v86
	v_bfi_b32 v184, s100, v184, v86
	v_lshrrev_b32_e32 v185, 5, v86
	v_bfi_b32 v184, 64, v185, v184
	v_mov_b32_e32 v185, v87
	global_store_dwordx2 v[184:185], v[70:71], off offset:160
	v_add_f32_e32 v70, v84, v85
	v_add_f32_e32 v71, v78, v79
	v_add_f32_e32 v70, v88, v70
	v_add_f32_e32 v71, v80, v71
	v_add_f32_e32 v70, v89, v70
	v_add_f32_e32 v71, v81, v71
	v_pk_mul_f32 v[66:67], v[66:67], v[66:67]
	v_add_f32_e32 v70, v70, v71
	v_add_f32_e32 v71, v74, v75
	v_pk_mul_f32 v[68:69], v[68:69], v[68:69]
	v_add_f32_e32 v71, v76, v71
	v_add_f32_e32 v66, v66, v67
	v_add_f32_e32 v71, v77, v71
	v_add_f32_e32 v66, v68, v66
	v_add_f32_e32 v70, v70, v71
	v_add_f32_e32 v66, v69, v66
	v_add_f32_e32 v66, v70, v66
	ds_bpermute_b32 v67, v118, v66
	s_waitcnt lgkmcnt(0)
	v_add_f32_e32 v66, v66, v67
	ds_bpermute_b32 v67, v119, v66
	s_and_saveexec_b64 s[2:3], vcc
	s_cbranch_execz .LBB0_1153
	v_readlane_b32 s10, v252, 9
	v_readlane_b32 s11, v252, 10
	s_waitcnt lgkmcnt(0)
	v_add_f32_e32 v66, v66, v67
	v_lshl_add_u64 v[68:69], v[82:83], 2, s[10:11]
	global_atomic_add_f32 v[68:69], v66, off
.LBB0_1153:
	s_or_b64 exec, exec, s[2:3]
	s_waitcnt lgkmcnt(0)
	v_or_b32_e32 v66, 64, v136
	s_mov_b32 s2, 0xffff
	v_cmp_lt_i32_e64 s[12:13], s2, v66
	s_and_saveexec_b64 s[2:3], s[12:13]
	s_xor_b64 s[2:3], exec, s[2:3]
	v_add_u32_e32 v68, 0xffff0040, v136
	v_mov_b32_e32 v69, v0
	v_lshlrev_b64 v[68:69], 12, v[68:69]
	v_lshl_add_u64 v[68:69], s[72:73], 0, v[68:69]
	v_mov_b32_e32 v67, v0
	s_andn2_saveexec_b64 s[2:3], s[2:3]
	v_ashrrev_i32_e32 v67, 31, v66
	v_lshlrev_b64 v[68:69], 12, v[66:67]
	v_lshl_add_u64 v[68:69], s[26:27], 0, v[68:69]
	s_or_b64 exec, exec, s[2:3]
	v_lshlrev_b64 v[70:71], 12, v[66:67]
	v_mov_b32_e32 v139, v0
	v_lshl_add_u64 v[70:71], s[26:27], 0, v[70:71]
	v_lshl_add_u64 v[74:75], v[68:69], 0, v[138:139]
	v_lshl_add_u64 v[76:77], v[70:71], 0, v[138:139]
	global_load_dwordx4 v[68:71], v[74:75], off
	global_load_dwordx4 v[172:175], v[74:75], off offset:64
	global_load_dwordx4 v[176:179], v[74:75], off offset:128
	global_load_dwordx4 v[180:183], v[74:75], off offset:192
	v_lshlrev_b64 v[72:73], 11, v[66:67]
	v_lshl_add_u64 v[72:73], s[28:29], 0, v[72:73]
	v_mov_b32_e32 v127, v0
	s_waitcnt vmcnt(0)
	v_pk_add_f32 v[62:63], v[62:63], v[68:69]
	v_pk_add_f32 v[64:65], v[64:65], v[70:71]
	v_cvt_pk_bf16_f32 v68, v62, v63
	v_cvt_pk_bf16_f32 v69, v64, v65
	v_lshl_add_u64 v[70:71], v[72:73], 0, v[126:127]
	global_store_dwordx4 v[76:77], v[62:65], off
	v_lshlrev_b32_e32 v184, 1, v70
	v_bfi_b32 v184, s100, v184, v70
	v_lshrrev_b32_e32 v185, 5, v70
	v_bfi_b32 v184, 64, v185, v184
	v_mov_b32_e32 v185, v71
	global_store_dwordx2 v[184:185], v[68:69], off
	v_pk_mul_f32 v[68:69], v[62:63], v[62:63]
	v_pk_mul_f32 v[72:73], v[64:65], v[64:65]
	s_nop 0
	s_nop 0
	v_pk_add_f32 v[58:59], v[58:59], v[172:173]
	v_pk_add_f32 v[60:61], v[60:61], v[174:175]
	v_cvt_pk_bf16_f32 v62, v58, v59
	v_cvt_pk_bf16_f32 v63, v60, v61
	global_store_dwordx4 v[76:77], v[58:61], off offset:64
	v_lshlrev_b32_e32 v184, 1, v70
	v_bfi_b32 v184, s100, v184, v70
	v_lshrrev_b32_e32 v185, 5, v70
	v_bfi_b32 v184, 64, v185, v184
	v_mov_b32_e32 v185, v71
	global_store_dwordx2 v[184:185], v[62:63], off offset:32
	v_pk_mul_f32 v[62:63], v[58:59], v[58:59]
	v_pk_mul_f32 v[64:65], v[60:61], v[60:61]
	s_nop 0
	s_nop 0
	v_pk_add_f32 v[54:55], v[54:55], v[176:177]
	v_pk_add_f32 v[56:57], v[56:57], v[178:179]
	v_cvt_pk_bf16_f32 v58, v54, v55
	v_cvt_pk_bf16_f32 v59, v56, v57
	global_store_dwordx4 v[76:77], v[54:57], off offset:128
	v_lshlrev_b32_e32 v184, 1, v70
	v_bfi_b32 v184, s100, v184, v70
	v_lshrrev_b32_e32 v185, 5, v70
	v_bfi_b32 v184, 64, v185, v184
	v_mov_b32_e32 v185, v71
	global_store_dwordx2 v[184:185], v[58:59], off offset:128
	v_pk_mul_f32 v[58:59], v[54:55], v[54:55]
	v_pk_mul_f32 v[60:61], v[56:57], v[56:57]
	s_nop 0
	s_nop 0
	v_pk_add_f32 v[50:51], v[50:51], v[180:181]
	v_pk_add_f32 v[52:53], v[52:53], v[182:183]
	v_cvt_pk_bf16_f32 v54, v50, v51
	v_cvt_pk_bf16_f32 v55, v52, v53
	global_store_dwordx4 v[76:77], v[50:53], off offset:192
	v_lshlrev_b32_e32 v184, 1, v70
	v_bfi_b32 v184, s100, v184, v70
	v_lshrrev_b32_e32 v185, 5, v70
	v_bfi_b32 v184, 64, v185, v184
	v_mov_b32_e32 v185, v71
	global_store_dwordx2 v[184:185], v[54:55], off offset:160
	v_add_f32_e32 v54, v68, v69
	v_add_f32_e32 v55, v62, v63
	v_add_f32_e32 v54, v72, v54
	v_add_f32_e32 v55, v64, v55
	v_add_f32_e32 v54, v73, v54
	v_add_f32_e32 v55, v65, v55
	v_pk_mul_f32 v[50:51], v[50:51], v[50:51]
	v_add_f32_e32 v54, v54, v55
	v_add_f32_e32 v55, v58, v59
	v_pk_mul_f32 v[52:53], v[52:53], v[52:53]
	v_add_f32_e32 v55, v60, v55
	v_add_f32_e32 v50, v50, v51
	v_add_f32_e32 v55, v61, v55
	v_add_f32_e32 v50, v52, v50
	v_add_f32_e32 v54, v54, v55
	v_add_f32_e32 v50, v53, v50
	v_add_f32_e32 v50, v54, v50
	ds_bpermute_b32 v51, v118, v50
	s_waitcnt lgkmcnt(0)
	v_add_f32_e32 v50, v50, v51
	ds_bpermute_b32 v51, v119, v50
	s_and_saveexec_b64 s[2:3], vcc
	s_cbranch_execz .LBB0_1159
	v_readlane_b32 s10, v252, 9
	v_readlane_b32 s11, v252, 10
	s_waitcnt lgkmcnt(0)
	v_add_f32_e32 v50, v50, v51
	v_lshl_add_u64 v[52:53], v[66:67], 2, s[10:11]
	global_atomic_add_f32 v[52:53], v50, off
; template <int EPI, int MF>
; __device__ __forceinline__ void gemm_part(const u16* __restrict__ A, int lda, const u16* __restrict__ Bt, int K, int ntn, GemmEpi ep, char* smem,
;                                           int mbase, int mrows) {
;     ...
;       } else if (EPI == EPI_RESID) {
;         const float* rp = (row < MP) ? ep.res0 + (size_t)row * DM : ep.res1 + (size_t)(row - MP) * DM;
;         float ssq = 0.f;
; #pragma unroll
;         for (int n = 0; n < 4; ++n) {
;           const int col = cb + n * 16;
;           const float4 r = *(const float4*)(rp + col);
;           float4 v;
;           v.x = r.x + ep.scale * acc[m][n][0]; v.y = r.y + ep.scale * acc[m][n][1];
;           v.z = r.z + ep.scale * acc[m][n][2]; v.w = r.w + ep.scale * acc[m][n][3];
;           *(float4*)(ep.outf + (size_t)row * DM + col) = v;
;           if (ep.xcopy) {
;             bf16x4 o;
;             o[0] = (short)f2bf(v.x); o[1] = (short)f2bf(v.y); o[2] = (short)f2bf(v.z); o[3] = (short)f2bf(v.w);
;             *(bf16x4*)(ep.xcopy + (size_t)row * DM + col) = o;
;           }
;           ssq += v.x * v.x + v.y * v.y + v.z * v.z + v.w * v.w;
;         }
;         if (ep.rss_out) {
;           ssq += __shfl_xor(ssq, 16);
;           ssq += __shfl_xor(ssq, 32);
;           if (fq == 0) atomicAdd(ep.rss_out + row, ssq);
;         }
.LBB0_1159:
	s_or_b64 exec, exec, s[2:3]
	s_waitcnt lgkmcnt(0)
	v_or_b32_e32 v50, 0x50, v136
	s_mov_b32 s2, 0xffff
	v_cmp_lt_i32_e64 s[12:13], s2, v50
	s_and_saveexec_b64 s[2:3], s[12:13]
	s_xor_b64 s[2:3], exec, s[2:3]
	v_add_u32_e32 v52, 0xffff0050, v136
	v_mov_b32_e32 v53, v0
	v_lshlrev_b64 v[52:53], 12, v[52:53]
	v_lshl_add_u64 v[52:53], s[72:73], 0, v[52:53]
	v_mov_b32_e32 v51, v0
	s_andn2_saveexec_b64 s[2:3], s[2:3]
	v_ashrrev_i32_e32 v51, 31, v50
	v_lshlrev_b64 v[52:53], 12, v[50:51]
	v_lshl_add_u64 v[52:53], s[26:27], 0, v[52:53]
	s_or_b64 exec, exec, s[2:3]
	v_lshlrev_b64 v[54:55], 12, v[50:51]
	v_mov_b32_e32 v139, v0
	v_lshl_add_u64 v[54:55], s[26:27], 0, v[54:55]
	v_lshl_add_u64 v[58:59], v[52:53], 0, v[138:139]
	v_lshl_add_u64 v[60:61], v[54:55], 0, v[138:139]
	global_load_dwordx4 v[52:55], v[58:59], off
	global_load_dwordx4 v[172:175], v[58:59], off offset:64
	global_load_dwordx4 v[176:179], v[58:59], off offset:128
	global_load_dwordx4 v[180:183], v[58:59], off offset:192
	v_lshlrev_b64 v[56:57], 11, v[50:51]
	v_lshl_add_u64 v[56:57], s[28:29], 0, v[56:57]
	v_mov_b32_e32 v127, v0
	s_waitcnt vmcnt(0)
	v_pk_add_f32 v[46:47], v[46:47], v[52:53]
	v_pk_add_f32 v[48:49], v[48:49], v[54:55]
	v_cvt_pk_bf16_f32 v52, v46, v47
	v_cvt_pk_bf16_f32 v53, v48, v49
	v_lshl_add_u64 v[54:55], v[56:57], 0, v[126:127]
	global_store_dwordx4 v[60:61], v[46:49], off
	v_lshlrev_b32_e32 v184, 1, v54
	v_bfi_b32 v184, s100, v184, v54
	v_lshrrev_b32_e32 v185, 5, v54
	v_bfi_b32 v184, 64, v185, v184
	v_mov_b32_e32 v185, v55
	global_store_dwordx2 v[184:185], v[52:53], off
	v_pk_mul_f32 v[52:53], v[46:47], v[46:47]
	v_pk_mul_f32 v[56:57], v[48:49], v[48:49]
	s_nop 0
	s_nop 0
	v_pk_add_f32 v[42:43], v[42:43], v[172:173]
	v_pk_add_f32 v[44:45], v[44:45], v[174:175]
	v_cvt_pk_bf16_f32 v46, v42, v43
	v_cvt_pk_bf16_f32 v47, v44, v45
	global_store_dwordx4 v[60:61], v[42:45], off offset:64
	v_lshlrev_b32_e32 v184, 1, v54
	v_bfi_b32 v184, s100, v184, v54
	v_lshrrev_b32_e32 v185, 5, v54
	v_bfi_b32 v184, 64, v185, v184
	v_mov_b32_e32 v185, v55
	global_store_dwordx2 v[184:185], v[46:47], off offset:32
	v_pk_mul_f32 v[46:47], v[42:43], v[42:43]
	v_pk_mul_f32 v[48:49], v[44:45], v[44:45]
	s_nop 0
	s_nop 0
	v_pk_add_f32 v[38:39], v[38:39], v[176:177]
	v_pk_add_f32 v[40:41], v[40:41], v[178:179]
	v_cvt_pk_bf16_f32 v42, v38, v39
	v_cvt_pk_bf16_f32 v43, v40, v41
	global_store_dwordx4 v[60:61], v[38:41], off offset:128
	v_lshlrev_b32_e32 v184, 1, v54
	v_bfi_b32 v184, s100, v184, v54
	v_lshrrev_b32_e32 v185, 5, v54
	v_bfi_b32 v184, 64, v185, v184
	v_mov_b32_e32 v185, v55
	global_store_dwordx2 v[184:185], v[42:43], off offset:128
	v_pk_mul_f32 v[42:43], v[38:39], v[38:39]
	v_pk_mul_f32 v[44:45], v[40:41], v[40:41]
	s_nop 0
	s_nop 0
	v_pk_add_f32 v[34:35], v[34:35], v[180:181]
	v_pk_add_f32 v[36:37], v[36:37], v[182:183]
	v_cvt_pk_bf16_f32 v38, v34, v35
	v_cvt_pk_bf16_f32 v39, v36, v37
	global_store_dwordx4 v[60:61], v[34:37], off offset:192
	v_lshlrev_b32_e32 v184, 1, v54
	v_bfi_b32 v184, s100, v184, v54
	v_lshrrev_b32_e32 v185, 5, v54
	v_bfi_b32 v184, 64, v185, v184
	v_mov_b32_e32 v185, v55
	global_store_dwordx2 v[184:185], v[38:39], off offset:160
	v_add_f32_e32 v38, v52, v53
	v_add_f32_e32 v39, v46, v47
	v_add_f32_e32 v38, v56, v38
	v_add_f32_e32 v39, v48, v39
	v_add_f32_e32 v38, v57, v38
	v_add_f32_e32 v39, v49, v39
	v_pk_mul_f32 v[34:35], v[34:35], v[34:35]
	v_add_f32_e32 v38, v38, v39
	v_add_f32_e32 v39, v42, v43
	v_pk_mul_f32 v[36:37], v[36:37], v[36:37]
	v_add_f32_e32 v39, v44, v39
	v_add_f32_e32 v34, v34, v35
	v_add_f32_e32 v39, v45, v39
	v_add_f32_e32 v34, v36, v34
	v_add_f32_e32 v38, v38, v39
	v_add_f32_e32 v34, v37, v34
	v_add_f32_e32 v34, v38, v34
	ds_bpermute_b32 v35, v118, v34
	s_waitcnt lgkmcnt(0)
	v_add_f32_e32 v34, v34, v35
	ds_bpermute_b32 v35, v119, v34
	s_and_saveexec_b64 s[2:3], vcc
	s_cbranch_execz .LBB0_1165
	v_readlane_b32 s10, v252, 9
	v_readlane_b32 s11, v252, 10
	s_waitcnt lgkmcnt(0)
	v_add_f32_e32 v34, v34, v35
	v_lshl_add_u64 v[36:37], v[50:51], 2, s[10:11]
	global_atomic_add_f32 v[36:37], v34, off
.LBB0_1165:
	s_or_b64 exec, exec, s[2:3]
	s_waitcnt lgkmcnt(0)
	v_or_b32_e32 v34, 0x60, v136
	s_mov_b32 s2, 0xffff
	v_cmp_lt_i32_e64 s[12:13], s2, v34
	s_and_saveexec_b64 s[2:3], s[12:13]
	s_xor_b64 s[2:3], exec, s[2:3]
	v_add_u32_e32 v36, 0xffff0060, v136
	v_mov_b32_e32 v37, v0
	v_lshlrev_b64 v[36:37], 12, v[36:37]
	v_lshl_add_u64 v[36:37], s[72:73], 0, v[36:37]
	v_mov_b32_e32 v35, v0
	s_andn2_saveexec_b64 s[2:3], s[2:3]
	v_ashrrev_i32_e32 v35, 31, v34
	v_lshlrev_b64 v[36:37], 12, v[34:35]
	v_lshl_add_u64 v[36:37], s[26:27], 0, v[36:37]
	s_or_b64 exec, exec, s[2:3]
	v_lshlrev_b64 v[38:39], 12, v[34:35]
	v_mov_b32_e32 v139, v0
	v_lshl_add_u64 v[38:39], s[26:27], 0, v[38:39]
	v_lshl_add_u64 v[42:43], v[36:37], 0, v[138:139]
	v_lshl_add_u64 v[44:45], v[38:39], 0, v[138:139]
	global_load_dwordx4 v[36:39], v[42:43], off
	global_load_dwordx4 v[172:175], v[42:43], off offset:64
	global_load_dwordx4 v[176:179], v[42:43], off offset:128
	global_load_dwordx4 v[180:183], v[42:43], off offset:192
	v_lshlrev_b64 v[40:41], 11, v[34:35]
	v_lshl_add_u64 v[40:41], s[28:29], 0, v[40:41]
	v_mov_b32_e32 v127, v0
	s_waitcnt vmcnt(0)
; template <int EPI, int MF>
; __device__ __forceinline__ void gemm_part(const u16* __restrict__ A, int lda, const u16* __restrict__ Bt, int K, int ntn, GemmEpi ep, char* smem,
;                                           int mbase, int mrows) {
;     ...
;         const float* rp = (row < MP) ? ep.res0 + (size_t)row * DM : ep.res1 + (size_t)(row - MP) * DM;
;         float ssq = 0.f;
; #pragma unroll
;         for (int n = 0; n < 4; ++n) {
;           const int col = cb + n * 16;
;           const float4 r = *(const float4*)(rp + col);
;           float4 v;
;           v.x = r.x + ep.scale * acc[m][n][0]; v.y = r.y + ep.scale * acc[m][n][1];
;           v.z = r.z + ep.scale * acc[m][n][2]; v.w = r.w + ep.scale * acc[m][n][3];
;           *(float4*)(ep.outf + (size_t)row * DM + col) = v;
;           if (ep.xcopy) {
;             bf16x4 o;
;             o[0] = (short)f2bf(v.x); o[1] = (short)f2bf(v.y); o[2] = (short)f2bf(v.z); o[3] = (short)f2bf(v.w);
;             *(bf16x4*)(ep.xcopy + (size_t)row * DM + col) = o;
;           }
;           ssq += v.x * v.x + v.y * v.y + v.z * v.z + v.w * v.w;
;         }
;         if (ep.rss_out) {
;           ssq += __shfl_xor(ssq, 16);
;           ssq += __shfl_xor(ssq, 32);
;           if (fq == 0) atomicAdd(ep.rss_out + row, ssq);
;         }
	v_pk_add_f32 v[30:31], v[30:31], v[36:37]
	v_pk_add_f32 v[32:33], v[32:33], v[38:39]
	v_cvt_pk_bf16_f32 v36, v30, v31
	v_cvt_pk_bf16_f32 v37, v32, v33
	v_lshl_add_u64 v[38:39], v[40:41], 0, v[126:127]
	global_store_dwordx4 v[44:45], v[30:33], off
	v_lshlrev_b32_e32 v184, 1, v38
	v_bfi_b32 v184, s100, v184, v38
	v_lshrrev_b32_e32 v185, 5, v38
	v_bfi_b32 v184, 64, v185, v184
	v_mov_b32_e32 v185, v39
	global_store_dwordx2 v[184:185], v[36:37], off
	v_pk_mul_f32 v[36:37], v[30:31], v[30:31]
	v_pk_mul_f32 v[40:41], v[32:33], v[32:33]
	s_nop 0
	s_nop 0
	v_pk_add_f32 v[26:27], v[26:27], v[172:173]
	v_pk_add_f32 v[28:29], v[28:29], v[174:175]
	v_cvt_pk_bf16_f32 v30, v26, v27
	v_cvt_pk_bf16_f32 v31, v28, v29
	global_store_dwordx4 v[44:45], v[26:29], off offset:64
	v_lshlrev_b32_e32 v184, 1, v38
	v_bfi_b32 v184, s100, v184, v38
	v_lshrrev_b32_e32 v185, 5, v38
	v_bfi_b32 v184, 64, v185, v184
	v_mov_b32_e32 v185, v39
	global_store_dwordx2 v[184:185], v[30:31], off offset:32
	v_pk_mul_f32 v[30:31], v[26:27], v[26:27]
	v_pk_mul_f32 v[32:33], v[28:29], v[28:29]
	s_nop 0
	s_nop 0
	v_pk_add_f32 v[22:23], v[22:23], v[176:177]
	v_pk_add_f32 v[24:25], v[24:25], v[178:179]
	v_cvt_pk_bf16_f32 v26, v22, v23
	v_cvt_pk_bf16_f32 v27, v24, v25
	global_store_dwordx4 v[44:45], v[22:25], off offset:128
	v_lshlrev_b32_e32 v184, 1, v38
	v_bfi_b32 v184, s100, v184, v38
	v_lshrrev_b32_e32 v185, 5, v38
	v_bfi_b32 v184, 64, v185, v184
	v_mov_b32_e32 v185, v39
	global_store_dwordx2 v[184:185], v[26:27], off offset:128
	v_pk_mul_f32 v[26:27], v[22:23], v[22:23]
	v_pk_mul_f32 v[28:29], v[24:25], v[24:25]
	s_nop 0
	s_nop 0
	v_pk_add_f32 v[18:19], v[18:19], v[180:181]
	v_pk_add_f32 v[20:21], v[20:21], v[182:183]
	v_cvt_pk_bf16_f32 v22, v18, v19
	v_cvt_pk_bf16_f32 v23, v20, v21
	global_store_dwordx4 v[44:45], v[18:21], off offset:192
	v_lshlrev_b32_e32 v184, 1, v38
	v_bfi_b32 v184, s100, v184, v38
	v_lshrrev_b32_e32 v185, 5, v38
	v_bfi_b32 v184, 64, v185, v184
	v_mov_b32_e32 v185, v39
	global_store_dwordx2 v[184:185], v[22:23], off offset:160
	v_add_f32_e32 v22, v36, v37
	v_add_f32_e32 v23, v30, v31
	v_add_f32_e32 v22, v40, v22
	v_add_f32_e32 v23, v32, v23
	v_add_f32_e32 v22, v41, v22
	v_add_f32_e32 v23, v33, v23
	v_pk_mul_f32 v[18:19], v[18:19], v[18:19]
	v_add_f32_e32 v22, v22, v23
	v_add_f32_e32 v23, v26, v27
	v_pk_mul_f32 v[20:21], v[20:21], v[20:21]
	v_add_f32_e32 v23, v28, v23
	v_add_f32_e32 v18, v18, v19
	v_add_f32_e32 v23, v29, v23
	v_add_f32_e32 v18, v20, v18
	v_add_f32_e32 v22, v22, v23
	v_add_f32_e32 v18, v21, v18
	v_add_f32_e32 v18, v22, v18
	ds_bpermute_b32 v19, v118, v18
	s_waitcnt lgkmcnt(0)
	v_add_f32_e32 v18, v18, v19
	ds_bpermute_b32 v19, v119, v18
	s_and_saveexec_b64 s[2:3], vcc
	s_cbranch_execz .LBB0_1171
	v_readlane_b32 s10, v252, 9
	v_readlane_b32 s11, v252, 10
	s_waitcnt lgkmcnt(0)
	v_add_f32_e32 v18, v18, v19
	v_lshl_add_u64 v[20:21], v[34:35], 2, s[10:11]
	global_atomic_add_f32 v[20:21], v18, off
.LBB0_1171:
	s_or_b64 exec, exec, s[2:3]
	s_waitcnt lgkmcnt(0)
	v_or_b32_e32 v18, 0x70, v136
	s_mov_b32 s2, 0xffff
	v_cmp_lt_i32_e64 s[12:13], s2, v18
	s_and_saveexec_b64 s[2:3], s[12:13]
	s_xor_b64 s[2:3], exec, s[2:3]
	v_add_u32_e32 v20, 0xffff0070, v136
	v_mov_b32_e32 v21, v0
	v_lshlrev_b64 v[20:21], 12, v[20:21]
	v_lshl_add_u64 v[20:21], s[72:73], 0, v[20:21]
	v_mov_b32_e32 v19, v0
	s_andn2_saveexec_b64 s[2:3], s[2:3]
	v_ashrrev_i32_e32 v19, 31, v18
	v_lshlrev_b64 v[20:21], 12, v[18:19]
	v_lshl_add_u64 v[20:21], s[26:27], 0, v[20:21]
	s_or_b64 exec, exec, s[2:3]
	v_lshlrev_b64 v[22:23], 12, v[18:19]
	v_mov_b32_e32 v139, v0
	v_lshl_add_u64 v[22:23], s[26:27], 0, v[22:23]
	v_lshl_add_u64 v[26:27], v[20:21], 0, v[138:139]
	v_lshl_add_u64 v[28:29], v[22:23], 0, v[138:139]
	global_load_dwordx4 v[20:23], v[26:27], off
	global_load_dwordx4 v[172:175], v[26:27], off offset:64
	global_load_dwordx4 v[176:179], v[26:27], off offset:128
	global_load_dwordx4 v[180:183], v[26:27], off offset:192
	v_lshlrev_b64 v[24:25], 11, v[18:19]
	v_lshl_add_u64 v[24:25], s[28:29], 0, v[24:25]
	v_mov_b32_e32 v127, v0
	s_waitcnt vmcnt(0)
	v_pk_add_f32 v[14:15], v[14:15], v[20:21]
	v_pk_add_f32 v[16:17], v[16:17], v[22:23]
	v_cvt_pk_bf16_f32 v20, v14, v15
	v_cvt_pk_bf16_f32 v21, v16, v17
	v_lshl_add_u64 v[22:23], v[24:25], 0, v[126:127]
	global_store_dwordx4 v[28:29], v[14:17], off
	v_lshlrev_b32_e32 v184, 1, v22
	v_bfi_b32 v184, s100, v184, v22
	v_lshrrev_b32_e32 v185, 5, v22
	v_bfi_b32 v184, 64, v185, v184
	v_mov_b32_e32 v185, v23
	global_store_dwordx2 v[184:185], v[20:21], off
	v_pk_mul_f32 v[20:21], v[14:15], v[14:15]
	v_pk_mul_f32 v[24:25], v[16:17], v[16:17]
	s_nop 0
	s_nop 0
	v_pk_add_f32 v[10:11], v[10:11], v[172:173]
	v_pk_add_f32 v[12:13], v[12:13], v[174:175]
	v_cvt_pk_bf16_f32 v14, v10, v11
	v_cvt_pk_bf16_f32 v15, v12, v13
	global_store_dwordx4 v[28:29], v[10:13], off offset:64
	v_lshlrev_b32_e32 v184, 1, v22
	v_bfi_b32 v184, s100, v184, v22
	v_lshrrev_b32_e32 v185, 5, v22
	v_bfi_b32 v184, 64, v185, v184
	v_mov_b32_e32 v185, v23
	global_store_dwordx2 v[184:185], v[14:15], off offset:32
	v_pk_mul_f32 v[14:15], v[10:11], v[10:11]
	v_pk_mul_f32 v[16:17], v[12:13], v[12:13]
	s_nop 0
	s_nop 0
	v_pk_add_f32 v[6:7], v[6:7], v[176:177]
	v_pk_add_f32 v[8:9], v[8:9], v[178:179]
	v_cvt_pk_bf16_f32 v10, v6, v7
	v_cvt_pk_bf16_f32 v11, v8, v9
	global_store_dwordx4 v[28:29], v[6:9], off offset:128
	v_lshlrev_b32_e32 v184, 1, v22
	v_bfi_b32 v184, s100, v184, v22
	v_lshrrev_b32_e32 v185, 5, v22
	v_bfi_b32 v184, 64, v185, v184
	v_mov_b32_e32 v185, v23
	global_store_dwordx2 v[184:185], v[10:11], off offset:128
	v_pk_mul_f32 v[10:11], v[6:7], v[6:7]
	v_pk_mul_f32 v[12:13], v[8:9], v[8:9]
	s_nop 0
	s_nop 0
	v_pk_add_f32 v[2:3], v[2:3], v[180:181]
	v_pk_add_f32 v[4:5], v[4:5], v[182:183]
	v_cvt_pk_bf16_f32 v6, v2, v3
	v_cvt_pk_bf16_f32 v7, v4, v5
	global_store_dwordx4 v[28:29], v[2:5], off offset:192
	v_lshlrev_b32_e32 v184, 1, v22
	v_bfi_b32 v184, s100, v184, v22
	v_lshrrev_b32_e32 v185, 5, v22
	v_bfi_b32 v184, 64, v185, v184
	v_mov_b32_e32 v185, v23
	global_store_dwordx2 v[184:185], v[6:7], off offset:160
	v_add_f32_e32 v6, v20, v21
	v_add_f32_e32 v7, v14, v15
	v_add_f32_e32 v6, v24, v6
	v_add_f32_e32 v7, v16, v7
	v_add_f32_e32 v6, v25, v6
	v_add_f32_e32 v7, v17, v7
	v_pk_mul_f32 v[2:3], v[2:3], v[2:3]
	v_add_f32_e32 v6, v6, v7
	v_add_f32_e32 v7, v10, v11
	v_pk_mul_f32 v[4:5], v[4:5], v[4:5]
	v_add_f32_e32 v7, v12, v7
	v_add_f32_e32 v2, v2, v3
	v_add_f32_e32 v7, v13, v7
	v_add_f32_e32 v2, v4, v2
	v_add_f32_e32 v6, v6, v7
	v_add_f32_e32 v2, v5, v2
	v_add_f32_e32 v2, v6, v2
	ds_bpermute_b32 v3, v118, v2
	s_waitcnt lgkmcnt(0)
	v_add_f32_e32 v2, v2, v3
	ds_bpermute_b32 v3, v119, v2
	s_and_saveexec_b64 s[2:3], vcc
	s_cbranch_execz .LBB0_1124
	v_readlane_b32 s10, v252, 9
	v_readlane_b32 s11, v252, 10
	s_waitcnt lgkmcnt(0)
	v_add_f32_e32 v2, v2, v3
	v_lshl_add_u64 v[4:5], v[18:19], 2, s[10:11]
	global_atomic_add_f32 v[4:5], v2, off
	s_branch .LBB0_1124

; #define MFMA(a, b, c) __builtin_amdgcn_mfma_f32_16x16x32_bf16((a), (b), (c), 0, 0, 0)
; template <int EPI, int MF>
; __device__ __forceinline__ void gemm_part(const u16* __restrict__ A, int lda, const u16* __restrict__ Bt, int K, int ntn, GemmEpi ep, char* smem,
;                                           int mbase, int mrows) {
;     ...
;     for (int kt = 0; kt < nk; ++kt) {
;       if (kt + 1 < nk) {
;         if (MF == 8) asm volatile("s_waitcnt vmcnt(6)" ::: "memory");
;         else asm volatile("s_waitcnt vmcnt(3)" ::: "memory");
;       } else asm volatile("s_waitcnt vmcnt(0)" ::: "memory");
;       asm volatile("s_waitcnt lgkmcnt(0)" ::: "memory");
;       __builtin_amdgcn_s_barrier();
;       const u16* a_ = sbase + (kt % 3) * STG;
;       const u16* b_ = a_ + BM * 32;
;       bf16x8 bfr[4], afc[2], afn[2];
;       const u16* ap_ = a_ + (wr * (16 * MF) + fr) * 32 + fq * 8;
; #pragma unroll
;       for (int n = 0; n < 4; ++n) bfr[n] = rd_std(b_ + (wc * 64 + n * 16 + fr) * 32 + fq * 8);
;       afc[0] = rd_std(ap_); afc[1] = rd_std(ap_ + 16 * 32);
;       __builtin_amdgcn_sched_barrier(0);
;       if (kt + 2 < nk) GEMM_ISSUE(kt + 2);
;       __builtin_amdgcn_sched_barrier(0);
; #pragma unroll
;       for (int mh = 0; mh < MF / 2; ++mh) {
;         if (mh + 1 < MF / 2) {
;           afn[0] = rd_std(ap_ + ((mh + 1) * 2) * 16 * 32);
;           afn[1] = rd_std(ap_ + ((mh + 1) * 2 + 1) * 16 * 32);
;         }
;         __builtin_amdgcn_sched_barrier(0);
; #pragma unroll
;         for (int m = 0; m < 2; ++m)
; #pragma unroll
;           for (int n = 0; n < 4; ++n) acc[mh * 2 + m][n] = MFMA(bfr[n], afc[m], acc[mh * 2 + m][n]);
;         __builtin_amdgcn_sched_barrier(0);
;         afc[0] = afn[0]; afc[1] = afn[1];
;       }
;     }
.LBB0_1182:
	s_mul_hi_u32 s13, s11, 0xaaaaaaab
	s_lshr_b32 s13, s13, 1
	s_mul_i32 s13, s13, 0x9000
	s_mul_hi_u32 s12, s9, 0xaaaaaaab
	v_subrev_u32_e32 v44, s13, v56
	v_add_u32_e32 v98, s3, v54
	s_lshr_b32 s12, s12, 1
	s_waitcnt vmcnt(3)
	v_add_u32_e32 v76, v98, v44
	s_mul_i32 s12, s12, 0x9000
	v_subrev_u32_e32 v80, s13, v57
	s_waitcnt lgkmcnt(0)
	s_barrier
	ds_read_b128 v[44:47], v76 offset:4096
	ds_read_b128 v[68:71], v76 offset:5120
	ds_read_b128 v[72:75], v76 offset:6144
	ds_read_b128 v[76:79], v76 offset:7168
	v_subrev_u32_e32 v67, s12, v56
	v_subrev_u32_e32 v94, s12, v58
	s_mul_hi_u32 s12, s8, 0xaaaaaaab
	v_add_u32_e32 v84, v98, v80
	s_lshr_b32 s12, s12, 1
	ds_read_b128 v[80:83], v84
	ds_read_b128 v[84:87], v84 offset:1024
	s_mul_i32 s12, s12, 0x9000
	v_subrev_u32_e32 v95, s12, v59
	v_subrev_u32_e32 v96, s12, v60
	v_subrev_u32_e32 v97, s12, v61
	s_mul_hi_u32 s12, s10, 0xaaaaaaab
	s_lshr_b32 s12, s12, 1
	s_mul_i32 s12, s12, 0x9000
	v_subrev_u32_e32 v92, s12, v62
	v_subrev_u32_e32 v99, s12, v63
	v_subrev_u32_e32 v100, s12, v64
	s_add_i32 s12, s3, 0
	v_add_u32_e32 v92, s12, v92
	v_lshl_add_u64 v[88:89], v[42:43], 0, v[38:39]
	v_readfirstlane_b32 s13, v92
	v_lshl_add_u64 v[90:91], v[88:89], 0, s[74:75]
	s_mov_b32 m0, s13
	v_add_u32_e32 v99, s12, v99
	global_load_lds_dwordx4 v[90:91], off
	v_lshl_add_u64 v[90:91], v[40:41], 0, v[38:39]
	v_readfirstlane_b32 s13, v99
	v_add_u32_e32 v99, s12, v100
	v_lshl_add_u64 v[92:93], v[90:91], 0, s[74:75]
	s_mov_b32 m0, s13
	v_readfirstlane_b32 s13, v99
	global_load_lds_dwordx4 v[92:93], off
	v_lshl_add_u64 v[92:93], v[90:91], 0, s[92:93]
	s_mov_b32 m0, s13
	s_add_i32 s11, s11, 2
	global_load_lds_dwordx4 v[92:93], off
	s_waitcnt lgkmcnt(0)
	v_mfma_f32_16x16x32_bf16 v[30:33], v[44:47], v[80:83], v[30:33]
	v_mfma_f32_16x16x32_bf16 v[26:29], v[68:71], v[80:83], v[26:29]
	v_mfma_f32_16x16x32_bf16 v[22:25], v[72:75], v[80:83], v[22:25]
	v_mfma_f32_16x16x32_bf16 v[18:21], v[76:79], v[80:83], v[18:21]
	v_mfma_f32_16x16x32_bf16 v[14:17], v[44:47], v[84:87], v[14:17]
	v_mfma_f32_16x16x32_bf16 v[10:13], v[68:71], v[84:87], v[10:13]
	v_mfma_f32_16x16x32_bf16 v[6:9], v[72:75], v[84:87], v[6:9]
	v_mfma_f32_16x16x32_bf16 v[2:5], v[76:79], v[84:87], v[2:5]
	s_waitcnt vmcnt(3)
	v_add_u32_e32 v67, v98, v67
	s_waitcnt lgkmcnt(0)
	s_barrier
	ds_read_b128 v[44:47], v67 offset:16384
	ds_read_b128 v[68:71], v67 offset:17408
	ds_read_b128 v[72:75], v67 offset:18432
	ds_read_b128 v[76:79], v67 offset:19456
	v_add_u32_e32 v67, v98, v94
	ds_read_b128 v[80:83], v67
	ds_read_b128 v[84:87], v67 offset:1024
	v_add_u32_e32 v67, s12, v97
	v_lshl_add_u64 v[88:89], v[88:89], 0, s[52:53]
	v_readfirstlane_b32 s13, v67
	v_add_u32_e32 v67, s12, v96
	s_mov_b32 m0, s13
	v_readfirstlane_b32 s13, v67
	v_add_u32_e32 v67, s12, v95
	global_load_lds_dwordx4 v[88:89], off
	v_lshl_add_u64 v[88:89], v[90:91], 0, s[52:53]
	s_mov_b32 m0, s13
	v_readfirstlane_b32 s12, v67
	global_load_lds_dwordx4 v[88:89], off
	v_lshl_add_u64 v[88:89], v[90:91], 0, s[54:55]
	s_mov_b32 m0, s12
	s_nop 0
	global_load_lds_dwordx4 v[88:89], off
	s_waitcnt lgkmcnt(0)
	v_mfma_f32_16x16x32_bf16 v[30:33], v[44:47], v[80:83], v[30:33]
	v_mfma_f32_16x16x32_bf16 v[26:29], v[68:71], v[80:83], v[26:29]
	v_mfma_f32_16x16x32_bf16 v[22:25], v[72:75], v[80:83], v[22:25]
	v_mfma_f32_16x16x32_bf16 v[18:21], v[76:79], v[80:83], v[18:21]
	v_mfma_f32_16x16x32_bf16 v[14:17], v[44:47], v[84:87], v[14:17]
	v_mfma_f32_16x16x32_bf16 v[10:13], v[68:71], v[84:87], v[10:13]
	v_mfma_f32_16x16x32_bf16 v[6:9], v[72:75], v[84:87], v[6:9]
	v_mfma_f32_16x16x32_bf16 v[2:5], v[76:79], v[84:87], v[2:5]
	s_addk_i32 s3, 0x6000
	s_add_i32 s9, s9, 2
	s_add_i32 s8, s8, 2
	s_add_i32 s10, s10, 2
	v_lshl_add_u64 v[40:41], v[40:41], 0, s[74:75]
	s_cmp_eq_u32 s3, 0x5a000
	v_lshl_add_u64 v[42:43], v[42:43], 0, s[74:75]
	s_cbranch_scc0 .LBB0_1182
	s_waitcnt vmcnt(3)
	s_waitcnt lgkmcnt(0)
	s_barrier
	ds_read_b128 v[40:43], v65 offset:4096
	ds_read_b128 v[44:47], v65 offset:5120
	ds_read_b128 v[68:71], v65 offset:6144
	ds_read_b128 v[72:75], v65 offset:7168
	ds_read_b128 v[76:79], v55
	ds_read_b128 v[80:83], v55 offset:1024
	s_mul_hi_u32 s8, s9, 0xaaaaaaab
	s_lshr_b32 s8, s8, 1
	s_mul_i32 s8, s8, 0x9000
	s_sub_i32 s3, s3, s8
	s_add_i32 s3, s3, 0
	s_addk_i32 s3, 0x3000
	s_waitcnt lgkmcnt(0)
	v_mfma_f32_16x16x32_bf16 v[30:33], v[40:43], v[76:79], v[30:33]
	v_mfma_f32_16x16x32_bf16 v[26:29], v[44:47], v[76:79], v[26:29]
	v_mfma_f32_16x16x32_bf16 v[22:25], v[68:71], v[76:79], v[22:25]
	v_mfma_f32_16x16x32_bf16 v[18:21], v[72:75], v[76:79], v[18:21]
	v_mfma_f32_16x16x32_bf16 v[14:17], v[40:43], v[80:83], v[14:17]
	v_mfma_f32_16x16x32_bf16 v[10:13], v[44:47], v[80:83], v[10:13]
	v_mfma_f32_16x16x32_bf16 v[6:9], v[68:71], v[80:83], v[6:9]
	v_mfma_f32_16x16x32_bf16 v[2:5], v[72:75], v[80:83], v[2:5]
	v_add_u32_e32 v40, s3, v66
	s_waitcnt vmcnt(0)
	v_add3_u32 v72, v40, v53, v50
	s_waitcnt lgkmcnt(0)
	s_barrier
	v_add_u32_e32 v67, s3, v49
	ds_read_b128 v[40:43], v72 offset:4096
	ds_read_b128 v[44:47], v72 offset:5120
	ds_read_b128 v[68:71], v72 offset:6144
	ds_read_b128 v[72:75], v72 offset:7168
	v_add3_u32 v67, v67, v50, v66
	ds_read_b128 v[76:79], v67
	ds_read_b128 v[80:83], v67 offset:1024
	s_waitcnt lgkmcnt(0)
	v_mfma_f32_16x16x32_bf16 v[30:33], v[40:43], v[76:79], v[30:33]
	v_mfma_f32_16x16x32_bf16 v[26:29], v[44:47], v[76:79], v[26:29]
	v_mfma_f32_16x16x32_bf16 v[22:25], v[68:71], v[76:79], v[22:25]
	v_mfma_f32_16x16x32_bf16 v[18:21], v[72:75], v[76:79], v[18:21]
	v_mfma_f32_16x16x32_bf16 v[14:17], v[40:43], v[80:83], v[14:17]
	v_mfma_f32_16x16x32_bf16 v[10:13], v[44:47], v[80:83], v[10:13]
	v_mfma_f32_16x16x32_bf16 v[6:9], v[68:71], v[80:83], v[6:9]
	v_mfma_f32_16x16x32_bf16 v[2:5], v[72:75], v[80:83], v[2:5]
	v_add_u32_e32 v44, s2, v51
	s_waitcnt vmcnt(0)
	s_barrier
; template <int EPI, int MF>
; __device__ __forceinline__ void gemm_part(const u16* __restrict__ A, int lda, const u16* __restrict__ Bt, int K, int ntn, GemmEpi ep, char* smem,
;                                           int mbase, int mrows) {
;     ...
;         const float* rp = (row < MP) ? ep.res0 + (size_t)row * DM : ep.res1 + (size_t)(row - MP) * DM;
;         float ssq = 0.f;
; #pragma unroll
;         for (int n = 0; n < 4; ++n) {
;           const int col = cb + n * 16;
;           const float4 r = *(const float4*)(rp + col);
;           float4 v;
;           v.x = r.x + ep.scale * acc[m][n][0]; v.y = r.y + ep.scale * acc[m][n][1];
;           v.z = r.z + ep.scale * acc[m][n][2]; v.w = r.w + ep.scale * acc[m][n][3];
;           *(float4*)(ep.outf + (size_t)row * DM + col) = v;
;           if (ep.xcopy) {
;             bf16x4 o;
;             o[0] = (short)f2bf(v.x); o[1] = (short)f2bf(v.y); o[2] = (short)f2bf(v.z); o[3] = (short)f2bf(v.w);
;             *(bf16x4*)(ep.xcopy + (size_t)row * DM + col) = o;
;           }
;           ssq += v.x * v.x + v.y * v.y + v.z * v.z + v.w * v.w;
;         }
;         if (ep.rss_out) {
;           ssq += __shfl_xor(ssq, 16);
;           ssq += __shfl_xor(ssq, 32);
;           if (fq == 0) atomicAdd(ep.rss_out + row, ssq);
;         }
	s_mov_b32 s2, 0xffff
	v_cmp_lt_i32_e64 s[12:13], s2, v44
	s_and_saveexec_b64 s[2:3], s[12:13]
	s_xor_b64 s[2:3], exec, s[2:3]
	v_add_u32_e32 v40, 0xffff0000, v44
	v_mov_b32_e32 v41, v0
	v_lshlrev_b64 v[40:41], 12, v[40:41]
	v_lshl_add_u64 v[46:47], s[72:73], 0, v[40:41]
	v_mov_b32_e32 v45, v0
	s_andn2_saveexec_b64 s[2:3], s[2:3]
	v_ashrrev_i32_e32 v45, 31, v44
	v_lshlrev_b64 v[40:41], 12, v[44:45]
	v_lshl_add_u64 v[46:47], s[26:27], 0, v[40:41]
	s_or_b64 exec, exec, s[2:3]
	v_or_b32_e32 v40, s5, v52
	v_ashrrev_i32_e32 v41, 31, v40
	v_lshlrev_b64 v[42:43], 2, v[40:41]
	v_lshl_add_u64 v[46:47], v[46:47], 0, v[42:43]
	global_load_dwordx4 v[68:71], v[46:47], off
	v_lshlrev_b64 v[72:73], 12, v[44:45]
	v_lshlrev_b64 v[74:75], 11, v[44:45]
	v_lshl_add_u64 v[72:73], s[26:27], 0, v[72:73]
	v_lshl_add_u64 v[74:75], s[28:29], 0, v[74:75]
	v_lshl_add_u64 v[76:77], v[40:41], 1, v[74:75]
	v_lshl_add_u64 v[78:79], v[72:73], 0, v[42:43]
	s_waitcnt vmcnt(0)
	v_pk_add_f32 v[30:31], v[30:31], v[68:69]
	v_pk_add_f32 v[32:33], v[32:33], v[70:71]
	v_cvt_pk_bf16_f32 v68, v30, v31
	v_cvt_pk_bf16_f32 v69, v32, v33
	global_store_dwordx4 v[78:79], v[30:33], off
	v_lshlrev_b32_e32 v84, 1, v76
	v_bfi_b32 v84, s100, v84, v76
	v_lshrrev_b32_e32 v85, 5, v76
	v_bfi_b32 v84, 64, v85, v84
	v_mov_b32_e32 v85, v77
	global_store_dwordx2 v[84:85], v[68:69], off
	global_load_dwordx4 v[68:71], v[46:47], off offset:64
	s_waitcnt vmcnt(0)
	v_pk_add_f32 v[26:27], v[26:27], v[68:69]
	v_pk_add_f32 v[28:29], v[28:29], v[70:71]
	v_cvt_pk_bf16_f32 v68, v26, v27
	v_cvt_pk_bf16_f32 v69, v28, v29
	global_store_dwordx4 v[78:79], v[26:29], off offset:64
	v_lshlrev_b32_e32 v84, 1, v76
	v_bfi_b32 v84, s100, v84, v76
	v_lshrrev_b32_e32 v85, 5, v76
	v_bfi_b32 v84, 64, v85, v84
	v_mov_b32_e32 v85, v77
	global_store_dwordx2 v[84:85], v[68:69], off offset:32
	global_load_dwordx4 v[68:71], v[46:47], off offset:128
	s_waitcnt vmcnt(0)
	v_pk_add_f32 v[68:69], v[22:23], v[68:69]
	v_pk_add_f32 v[70:71], v[24:25], v[70:71]
	v_cvt_pk_bf16_f32 v22, v68, v69
	v_cvt_pk_bf16_f32 v23, v70, v71
	global_store_dwordx4 v[78:79], v[68:71], off offset:128
	v_lshlrev_b32_e32 v84, 1, v76
	v_bfi_b32 v84, s100, v84, v76
	v_lshrrev_b32_e32 v85, 5, v76
	v_bfi_b32 v84, 64, v85, v84
	v_mov_b32_e32 v85, v77
	global_store_dwordx2 v[84:85], v[22:23], off offset:128
	global_load_dwordx4 v[72:75], v[46:47], off offset:192
	v_pk_mul_f32 v[24:25], v[30:31], v[30:31]
	v_pk_mul_f32 v[30:31], v[32:33], v[32:33]
	v_add_f32_e32 v24, v24, v25
	v_add_f32_e32 v24, v30, v24
	v_add_f32_e32 v30, v31, v24
	v_pk_mul_f32 v[24:25], v[26:27], v[26:27]
	v_pk_mul_f32 v[26:27], v[28:29], v[28:29]
	v_add_f32_e32 v24, v24, v25
	v_add_f32_e32 v24, v26, v24
	v_add_f32_e32 v24, v27, v24
	v_add_f32_e32 v28, v30, v24
	v_pk_mul_f32 v[24:25], v[68:69], v[68:69]
	v_pk_mul_f32 v[26:27], v[70:71], v[70:71]
	v_add_f32_e32 v24, v24, v25
	v_add_f32_e32 v24, v26, v24
	v_add_f32_e32 v24, v27, v24
	v_add_f32_e32 v28, v28, v24
	v_and_b32_e32 v23, 64, v141
	v_xor_b32_e32 v22, 16, v141
	v_add_u32_e32 v23, 64, v23
	v_cmp_lt_i32_e64 s[12:13], v22, v23
	s_waitcnt vmcnt(0)
	v_pk_add_f32 v[24:25], v[18:19], v[72:73]
	v_pk_add_f32 v[26:27], v[20:21], v[74:75]
	v_pk_mul_f32 v[20:21], v[24:25], v[24:25]
	v_pk_mul_f32 v[18:19], v[26:27], v[26:27]
	v_add_f32_e32 v20, v20, v21
	v_add_f32_e32 v18, v18, v20
	v_cndmask_b32_e64 v22, v141, v22, s[12:13]
	v_add_f32_e32 v18, v19, v18
	v_lshlrev_b32_e32 v22, 2, v22
	v_add_f32_e32 v18, v28, v18
	ds_bpermute_b32 v19, v22, v18
	v_xor_b32_e32 v20, 32, v141
	v_cmp_lt_i32_e64 s[12:13], v20, v23
	v_cvt_pk_bf16_f32 v21, v26, v27
	global_store_dwordx4 v[78:79], v[24:27], off offset:192
	v_cndmask_b32_e64 v20, v141, v20, s[12:13]
	s_waitcnt lgkmcnt(0)
	v_add_f32_e32 v18, v18, v19
	v_lshlrev_b32_e32 v23, 2, v20
	ds_bpermute_b32 v19, v23, v18
	v_cvt_pk_bf16_f32 v20, v24, v25
	v_lshlrev_b32_e32 v84, 1, v76
	v_bfi_b32 v84, s100, v84, v76
	v_lshrrev_b32_e32 v85, 5, v76
	v_bfi_b32 v84, 64, v85, v84
	v_mov_b32_e32 v85, v77
	global_store_dwordx2 v[84:85], v[20:21], off offset:160
	s_and_saveexec_b64 s[2:3], vcc
	s_cbranch_execz .LBB0_1189
	v_readlane_b32 s8, v252, 9
	v_readlane_b32 s9, v252, 10
	s_waitcnt lgkmcnt(0)
	v_add_f32_e32 v18, v18, v19
	v_lshl_add_u64 v[20:21], v[44:45], 2, s[8:9]
	global_atomic_add_f32 v[20:21], v18, off
; template <int EPI, int MF>
; __device__ __forceinline__ void gemm_part(const u16* __restrict__ A, int lda, const u16* __restrict__ Bt, int K, int ntn, GemmEpi ep, char* smem,
;                                           int mbase, int mrows) {
;     ...
;         const float* rp = (row < MP) ? ep.res0 + (size_t)row * DM : ep.res1 + (size_t)(row - MP) * DM;
;         float ssq = 0.f;
; #pragma unroll
;         for (int n = 0; n < 4; ++n) {
;           const int col = cb + n * 16;
;           const float4 r = *(const float4*)(rp + col);
;           float4 v;
;           v.x = r.x + ep.scale * acc[m][n][0]; v.y = r.y + ep.scale * acc[m][n][1];
;           v.z = r.z + ep.scale * acc[m][n][2]; v.w = r.w + ep.scale * acc[m][n][3];
;           *(float4*)(ep.outf + (size_t)row * DM + col) = v;
;           if (ep.xcopy) {
;             bf16x4 o;
;             o[0] = (short)f2bf(v.x); o[1] = (short)f2bf(v.y); o[2] = (short)f2bf(v.z); o[3] = (short)f2bf(v.w);
;             *(bf16x4*)(ep.xcopy + (size_t)row * DM + col) = o;
;           }
;           ssq += v.x * v.x + v.y * v.y + v.z * v.z + v.w * v.w;
;         }
;         if (ep.rss_out) {
;           ssq += __shfl_xor(ssq, 16);
;           ssq += __shfl_xor(ssq, 32);
;           if (fq == 0) atomicAdd(ep.rss_out + row, ssq);
;         }
.LBB0_1189:
	s_or_b64 exec, exec, s[2:3]
	s_waitcnt lgkmcnt(0)
	v_or_b32_e32 v18, 16, v44
	s_mov_b32 s2, 0xffff
	v_cmp_lt_i32_e64 s[12:13], s2, v18
	s_and_saveexec_b64 s[2:3], s[12:13]
	s_xor_b64 s[2:3], exec, s[2:3]
	v_add_u32_e32 v20, 0xffff0010, v44
	v_mov_b32_e32 v21, v0
	v_lshlrev_b64 v[20:21], 12, v[20:21]
	v_lshl_add_u64 v[20:21], s[72:73], 0, v[20:21]
	v_mov_b32_e32 v19, v0
	s_andn2_saveexec_b64 s[2:3], s[2:3]
	v_ashrrev_i32_e32 v19, 31, v18
	v_lshlrev_b64 v[20:21], 12, v[18:19]
	v_lshl_add_u64 v[20:21], s[26:27], 0, v[20:21]
	s_or_b64 exec, exec, s[2:3]
	v_lshlrev_b64 v[24:25], 12, v[18:19]
	v_lshl_add_u64 v[24:25], s[26:27], 0, v[24:25]
	v_lshlrev_b64 v[26:27], 11, v[18:19]
	v_lshl_add_u64 v[20:21], v[20:21], 0, v[42:43]
	v_lshl_add_u64 v[28:29], s[28:29], 0, v[26:27]
	v_lshl_add_u64 v[30:31], v[24:25], 0, v[42:43]
	global_load_dwordx4 v[24:27], v[20:21], off
	s_waitcnt vmcnt(0)
	v_pk_add_f32 v[14:15], v[14:15], v[24:25]
	v_pk_add_f32 v[16:17], v[16:17], v[26:27]
	v_cvt_pk_bf16_f32 v24, v14, v15
	v_cvt_pk_bf16_f32 v25, v16, v17
	v_lshl_add_u64 v[26:27], v[40:41], 1, v[28:29]
	global_store_dwordx4 v[30:31], v[14:17], off
	v_lshlrev_b32_e32 v84, 1, v26
	v_bfi_b32 v84, s100, v84, v26
	v_lshrrev_b32_e32 v85, 5, v26
	v_bfi_b32 v84, 64, v85, v84
	v_mov_b32_e32 v85, v27
	global_store_dwordx2 v[84:85], v[24:25], off
	v_pk_mul_f32 v[24:25], v[14:15], v[14:15]
	v_pk_mul_f32 v[28:29], v[16:17], v[16:17]
	global_load_dwordx4 v[14:17], v[20:21], off offset:64
	s_waitcnt vmcnt(0)
	v_pk_add_f32 v[10:11], v[10:11], v[14:15]
	v_pk_add_f32 v[12:13], v[12:13], v[16:17]
	v_cvt_pk_bf16_f32 v14, v10, v11
	v_cvt_pk_bf16_f32 v15, v12, v13
	global_store_dwordx4 v[30:31], v[10:13], off offset:64
	v_lshlrev_b32_e32 v84, 1, v26
	v_bfi_b32 v84, s100, v84, v26
	v_lshrrev_b32_e32 v85, 5, v26
	v_bfi_b32 v84, 64, v85, v84
	v_mov_b32_e32 v85, v27
	global_store_dwordx2 v[84:85], v[14:15], off offset:32
	v_pk_mul_f32 v[14:15], v[10:11], v[10:11]
	v_pk_mul_f32 v[16:17], v[12:13], v[12:13]
	global_load_dwordx4 v[10:13], v[20:21], off offset:128
	s_waitcnt vmcnt(0)
	v_pk_add_f32 v[6:7], v[6:7], v[10:11]
	v_pk_add_f32 v[8:9], v[8:9], v[12:13]
	v_cvt_pk_bf16_f32 v10, v6, v7
	v_cvt_pk_bf16_f32 v11, v8, v9
	global_store_dwordx4 v[30:31], v[6:9], off offset:128
	v_lshlrev_b32_e32 v84, 1, v26
	v_bfi_b32 v84, s100, v84, v26
	v_lshrrev_b32_e32 v85, 5, v26
	v_bfi_b32 v84, 64, v85, v84
	v_mov_b32_e32 v85, v27
	global_store_dwordx2 v[84:85], v[10:11], off offset:128
	v_pk_mul_f32 v[10:11], v[6:7], v[6:7]
	v_pk_mul_f32 v[12:13], v[8:9], v[8:9]
	global_load_dwordx4 v[6:9], v[20:21], off offset:192
	s_waitcnt vmcnt(0)
	v_pk_add_f32 v[2:3], v[2:3], v[6:7]
	v_pk_add_f32 v[4:5], v[4:5], v[8:9]
	v_cvt_pk_bf16_f32 v6, v2, v3
	v_cvt_pk_bf16_f32 v7, v4, v5
	global_store_dwordx4 v[30:31], v[2:5], off offset:192
	v_lshlrev_b32_e32 v84, 1, v26
	v_bfi_b32 v84, s100, v84, v26
	v_lshrrev_b32_e32 v85, 5, v26
	v_bfi_b32 v84, 64, v85, v84
	v_mov_b32_e32 v85, v27
	global_store_dwordx2 v[84:85], v[6:7], off offset:160
	v_add_f32_e32 v6, v24, v25
	v_add_f32_e32 v7, v14, v15
	v_add_f32_e32 v6, v28, v6
	v_add_f32_e32 v7, v16, v7
	v_add_f32_e32 v6, v29, v6
	v_add_f32_e32 v7, v17, v7
	v_pk_mul_f32 v[2:3], v[2:3], v[2:3]
	v_add_f32_e32 v6, v6, v7
	v_add_f32_e32 v7, v10, v11
	v_pk_mul_f32 v[4:5], v[4:5], v[4:5]
	v_add_f32_e32 v7, v12, v7
	v_add_f32_e32 v2, v2, v3
	v_add_f32_e32 v7, v13, v7
	v_add_f32_e32 v2, v4, v2
	v_add_f32_e32 v6, v6, v7
	v_add_f32_e32 v2, v5, v2
	v_add_f32_e32 v2, v6, v2
	ds_bpermute_b32 v3, v22, v2
	s_waitcnt lgkmcnt(0)
	v_add_f32_e32 v2, v2, v3
	ds_bpermute_b32 v3, v23, v2
	s_and_saveexec_b64 s[2:3], vcc
	s_cbranch_execz .LBB0_1178
	v_readlane_b32 s8, v252, 9
	v_readlane_b32 s9, v252, 10
	s_waitcnt lgkmcnt(0)
	v_add_f32_e32 v2, v2, v3
	v_lshl_add_u64 v[4:5], v[18:19], 2, s[8:9]
	global_atomic_add_f32 v[4:5], v2, off
	s_branch .LBB0_1178

; __device__ __forceinline__ int opaque_tid() { int t = threadIdx.x; asm volatile("" : "+v"(t)); return t; }
; template <int EPI, int MF>
; __device__ __forceinline__ void gemm_part(const u16* __restrict__ A, int lda, const u16* __restrict__ Bt, int K, int ntn, GemmEpi ep, char* smem,
;                                           int mbase, int mrows) {
;   const int tid = opaque_tid(), lane = tid & 63, wid = tid >> 6, wr = wid >> 1, wc = wid & 1, fr = lane & 15, fq = lane >> 4;
;   constexpr int BM = 32 * MF;
;   constexpr int STG = BM * 32 + 4096;
;   constexpr int NA = MF / 2;
;   u16* const sbase = (u16*)smem;
;   const int ntm = mrows / BM;
;   const int total = ntm * ntn;
;   const int nk = K / 32;
;   const int nbx = (MF == 2) ? (int)gridDim.x : (int)(gridDim.x >> 3);
;   const int xcd = (MF == 2) ? 0 : (int)(blockIdx.x & 7), li = (MF == 2) ? (int)blockIdx.x : (int)(blockIdx.x >> 3);
;   for (int q = xcd; q * nbx < total; q += (MF == 2) ? 1 : 8) {
;     const int L = q * nbx + li;
;     if (L >= total) continue;
;     const int g = L / (8 * ntn), rr = L % (8 * ntn);
;     const int rows = min(8, ntm - 8 * g);
;     const int tm = 8 * g + rr % rows, tn = rr / rows;
;     const int row0 = mbase + tm * BM, col0 = tn * 128;
;     f32x4 acc[MF][4];
; #pragma unroll
;     for (int m = 0; m < MF; ++m)
; #pragma unroll
;       for (int n = 0; n < 4; ++n) acc[m][n] = (f32x4){0.f, 0.f, 0.f, 0.f};
;     const u16* gA = A + (size_t)(row0 + (tid >> 2)) * lda + (tid & 3) * 8;
;     const u16* gB = Bt + (size_t)(col0 + (tid >> 2)) * K + (tid & 3) * 8;
;     ...
;           *(bf16x4*)(ep.outb + (size_t)row * FF + (col0 >> 1) + wc * 32 + n * 16 + 4 * fq) = o;
.LBB0_1942:
	s_or_b64 exec, exec, s[2:3]
	v_readlane_b32 s2, v252, 3
	v_readlane_b32 s3, v252, 4
	s_barrier
	s_load_dwordx2 s[10:11], s[2:3], 0xe8
	v_readlane_b32 s2, v252, 5
	v_readlane_b32 s3, v252, 6
	v_mov_b32_e32 v2, v140
	s_and_b64 vcc, exec, s[2:3]
	s_cbranch_vccnz .LBB0_1949
	v_lshlrev_b32_e32 v7, 4, v2
	v_and_b32_e32 v4, 48, v7
	v_mov_b32_e32 v5, v0
	v_bfe_u32 v6, v2, 6, 1
	v_lshl_add_u64 v[130:131], s[28:29], 0, v[4:5]
	s_waitcnt lgkmcnt(0)
	v_lshl_add_u64 v[132:133], s[10:11], 0, v[4:5]
	v_lshlrev_b32_e32 v4, 5, v2
	v_bfe_u32 v3, v2, 4, 2
	v_and_b32_e32 v151, 0xfffff1e0, v4
	v_lshlrev_b32_e32 v4, 6, v6
	v_lshlrev_b32_e32 v134, 3, v3
	v_lshl_add_u64 v[4:5], s[46:47], 0, v[4:5]
	v_mov_b32_e32 v135, v0
	v_ashrrev_i32_e32 v1, 2, v2
	v_and_b32_e32 v152, 0xffffff8f, v2
	v_lshl_add_u64 v[136:137], v[4:5], 0, v[134:135]
	v_and_b32_e32 v8, 1, v140
	v_mul_u32_u24_e32 v8, 0x15c0, v8
	v_bfe_u32 v9, v140, 6, 1
	v_lshlrev_b32_e32 v9, 6, v9
	v_sub_u32_e32 v8, v9, v8
	v_ashrrev_i32_e32 v9, 31, v8
	v_lshl_add_u64 v[136:137], v[136:137], 0, v[8:9]
	v_lshlrev_b32_e32 v135, 12, v6
	v_lshlrev_b32_e32 v4, 6, v2
	v_lshl_add_u32 v3, v3, 4, 0
	v_and_b32_e32 v2, 3, v2
	v_readlane_b32 s2, v253, 0
	v_and_b32_e32 v153, 0x3c0, v4
	v_lshl_add_u32 v154, v151, 1, v3
	v_add_u32_e32 v4, v3, v135
	v_lshlrev_b32_e32 v2, 4, v2
	v_mov_b32_e32 v3, v0
	v_readlane_b32 s3, v253, 1
	v_add_u32_e32 v150, 0, v7
	v_add_u32_e32 v155, v4, v153
	v_lshl_add_u64 v[138:139], s[2:3], 0, v[2:3]
	v_readlane_b32 s2, v253, 56
	v_readlane_b32 s4, v253, 9
	s_branch .LBB0_1945

; template <int EPI, int MF>
; __device__ __forceinline__ void gemm_part(const u16* __restrict__ A, int lda, const u16* __restrict__ Bt, int K, int ntn, GemmEpi ep, char* smem,
;                                           int mbase, int mrows) {
;     ...
;   for (int q = xcd; q * nbx < total; q += (MF == 2) ? 1 : 8) {
;     const int L = q * nbx + li;
;     if (L >= total) continue;
;     const int g = L / (8 * ntn), rr = L % (8 * ntn);
;     const int rows = min(8, ntm - 8 * g);
;     const int tm = 8 * g + rr % rows, tn = rr / rows;
;     const int row0 = mbase + tm * BM, col0 = tn * 128;
;     f32x4 acc[MF][4];
; #pragma unroll
;     for (int m = 0; m < MF; ++m)
; #pragma unroll
;       for (int n = 0; n < 4; ++n) acc[m][n] = (f32x4){0.f, 0.f, 0.f, 0.f};
;     const u16* gA = A + (size_t)(row0 + (tid >> 2)) * lda + (tid & 3) * 8;
;     const u16* gB = Bt + (size_t)(col0 + (tid >> 2)) * K + (tid & 3) * 8;
;     ...
;     GEMM_ISSUE(0);
;     GEMM_ISSUE(1);
.LBB0_1945:
	s_add_i32 s2, s2, s63
	s_cmpk_gt_u32 s2, 0x2bff
	s_cbranch_scc1 .LBB0_1944
	s_and_b32 s3, s2, 0xffff
	s_mul_i32 s3, s3, 0xba2f
	s_lshr_b32 s3, s3, 24
	s_mul_i32 s5, s3, 0x160
	s_sub_i32 s2, s2, s5
	s_lshl_b32 s3, s3, 3
	s_and_b32 s5, s2, 7
	s_or_b32 s3, s3, s5
	s_and_b32 s3, s3, 0x7ff
	s_lshl_b32 s8, s3, 8
	v_add_u32_e32 v2, s8, v1
	v_ashrrev_i32_e32 v3, 31, v2
	s_bfe_u32 s5, s2, 0xd0003
	v_lshlrev_b64 v[2:3], 11, v[2:3]
	v_readfirstlane_b32 s2, v150
	v_add_u32_e32 v10, 0x1000, v150
	v_lshl_add_u64 v[4:5], v[130:131], 0, v[2:3]
	v_lshlrev_b32_e32 v255, 1, v4
	v_bfi_b32 v255, s100, v255, v4
	v_lshrrev_b32_e32 v4, 5, v4
	v_bfi_b32 v4, 64, v4, v255
	s_mov_b32 m0, s2
	s_mov_b64 s[12:13], 0x20000
	v_readfirstlane_b32 s2, v10
	global_load_lds_dwordx4 v[4:5], off
	v_lshl_add_u64 v[8:9], v[4:5], 0, s[12:13]
	s_mov_b32 m0, s2
	s_mov_b64 s[2:3], 0x40000
	v_add_u32_e32 v10, 0x2000, v150
	v_lshl_add_u32 v6, s5, 7, v1
	global_load_lds_dwordx4 v[8:9], off
	v_lshl_add_u64 v[8:9], v[4:5], 0, s[2:3]
	v_readfirstlane_b32 s2, v10
	v_ashrrev_i32_e32 v7, 31, v6
	s_mov_b32 m0, s2
	s_mov_b64 s[2:3], 0x60000
	v_add_u32_e32 v10, 0x3000, v150
	v_lshlrev_b64 v[6:7], 11, v[6:7]
	global_load_lds_dwordx4 v[8:9], off
	v_lshl_add_u64 v[8:9], v[4:5], 0, s[2:3]
	v_readfirstlane_b32 s2, v10
	s_mov_b32 m0, s2
	v_lshl_add_u64 v[146:147], v[132:133], 0, v[6:7]
	v_lshlrev_b32_e32 v255, 1, v146
	v_bfi_b32 v255, s100, v255, v146
	v_lshrrev_b32_e32 v146, 5, v146
	v_bfi_b32 v146, 64, v146, v255
	v_add_u32_e32 v6, 0x4000, v150
	global_load_lds_dwordx4 v[8:9], off
	v_readfirstlane_b32 s2, v6
	v_add_u32_e32 v8, 0x5000, v150
	s_mov_b32 m0, s2
	v_readfirstlane_b32 s2, v8
	v_add_u32_e32 v8, 0x6000, v150
	global_load_lds_dwordx4 v[146:147], off
	v_lshl_add_u64 v[6:7], v[146:147], 0, s[12:13]
	s_mov_b32 m0, s2
	v_readfirstlane_b32 s2, v8
	v_add_u32_e32 v8, 0x7000, v150
	global_load_lds_dwordx4 v[6:7], off
	v_lshl_add_u64 v[6:7], v[4:5], 0, 64
	v_lshl_add_u64 v[6:7], v[6:7], 0, 64
	s_mov_b32 m0, s2
	s_mov_b64 s[12:13], 0x20040
	v_readfirstlane_b32 s2, v8
	global_load_lds_dwordx4 v[6:7], off
	v_lshl_add_u64 v[6:7], v[4:5], 0, s[12:13]
	v_lshl_add_u64 v[6:7], v[6:7], 0, 64
	s_mov_b32 m0, s2
	s_mov_b64 s[2:3], 0x40040
	v_add_u32_e32 v8, 0x8000, v150
	global_load_lds_dwordx4 v[6:7], off
	v_lshl_add_u64 v[6:7], v[4:5], 0, s[2:3]
	v_lshl_add_u64 v[6:7], v[6:7], 0, 64
	v_readfirstlane_b32 s2, v8
	s_mov_b32 m0, s2
	s_mov_b64 s[2:3], 0x60040
	global_load_lds_dwordx4 v[6:7], off
	v_add_u32_e32 v6, 0x9000, v150
	v_lshl_add_u64 v[4:5], v[4:5], 0, s[2:3]
	v_lshl_add_u64 v[4:5], v[4:5], 0, 64
	v_readfirstlane_b32 s2, v6
	v_add_u32_e32 v6, 0xa000, v150
	s_mov_b32 m0, s2
	v_readfirstlane_b32 s2, v6
	v_add_u32_e32 v6, 0xb000, v150
	global_load_lds_dwordx4 v[4:5], off
	v_lshl_add_u64 v[4:5], v[146:147], 0, 64
	v_lshl_add_u64 v[4:5], v[4:5], 0, 64
	s_mov_b32 m0, s2
	v_readfirstlane_b32 s2, v6
	global_load_lds_dwordx4 v[4:5], off
	v_lshl_add_u64 v[4:5], v[146:147], 0, s[12:13]
	v_lshl_add_u64 v[4:5], v[4:5], 0, 64
	s_mov_b32 m0, s2
	v_lshl_add_u64 v[148:149], v[138:139], 0, v[2:3]
	v_lshlrev_b32_e32 v255, 1, v148
	v_bfi_b32 v255, s100, v255, v148
	v_lshrrev_b32_e32 v148, 5, v148
	v_bfi_b32 v148, 64, v148, v255
	v_lshl_add_u64 v[148:149], v[148:149], 0, 64
	v_lshl_add_u64 v[148:149], v[148:149], 0, 64
	global_load_lds_dwordx4 v[4:5], off
	v_lshl_add_u64 v[146:147], v[146:147], 0, 64
	v_lshl_add_u64 v[146:147], v[146:147], 0, 64
	v_mov_b32_e32 v2, 0
	s_mov_b64 s[2:3], 0
	s_mov_b32 s9, 2
	v_mov_b32_e32 v3, v2
	v_mov_b32_e32 v4, v2
	v_mov_b32_e32 v5, v2
	v_mov_b32_e32 v6, v2
	v_mov_b32_e32 v7, v2
	v_mov_b32_e32 v8, v2
	v_mov_b32_e32 v9, v2
	v_mov_b32_e32 v10, v2
	v_mov_b32_e32 v11, v2
	v_mov_b32_e32 v12, v2
	v_mov_b32_e32 v13, v2
	v_mov_b32_e32 v14, v2
	v_mov_b32_e32 v15, v2
	v_mov_b32_e32 v16, v2
	v_mov_b32_e32 v17, v2
	v_mov_b32_e32 v18, v2
	v_mov_b32_e32 v19, v2
	v_mov_b32_e32 v20, v2
	v_mov_b32_e32 v21, v2
	v_mov_b32_e32 v22, v2
	v_mov_b32_e32 v23, v2
	v_mov_b32_e32 v24, v2
	v_mov_b32_e32 v25, v2
	v_mov_b32_e32 v26, v2
	v_mov_b32_e32 v27, v2
	v_mov_b32_e32 v28, v2
	v_mov_b32_e32 v29, v2
	v_mov_b32_e32 v30, v2
	v_mov_b32_e32 v31, v2
	v_mov_b32_e32 v32, v2
	v_mov_b32_e32 v33, v2
	v_mov_b32_e32 v34, v2
	v_mov_b32_e32 v35, v2
	v_mov_b32_e32 v36, v2
	v_mov_b32_e32 v37, v2
	v_mov_b32_e32 v38, v2
	v_mov_b32_e32 v39, v2
	v_mov_b32_e32 v40, v2
	v_mov_b32_e32 v41, v2
	v_mov_b32_e32 v42, v2
	v_mov_b32_e32 v43, v2
	v_mov_b32_e32 v44, v2
	v_mov_b32_e32 v45, v2
	v_mov_b32_e32 v46, v2
	v_mov_b32_e32 v47, v2
	v_mov_b32_e32 v48, v2
	v_mov_b32_e32 v49, v2
	v_mov_b32_e32 v50, v2
	v_mov_b32_e32 v51, v2
	v_mov_b32_e32 v52, v2
	v_mov_b32_e32 v53, v2
	v_mov_b32_e32 v54, v2
	v_mov_b32_e32 v55, v2
	v_mov_b32_e32 v56, v2
	v_mov_b32_e32 v57, v2
	v_mov_b32_e32 v58, v2
	v_mov_b32_e32 v59, v2
	v_mov_b32_e32 v60, v2
	v_mov_b32_e32 v61, v2
	v_mov_b32_e32 v62, v2
	v_mov_b32_e32 v63, v2
	v_mov_b32_e32 v64, v2
	v_mov_b32_e32 v65, v2
	v_mov_b32_e32 v66, v2
	v_mov_b32_e32 v67, v2
	v_mov_b32_e32 v68, v2
	v_mov_b32_e32 v69, v2
	v_mov_b32_e32 v70, v2
	v_mov_b32_e32 v71, v2
	v_mov_b32_e32 v72, v2
	v_mov_b32_e32 v73, v2
	v_mov_b32_e32 v74, v2
	v_mov_b32_e32 v75, v2
	v_mov_b32_e32 v76, v2
	v_mov_b32_e32 v77, v2
	v_mov_b32_e32 v78, v2
	v_mov_b32_e32 v79, v2
	v_mov_b32_e32 v80, v2
	v_mov_b32_e32 v81, v2
	v_mov_b32_e32 v82, v2
	v_mov_b32_e32 v83, v2
	v_mov_b32_e32 v84, v2
	v_mov_b32_e32 v85, v2
	v_mov_b32_e32 v86, v2
	v_mov_b32_e32 v87, v2
	s_waitcnt vmcnt(0)
	v_mov_b32_e32 v88, v2
	v_mov_b32_e32 v89, v2
	v_mov_b32_e32 v90, v2
	v_mov_b32_e32 v91, v2
	v_mov_b32_e32 v92, v2
	v_mov_b32_e32 v93, v2
	v_mov_b32_e32 v94, v2
	v_mov_b32_e32 v95, v2
	v_mov_b32_e32 v96, v2
	v_mov_b32_e32 v97, v2
	v_mov_b32_e32 v98, v2
	v_mov_b32_e32 v99, v2
	v_mov_b32_e32 v100, v2
	v_mov_b32_e32 v101, v2
	v_mov_b32_e32 v102, v2
	v_mov_b32_e32 v103, v2
	v_mov_b32_e32 v104, v2
	v_mov_b32_e32 v105, v2
	v_mov_b32_e32 v106, v2
	v_mov_b32_e32 v107, v2
	v_mov_b32_e32 v108, v2
	v_mov_b32_e32 v109, v2
	v_mov_b32_e32 v110, v2
	v_mov_b32_e32 v111, v2
	v_mov_b32_e32 v112, v2
	v_mov_b32_e32 v113, v2
	v_mov_b32_e32 v114, v2
	v_mov_b32_e32 v115, v2
	v_mov_b32_e32 v116, v2
	v_mov_b32_e32 v117, v2
	v_mov_b32_e32 v118, v2
	v_mov_b32_e32 v119, v2
	v_mov_b32_e32 v120, v2
	v_mov_b32_e32 v121, v2
	v_mov_b32_e32 v122, v2
	v_mov_b32_e32 v123, v2
	v_mov_b32_e32 v124, v2
	v_mov_b32_e32 v125, v2
	v_mov_b32_e32 v126, v2
	v_mov_b32_e32 v127, v2
	v_mov_b32_e32 v128, v2
	v_mov_b32_e32 v129, v2
; #define MFMA(a, b, c) __builtin_amdgcn_mfma_f32_16x16x32_bf16((a), (b), (c), 0, 0, 0)
; template <int EPI, int MF>
; __device__ __forceinline__ void gemm_part(const u16* __restrict__ A, int lda, const u16* __restrict__ Bt, int K, int ntn, GemmEpi ep, char* smem,
;                                           int mbase, int mrows) {
;     ...
;     for (int kt = 0; kt < nk; ++kt) {
;       if (kt + 1 < nk) {
;         if (MF == 8) asm volatile("s_waitcnt vmcnt(6)" ::: "memory");
;         else asm volatile("s_waitcnt vmcnt(3)" ::: "memory");
;       } else asm volatile("s_waitcnt vmcnt(0)" ::: "memory");
;       asm volatile("s_waitcnt lgkmcnt(0)" ::: "memory");
;       __builtin_amdgcn_s_barrier();
;       const u16* a_ = sbase + (kt % 3) * STG;
;       const u16* b_ = a_ + BM * 32;
;       bf16x8 bfr[4], afc[2], afn[2];
;       const u16* ap_ = a_ + (wr * (16 * MF) + fr) * 32 + fq * 8;
; #pragma unroll
;       for (int n = 0; n < 4; ++n) bfr[n] = rd_std(b_ + (wc * 64 + n * 16 + fr) * 32 + fq * 8);
;       afc[0] = rd_std(ap_); afc[1] = rd_std(ap_ + 16 * 32);
;       __builtin_amdgcn_sched_barrier(0);
;       if (kt + 2 < nk) GEMM_ISSUE(kt + 2);
;       __builtin_amdgcn_sched_barrier(0);
; #pragma unroll
;       for (int mh = 0; mh < MF / 2; ++mh) {
;         if (mh + 1 < MF / 2) {
;           afn[0] = rd_std(ap_ + ((mh + 1) * 2) * 16 * 32);
;           afn[1] = rd_std(ap_ + ((mh + 1) * 2 + 1) * 16 * 32);
;         }
;         __builtin_amdgcn_sched_barrier(0);
; #pragma unroll
;         for (int m = 0; m < 2; ++m)
; #pragma unroll
;           for (int n = 0; n < 4; ++n) acc[mh * 2 + m][n] = MFMA(bfr[n], afc[m], acc[mh * 2 + m][n]);
;         __builtin_amdgcn_sched_barrier(0);
;         afc[0] = afn[0]; afc[1] = afn[1];
;       }
;     }
.LBB0_1947:
	s_mul_i32 s12, s9, 0xab
	s_add_i32 s13, s12, 0xfeaa
	s_bfe_u32 s13, s13, 0x70009
	s_mul_i32 s13, s13, 3
	s_sub_i32 s13, s9, s13
	s_add_i32 s13, s13, 0xfffe
	s_and_b32 s13, s13, 0xff
	s_mulk_i32 s13, 0x6000
	s_add_i32 s13, s13, 0
	v_lshl_add_u32 v172, v134, 1, s13
	s_waitcnt vmcnt(6)
	v_add3_u32 v168, v172, v135, v153
	s_waitcnt lgkmcnt(0)
	s_barrier
	ds_read_b128 v[156:159], v168 offset:16384
	ds_read_b128 v[160:163], v168 offset:17408
	ds_read_b128 v[164:167], v168 offset:18432
	ds_read_b128 v[168:171], v168 offset:19456
	v_lshl_add_u32 v188, v151, 1, v172
	ds_read_b128 v[172:175], v188
	ds_read_b128 v[176:179], v188 offset:1024
	s_bfe_u32 s12, s12, 0x70009
	s_mul_i32 s12, s12, 3
	s_sub_i32 s12, s9, s12
	s_and_b32 s12, s12, 0xff
	s_mulk_i32 s12, 0x6000
	v_add_u32_e32 v184, s12, v150
	v_lshl_add_u64 v[180:181], s[2:3], 1, v[148:149]
	v_readfirstlane_b32 s12, v184
	v_lshl_add_u64 v[182:183], v[180:181], 0, s[30:31]
	s_mov_b32 m0, s12
	s_mov_b64 s[12:13], 0x162e0080
	v_add_u32_e32 v185, 0x1000, v184
	global_load_lds_dwordx4 v[182:183], off
	v_lshl_add_u64 v[182:183], v[180:181], 0, s[12:13]
	v_readfirstlane_b32 s12, v185
	s_mov_b32 m0, s12
	s_mov_b64 s[12:13], 0x16300080
	v_add_u32_e32 v185, 0x2000, v184
	global_load_lds_dwordx4 v[182:183], off
	v_lshl_add_u64 v[182:183], v[180:181], 0, s[12:13]
	v_readfirstlane_b32 s12, v185
	s_mov_b32 m0, s12
	s_mov_b64 s[12:13], 0x16320080
	global_load_lds_dwordx4 v[182:183], off
	v_add_u32_e32 v182, 0x3000, v184
	v_lshl_add_u64 v[180:181], v[180:181], 0, s[12:13]
	v_readfirstlane_b32 s12, v182
	s_mov_b32 m0, s12
	v_add_u32_e32 v185, 0x4000, v184
	global_load_lds_dwordx4 v[180:181], off
	v_lshl_add_u64 v[180:181], s[2:3], 1, v[146:147]
	v_readfirstlane_b32 s12, v185
	v_lshl_add_u64 v[182:183], v[180:181], 0, s[74:75]
	s_mov_b32 m0, s12
	v_lshl_add_u64 v[180:181], v[180:181], 0, s[92:93]
	global_load_lds_dwordx4 v[182:183], off
	v_add_u32_e32 v182, 0x5000, v184
	s_nop 0
	v_readfirstlane_b32 s12, v182
	s_mov_b32 m0, s12
	s_nop 0
	global_load_lds_dwordx4 v[180:181], off
	ds_read_b128 v[180:183], v188 offset:2048
	ds_read_b128 v[184:187], v188 offset:3072
	s_waitcnt lgkmcnt(0)
	v_mfma_f32_16x16x32_bf16 v[126:129], v[156:159], v[172:175], v[126:129]
	v_mfma_f32_16x16x32_bf16 v[122:125], v[160:163], v[172:175], v[122:125]
	v_mfma_f32_16x16x32_bf16 v[118:121], v[164:167], v[172:175], v[118:121]
	v_mfma_f32_16x16x32_bf16 v[114:117], v[168:171], v[172:175], v[114:117]
	v_mfma_f32_16x16x32_bf16 v[110:113], v[156:159], v[176:179], v[110:113]
	v_mfma_f32_16x16x32_bf16 v[106:109], v[160:163], v[176:179], v[106:109]
	v_mfma_f32_16x16x32_bf16 v[102:105], v[164:167], v[176:179], v[102:105]
	v_mfma_f32_16x16x32_bf16 v[98:101], v[168:171], v[176:179], v[98:101]
	ds_read_b128 v[172:175], v188 offset:4096
	ds_read_b128 v[176:179], v188 offset:5120
	v_mfma_f32_16x16x32_bf16 v[94:97], v[156:159], v[180:183], v[94:97]
	v_mfma_f32_16x16x32_bf16 v[90:93], v[160:163], v[180:183], v[90:93]
	v_mfma_f32_16x16x32_bf16 v[86:89], v[164:167], v[180:183], v[86:89]
	v_mfma_f32_16x16x32_bf16 v[82:85], v[168:171], v[180:183], v[82:85]
	v_mfma_f32_16x16x32_bf16 v[78:81], v[156:159], v[184:187], v[78:81]
	v_mfma_f32_16x16x32_bf16 v[74:77], v[160:163], v[184:187], v[74:77]
	v_mfma_f32_16x16x32_bf16 v[70:73], v[164:167], v[184:187], v[70:73]
	v_mfma_f32_16x16x32_bf16 v[66:69], v[168:171], v[184:187], v[66:69]
	ds_read_b128 v[180:183], v188 offset:6144
	ds_read_b128 v[184:187], v188 offset:7168
	s_waitcnt lgkmcnt(0)
	v_mfma_f32_16x16x32_bf16 v[62:65], v[156:159], v[172:175], v[62:65]
	v_mfma_f32_16x16x32_bf16 v[58:61], v[160:163], v[172:175], v[58:61]
	v_mfma_f32_16x16x32_bf16 v[54:57], v[164:167], v[172:175], v[54:57]
	v_mfma_f32_16x16x32_bf16 v[50:53], v[168:171], v[172:175], v[50:53]
	v_mfma_f32_16x16x32_bf16 v[46:49], v[156:159], v[176:179], v[46:49]
	v_mfma_f32_16x16x32_bf16 v[42:45], v[160:163], v[176:179], v[42:45]
	v_mfma_f32_16x16x32_bf16 v[38:41], v[164:167], v[176:179], v[38:41]
	v_mfma_f32_16x16x32_bf16 v[34:37], v[168:171], v[176:179], v[34:37]
	v_mfma_f32_16x16x32_bf16 v[30:33], v[156:159], v[180:183], v[30:33]
	v_mfma_f32_16x16x32_bf16 v[26:29], v[160:163], v[180:183], v[26:29]
	v_mfma_f32_16x16x32_bf16 v[22:25], v[164:167], v[180:183], v[22:25]
	v_mfma_f32_16x16x32_bf16 v[18:21], v[168:171], v[180:183], v[18:21]
	v_mfma_f32_16x16x32_bf16 v[14:17], v[156:159], v[184:187], v[14:17]
	v_mfma_f32_16x16x32_bf16 v[10:13], v[160:163], v[184:187], v[10:13]
	v_mfma_f32_16x16x32_bf16 v[6:9], v[164:167], v[184:187], v[6:9]
	v_mfma_f32_16x16x32_bf16 v[2:5], v[168:171], v[184:187], v[2:5]
	s_add_u32 s2, s2, 64
	s_addc_u32 s3, s3, 0
	s_add_i32 s9, s9, 1
	s_cmpk_eq_i32 s2, 0x780
	s_cbranch_scc0 .LBB0_1947
	s_waitcnt vmcnt(6)
	s_waitcnt lgkmcnt(0)
	s_barrier
; #define MFMA(a, b, c) __builtin_amdgcn_mfma_f32_16x16x32_bf16((a), (b), (c), 0, 0, 0)
; template <int EPI, int MF>
; __device__ __forceinline__ void gemm_part(const u16* __restrict__ A, int lda, const u16* __restrict__ Bt, int K, int ntn, GemmEpi ep, char* smem,
;                                           int mbase, int mrows) {
;     ...
;     for (int kt = 0; kt < nk; ++kt) {
;       if (kt + 1 < nk) {
;         if (MF == 8) asm volatile("s_waitcnt vmcnt(6)" ::: "memory");
;         else asm volatile("s_waitcnt vmcnt(3)" ::: "memory");
;       } else asm volatile("s_waitcnt vmcnt(0)" ::: "memory");
;       asm volatile("s_waitcnt lgkmcnt(0)" ::: "memory");
;       __builtin_amdgcn_s_barrier();
;       const u16* a_ = sbase + (kt % 3) * STG;
;       const u16* b_ = a_ + BM * 32;
;       bf16x8 bfr[4], afc[2], afn[2];
;       const u16* ap_ = a_ + (wr * (16 * MF) + fr) * 32 + fq * 8;
; #pragma unroll
;       for (int n = 0; n < 4; ++n) bfr[n] = rd_std(b_ + (wc * 64 + n * 16 + fr) * 32 + fq * 8);
;       afc[0] = rd_std(ap_); afc[1] = rd_std(ap_ + 16 * 32);
;       __builtin_amdgcn_sched_barrier(0);
;       if (kt + 2 < nk) GEMM_ISSUE(kt + 2);
;       __builtin_amdgcn_sched_barrier(0);
; #pragma unroll
;       for (int mh = 0; mh < MF / 2; ++mh) {
;         if (mh + 1 < MF / 2) {
;           afn[0] = rd_std(ap_ + ((mh + 1) * 2) * 16 * 32);
;           afn[1] = rd_std(ap_ + ((mh + 1) * 2 + 1) * 16 * 32);
;         }
;         __builtin_amdgcn_sched_barrier(0);
; #pragma unroll
;         for (int m = 0; m < 2; ++m)
; #pragma unroll
;           for (int n = 0; n < 4; ++n) acc[mh * 2 + m][n] = MFMA(bfr[n], afc[m], acc[mh * 2 + m][n]);
;         __builtin_amdgcn_sched_barrier(0);
;         afc[0] = afn[0]; afc[1] = afn[1];
;       }
;     }
;     ...
;     __syncthreads();
;     ...
;           *(bf16x4*)(ep.outb + (size_t)row * FF + (col0 >> 1) + wc * 32 + n * 16 + 4 * fq) = o;
	ds_read_b128 v[146:149], v155 offset:16384
	ds_read_b128 v[156:159], v155 offset:17408
	ds_read_b128 v[160:163], v155 offset:18432
	ds_read_b128 v[164:167], v155 offset:19456
	ds_read_b128 v[168:171], v154
	ds_read_b128 v[172:175], v154 offset:1024
	ds_read_b128 v[176:179], v154 offset:2048
	ds_read_b128 v[180:183], v154 offset:3072
	s_waitcnt lgkmcnt(0)
	v_mfma_f32_16x16x32_bf16 v[126:129], v[146:149], v[168:171], v[126:129]
	v_mfma_f32_16x16x32_bf16 v[122:125], v[156:159], v[168:171], v[122:125]
	v_mfma_f32_16x16x32_bf16 v[184:187], v[160:163], v[168:171], v[118:121]
	v_mfma_f32_16x16x32_bf16 v[114:117], v[164:167], v[168:171], v[114:117]
	v_mfma_f32_16x16x32_bf16 v[110:113], v[146:149], v[172:175], v[110:113]
	v_mfma_f32_16x16x32_bf16 v[106:109], v[156:159], v[172:175], v[106:109]
	v_mfma_f32_16x16x32_bf16 v[168:171], v[160:163], v[172:175], v[102:105]
	v_mfma_f32_16x16x32_bf16 v[98:101], v[164:167], v[172:175], v[98:101]
	s_nop 1
	ds_read_b128 v[102:105], v154 offset:4096
	ds_read_b128 v[118:121], v154 offset:5120
	v_mfma_f32_16x16x32_bf16 v[94:97], v[146:149], v[176:179], v[94:97]
	v_mfma_f32_16x16x32_bf16 v[90:93], v[156:159], v[176:179], v[90:93]
	v_mfma_f32_16x16x32_bf16 v[172:175], v[160:163], v[176:179], v[86:89]
	v_mfma_f32_16x16x32_bf16 v[82:85], v[164:167], v[176:179], v[82:85]
	v_mfma_f32_16x16x32_bf16 v[78:81], v[146:149], v[180:183], v[78:81]
	v_mfma_f32_16x16x32_bf16 v[74:77], v[156:159], v[180:183], v[74:77]
	v_mfma_f32_16x16x32_bf16 v[176:179], v[160:163], v[180:183], v[70:73]
	v_mfma_f32_16x16x32_bf16 v[66:69], v[164:167], v[180:183], v[66:69]
	s_nop 1
	ds_read_b128 v[70:73], v154 offset:6144
	ds_read_b128 v[86:89], v154 offset:7168
	s_waitcnt lgkmcnt(0)
	v_mfma_f32_16x16x32_bf16 v[62:65], v[146:149], v[102:105], v[62:65]
	v_mfma_f32_16x16x32_bf16 v[58:61], v[156:159], v[102:105], v[58:61]
	v_mfma_f32_16x16x32_bf16 v[180:183], v[160:163], v[102:105], v[54:57]
	v_mfma_f32_16x16x32_bf16 v[50:53], v[164:167], v[102:105], v[50:53]
	v_mfma_f32_16x16x32_bf16 v[46:49], v[146:149], v[118:121], v[46:49]
	v_mfma_f32_16x16x32_bf16 v[42:45], v[156:159], v[118:121], v[42:45]
	v_mfma_f32_16x16x32_bf16 v[188:191], v[160:163], v[118:121], v[38:41]
	v_mfma_f32_16x16x32_bf16 v[34:37], v[164:167], v[118:121], v[34:37]
	v_mfma_f32_16x16x32_bf16 v[30:33], v[146:149], v[70:73], v[30:33]
	v_mfma_f32_16x16x32_bf16 v[26:29], v[156:159], v[70:73], v[26:29]
	v_mfma_f32_16x16x32_bf16 v[192:195], v[160:163], v[70:73], v[22:25]
	v_mfma_f32_16x16x32_bf16 v[18:21], v[164:167], v[70:73], v[18:21]
	v_mfma_f32_16x16x32_bf16 v[14:17], v[146:149], v[86:89], v[14:17]
	v_mfma_f32_16x16x32_bf16 v[10:13], v[156:159], v[86:89], v[10:13]
	v_mfma_f32_16x16x32_bf16 v[146:149], v[160:163], v[86:89], v[6:9]
	v_mfma_f32_16x16x32_bf16 v[2:5], v[164:167], v[86:89], v[2:5]
	s_waitcnt vmcnt(0)
	s_waitcnt lgkmcnt(0)
	s_barrier
	s_nop 0
	ds_read_b128 v[6:9], v155 offset:40960
	ds_read_b128 v[156:159], v155 offset:41984
	ds_read_b128 v[160:163], v155 offset:43008
	ds_read_b128 v[164:167], v155 offset:44032
	ds_read_b128 v[22:25], v154 offset:24576
	ds_read_b128 v[38:41], v154 offset:25600
	ds_read_b128 v[54:57], v154 offset:26624
	ds_read_b128 v[196:199], v154 offset:27648
	s_waitcnt lgkmcnt(0)
	v_mfma_f32_16x16x32_bf16 v[210:213], v[6:9], v[22:25], v[126:129]
	v_mfma_f32_16x16x32_bf16 v[118:121], v[156:159], v[22:25], v[122:125]
	v_mfma_f32_16x16x32_bf16 v[184:187], v[160:163], v[22:25], v[184:187]
	v_mfma_f32_16x16x32_bf16 v[114:117], v[164:167], v[22:25], v[114:117]
	v_mfma_f32_16x16x32_bf16 v[110:113], v[6:9], v[38:41], v[110:113]
	v_mfma_f32_16x16x32_bf16 v[102:105], v[156:159], v[38:41], v[106:109]
	v_mfma_f32_16x16x32_bf16 v[106:109], v[160:163], v[38:41], v[168:171]
	v_mfma_f32_16x16x32_bf16 v[98:101], v[164:167], v[38:41], v[98:101]
	ds_read_b128 v[22:25], v154 offset:28672
	ds_read_b128 v[122:125], v154 offset:29696
	v_mfma_f32_16x16x32_bf16 v[94:97], v[6:9], v[54:57], v[94:97]
	v_mfma_f32_16x16x32_bf16 v[86:89], v[156:159], v[54:57], v[90:93]
	v_mfma_f32_16x16x32_bf16 v[90:93], v[160:163], v[54:57], v[172:175]
	v_mfma_f32_16x16x32_bf16 v[82:85], v[164:167], v[54:57], v[82:85]
	v_mfma_f32_16x16x32_bf16 v[78:81], v[6:9], v[196:199], v[78:81]
	v_mfma_f32_16x16x32_bf16 v[70:73], v[156:159], v[196:199], v[74:77]
	v_mfma_f32_16x16x32_bf16 v[74:77], v[160:163], v[196:199], v[176:179]
	v_mfma_f32_16x16x32_bf16 v[66:69], v[164:167], v[196:199], v[66:69]
	ds_read_b128 v[126:129], v154 offset:30720
	ds_read_b128 v[168:171], v154 offset:31744
	s_waitcnt lgkmcnt(0)
	v_mfma_f32_16x16x32_bf16 v[62:65], v[6:9], v[22:25], v[62:65]
	v_mfma_f32_16x16x32_bf16 v[54:57], v[156:159], v[22:25], v[58:61]
	v_mfma_f32_16x16x32_bf16 v[58:61], v[160:163], v[22:25], v[180:183]
	v_mfma_f32_16x16x32_bf16 v[50:53], v[164:167], v[22:25], v[50:53]
	v_mfma_f32_16x16x32_bf16 v[46:49], v[6:9], v[122:125], v[46:49]
	v_mfma_f32_16x16x32_bf16 v[38:41], v[156:159], v[122:125], v[42:45]
	v_mfma_f32_16x16x32_bf16 v[42:45], v[160:163], v[122:125], v[188:191]
	v_mfma_f32_16x16x32_bf16 v[34:37], v[164:167], v[122:125], v[34:37]
	v_mfma_f32_16x16x32_bf16 v[30:33], v[6:9], v[126:129], v[30:33]
	v_mfma_f32_16x16x32_bf16 v[22:25], v[156:159], v[126:129], v[26:29]
	v_mfma_f32_16x16x32_bf16 v[26:29], v[160:163], v[126:129], v[192:195]
	v_mfma_f32_16x16x32_bf16 v[18:21], v[164:167], v[126:129], v[18:21]
	v_mfma_f32_16x16x32_bf16 v[14:17], v[6:9], v[168:171], v[14:17]
	v_mfma_f32_16x16x32_bf16 v[6:9], v[156:159], v[168:171], v[10:13]
	v_mfma_f32_16x16x32_bf16 v[10:13], v[160:163], v[168:171], v[146:149]
	v_mfma_f32_16x16x32_bf16 v[2:5], v[164:167], v[168:171], v[2:5]
	s_lshl_b32 s90, s5, 8
	s_waitcnt vmcnt(0)
	s_barrier
; __device__ __forceinline__ float siluf_(float x) { return x * __builtin_amdgcn_rcpf(1.f + __expf(-x)); }
; template <int EPI, int MF>
; __device__ __forceinline__ void gemm_part(const u16* __restrict__ A, int lda, const u16* __restrict__ Bt, int K, int ntn, GemmEpi ep, char* smem,
;                                           int mbase, int mrows) {
;     ...
;     for (int m = 0; m < MF; ++m) {
;       if (EPI == EPI_SWIGLU || (m & 1) == 0) __builtin_amdgcn_sched_barrier(0);
;       const int row = row0 + wr * (16 * MF) + m * 16 + fr;
;       const int cb = col0 + wc * 64 + 4 * fq;
;       float rstd = 1.f;
;       if (EPI != EPI_RESID) { if (ep.rss_in) rstd = rsqrtf(ep.rss_in[row] * (1.f / DM) + 1e-6f); }
;       if (EPI == EPI_SWIGLU) {
; #pragma unroll
;         for (int n = 0; n < 2; ++n) {
;           bf16x4 o;
; #pragma unroll
;           for (int jj = 0; jj < 4; ++jj) o[jj] = (short)f2bf(siluf_(acc[m][n][jj] * rstd) * (acc[m][n + 2][jj] * rstd));
;           *(bf16x4*)(ep.outb + (size_t)row * FF + (col0 >> 1) + wc * 32 + n * 16 + 4 * fq) = o;
;         }
	v_add_u32_e32 v124, s8, v152
	v_lshl_add_u64 v[122:123], v[136:137], 0, s[90:91]
	v_readlane_b32 s2, v252, 9
	v_ashrrev_i32_e32 v125, 31, v124
	v_readlane_b32 s3, v252, 10
	s_nop 1
	v_lshl_add_u64 v[126:127], v[124:125], 2, s[2:3]
	global_load_dword v125, v[126:127], off
	s_waitcnt vmcnt(0)
	v_fmamk_f32 v125, v125, 0x3a800000, v142
	v_cmp_gt_f32_e32 vcc, s69, v125
	v_mul_f32_e32 v128, 0x4b800000, v125
	s_nop 0
	v_cndmask_b32_e32 v125, v125, v128, vcc
	v_rsq_f32_e32 v125, v125
	s_nop 0
	v_mul_f32_e32 v128, 0x45800000, v125
	v_cndmask_b32_e32 v146, v125, v128, vcc
	v_pk_mul_f32 v[148:149], v[210:211], v[146:147] op_sel_hi:[1,0]
	v_pk_mul_f32 v[118:119], v[118:119], v[146:147] op_sel_hi:[1,0]
	v_mul_f32_e32 v125, 0xbfb8aa3b, v148
	v_exp_f32_e32 v125, v125
	v_mad_i64_i32 v[128:129], s[2:3], v124, s33, v[122:123]
	v_pk_mul_f32 v[114:115], v[114:115], v[146:147] op_sel_hi:[1,0]
	v_add_f32_e32 v125, 1.0, v125
	v_rcp_f32_e32 v156, v125
	v_mul_f32_e32 v125, 0xbfb8aa3b, v149
	v_exp_f32_e32 v125, v125
	v_pk_mul_f32 v[116:117], v[116:117], v[146:147] op_sel_hi:[1,0]
	v_add_f32_e32 v125, 1.0, v125
	v_rcp_f32_e32 v157, v125
	s_nop 0
	v_pk_mul_f32 v[148:149], v[148:149], v[156:157]
	v_pk_mul_f32 v[156:157], v[184:185], v[146:147] op_sel_hi:[1,0]
	s_nop 0
	v_pk_mul_f32 v[148:149], v[156:157], v[148:149]
	v_pk_mul_f32 v[156:157], v[212:213], v[146:147] op_sel_hi:[1,0]
	v_cvt_pk_bf16_f32 v148, v148, v149
	v_mul_f32_e32 v125, 0xbfb8aa3b, v156
	v_exp_f32_e32 v125, v125
	s_nop 0
	v_add_f32_e32 v125, 1.0, v125
	v_rcp_f32_e32 v158, v125
	v_mul_f32_e32 v125, 0xbfb8aa3b, v157
	v_exp_f32_e32 v125, v125
	s_nop 0
	v_add_f32_e32 v125, 1.0, v125
	v_rcp_f32_e32 v159, v125
	v_mul_f32_e32 v125, 0xbfb8aa3b, v118
	v_exp_f32_e32 v125, v125
	v_pk_mul_f32 v[156:157], v[156:157], v[158:159]
	v_pk_mul_f32 v[158:159], v[186:187], v[146:147] op_sel_hi:[1,0]
	v_add_f32_e32 v125, 1.0, v125
	v_pk_mul_f32 v[156:157], v[158:159], v[156:157]
	s_nop 0
	v_cvt_pk_bf16_f32 v149, v156, v157
	global_store_dwordx2 v[128:129], v[148:149], off
	v_rcp_f32_e32 v148, v125
	v_mul_f32_e32 v125, 0xbfb8aa3b, v119
	v_exp_f32_e32 v125, v125
	s_nop 0
	v_add_f32_e32 v125, 1.0, v125
	v_rcp_f32_e32 v149, v125
	s_nop 0
	v_pk_mul_f32 v[118:119], v[118:119], v[148:149]
	s_nop 0
	v_pk_mul_f32 v[114:115], v[114:115], v[118:119]
	v_pk_mul_f32 v[118:119], v[120:121], v[146:147] op_sel_hi:[1,0]
	v_cvt_pk_bf16_f32 v114, v114, v115
	v_mul_f32_e32 v115, 0xbfb8aa3b, v118
	v_exp_f32_e32 v115, v115
	s_nop 0
	v_add_f32_e32 v115, 1.0, v115
	v_rcp_f32_e32 v120, v115
	v_mul_f32_e32 v115, 0xbfb8aa3b, v119
	v_exp_f32_e32 v115, v115
	s_nop 0
	v_add_f32_e32 v115, 1.0, v115
	v_rcp_f32_e32 v121, v115
	s_nop 0
	v_pk_mul_f32 v[118:119], v[118:119], v[120:121]
	s_nop 0
	v_pk_mul_f32 v[116:117], v[116:117], v[118:119]
	s_nop 0
	v_cvt_pk_bf16_f32 v115, v116, v117
	global_store_dwordx2 v[128:129], v[114:115], off offset:32
	global_load_dword v115, v[126:127], off offset:64
	v_or_b32_e32 v114, 16, v124
	s_waitcnt vmcnt(0)
	v_fmamk_f32 v115, v115, 0x3a800000, v142
	v_cmp_gt_f32_e32 vcc, s69, v115
	v_mul_f32_e32 v116, 0x4b800000, v115
	s_nop 0
	v_cndmask_b32_e32 v115, v115, v116, vcc
	v_rsq_f32_e32 v115, v115
	s_nop 0
	v_mul_f32_e32 v116, 0x45800000, v115
	v_cndmask_b32_e32 v116, v115, v116, vcc
	v_pk_mul_f32 v[110:111], v[110:111], v[116:117] op_sel_hi:[1,0]
	v_mad_i64_i32 v[114:115], s[2:3], v114, s33, v[122:123]
	v_mul_f32_e32 v117, 0xbfb8aa3b, v110
	v_exp_f32_e32 v117, v117
	s_nop 0
	v_add_f32_e32 v117, 1.0, v117
	v_rcp_f32_e32 v118, v117
	v_mul_f32_e32 v117, 0xbfb8aa3b, v111
	v_exp_f32_e32 v117, v117
	s_nop 0
	v_add_f32_e32 v117, 1.0, v117
	v_rcp_f32_e32 v119, v117
	v_pk_mul_f32 v[106:107], v[106:107], v[116:117] op_sel_hi:[1,0]
	v_pk_mul_f32 v[108:109], v[108:109], v[116:117] op_sel_hi:[1,0]
	v_pk_mul_f32 v[102:103], v[102:103], v[116:117] op_sel_hi:[1,0]
	v_pk_mul_f32 v[110:111], v[110:111], v[118:119]
	v_pk_mul_f32 v[98:99], v[98:99], v[116:117] op_sel_hi:[1,0]
	v_pk_mul_f32 v[106:107], v[106:107], v[110:111]
	v_pk_mul_f32 v[110:111], v[112:113], v[116:117] op_sel_hi:[1,0]
	v_cvt_pk_bf16_f32 v106, v106, v107
	v_mul_f32_e32 v107, 0xbfb8aa3b, v110
	v_exp_f32_e32 v107, v107
	v_pk_mul_f32 v[100:101], v[100:101], v[116:117] op_sel_hi:[1,0]
	v_add_f32_e32 v107, 1.0, v107
	v_rcp_f32_e32 v112, v107
	v_mul_f32_e32 v107, 0xbfb8aa3b, v111
	v_exp_f32_e32 v107, v107
	s_nop 0
	v_add_f32_e32 v107, 1.0, v107
	v_rcp_f32_e32 v113, v107
	s_nop 0
	v_pk_mul_f32 v[110:111], v[110:111], v[112:113]
	s_nop 0
	v_pk_mul_f32 v[108:109], v[108:109], v[110:111]
	s_nop 0
	v_cvt_pk_bf16_f32 v107, v108, v109
	global_store_dwordx2 v[114:115], v[106:107], off
	v_mul_f32_e32 v106, 0xbfb8aa3b, v102
	v_mul_f32_e32 v107, 0xbfb8aa3b, v103
	v_exp_f32_e32 v106, v106
	v_exp_f32_e32 v107, v107
	v_add_f32_e32 v106, 1.0, v106
	v_add_f32_e32 v107, 1.0, v107
	v_rcp_f32_e32 v106, v106
	v_rcp_f32_e32 v107, v107
	s_nop 0
	v_pk_mul_f32 v[102:103], v[102:103], v[106:107]
	s_nop 0
	v_pk_mul_f32 v[98:99], v[98:99], v[102:103]
	v_pk_mul_f32 v[102:103], v[104:105], v[116:117] op_sel_hi:[1,0]
	v_cvt_pk_bf16_f32 v98, v98, v99
	v_mul_f32_e32 v99, 0xbfb8aa3b, v102
	v_exp_f32_e32 v99, v99
	s_nop 0
	v_add_f32_e32 v99, 1.0, v99
	v_rcp_f32_e32 v104, v99
	v_mul_f32_e32 v99, 0xbfb8aa3b, v103
	v_exp_f32_e32 v99, v99
	s_nop 0
	v_add_f32_e32 v99, 1.0, v99
	v_rcp_f32_e32 v105, v99
	s_nop 0
	v_pk_mul_f32 v[102:103], v[102:103], v[104:105]
	s_nop 0
	v_pk_mul_f32 v[100:101], v[100:101], v[102:103]
	s_nop 0
	v_cvt_pk_bf16_f32 v99, v100, v101
	global_store_dwordx2 v[114:115], v[98:99], off offset:32
	global_load_dword v99, v[126:127], off offset:128
	v_or_b32_e32 v98, 32, v124
	s_waitcnt vmcnt(0)
; __device__ __forceinline__ float siluf_(float x) { return x * __builtin_amdgcn_rcpf(1.f + __expf(-x)); }
; template <int EPI, int MF>
; __device__ __forceinline__ void gemm_part(const u16* __restrict__ A, int lda, const u16* __restrict__ Bt, int K, int ntn, GemmEpi ep, char* smem,
;                                           int mbase, int mrows) {
;     ...
;     for (int m = 0; m < MF; ++m) {
;       if (EPI == EPI_SWIGLU || (m & 1) == 0) __builtin_amdgcn_sched_barrier(0);
;       const int row = row0 + wr * (16 * MF) + m * 16 + fr;
;       const int cb = col0 + wc * 64 + 4 * fq;
;       float rstd = 1.f;
;       if (EPI != EPI_RESID) { if (ep.rss_in) rstd = rsqrtf(ep.rss_in[row] * (1.f / DM) + 1e-6f); }
;       if (EPI == EPI_SWIGLU) {
; #pragma unroll
;         for (int n = 0; n < 2; ++n) {
;           bf16x4 o;
; #pragma unroll
;           for (int jj = 0; jj < 4; ++jj) o[jj] = (short)f2bf(siluf_(acc[m][n][jj] * rstd) * (acc[m][n + 2][jj] * rstd));
;           *(bf16x4*)(ep.outb + (size_t)row * FF + (col0 >> 1) + wc * 32 + n * 16 + 4 * fq) = o;
;         }
	v_fmamk_f32 v99, v99, 0x3a800000, v142
	v_cmp_gt_f32_e32 vcc, s69, v99
	v_mul_f32_e32 v100, 0x4b800000, v99
	s_nop 0
	v_cndmask_b32_e32 v99, v99, v100, vcc
	v_rsq_f32_e32 v99, v99
	s_nop 0
	v_mul_f32_e32 v100, 0x45800000, v99
	v_cndmask_b32_e32 v100, v99, v100, vcc
	v_pk_mul_f32 v[94:95], v[94:95], v[100:101] op_sel_hi:[1,0]
	v_mad_i64_i32 v[98:99], s[2:3], v98, s33, v[122:123]
	v_mul_f32_e32 v101, 0xbfb8aa3b, v94
	v_exp_f32_e32 v101, v101
	s_nop 0
	v_add_f32_e32 v101, 1.0, v101
	v_rcp_f32_e32 v102, v101
	v_mul_f32_e32 v101, 0xbfb8aa3b, v95
	v_exp_f32_e32 v101, v101
	s_nop 0
	v_add_f32_e32 v101, 1.0, v101
	v_rcp_f32_e32 v103, v101
	v_pk_mul_f32 v[90:91], v[90:91], v[100:101] op_sel_hi:[1,0]
	v_pk_mul_f32 v[92:93], v[92:93], v[100:101] op_sel_hi:[1,0]
	v_pk_mul_f32 v[86:87], v[86:87], v[100:101] op_sel_hi:[1,0]
	v_pk_mul_f32 v[94:95], v[94:95], v[102:103]
	v_pk_mul_f32 v[82:83], v[82:83], v[100:101] op_sel_hi:[1,0]
	v_pk_mul_f32 v[90:91], v[90:91], v[94:95]
	v_pk_mul_f32 v[94:95], v[96:97], v[100:101] op_sel_hi:[1,0]
	v_cvt_pk_bf16_f32 v90, v90, v91
	v_mul_f32_e32 v91, 0xbfb8aa3b, v94
	v_exp_f32_e32 v91, v91
	v_pk_mul_f32 v[84:85], v[84:85], v[100:101] op_sel_hi:[1,0]
	v_add_f32_e32 v91, 1.0, v91
	v_rcp_f32_e32 v96, v91
	v_mul_f32_e32 v91, 0xbfb8aa3b, v95
	v_exp_f32_e32 v91, v91
	s_nop 0
	v_add_f32_e32 v91, 1.0, v91
	v_rcp_f32_e32 v97, v91
	s_nop 0
	v_pk_mul_f32 v[94:95], v[94:95], v[96:97]
	s_nop 0
	v_pk_mul_f32 v[92:93], v[92:93], v[94:95]
	s_nop 0
	v_cvt_pk_bf16_f32 v91, v92, v93
	global_store_dwordx2 v[98:99], v[90:91], off
	v_mul_f32_e32 v90, 0xbfb8aa3b, v86
	v_mul_f32_e32 v91, 0xbfb8aa3b, v87
	v_exp_f32_e32 v90, v90
	v_exp_f32_e32 v91, v91
	v_add_f32_e32 v90, 1.0, v90
	v_add_f32_e32 v91, 1.0, v91
	v_rcp_f32_e32 v90, v90
	v_rcp_f32_e32 v91, v91
	s_nop 0
	v_pk_mul_f32 v[86:87], v[86:87], v[90:91]
	s_nop 0
	v_pk_mul_f32 v[82:83], v[82:83], v[86:87]
	v_pk_mul_f32 v[86:87], v[88:89], v[100:101] op_sel_hi:[1,0]
	v_cvt_pk_bf16_f32 v82, v82, v83
	v_mul_f32_e32 v83, 0xbfb8aa3b, v86
	v_exp_f32_e32 v83, v83
	s_nop 0
	v_add_f32_e32 v83, 1.0, v83
	v_rcp_f32_e32 v88, v83
	v_mul_f32_e32 v83, 0xbfb8aa3b, v87
	v_exp_f32_e32 v83, v83
	s_nop 0
	v_add_f32_e32 v83, 1.0, v83
	v_rcp_f32_e32 v89, v83
	s_nop 0
	v_pk_mul_f32 v[86:87], v[86:87], v[88:89]
	s_nop 0
	v_pk_mul_f32 v[84:85], v[84:85], v[86:87]
	s_nop 0
	v_cvt_pk_bf16_f32 v83, v84, v85
	global_store_dwordx2 v[98:99], v[82:83], off offset:32
	global_load_dword v83, v[126:127], off offset:192
	v_or_b32_e32 v82, 48, v124
	s_waitcnt vmcnt(0)
	v_fmamk_f32 v83, v83, 0x3a800000, v142
	v_cmp_gt_f32_e32 vcc, s69, v83
	v_mul_f32_e32 v84, 0x4b800000, v83
	s_nop 0
	v_cndmask_b32_e32 v83, v83, v84, vcc
	v_rsq_f32_e32 v83, v83
	s_nop 0
	v_mul_f32_e32 v84, 0x45800000, v83
	v_cndmask_b32_e32 v84, v83, v84, vcc
	v_pk_mul_f32 v[78:79], v[78:79], v[84:85] op_sel_hi:[1,0]
	v_mad_i64_i32 v[82:83], s[2:3], v82, s33, v[122:123]
	v_mul_f32_e32 v85, 0xbfb8aa3b, v78
	v_exp_f32_e32 v85, v85
	s_nop 0
	v_add_f32_e32 v85, 1.0, v85
	v_rcp_f32_e32 v86, v85
	v_mul_f32_e32 v85, 0xbfb8aa3b, v79
	v_exp_f32_e32 v85, v85
	s_nop 0
	v_add_f32_e32 v85, 1.0, v85
	v_rcp_f32_e32 v87, v85
	v_pk_mul_f32 v[74:75], v[74:75], v[84:85] op_sel_hi:[1,0]
	v_pk_mul_f32 v[76:77], v[76:77], v[84:85] op_sel_hi:[1,0]
	v_pk_mul_f32 v[70:71], v[70:71], v[84:85] op_sel_hi:[1,0]
	v_pk_mul_f32 v[78:79], v[78:79], v[86:87]
	v_pk_mul_f32 v[66:67], v[66:67], v[84:85] op_sel_hi:[1,0]
	v_pk_mul_f32 v[74:75], v[74:75], v[78:79]
	v_pk_mul_f32 v[78:79], v[80:81], v[84:85] op_sel_hi:[1,0]
	v_cvt_pk_bf16_f32 v74, v74, v75
	v_mul_f32_e32 v75, 0xbfb8aa3b, v78
	v_exp_f32_e32 v75, v75
	v_pk_mul_f32 v[68:69], v[68:69], v[84:85] op_sel_hi:[1,0]
	v_add_f32_e32 v75, 1.0, v75
	v_rcp_f32_e32 v80, v75
	v_mul_f32_e32 v75, 0xbfb8aa3b, v79
	v_exp_f32_e32 v75, v75
	s_nop 0
	v_add_f32_e32 v75, 1.0, v75
	v_rcp_f32_e32 v81, v75
	s_nop 0
	v_pk_mul_f32 v[78:79], v[78:79], v[80:81]
	s_nop 0
	v_pk_mul_f32 v[76:77], v[76:77], v[78:79]
	s_nop 0
	v_cvt_pk_bf16_f32 v75, v76, v77
	global_store_dwordx2 v[82:83], v[74:75], off
	v_mul_f32_e32 v74, 0xbfb8aa3b, v70
	v_mul_f32_e32 v75, 0xbfb8aa3b, v71
	v_exp_f32_e32 v74, v74
	v_exp_f32_e32 v75, v75
	v_add_f32_e32 v74, 1.0, v74
	v_add_f32_e32 v75, 1.0, v75
	v_rcp_f32_e32 v74, v74
	v_rcp_f32_e32 v75, v75
	s_nop 0
	v_pk_mul_f32 v[70:71], v[70:71], v[74:75]
	s_nop 0
	v_pk_mul_f32 v[66:67], v[66:67], v[70:71]
	v_pk_mul_f32 v[70:71], v[72:73], v[84:85] op_sel_hi:[1,0]
	v_cvt_pk_bf16_f32 v66, v66, v67
	v_mul_f32_e32 v67, 0xbfb8aa3b, v70
	v_exp_f32_e32 v67, v67
	s_nop 0
	v_add_f32_e32 v67, 1.0, v67
	v_rcp_f32_e32 v72, v67
	v_mul_f32_e32 v67, 0xbfb8aa3b, v71
	v_exp_f32_e32 v67, v67
	s_nop 0
	v_add_f32_e32 v67, 1.0, v67
	v_rcp_f32_e32 v73, v67
	s_nop 0
	v_pk_mul_f32 v[70:71], v[70:71], v[72:73]
	s_nop 0
	v_pk_mul_f32 v[68:69], v[68:69], v[70:71]
	s_nop 0
	v_cvt_pk_bf16_f32 v67, v68, v69
	global_store_dwordx2 v[82:83], v[66:67], off offset:32
	global_load_dword v67, v[126:127], off offset:256
	v_or_b32_e32 v66, 64, v124
	s_waitcnt vmcnt(0)
; __device__ __forceinline__ float siluf_(float x) { return x * __builtin_amdgcn_rcpf(1.f + __expf(-x)); }
; template <int EPI, int MF>
; __device__ __forceinline__ void gemm_part(const u16* __restrict__ A, int lda, const u16* __restrict__ Bt, int K, int ntn, GemmEpi ep, char* smem,
;                                           int mbase, int mrows) {
;     ...
;     for (int m = 0; m < MF; ++m) {
;       if (EPI == EPI_SWIGLU || (m & 1) == 0) __builtin_amdgcn_sched_barrier(0);
;       const int row = row0 + wr * (16 * MF) + m * 16 + fr;
;       const int cb = col0 + wc * 64 + 4 * fq;
;       float rstd = 1.f;
;       if (EPI != EPI_RESID) { if (ep.rss_in) rstd = rsqrtf(ep.rss_in[row] * (1.f / DM) + 1e-6f); }
;       if (EPI == EPI_SWIGLU) {
; #pragma unroll
;         for (int n = 0; n < 2; ++n) {
;           bf16x4 o;
; #pragma unroll
;           for (int jj = 0; jj < 4; ++jj) o[jj] = (short)f2bf(siluf_(acc[m][n][jj] * rstd) * (acc[m][n + 2][jj] * rstd));
;           *(bf16x4*)(ep.outb + (size_t)row * FF + (col0 >> 1) + wc * 32 + n * 16 + 4 * fq) = o;
;         }
	v_fmamk_f32 v67, v67, 0x3a800000, v142
	v_cmp_gt_f32_e32 vcc, s69, v67
	v_mul_f32_e32 v68, 0x4b800000, v67
	s_nop 0
	v_cndmask_b32_e32 v67, v67, v68, vcc
	v_rsq_f32_e32 v67, v67
	s_nop 0
	v_mul_f32_e32 v68, 0x45800000, v67
	v_cndmask_b32_e32 v68, v67, v68, vcc
	v_pk_mul_f32 v[62:63], v[62:63], v[68:69] op_sel_hi:[1,0]
	v_mad_i64_i32 v[66:67], s[2:3], v66, s33, v[122:123]
	v_mul_f32_e32 v69, 0xbfb8aa3b, v62
	v_exp_f32_e32 v69, v69
	s_nop 0
	v_add_f32_e32 v69, 1.0, v69
	v_rcp_f32_e32 v70, v69
	v_mul_f32_e32 v69, 0xbfb8aa3b, v63
	v_exp_f32_e32 v69, v69
	s_nop 0
	v_add_f32_e32 v69, 1.0, v69
	v_rcp_f32_e32 v71, v69
	v_pk_mul_f32 v[58:59], v[58:59], v[68:69] op_sel_hi:[1,0]
	v_pk_mul_f32 v[60:61], v[60:61], v[68:69] op_sel_hi:[1,0]
	v_pk_mul_f32 v[54:55], v[54:55], v[68:69] op_sel_hi:[1,0]
	v_pk_mul_f32 v[62:63], v[62:63], v[70:71]
	v_pk_mul_f32 v[50:51], v[50:51], v[68:69] op_sel_hi:[1,0]
	v_pk_mul_f32 v[58:59], v[58:59], v[62:63]
	v_pk_mul_f32 v[62:63], v[64:65], v[68:69] op_sel_hi:[1,0]
	v_cvt_pk_bf16_f32 v58, v58, v59
	v_mul_f32_e32 v59, 0xbfb8aa3b, v62
	v_exp_f32_e32 v59, v59
	v_pk_mul_f32 v[52:53], v[52:53], v[68:69] op_sel_hi:[1,0]
	v_add_f32_e32 v59, 1.0, v59
	v_rcp_f32_e32 v64, v59
	v_mul_f32_e32 v59, 0xbfb8aa3b, v63
	v_exp_f32_e32 v59, v59
	s_nop 0
	v_add_f32_e32 v59, 1.0, v59
	v_rcp_f32_e32 v65, v59
	s_nop 0
	v_pk_mul_f32 v[62:63], v[62:63], v[64:65]
	s_nop 0
	v_pk_mul_f32 v[60:61], v[60:61], v[62:63]
	s_nop 0
	v_cvt_pk_bf16_f32 v59, v60, v61
	global_store_dwordx2 v[66:67], v[58:59], off
	v_mul_f32_e32 v58, 0xbfb8aa3b, v54
	v_mul_f32_e32 v59, 0xbfb8aa3b, v55
	v_exp_f32_e32 v58, v58
	v_exp_f32_e32 v59, v59
	v_add_f32_e32 v58, 1.0, v58
	v_add_f32_e32 v59, 1.0, v59
	v_rcp_f32_e32 v58, v58
	v_rcp_f32_e32 v59, v59
	s_nop 0
	v_pk_mul_f32 v[54:55], v[54:55], v[58:59]
	s_nop 0
	v_pk_mul_f32 v[50:51], v[50:51], v[54:55]
	v_pk_mul_f32 v[54:55], v[56:57], v[68:69] op_sel_hi:[1,0]
	v_cvt_pk_bf16_f32 v50, v50, v51
	v_mul_f32_e32 v51, 0xbfb8aa3b, v54
	v_exp_f32_e32 v51, v51
	s_nop 0
	v_add_f32_e32 v51, 1.0, v51
	v_rcp_f32_e32 v56, v51
	v_mul_f32_e32 v51, 0xbfb8aa3b, v55
	v_exp_f32_e32 v51, v51
	s_nop 0
	v_add_f32_e32 v51, 1.0, v51
	v_rcp_f32_e32 v57, v51
	s_nop 0
	v_pk_mul_f32 v[54:55], v[54:55], v[56:57]
	s_nop 0
	v_pk_mul_f32 v[52:53], v[52:53], v[54:55]
	s_nop 0
	v_cvt_pk_bf16_f32 v51, v52, v53
	global_store_dwordx2 v[66:67], v[50:51], off offset:32
	global_load_dword v51, v[126:127], off offset:320
	v_or_b32_e32 v50, 0x50, v124
	s_waitcnt vmcnt(0)
	v_fmamk_f32 v51, v51, 0x3a800000, v142
	v_cmp_gt_f32_e32 vcc, s69, v51
	v_mul_f32_e32 v52, 0x4b800000, v51
	s_nop 0
	v_cndmask_b32_e32 v51, v51, v52, vcc
	v_rsq_f32_e32 v51, v51
	s_nop 0
	v_mul_f32_e32 v52, 0x45800000, v51
	v_cndmask_b32_e32 v52, v51, v52, vcc
	v_pk_mul_f32 v[46:47], v[46:47], v[52:53] op_sel_hi:[1,0]
	v_mad_i64_i32 v[50:51], s[2:3], v50, s33, v[122:123]
	v_mul_f32_e32 v53, 0xbfb8aa3b, v46
	v_exp_f32_e32 v53, v53
	s_nop 0
	v_add_f32_e32 v53, 1.0, v53
	v_rcp_f32_e32 v54, v53
	v_mul_f32_e32 v53, 0xbfb8aa3b, v47
	v_exp_f32_e32 v53, v53
	s_nop 0
	v_add_f32_e32 v53, 1.0, v53
	v_rcp_f32_e32 v55, v53
	v_pk_mul_f32 v[42:43], v[42:43], v[52:53] op_sel_hi:[1,0]
	v_pk_mul_f32 v[44:45], v[44:45], v[52:53] op_sel_hi:[1,0]
	v_pk_mul_f32 v[38:39], v[38:39], v[52:53] op_sel_hi:[1,0]
	v_pk_mul_f32 v[46:47], v[46:47], v[54:55]
	v_pk_mul_f32 v[34:35], v[34:35], v[52:53] op_sel_hi:[1,0]
	v_pk_mul_f32 v[42:43], v[42:43], v[46:47]
	v_pk_mul_f32 v[46:47], v[48:49], v[52:53] op_sel_hi:[1,0]
	v_cvt_pk_bf16_f32 v42, v42, v43
	v_mul_f32_e32 v43, 0xbfb8aa3b, v46
	v_exp_f32_e32 v43, v43
	v_pk_mul_f32 v[36:37], v[36:37], v[52:53] op_sel_hi:[1,0]
	v_add_f32_e32 v43, 1.0, v43
	v_rcp_f32_e32 v48, v43
	v_mul_f32_e32 v43, 0xbfb8aa3b, v47
	v_exp_f32_e32 v43, v43
	s_nop 0
	v_add_f32_e32 v43, 1.0, v43
	v_rcp_f32_e32 v49, v43
	s_nop 0
	v_pk_mul_f32 v[46:47], v[46:47], v[48:49]
	s_nop 0
	v_pk_mul_f32 v[44:45], v[44:45], v[46:47]
	s_nop 0
	v_cvt_pk_bf16_f32 v43, v44, v45
	global_store_dwordx2 v[50:51], v[42:43], off
	v_mul_f32_e32 v42, 0xbfb8aa3b, v38
	v_mul_f32_e32 v43, 0xbfb8aa3b, v39
	v_exp_f32_e32 v42, v42
	v_exp_f32_e32 v43, v43
	v_add_f32_e32 v42, 1.0, v42
	v_add_f32_e32 v43, 1.0, v43
	v_rcp_f32_e32 v42, v42
	v_rcp_f32_e32 v43, v43
	s_nop 0
	v_pk_mul_f32 v[38:39], v[38:39], v[42:43]
	s_nop 0
	v_pk_mul_f32 v[34:35], v[34:35], v[38:39]
	v_pk_mul_f32 v[38:39], v[40:41], v[52:53] op_sel_hi:[1,0]
	v_cvt_pk_bf16_f32 v34, v34, v35
	v_mul_f32_e32 v35, 0xbfb8aa3b, v38
	v_exp_f32_e32 v35, v35
	s_nop 0
	v_add_f32_e32 v35, 1.0, v35
	v_rcp_f32_e32 v40, v35
	v_mul_f32_e32 v35, 0xbfb8aa3b, v39
	v_exp_f32_e32 v35, v35
	s_nop 0
	v_add_f32_e32 v35, 1.0, v35
	v_rcp_f32_e32 v41, v35
	s_nop 0
	v_pk_mul_f32 v[38:39], v[38:39], v[40:41]
	s_nop 0
	v_pk_mul_f32 v[36:37], v[36:37], v[38:39]
	s_nop 0
	v_cvt_pk_bf16_f32 v35, v36, v37
	global_store_dwordx2 v[50:51], v[34:35], off offset:32
	global_load_dword v35, v[126:127], off offset:384
	v_or_b32_e32 v34, 0x60, v124
	s_waitcnt vmcnt(0)
; __device__ __forceinline__ float siluf_(float x) { return x * __builtin_amdgcn_rcpf(1.f + __expf(-x)); }
; __device__ __forceinline__ int opaque_tid() { int t = threadIdx.x; asm volatile("" : "+v"(t)); return t; }
; template <int EPI, int MF>
; __device__ __forceinline__ void gemm_part(const u16* __restrict__ A, int lda, const u16* __restrict__ Bt, int K, int ntn, GemmEpi ep, char* smem,
;                                           int mbase, int mrows) {
;   const int tid = opaque_tid(), lane = tid & 63, wid = tid >> 6, wr = wid >> 1, wc = wid & 1, fr = lane & 15, fq = lane >> 4;
;   constexpr int BM = 32 * MF;
;   constexpr int STG = BM * 32 + 4096;
;   constexpr int NA = MF / 2;
;   u16* const sbase = (u16*)smem;
;   const int ntm = mrows / BM;
;   const int total = ntm * ntn;
;   const int nk = K / 32;
;   const int nbx = (MF == 2) ? (int)gridDim.x : (int)(gridDim.x >> 3);
;   const int xcd = (MF == 2) ? 0 : (int)(blockIdx.x & 7), li = (MF == 2) ? (int)blockIdx.x : (int)(blockIdx.x >> 3);
;   for (int q = xcd; q * nbx < total; q += (MF == 2) ? 1 : 8) {
;     const int L = q * nbx + li;
;     if (L >= total) continue;
;     const int g = L / (8 * ntn), rr = L % (8 * ntn);
;     const int rows = min(8, ntm - 8 * g);
;     const int tm = 8 * g + rr % rows, tn = rr / rows;
;     const int row0 = mbase + tm * BM, col0 = tn * 128;
;     f32x4 acc[MF][4];
; #pragma unroll
;     for (int m = 0; m < MF; ++m)
; #pragma unroll
;       for (int n = 0; n < 4; ++n) acc[m][n] = (f32x4){0.f, 0.f, 0.f, 0.f};
;     const u16* gA = A + (size_t)(row0 + (tid >> 2)) * lda + (tid & 3) * 8;
;     const u16* gB = Bt + (size_t)(col0 + (tid >> 2)) * K + (tid & 3) * 8;
;     ...
;     for (int m = 0; m < MF; ++m) {
;       if (EPI == EPI_SWIGLU || (m & 1) == 0) __builtin_amdgcn_sched_barrier(0);
;       const int row = row0 + wr * (16 * MF) + m * 16 + fr;
;       const int cb = col0 + wc * 64 + 4 * fq;
;       float rstd = 1.f;
;       if (EPI != EPI_RESID) { if (ep.rss_in) rstd = rsqrtf(ep.rss_in[row] * (1.f / DM) + 1e-6f); }
;       if (EPI == EPI_SWIGLU) {
; #pragma unroll
;         for (int n = 0; n < 2; ++n) {
;           bf16x4 o;
; #pragma unroll
;           for (int jj = 0; jj < 4; ++jj) o[jj] = (short)f2bf(siluf_(acc[m][n][jj] * rstd) * (acc[m][n + 2][jj] * rstd));
;           *(bf16x4*)(ep.outb + (size_t)row * FF + (col0 >> 1) + wc * 32 + n * 16 + 4 * fq) = o;
;         }
	v_fmamk_f32 v35, v35, 0x3a800000, v142
	v_cmp_gt_f32_e32 vcc, s69, v35
	v_mul_f32_e32 v36, 0x4b800000, v35
	s_nop 0
	v_cndmask_b32_e32 v35, v35, v36, vcc
	v_rsq_f32_e32 v35, v35
	s_nop 0
	v_mul_f32_e32 v36, 0x45800000, v35
	v_cndmask_b32_e32 v36, v35, v36, vcc
	v_pk_mul_f32 v[30:31], v[30:31], v[36:37] op_sel_hi:[1,0]
	v_mad_i64_i32 v[34:35], s[2:3], v34, s33, v[122:123]
	v_mul_f32_e32 v37, 0xbfb8aa3b, v30
	v_exp_f32_e32 v37, v37
	s_nop 0
	v_add_f32_e32 v37, 1.0, v37
	v_rcp_f32_e32 v38, v37
	v_mul_f32_e32 v37, 0xbfb8aa3b, v31
	v_exp_f32_e32 v37, v37
	s_nop 0
	v_add_f32_e32 v37, 1.0, v37
	v_rcp_f32_e32 v39, v37
	v_pk_mul_f32 v[26:27], v[26:27], v[36:37] op_sel_hi:[1,0]
	v_pk_mul_f32 v[28:29], v[28:29], v[36:37] op_sel_hi:[1,0]
	v_pk_mul_f32 v[22:23], v[22:23], v[36:37] op_sel_hi:[1,0]
	v_pk_mul_f32 v[30:31], v[30:31], v[38:39]
	v_pk_mul_f32 v[18:19], v[18:19], v[36:37] op_sel_hi:[1,0]
	v_pk_mul_f32 v[26:27], v[26:27], v[30:31]
	v_pk_mul_f32 v[30:31], v[32:33], v[36:37] op_sel_hi:[1,0]
	v_cvt_pk_bf16_f32 v26, v26, v27
	v_mul_f32_e32 v27, 0xbfb8aa3b, v30
	v_exp_f32_e32 v27, v27
	v_pk_mul_f32 v[20:21], v[20:21], v[36:37] op_sel_hi:[1,0]
	v_add_f32_e32 v27, 1.0, v27
	v_rcp_f32_e32 v32, v27
	v_mul_f32_e32 v27, 0xbfb8aa3b, v31
	v_exp_f32_e32 v27, v27
	s_nop 0
	v_add_f32_e32 v27, 1.0, v27
	v_rcp_f32_e32 v33, v27
	s_nop 0
	v_pk_mul_f32 v[30:31], v[30:31], v[32:33]
	s_nop 0
	v_pk_mul_f32 v[28:29], v[28:29], v[30:31]
	s_nop 0
	v_cvt_pk_bf16_f32 v27, v28, v29
	global_store_dwordx2 v[34:35], v[26:27], off
	v_mul_f32_e32 v26, 0xbfb8aa3b, v22
	v_mul_f32_e32 v27, 0xbfb8aa3b, v23
	v_exp_f32_e32 v26, v26
	v_exp_f32_e32 v27, v27
	v_add_f32_e32 v26, 1.0, v26
	v_add_f32_e32 v27, 1.0, v27
	v_rcp_f32_e32 v26, v26
	v_rcp_f32_e32 v27, v27
	s_nop 0
	v_pk_mul_f32 v[22:23], v[22:23], v[26:27]
	s_nop 0
	v_pk_mul_f32 v[18:19], v[18:19], v[22:23]
	v_pk_mul_f32 v[22:23], v[24:25], v[36:37] op_sel_hi:[1,0]
	v_cvt_pk_bf16_f32 v18, v18, v19
	v_mul_f32_e32 v19, 0xbfb8aa3b, v22
	v_exp_f32_e32 v19, v19
	s_nop 0
	v_add_f32_e32 v19, 1.0, v19
	v_rcp_f32_e32 v24, v19
	v_mul_f32_e32 v19, 0xbfb8aa3b, v23
	v_exp_f32_e32 v19, v19
	s_nop 0
	v_add_f32_e32 v19, 1.0, v19
	v_rcp_f32_e32 v25, v19
	s_nop 0
	v_pk_mul_f32 v[22:23], v[22:23], v[24:25]
	s_nop 0
	v_pk_mul_f32 v[20:21], v[20:21], v[22:23]
	s_nop 0
	v_cvt_pk_bf16_f32 v19, v20, v21
	global_store_dwordx2 v[34:35], v[18:19], off offset:32
	global_load_dword v19, v[126:127], off offset:448
	v_or_b32_e32 v18, 0x70, v124
	s_waitcnt vmcnt(0)
	v_fmamk_f32 v19, v19, 0x3a800000, v142
	v_cmp_gt_f32_e32 vcc, s69, v19
	v_mul_f32_e32 v20, 0x4b800000, v19
	s_nop 0
	v_cndmask_b32_e32 v19, v19, v20, vcc
	v_rsq_f32_e32 v19, v19
	s_nop 0
	v_mul_f32_e32 v20, 0x45800000, v19
	v_cndmask_b32_e32 v20, v19, v20, vcc
	v_pk_mul_f32 v[14:15], v[14:15], v[20:21] op_sel_hi:[1,0]
	v_mad_i64_i32 v[18:19], s[2:3], v18, s33, v[122:123]
	v_mul_f32_e32 v21, 0xbfb8aa3b, v14
	v_exp_f32_e32 v21, v21
	s_nop 0
	v_add_f32_e32 v21, 1.0, v21
	v_rcp_f32_e32 v22, v21
	v_mul_f32_e32 v21, 0xbfb8aa3b, v15
	v_exp_f32_e32 v21, v21
	s_nop 0
	v_add_f32_e32 v21, 1.0, v21
	v_rcp_f32_e32 v23, v21
	v_pk_mul_f32 v[10:11], v[10:11], v[20:21] op_sel_hi:[1,0]
	v_pk_mul_f32 v[12:13], v[12:13], v[20:21] op_sel_hi:[1,0]
	v_pk_mul_f32 v[6:7], v[6:7], v[20:21] op_sel_hi:[1,0]
	v_pk_mul_f32 v[14:15], v[14:15], v[22:23]
	v_pk_mul_f32 v[2:3], v[2:3], v[20:21] op_sel_hi:[1,0]
	v_pk_mul_f32 v[10:11], v[10:11], v[14:15]
	v_pk_mul_f32 v[14:15], v[16:17], v[20:21] op_sel_hi:[1,0]
	v_cvt_pk_bf16_f32 v10, v10, v11
	v_mul_f32_e32 v11, 0xbfb8aa3b, v14
	v_exp_f32_e32 v11, v11
	v_pk_mul_f32 v[4:5], v[4:5], v[20:21] op_sel_hi:[1,0]
	v_add_f32_e32 v11, 1.0, v11
	v_rcp_f32_e32 v16, v11
	v_mul_f32_e32 v11, 0xbfb8aa3b, v15
	v_exp_f32_e32 v11, v11
	s_nop 0
	v_add_f32_e32 v11, 1.0, v11
	v_rcp_f32_e32 v17, v11
	s_nop 0
	v_pk_mul_f32 v[14:15], v[14:15], v[16:17]
	s_nop 0
	v_pk_mul_f32 v[12:13], v[12:13], v[14:15]
	s_nop 0
	v_cvt_pk_bf16_f32 v11, v12, v13
	global_store_dwordx2 v[18:19], v[10:11], off
	v_mul_f32_e32 v10, 0xbfb8aa3b, v6
	v_mul_f32_e32 v11, 0xbfb8aa3b, v7
	v_exp_f32_e32 v10, v10
	v_exp_f32_e32 v11, v11
	v_add_f32_e32 v10, 1.0, v10
	v_add_f32_e32 v11, 1.0, v11
	v_rcp_f32_e32 v10, v10
	v_rcp_f32_e32 v11, v11
	s_nop 0
	v_pk_mul_f32 v[6:7], v[6:7], v[10:11]
	s_nop 0
	v_pk_mul_f32 v[2:3], v[2:3], v[6:7]
	v_pk_mul_f32 v[6:7], v[8:9], v[20:21] op_sel_hi:[1,0]
	v_cvt_pk_bf16_f32 v2, v2, v3
	v_mul_f32_e32 v3, 0xbfb8aa3b, v6
	v_exp_f32_e32 v3, v3
	s_nop 0
	v_add_f32_e32 v3, 1.0, v3
	v_rcp_f32_e32 v8, v3
	v_mul_f32_e32 v3, 0xbfb8aa3b, v7
	v_exp_f32_e32 v3, v3
	s_nop 0
	v_add_f32_e32 v3, 1.0, v3
	v_rcp_f32_e32 v9, v3
	s_nop 0
	v_pk_mul_f32 v[6:7], v[6:7], v[8:9]
	s_nop 0
	v_pk_mul_f32 v[4:5], v[4:5], v[6:7]
	s_nop 0
	v_cvt_pk_bf16_f32 v3, v4, v5
	global_store_dwordx2 v[18:19], v[2:3], off offset:32
	s_branch .LBB0_1944
.LBB0_1949:
	v_mov_b32_e32 v4, v140
	v_mov_b32_e32 v3, v0
	v_lshlrev_b32_e32 v9, 4, v4
	v_bfe_u32 v6, v4, 6, 1
	v_and_b32_e32 v2, 48, v9
	v_ashrrev_i32_e32 v5, 7, v4
	v_bfe_u32 v8, v4, 4, 2
	v_lshl_add_u64 v[34:35], s[28:29], 0, v[2:3]
	s_waitcnt lgkmcnt(0)
	v_lshl_add_u64 v[36:37], s[10:11], 0, v[2:3]
	v_lshlrev_b32_e32 v2, 6, v6
	v_and_b32_e32 v7, 15, v4
	v_lshlrev_b32_e32 v49, 11, v5
	v_lshlrev_b32_e32 v38, 3, v8
	v_lshl_add_u64 v[2:3], s[46:47], 0, v[2:3]
	v_mov_b32_e32 v39, v0
	v_lshlrev_b32_e32 v50, 6, v7
	v_lshl_add_u64 v[40:41], v[2:3], 0, v[38:39]
	v_and_b32_e32 v10, 1, v140
	v_mul_u32_u24_e32 v10, 0x15c0, v10
	v_bfe_u32 v11, v140, 6, 1
	v_lshlrev_b32_e32 v11, 6, v11
	v_sub_u32_e32 v10, v11, v10
	v_ashrrev_i32_e32 v11, 31, v10
	v_lshl_add_u64 v[40:41], v[40:41], 0, v[10:11]
	v_add_u32_e32 v2, 0, v49
	v_lshlrev_b32_e32 v3, 4, v8
	v_lshl_or_b32 v51, v5, 5, v7
	v_lshlrev_b32_e32 v39, 12, v6
	v_add_u32_e32 v5, 0, v3
	v_add3_u32 v52, v2, v50, v3
	v_and_b32_e32 v2, 3, v4
	v_readlane_b32 s2, v253, 0
	v_add_u32_e32 v6, v5, v50
	v_add_u32_e32 v5, v5, v39
	v_lshlrev_b32_e32 v2, 4, v2
	v_mov_b32_e32 v3, v0
	v_readlane_b32 s3, v253, 1
	v_ashrrev_i32_e32 v1, 2, v4
	v_add_u32_e32 v48, 0, v9
	v_lshl_add_u64 v[42:43], s[2:3], 0, v[2:3]
	s_mov_b32 s2, 0
	v_add_u32_e32 v53, v5, v50
	v_add_u32_e32 v54, v6, v39
	s_mov_b32 s4, 0
	s_branch .LBB0_1951

; template <int EPI, int MF>
; __device__ __forceinline__ void gemm_part(const u16* __restrict__ A, int lda, const u16* __restrict__ Bt, int K, int ntn, GemmEpi ep, char* smem,
;                                           int mbase, int mrows) {
;     ...
;   for (int q = xcd; q * nbx < total; q += (MF == 2) ? 1 : 8) {
;     const int L = q * nbx + li;
;     if (L >= total) continue;
;     const int g = L / (8 * ntn), rr = L % (8 * ntn);
;     const int rows = min(8, ntm - 8 * g);
;     const int tm = 8 * g + rr % rows, tn = rr / rows;
;     const int row0 = mbase + tm * BM, col0 = tn * 128;
;     f32x4 acc[MF][4];
; #pragma unroll
;     for (int m = 0; m < MF; ++m)
; #pragma unroll
;       for (int n = 0; n < 4; ++n) acc[m][n] = (f32x4){0.f, 0.f, 0.f, 0.f};
;     const u16* gA = A + (size_t)(row0 + (tid >> 2)) * lda + (tid & 3) * 8;
;     const u16* gB = Bt + (size_t)(col0 + (tid >> 2)) * K + (tid & 3) * 8;
;     ...
;     GEMM_ISSUE(0);
;     GEMM_ISSUE(1);
;     for (int kt = 0; kt < nk; ++kt) {
;       if (kt + 1 < nk) {
;         if (MF == 8) asm volatile("s_waitcnt vmcnt(6)" ::: "memory");
;         else asm volatile("s_waitcnt vmcnt(3)" ::: "memory");
;       } else asm volatile("s_waitcnt vmcnt(0)" ::: "memory");
;       asm volatile("s_waitcnt lgkmcnt(0)" ::: "memory");
;       __builtin_amdgcn_s_barrier();
;       const u16* a_ = sbase + (kt % 3) * STG;
;       const u16* b_ = a_ + BM * 32;
;       bf16x8 bfr[4], afc[2], afn[2];
;       const u16* ap_ = a_ + (wr * (16 * MF) + fr) * 32 + fq * 8;
; #pragma unroll
;       for (int n = 0; n < 4; ++n) bfr[n] = rd_std(b_ + (wc * 64 + n * 16 + fr) * 32 + fq * 8);
;       afc[0] = rd_std(ap_); afc[1] = rd_std(ap_ + 16 * 32);
;       __builtin_amdgcn_sched_barrier(0);
;       if (kt + 2 < nk) GEMM_ISSUE(kt + 2);
.LBB0_1951:
	s_add_i32 s2, s2, s64
	s_cmpk_gt_i32 s2, 0x15f
	s_cbranch_scc1 .LBB0_1950
	s_mul_hi_i32 s3, s2, 0x2e8ba2e9
	s_lshr_b32 s5, s3, 31
	s_ashr_i32 s3, s3, 6
	s_add_i32 s3, s3, s5
	s_mul_i32 s5, s3, 0x160
	s_sub_i32 s2, s2, s5
	s_sext_i32_i16 s5, s2
	s_bfe_u32 s5, s5, 0x3001c
	s_add_i32 s5, s2, s5
	s_sext_i32_i16 s8, s5
	s_and_b32 s5, s5, 0xfff8
	s_sub_i32 s2, s2, s5
	s_sext_i32_i16 s2, s2
	s_lshl_b32 s3, s3, 9
	s_lshl_b32 s2, s2, 6
	s_add_i32 s5, s3, s2
	s_ashr_i32 s8, s8, 3
	s_add_i32 s5, s5, 0x10000
	v_lshl_add_u32 v6, s8, 7, v1
	v_add_u32_e32 v2, s5, v1
	v_ashrrev_i32_e32 v7, 31, v6
	v_ashrrev_i32_e32 v3, 31, v2
	v_lshlrev_b64 v[6:7], 11, v[6:7]
	v_lshlrev_b64 v[2:3], 11, v[2:3]
	v_lshl_add_u64 v[44:45], v[36:37], 0, v[6:7]
	v_lshlrev_b32_e32 v255, 1, v44
	v_bfi_b32 v255, s100, v255, v44
	v_lshrrev_b32_e32 v44, 5, v44
	v_bfi_b32 v44, 64, v44, v255
	v_readfirstlane_b32 s2, v48
	v_add_u32_e32 v6, 0x1000, v48
	v_lshl_add_u64 v[4:5], v[34:35], 0, v[2:3]
	v_lshlrev_b32_e32 v255, 1, v4
	v_bfi_b32 v255, s100, v255, v4
	v_lshrrev_b32_e32 v4, 5, v4
	v_bfi_b32 v4, 64, v4, v255
	s_mov_b32 m0, s2
	v_readfirstlane_b32 s2, v6
	global_load_lds_dwordx4 v[4:5], off
	s_mov_b32 m0, s2
	s_mov_b64 s[2:3], 0x20000
	v_add_u32_e32 v8, 0x2000, v48
	v_lshl_add_u64 v[6:7], v[44:45], 0, s[2:3]
	v_readfirstlane_b32 s2, v8
	global_load_lds_dwordx4 v[44:45], off
	s_mov_b32 m0, s2
	v_lshl_add_u64 v[4:5], v[4:5], 0, 64
	v_lshl_add_u64 v[4:5], v[4:5], 0, 64
	global_load_lds_dwordx4 v[6:7], off
	v_add_u32_e32 v6, 0x3000, v48
	v_lshl_add_u64 v[46:47], v[42:43], 0, v[2:3]
	v_lshlrev_b32_e32 v255, 1, v46
	v_bfi_b32 v255, s100, v255, v46
	v_lshrrev_b32_e32 v46, 5, v46
	v_bfi_b32 v46, 64, v46, v255
	v_lshl_add_u64 v[46:47], v[46:47], 0, 64
	v_lshl_add_u64 v[46:47], v[46:47], 0, 64
	v_readfirstlane_b32 s2, v6
	v_add_u32_e32 v6, 0x4000, v48
	s_mov_b32 m0, s2
	v_readfirstlane_b32 s2, v6
	global_load_lds_dwordx4 v[4:5], off
	v_lshl_add_u64 v[4:5], v[44:45], 0, 64
	v_lshl_add_u64 v[4:5], v[4:5], 0, 64
	s_mov_b32 m0, s2
	s_mov_b64 s[2:3], 0x20080
	v_add_u32_e32 v6, 0x5000, v48
	global_load_lds_dwordx4 v[4:5], off
	v_lshl_add_u64 v[4:5], v[44:45], 0, s[2:3]
	v_readfirstlane_b32 s2, v6
	s_mov_b32 m0, s2
	v_mov_b32_e32 v2, 0
	global_load_lds_dwordx4 v[4:5], off
	v_lshl_add_u64 v[44:45], v[44:45], 0, 64
	v_lshl_add_u64 v[44:45], v[44:45], 0, 64
	s_mov_b32 s9, 3
	s_mov_b64 s[2:3], 0
	v_mov_b32_e32 v3, v2
	v_mov_b32_e32 v4, v2
	v_mov_b32_e32 v5, v2
	v_mov_b32_e32 v6, v2
	v_mov_b32_e32 v7, v2
	v_mov_b32_e32 v8, v2
	v_mov_b32_e32 v9, v2
	v_mov_b32_e32 v10, v2
	v_mov_b32_e32 v11, v2
	v_mov_b32_e32 v12, v2
	v_mov_b32_e32 v13, v2
	v_mov_b32_e32 v14, v2
	v_mov_b32_e32 v15, v2
	v_mov_b32_e32 v16, v2
	v_mov_b32_e32 v17, v2
	v_mov_b32_e32 v18, v2
	v_mov_b32_e32 v19, v2
	v_mov_b32_e32 v20, v2
	v_mov_b32_e32 v21, v2
	v_mov_b32_e32 v22, v2
	v_mov_b32_e32 v23, v2
	v_mov_b32_e32 v24, v2
	v_mov_b32_e32 v25, v2
	v_mov_b32_e32 v26, v2
	v_mov_b32_e32 v27, v2
	v_mov_b32_e32 v28, v2
	v_mov_b32_e32 v29, v2
	v_mov_b32_e32 v30, v2
	v_mov_b32_e32 v31, v2
	v_mov_b32_e32 v32, v2
	v_mov_b32_e32 v33, v2
.LBB0_1953:
	s_add_i32 s10, s9, 0xfffd
	s_and_b32 s11, s10, 0xff
	s_mulk_i32 s11, 0xab
	s_bfe_u32 s11, s11, 0x70009
	s_mul_i32 s11, s11, 3
	s_sub_i32 s11, s10, s11
	s_and_b32 s11, s11, 0xff
	s_mulk_i32 s11, 0x3000
	s_add_i32 s11, s11, 0
	v_lshlrev_b32_e32 v86, 1, v38
	v_add_u32_e32 v56, s11, v86
	s_waitcnt vmcnt(3)
	v_add3_u32 v68, v56, v39, v50
	s_waitcnt lgkmcnt(0)
	s_barrier
	v_add_u32_e32 v55, s11, v49
	ds_read_b128 v[56:59], v68 offset:4096
	ds_read_b128 v[60:63], v68 offset:5120
	ds_read_b128 v[64:67], v68 offset:6144
	ds_read_b128 v[68:71], v68 offset:7168
	v_add3_u32 v55, v55, v50, v86
	ds_read_b128 v[72:75], v55
	ds_read_b128 v[76:79], v55 offset:1024
	s_mul_i32 s11, s9, 0xab
	s_add_i32 s12, s11, 0xff55
	s_bfe_u32 s12, s12, 0x70009
	s_mul_i32 s12, s12, 3
	s_not_b32 s12, s12
	s_add_i32 s12, s12, s9
	s_and_b32 s12, s12, 0xff
	s_mulk_i32 s12, 0x3000
	v_add_u32_e32 v55, s12, v48
	v_lshl_add_u64 v[80:81], s[2:3], 1, v[46:47]
	v_readfirstlane_b32 s12, v55
	v_lshl_add_u64 v[82:83], v[80:81], 0, s[30:31]
	s_mov_b32 m0, s12
	v_add_u32_e32 v87, 0x1000, v55
	global_load_lds_dwordx4 v[82:83], off
	v_lshl_add_u64 v[82:83], s[2:3], 1, v[44:45]
	v_readfirstlane_b32 s12, v87
	v_add_u32_e32 v55, 0x2000, v55
	v_lshl_add_u64 v[84:85], v[82:83], 0, s[74:75]
	s_mov_b32 m0, s12
	v_readfirstlane_b32 s12, v55
	global_load_lds_dwordx4 v[84:85], off
	v_lshl_add_u64 v[84:85], v[82:83], 0, s[92:93]
	s_mov_b32 m0, s12
	s_nop 0
	global_load_lds_dwordx4 v[84:85], off
	s_waitcnt lgkmcnt(0)
	v_mfma_f32_16x16x32_bf16 v[30:33], v[56:59], v[72:75], v[30:33]
	v_mfma_f32_16x16x32_bf16 v[26:29], v[60:63], v[72:75], v[26:29]
	v_mfma_f32_16x16x32_bf16 v[22:25], v[64:67], v[72:75], v[22:25]
	v_mfma_f32_16x16x32_bf16 v[18:21], v[68:71], v[72:75], v[18:21]
	v_mfma_f32_16x16x32_bf16 v[14:17], v[56:59], v[76:79], v[14:17]
	v_mfma_f32_16x16x32_bf16 v[10:13], v[60:63], v[76:79], v[10:13]
	v_mfma_f32_16x16x32_bf16 v[6:9], v[64:67], v[76:79], v[6:9]
	v_mfma_f32_16x16x32_bf16 v[2:5], v[68:71], v[76:79], v[2:5]
	s_or_b32 s10, s10, 1
	s_and_b32 s12, s10, 0xff
	s_mulk_i32 s12, 0xab
	s_bfe_u32 s12, s12, 0x70009
	s_mul_i32 s12, s12, 3
	s_sub_i32 s10, s10, s12
	s_and_b32 s10, s10, 0xff
	s_mulk_i32 s10, 0x3000
	s_add_i32 s10, s10, 0
	v_add_u32_e32 v56, s10, v86
	s_waitcnt vmcnt(3)
	v_add3_u32 v68, v56, v39, v50
	s_waitcnt lgkmcnt(0)
	s_barrier
; #define MFMA(a, b, c) __builtin_amdgcn_mfma_f32_16x16x32_bf16((a), (b), (c), 0, 0, 0)
; template <int EPI, int MF>
; __device__ __forceinline__ void gemm_part(const u16* __restrict__ A, int lda, const u16* __restrict__ Bt, int K, int ntn, GemmEpi ep, char* smem,
;                                           int mbase, int mrows) {
;     ...
;     for (int kt = 0; kt < nk; ++kt) {
;       if (kt + 1 < nk) {
;         if (MF == 8) asm volatile("s_waitcnt vmcnt(6)" ::: "memory");
;         else asm volatile("s_waitcnt vmcnt(3)" ::: "memory");
;       } else asm volatile("s_waitcnt vmcnt(0)" ::: "memory");
;       asm volatile("s_waitcnt lgkmcnt(0)" ::: "memory");
;       __builtin_amdgcn_s_barrier();
;       const u16* a_ = sbase + (kt % 3) * STG;
;       const u16* b_ = a_ + BM * 32;
;       bf16x8 bfr[4], afc[2], afn[2];
;       const u16* ap_ = a_ + (wr * (16 * MF) + fr) * 32 + fq * 8;
; #pragma unroll
;       for (int n = 0; n < 4; ++n) bfr[n] = rd_std(b_ + (wc * 64 + n * 16 + fr) * 32 + fq * 8);
;       afc[0] = rd_std(ap_); afc[1] = rd_std(ap_ + 16 * 32);
;       __builtin_amdgcn_sched_barrier(0);
;       if (kt + 2 < nk) GEMM_ISSUE(kt + 2);
;       __builtin_amdgcn_sched_barrier(0);
; #pragma unroll
;       for (int mh = 0; mh < MF / 2; ++mh) {
;         if (mh + 1 < MF / 2) {
;           afn[0] = rd_std(ap_ + ((mh + 1) * 2) * 16 * 32);
;           afn[1] = rd_std(ap_ + ((mh + 1) * 2 + 1) * 16 * 32);
;         }
;         __builtin_amdgcn_sched_barrier(0);
; #pragma unroll
;         for (int m = 0; m < 2; ++m)
; #pragma unroll
;           for (int n = 0; n < 4; ++n) acc[mh * 2 + m][n] = MFMA(bfr[n], afc[m], acc[mh * 2 + m][n]);
;         __builtin_amdgcn_sched_barrier(0);
;         afc[0] = afn[0]; afc[1] = afn[1];
;       }
;     }
	v_add_u32_e32 v55, s10, v49
	ds_read_b128 v[56:59], v68 offset:4096
	ds_read_b128 v[60:63], v68 offset:5120
	ds_read_b128 v[64:67], v68 offset:6144
	ds_read_b128 v[68:71], v68 offset:7168
	v_add3_u32 v55, v55, v50, v86
	ds_read_b128 v[72:75], v55
	ds_read_b128 v[76:79], v55 offset:1024
	s_bfe_u32 s10, s11, 0x70009
	s_mul_i32 s10, s10, 3
	s_sub_i32 s10, s9, s10
	s_and_b32 s10, s10, 0xff
	s_mul_i32 s12, s10, 0x3000
	s_mov_b64 s[10:11], 0x162c00c0
	v_add_u32_e32 v55, s12, v48
	v_lshl_add_u64 v[80:81], v[80:81], 0, s[10:11]
	v_lshl_add_u64 v[80:81], v[80:81], 0, 64
	v_readfirstlane_b32 s10, v55
	v_add_u32_e32 v84, 0x1000, v55
	s_mov_b32 m0, s10
	v_readfirstlane_b32 s10, v84
	v_add_u32_e32 v55, 0x2000, v55
	global_load_lds_dwordx4 v[80:81], off
	v_lshl_add_u64 v[80:81], v[82:83], 0, s[52:53]
	v_lshl_add_u64 v[80:81], v[80:81], 0, 64
	s_mov_b32 m0, s10
	v_readfirstlane_b32 s10, v55
	global_load_lds_dwordx4 v[80:81], off
	v_lshl_add_u64 v[80:81], v[82:83], 0, s[54:55]
	v_lshl_add_u64 v[80:81], v[80:81], 0, 64
	s_mov_b32 m0, s10
	s_nop 0
	global_load_lds_dwordx4 v[80:81], off
	s_waitcnt lgkmcnt(0)
	v_mfma_f32_16x16x32_bf16 v[30:33], v[56:59], v[72:75], v[30:33]
	v_mfma_f32_16x16x32_bf16 v[26:29], v[60:63], v[72:75], v[26:29]
	v_mfma_f32_16x16x32_bf16 v[22:25], v[64:67], v[72:75], v[22:25]
	v_mfma_f32_16x16x32_bf16 v[18:21], v[68:71], v[72:75], v[18:21]
	v_mfma_f32_16x16x32_bf16 v[14:17], v[56:59], v[76:79], v[14:17]
	v_mfma_f32_16x16x32_bf16 v[10:13], v[60:63], v[76:79], v[10:13]
	v_mfma_f32_16x16x32_bf16 v[6:9], v[64:67], v[76:79], v[6:9]
	v_mfma_f32_16x16x32_bf16 v[2:5], v[68:71], v[76:79], v[2:5]
	s_add_u32 s2, s2, 0x80
	s_addc_u32 s3, s3, 0
	s_add_i32 s9, s9, 2
	s_cmpk_eq_i32 s2, 0x780
	s_cbranch_scc0 .LBB0_1953
	s_waitcnt vmcnt(3)
	s_waitcnt lgkmcnt(0)
	s_barrier
	ds_read_b128 v[44:47], v53 offset:4096
	ds_read_b128 v[56:59], v53 offset:5120
	ds_read_b128 v[60:63], v53 offset:6144
	ds_read_b128 v[64:67], v53 offset:7168
	ds_read_b128 v[68:71], v52
	ds_read_b128 v[72:75], v52 offset:1024
	s_waitcnt lgkmcnt(0)
	v_mfma_f32_16x16x32_bf16 v[30:33], v[44:47], v[68:71], v[30:33]
	v_mfma_f32_16x16x32_bf16 v[26:29], v[56:59], v[68:71], v[26:29]
	v_mfma_f32_16x16x32_bf16 v[22:25], v[60:63], v[68:71], v[22:25]
	v_mfma_f32_16x16x32_bf16 v[18:21], v[64:67], v[68:71], v[18:21]
	v_mfma_f32_16x16x32_bf16 v[14:17], v[44:47], v[72:75], v[14:17]
	v_mfma_f32_16x16x32_bf16 v[10:13], v[56:59], v[72:75], v[10:13]
	v_mfma_f32_16x16x32_bf16 v[44:47], v[60:63], v[72:75], v[6:9]
	v_mfma_f32_16x16x32_bf16 v[2:5], v[64:67], v[72:75], v[2:5]
	s_waitcnt vmcnt(0)
	s_waitcnt lgkmcnt(0)
	s_barrier
	s_nop 0
	ds_read_b128 v[6:9], v54 offset:16384
	ds_read_b128 v[56:59], v54 offset:17408
	ds_read_b128 v[60:63], v54 offset:18432
	ds_read_b128 v[64:67], v54 offset:19456
	ds_read_b128 v[68:71], v52 offset:12288
	ds_read_b128 v[72:75], v52 offset:13312
	s_waitcnt lgkmcnt(0)
	v_mfma_f32_16x16x32_bf16 v[76:79], v[6:9], v[68:71], v[30:33]
	v_mfma_f32_16x16x32_bf16 v[80:83], v[56:59], v[68:71], v[26:29]
	v_mfma_f32_16x16x32_bf16 v[84:87], v[60:63], v[68:71], v[22:25]
	v_mfma_f32_16x16x32_bf16 v[18:21], v[64:67], v[68:71], v[18:21]
	v_mfma_f32_16x16x32_bf16 v[14:17], v[6:9], v[72:75], v[14:17]
	v_mfma_f32_16x16x32_bf16 v[6:9], v[56:59], v[72:75], v[10:13]
	v_mfma_f32_16x16x32_bf16 v[10:13], v[60:63], v[72:75], v[44:47]
	v_mfma_f32_16x16x32_bf16 v[2:5], v[64:67], v[72:75], v[2:5]
	s_lshl_b32 s2, s8, 6
	s_ashr_i32 s3, s2, 31
	s_waitcnt vmcnt(0)
	s_barrier
; __device__ __forceinline__ float siluf_(float x) { return x * __builtin_amdgcn_rcpf(1.f + __expf(-x)); }
; template <int EPI, int MF>
; __device__ __forceinline__ void gemm_part(const u16* __restrict__ A, int lda, const u16* __restrict__ Bt, int K, int ntn, GemmEpi ep, char* smem,
;                                           int mbase, int mrows) {
;     ...
;     for (int m = 0; m < MF; ++m) {
;       if (EPI == EPI_SWIGLU || (m & 1) == 0) __builtin_amdgcn_sched_barrier(0);
;       const int row = row0 + wr * (16 * MF) + m * 16 + fr;
;       const int cb = col0 + wc * 64 + 4 * fq;
;       float rstd = 1.f;
;       if (EPI != EPI_RESID) { if (ep.rss_in) rstd = rsqrtf(ep.rss_in[row] * (1.f / DM) + 1e-6f); }
;       if (EPI == EPI_SWIGLU) {
; #pragma unroll
;         for (int n = 0; n < 2; ++n) {
;           bf16x4 o;
; #pragma unroll
;           for (int jj = 0; jj < 4; ++jj) o[jj] = (short)f2bf(siluf_(acc[m][n][jj] * rstd) * (acc[m][n + 2][jj] * rstd));
;           *(bf16x4*)(ep.outb + (size_t)row * FF + (col0 >> 1) + wc * 32 + n * 16 + 4 * fq) = o;
;         }
	v_add_u32_e32 v24, s5, v51
	v_lshl_add_u64 v[22:23], s[2:3], 2, v[40:41]
	v_readlane_b32 s2, v252, 9
	v_ashrrev_i32_e32 v25, 31, v24
	v_readlane_b32 s3, v252, 10
	s_nop 1
	v_lshl_add_u64 v[26:27], v[24:25], 2, s[2:3]
	global_load_dword v25, v[26:27], off
	s_waitcnt vmcnt(0)
	v_fmamk_f32 v25, v25, 0x3a800000, v142
	v_cmp_gt_f32_e32 vcc, s69, v25
	v_mul_f32_e32 v28, 0x4b800000, v25
	s_nop 0
	v_cndmask_b32_e32 v25, v25, v28, vcc
	v_rsq_f32_e32 v25, v25
	s_nop 0
	v_mul_f32_e32 v28, 0x45800000, v25
	v_cndmask_b32_e32 v30, v25, v28, vcc
	v_pk_mul_f32 v[32:33], v[76:77], v[30:31] op_sel_hi:[1,0]
	v_mad_i64_i32 v[28:29], s[2:3], v24, s33, v[22:23]
	v_mul_f32_e32 v25, 0xbfb8aa3b, v32
	v_exp_f32_e32 v25, v25
	v_pk_mul_f32 v[18:19], v[18:19], v[30:31] op_sel_hi:[1,0]
	v_pk_mul_f32 v[20:21], v[20:21], v[30:31] op_sel_hi:[1,0]
	v_add_f32_e32 v25, 1.0, v25
	v_rcp_f32_e32 v44, v25
	v_mul_f32_e32 v25, 0xbfb8aa3b, v33
	v_exp_f32_e32 v25, v25
	s_nop 0
	v_add_f32_e32 v25, 1.0, v25
	v_rcp_f32_e32 v45, v25
	s_nop 0
	v_pk_mul_f32 v[32:33], v[32:33], v[44:45]
	v_pk_mul_f32 v[44:45], v[84:85], v[30:31] op_sel_hi:[1,0]
	s_nop 0
	v_pk_mul_f32 v[32:33], v[44:45], v[32:33]
	v_pk_mul_f32 v[44:45], v[78:79], v[30:31] op_sel_hi:[1,0]
	v_cvt_pk_bf16_f32 v32, v32, v33
	v_mul_f32_e32 v25, 0xbfb8aa3b, v44
	v_exp_f32_e32 v25, v25
	s_nop 0
	v_add_f32_e32 v25, 1.0, v25
	v_rcp_f32_e32 v46, v25
	v_mul_f32_e32 v25, 0xbfb8aa3b, v45
	v_exp_f32_e32 v25, v25
	s_nop 0
	v_add_f32_e32 v25, 1.0, v25
	v_rcp_f32_e32 v47, v25
	s_nop 0
	v_pk_mul_f32 v[44:45], v[44:45], v[46:47]
	v_pk_mul_f32 v[46:47], v[86:87], v[30:31] op_sel_hi:[1,0]
	s_nop 0
	v_pk_mul_f32 v[44:45], v[46:47], v[44:45]
	s_nop 0
	v_cvt_pk_bf16_f32 v33, v44, v45
	global_store_dwordx2 v[28:29], v[32:33], off
	v_pk_mul_f32 v[32:33], v[80:81], v[30:31] op_sel_hi:[1,0]
	s_nop 0
	v_mul_f32_e32 v25, 0xbfb8aa3b, v32
	v_exp_f32_e32 v25, v25
	s_nop 0
	v_add_f32_e32 v25, 1.0, v25
	v_rcp_f32_e32 v44, v25
	v_mul_f32_e32 v25, 0xbfb8aa3b, v33
	v_exp_f32_e32 v25, v25
	s_nop 0
	v_add_f32_e32 v25, 1.0, v25
	v_rcp_f32_e32 v45, v25
	s_nop 0
	v_pk_mul_f32 v[32:33], v[32:33], v[44:45]
	s_nop 0
	v_pk_mul_f32 v[18:19], v[18:19], v[32:33]
	v_pk_mul_f32 v[32:33], v[82:83], v[30:31] op_sel_hi:[1,0]
	v_cvt_pk_bf16_f32 v18, v18, v19
	v_mul_f32_e32 v19, 0xbfb8aa3b, v32
	v_exp_f32_e32 v19, v19
	s_nop 0
	v_add_f32_e32 v19, 1.0, v19
	v_rcp_f32_e32 v44, v19
	v_mul_f32_e32 v19, 0xbfb8aa3b, v33
	v_exp_f32_e32 v19, v19
	s_nop 0
	v_add_f32_e32 v19, 1.0, v19
	v_rcp_f32_e32 v45, v19
	s_nop 0
	v_pk_mul_f32 v[32:33], v[32:33], v[44:45]
	s_nop 0
	v_pk_mul_f32 v[20:21], v[20:21], v[32:33]
	s_nop 0
	v_cvt_pk_bf16_f32 v19, v20, v21
	global_store_dwordx2 v[28:29], v[18:19], off offset:32
	global_load_dword v19, v[26:27], off offset:64
	v_or_b32_e32 v18, 16, v24
	s_waitcnt vmcnt(0)
	v_fmamk_f32 v19, v19, 0x3a800000, v142
	v_cmp_gt_f32_e32 vcc, s69, v19
	v_mul_f32_e32 v20, 0x4b800000, v19
	s_nop 0
	v_cndmask_b32_e32 v19, v19, v20, vcc
	v_rsq_f32_e32 v19, v19
	s_nop 0
	v_mul_f32_e32 v20, 0x45800000, v19
	v_cndmask_b32_e32 v20, v19, v20, vcc
	v_pk_mul_f32 v[14:15], v[14:15], v[20:21] op_sel_hi:[1,0]
	v_mad_i64_i32 v[18:19], s[2:3], v18, s33, v[22:23]
	v_mul_f32_e32 v21, 0xbfb8aa3b, v14
	v_exp_f32_e32 v21, v21
	s_nop 0
	v_add_f32_e32 v21, 1.0, v21
	v_rcp_f32_e32 v22, v21
	v_mul_f32_e32 v21, 0xbfb8aa3b, v15
	v_exp_f32_e32 v21, v21
	s_nop 0
	v_add_f32_e32 v21, 1.0, v21
	v_rcp_f32_e32 v23, v21
	v_pk_mul_f32 v[10:11], v[10:11], v[20:21] op_sel_hi:[1,0]
	v_pk_mul_f32 v[12:13], v[12:13], v[20:21] op_sel_hi:[1,0]
	v_pk_mul_f32 v[6:7], v[6:7], v[20:21] op_sel_hi:[1,0]
	v_pk_mul_f32 v[14:15], v[14:15], v[22:23]
	v_pk_mul_f32 v[2:3], v[2:3], v[20:21] op_sel_hi:[1,0]
	v_pk_mul_f32 v[10:11], v[10:11], v[14:15]
	v_pk_mul_f32 v[14:15], v[16:17], v[20:21] op_sel_hi:[1,0]
	v_cvt_pk_bf16_f32 v10, v10, v11
	v_mul_f32_e32 v11, 0xbfb8aa3b, v14
	v_exp_f32_e32 v11, v11
	v_pk_mul_f32 v[4:5], v[4:5], v[20:21] op_sel_hi:[1,0]
	v_add_f32_e32 v11, 1.0, v11
	v_rcp_f32_e32 v16, v11
	v_mul_f32_e32 v11, 0xbfb8aa3b, v15
	v_exp_f32_e32 v11, v11
	s_nop 0
	v_add_f32_e32 v11, 1.0, v11
	v_rcp_f32_e32 v17, v11
	s_nop 0
	v_pk_mul_f32 v[14:15], v[14:15], v[16:17]
	s_nop 0
	v_pk_mul_f32 v[12:13], v[12:13], v[14:15]
	s_nop 0
	v_cvt_pk_bf16_f32 v11, v12, v13
	global_store_dwordx2 v[18:19], v[10:11], off
	v_mul_f32_e32 v10, 0xbfb8aa3b, v6
	v_mul_f32_e32 v11, 0xbfb8aa3b, v7
	v_exp_f32_e32 v10, v10
	v_exp_f32_e32 v11, v11
	v_add_f32_e32 v10, 1.0, v10
	v_add_f32_e32 v11, 1.0, v11
	v_rcp_f32_e32 v10, v10
	v_rcp_f32_e32 v11, v11
	s_nop 0
	v_pk_mul_f32 v[6:7], v[6:7], v[10:11]
	s_nop 0
	v_pk_mul_f32 v[2:3], v[2:3], v[6:7]
	v_pk_mul_f32 v[6:7], v[8:9], v[20:21] op_sel_hi:[1,0]
	v_cvt_pk_bf16_f32 v2, v2, v3
	v_mul_f32_e32 v3, 0xbfb8aa3b, v6
	v_exp_f32_e32 v3, v3
	s_nop 0
	v_add_f32_e32 v3, 1.0, v3
	v_rcp_f32_e32 v8, v3
	v_mul_f32_e32 v3, 0xbfb8aa3b, v7
	v_exp_f32_e32 v3, v3
	s_nop 0
	v_add_f32_e32 v3, 1.0, v3
	v_rcp_f32_e32 v9, v3
	s_nop 0
	v_pk_mul_f32 v[6:7], v[6:7], v[8:9]
	s_nop 0
	v_pk_mul_f32 v[4:5], v[4:5], v[6:7]
	s_nop 0
	v_cvt_pk_bf16_f32 v3, v4, v5
	global_store_dwordx2 v[18:19], v[2:3], off offset:32
	s_branch .LBB0_1950

; template <int EPI, int MF>
; __device__ __forceinline__ void gemm_part(const u16* __restrict__ A, int lda, const u16* __restrict__ Bt, int K, int ntn, GemmEpi ep, char* smem,
;                                           int mbase, int mrows) {
;     ...
;   for (int q = xcd; q * nbx < total; q += (MF == 2) ? 1 : 8) {
;     const int L = q * nbx + li;
;     if (L >= total) continue;
;     const int g = L / (8 * ntn), rr = L % (8 * ntn);
;     const int rows = min(8, ntm - 8 * g);
;     const int tm = 8 * g + rr % rows, tn = rr / rows;
;     const int row0 = mbase + tm * BM, col0 = tn * 128;
;     f32x4 acc[MF][4];
; #pragma unroll
;     for (int m = 0; m < MF; ++m)
; #pragma unroll
;       for (int n = 0; n < 4; ++n) acc[m][n] = (f32x4){0.f, 0.f, 0.f, 0.f};
;     const u16* gA = A + (size_t)(row0 + (tid >> 2)) * lda + (tid & 3) * 8;
;     const u16* gB = Bt + (size_t)(col0 + (tid >> 2)) * K + (tid & 3) * 8;
;     ...
;     GEMM_ISSUE(0);
;     GEMM_ISSUE(1);
.LBB0_1996:
	s_add_i32 s4, s4, s63
	s_cmpk_gt_u32 s4, 0x7ff
	s_cbranch_scc1 .LBB0_1995
	s_lshl_b32 s5, s19, 5
	s_and_b32 s5, s5, 0xf800
	v_add_u32_e32 v4, s5, v163
	s_waitcnt lgkmcnt(0)
	v_mov_b64_e32 v[2:3], s[46:47]
	s_and_b32 s5, s18, 0x380
	v_mad_i64_i32 v[136:137], s[10:11], v4, s33, v[2:3]
	v_bfe_u32 v12, v140, 2, 1
	v_mul_u32_u24_e32 v12, 0x15c0, v12
	v_sub_u32_e32 v12, 0, v12
	v_ashrrev_i32_e32 v13, 31, v12
	v_lshl_add_u64 v[136:137], v[136:137], 0, v[12:13]
	v_lshl_add_u64 v[136:137], v[136:137], 0, 64
	v_lshl_add_u64 v[136:137], v[136:137], 0, 64
	v_add_u32_e32 v4, s5, v1
	v_mov_b64_e32 v[2:3], s[16:17]
	v_mad_i64_i32 v[138:139], s[10:11], v4, s33, v[2:3]
	v_lshl_add_u64 v[138:139], v[138:139], 0, v[12:13]
	v_lshl_add_u64 v[138:139], v[138:139], 0, 64
	v_lshl_add_u64 v[138:139], v[138:139], 0, 64
	s_lshr_b32 s5, s4, 3
	s_and_b32 s5, s5, 0xf8
	s_and_b32 s10, s4, 7
	s_or_b32 s5, s5, s10
	s_lshl_b32 s10, s4, 4
	s_lshl_b32 s4, s5, 8
	v_add_u32_e32 v2, s4, v1
	v_readfirstlane_b32 s5, v154
	v_add_u32_e32 v7, 0x1000, v154
	v_mad_i64_i32 v[2:3], s[12:13], v2, s33, v[130:131]
	v_lshl_add_u64 v[2:3], v[2:3], 0, v[12:13]
	s_mov_b32 m0, s5
	s_mov_b64 s[22:23], 0x58000
	v_readfirstlane_b32 s5, v7
	v_add_u32_e32 v7, 0x2000, v154
	global_load_lds_dwordx4 v[2:3], off
	v_lshl_add_u64 v[4:5], v[2:3], 0, s[22:23]
	s_mov_b32 m0, s5
	s_mov_b64 s[12:13], 0xb0000
	v_readfirstlane_b32 s5, v7
	v_add_u32_e32 v7, 0x3000, v154
	s_and_b32 s10, s10, 0x380
	global_load_lds_dwordx4 v[4:5], off
	v_lshl_add_u64 v[4:5], v[2:3], 0, s[12:13]
	s_mov_b32 m0, s5
	s_mov_b64 s[12:13], 0x108000
	v_readfirstlane_b32 s5, v7
	v_add_u32_e32 v6, s10, v1
	global_load_lds_dwordx4 v[4:5], off
	v_lshl_add_u64 v[4:5], v[2:3], 0, s[12:13]
	s_mov_b32 m0, s5
	v_add_u32_e32 v8, 0x5000, v154
	global_load_lds_dwordx4 v[4:5], off
	v_mad_i64_i32 v[4:5], s[12:13], v6, s33, v[132:133]
	v_lshl_add_u64 v[4:5], v[4:5], 0, v[12:13]
	v_add_u32_e32 v6, 0x4000, v154
	s_mov_b64 s[12:13], 0x58040
	v_readfirstlane_b32 s5, v6
	s_mov_b32 m0, s5
	v_readfirstlane_b32 s5, v8
	v_add_u32_e32 v8, 0x6000, v154
	global_load_lds_dwordx4 v[4:5], off
	v_lshl_add_u64 v[6:7], v[4:5], 0, s[22:23]
	s_mov_b32 m0, s5
	v_readfirstlane_b32 s5, v8
	v_add_u32_e32 v8, 0x7000, v154
	global_load_lds_dwordx4 v[6:7], off
	v_lshl_add_u64 v[6:7], v[2:3], 0, 64
	v_lshl_add_u64 v[6:7], v[6:7], 0, 64
	s_mov_b32 m0, s5
	v_readfirstlane_b32 s5, v8
	v_add_u32_e32 v8, 0x8000, v154
	global_load_lds_dwordx4 v[6:7], off
	v_lshl_add_u64 v[6:7], v[2:3], 0, s[12:13]
	v_lshl_add_u64 v[6:7], v[6:7], 0, 64
	s_mov_b32 m0, s5
	s_mov_b64 s[22:23], 0xb0040
	v_readfirstlane_b32 s5, v8
	global_load_lds_dwordx4 v[6:7], off
	v_lshl_add_u64 v[6:7], v[2:3], 0, s[22:23]
	v_lshl_add_u64 v[6:7], v[6:7], 0, 64
	s_mov_b32 m0, s5
	s_mov_b64 s[22:23], 0x108040
	global_load_lds_dwordx4 v[6:7], off
	v_add_u32_e32 v6, 0x9000, v154
	v_lshl_add_u64 v[2:3], v[2:3], 0, s[22:23]
	v_lshl_add_u64 v[2:3], v[2:3], 0, 64
	v_readfirstlane_b32 s5, v6
	v_add_u32_e32 v6, 0xa000, v154
	s_mov_b32 m0, s5
	v_readfirstlane_b32 s5, v6
	global_load_lds_dwordx4 v[2:3], off
	v_lshl_add_u64 v[2:3], v[4:5], 0, 64
	v_lshl_add_u64 v[2:3], v[2:3], 0, 64
	s_mov_b32 m0, s5
	s_mov_b32 s11, 1
	global_load_lds_dwordx4 v[2:3], off
	v_lshl_add_u64 v[2:3], v[4:5], 0, s[12:13]
	v_lshl_add_u64 v[2:3], v[2:3], 0, 64
	v_add_u32_e32 v4, 0xb000, v154
	s_mov_b32 s12, 2
	v_readfirstlane_b32 s5, v4
	s_mov_b32 m0, s5
	s_mov_b32 s5, 0
	global_load_lds_dwordx4 v[2:3], off
	v_mov_b32_e32 v2, 0
	s_mov_b32 s13, 0
	v_mov_b32_e32 v3, v2
	v_mov_b32_e32 v4, v2
	v_mov_b32_e32 v5, v2
	v_mov_b32_e32 v6, v2
	v_mov_b32_e32 v7, v2
	v_mov_b32_e32 v8, v2
	v_mov_b32_e32 v9, v2
	v_mov_b32_e32 v10, v2
	v_mov_b32_e32 v11, v2
	v_mov_b32_e32 v12, v2
	v_mov_b32_e32 v13, v2
	v_mov_b32_e32 v14, v2
	v_mov_b32_e32 v15, v2
	v_mov_b32_e32 v16, v2
	v_mov_b32_e32 v17, v2
	v_mov_b32_e32 v18, v2
	v_mov_b32_e32 v19, v2
	v_mov_b32_e32 v20, v2
	v_mov_b32_e32 v21, v2
	v_mov_b32_e32 v22, v2
	v_mov_b32_e32 v23, v2
	v_mov_b32_e32 v24, v2
	v_mov_b32_e32 v25, v2
	v_mov_b32_e32 v26, v2
	v_mov_b32_e32 v27, v2
	v_mov_b32_e32 v28, v2
	v_mov_b32_e32 v29, v2
	v_mov_b32_e32 v30, v2
	v_mov_b32_e32 v31, v2
	v_mov_b32_e32 v32, v2
	v_mov_b32_e32 v33, v2
	v_mov_b32_e32 v34, v2
	v_mov_b32_e32 v35, v2
	v_mov_b32_e32 v36, v2
	v_mov_b32_e32 v37, v2
	v_mov_b32_e32 v38, v2
	v_mov_b32_e32 v39, v2
	v_mov_b32_e32 v40, v2
	v_mov_b32_e32 v41, v2
	v_mov_b32_e32 v42, v2
	v_mov_b32_e32 v43, v2
	v_mov_b32_e32 v44, v2
	v_mov_b32_e32 v45, v2
	v_mov_b32_e32 v46, v2
	v_mov_b32_e32 v47, v2
	v_mov_b32_e32 v48, v2
	v_mov_b32_e32 v49, v2
	v_mov_b32_e32 v50, v2
	v_mov_b32_e32 v51, v2
	v_mov_b32_e32 v52, v2
	v_mov_b32_e32 v53, v2
	v_mov_b32_e32 v54, v2
	v_mov_b32_e32 v55, v2
	v_mov_b32_e32 v56, v2
	v_mov_b32_e32 v57, v2
	v_mov_b32_e32 v58, v2
	v_mov_b32_e32 v59, v2
	v_mov_b32_e32 v60, v2
	v_mov_b32_e32 v61, v2
	v_mov_b32_e32 v62, v2
	v_mov_b32_e32 v63, v2
	v_mov_b32_e32 v64, v2
	v_mov_b32_e32 v65, v2
	v_mov_b32_e32 v66, v2
	v_mov_b32_e32 v67, v2
	v_mov_b32_e32 v68, v2
	v_mov_b32_e32 v69, v2
	v_mov_b32_e32 v70, v2
	v_mov_b32_e32 v71, v2
	v_mov_b32_e32 v72, v2
	v_mov_b32_e32 v73, v2
	v_mov_b32_e32 v74, v2
	v_mov_b32_e32 v75, v2
	v_mov_b32_e32 v76, v2
	v_mov_b32_e32 v77, v2
	v_mov_b32_e32 v78, v2
	v_mov_b32_e32 v79, v2
	v_mov_b32_e32 v80, v2
	v_mov_b32_e32 v81, v2
	v_mov_b32_e32 v82, v2
	v_mov_b32_e32 v83, v2
	v_mov_b32_e32 v84, v2
	v_mov_b32_e32 v85, v2
	v_mov_b32_e32 v86, v2
	v_mov_b32_e32 v87, v2
	s_waitcnt vmcnt(0)
	v_mov_b32_e32 v88, v2
	v_mov_b32_e32 v89, v2
	v_mov_b32_e32 v90, v2
	v_mov_b32_e32 v91, v2
	v_mov_b32_e32 v92, v2
	v_mov_b32_e32 v93, v2
	v_mov_b32_e32 v94, v2
	v_mov_b32_e32 v95, v2
	v_mov_b32_e32 v96, v2
	v_mov_b32_e32 v97, v2
	v_mov_b32_e32 v98, v2
	v_mov_b32_e32 v99, v2
	v_mov_b32_e32 v100, v2
	v_mov_b32_e32 v101, v2
	v_mov_b32_e32 v102, v2
	v_mov_b32_e32 v103, v2
	v_mov_b32_e32 v104, v2
	v_mov_b32_e32 v105, v2
	v_mov_b32_e32 v106, v2
	v_mov_b32_e32 v107, v2
	v_mov_b32_e32 v108, v2
	v_mov_b32_e32 v109, v2
	v_mov_b32_e32 v110, v2
	v_mov_b32_e32 v111, v2
	v_mov_b32_e32 v112, v2
	v_mov_b32_e32 v113, v2
	v_mov_b32_e32 v114, v2
	v_mov_b32_e32 v115, v2
	v_mov_b32_e32 v116, v2
	v_mov_b32_e32 v117, v2
	v_mov_b32_e32 v118, v2
	v_mov_b32_e32 v119, v2
	v_mov_b32_e32 v120, v2
	v_mov_b32_e32 v121, v2
	v_mov_b32_e32 v122, v2
	v_mov_b32_e32 v123, v2
	v_mov_b32_e32 v124, v2
	v_mov_b32_e32 v125, v2
	v_mov_b32_e32 v126, v2
	v_mov_b32_e32 v127, v2
	v_mov_b32_e32 v128, v2
	v_mov_b32_e32 v129, v2
; #define MFMA(a, b, c) __builtin_amdgcn_mfma_f32_16x16x32_bf16((a), (b), (c), 0, 0, 0)
; template <int EPI, int MF>
; __device__ __forceinline__ void gemm_part(const u16* __restrict__ A, int lda, const u16* __restrict__ Bt, int K, int ntn, GemmEpi ep, char* smem,
;                                           int mbase, int mrows) {
;     ...
;     for (int kt = 0; kt < nk; ++kt) {
;       if (kt + 1 < nk) {
;         if (MF == 8) asm volatile("s_waitcnt vmcnt(6)" ::: "memory");
;         else asm volatile("s_waitcnt vmcnt(3)" ::: "memory");
;       } else asm volatile("s_waitcnt vmcnt(0)" ::: "memory");
;       asm volatile("s_waitcnt lgkmcnt(0)" ::: "memory");
;       __builtin_amdgcn_s_barrier();
;       const u16* a_ = sbase + (kt % 3) * STG;
;       const u16* b_ = a_ + BM * 32;
;       bf16x8 bfr[4], afc[2], afn[2];
;       const u16* ap_ = a_ + (wr * (16 * MF) + fr) * 32 + fq * 8;
; #pragma unroll
;       for (int n = 0; n < 4; ++n) bfr[n] = rd_std(b_ + (wc * 64 + n * 16 + fr) * 32 + fq * 8);
;       afc[0] = rd_std(ap_); afc[1] = rd_std(ap_ + 16 * 32);
;       __builtin_amdgcn_sched_barrier(0);
;       if (kt + 2 < nk) GEMM_ISSUE(kt + 2);
;       __builtin_amdgcn_sched_barrier(0);
; #pragma unroll
;       for (int mh = 0; mh < MF / 2; ++mh) {
;         if (mh + 1 < MF / 2) {
;           afn[0] = rd_std(ap_ + ((mh + 1) * 2) * 16 * 32);
;           afn[1] = rd_std(ap_ + ((mh + 1) * 2 + 1) * 16 * 32);
;         }
;         __builtin_amdgcn_sched_barrier(0);
; #pragma unroll
;         for (int m = 0; m < 2; ++m)
; #pragma unroll
;           for (int n = 0; n < 4; ++n) acc[mh * 2 + m][n] = MFMA(bfr[n], afc[m], acc[mh * 2 + m][n]);
;         __builtin_amdgcn_sched_barrier(0);
;         afc[0] = afn[0]; afc[1] = afn[1];
;       }
;     }
.LBB0_1998:
	s_mul_hi_u32 s21, s13, 0xaaaaaaab
	s_lshr_b32 s21, s21, 1
	s_mul_i32 s21, s21, 0x12000
	v_add_u32_e32 v146, s5, v161
	v_subrev_u32_e32 v147, s21, v164
	s_waitcnt vmcnt(6)
	v_subrev_u32_e32 v148, s21, v160
	v_add_u32_e32 v170, v146, v147
	s_waitcnt lgkmcnt(0)
	s_barrier
	v_add_u32_e32 v190, v146, v148
	ds_read_b128 v[146:149], v170 offset:16384
	ds_read_b128 v[150:153], v170 offset:17408
	ds_read_b128 v[166:169], v170 offset:18432
	ds_read_b128 v[170:173], v170 offset:19456
	ds_read_b128 v[174:177], v190
	ds_read_b128 v[178:181], v190 offset:1024
	s_mul_hi_u32 s21, s12, 0xaaaaaaab
	s_add_i32 s13, s13, 1
	s_lshr_b32 s21, s21, 1
	s_mul_i32 s21, s21, 0x12000
	s_sub_i32 s21, s5, s21
	s_add_i32 s22, s21, 0xc000
	v_add_u32_e32 v186, s22, v154
	v_lshl_add_u64 v[182:183], v[136:137], 0, v[134:135]
	v_readfirstlane_b32 s22, v186
	s_mov_b32 m0, s22
	s_add_i32 s22, s21, 0xd000
	v_add_u32_e32 v186, s22, v154
	v_lshl_add_u64 v[184:185], v[182:183], 0, s[74:75]
	v_readfirstlane_b32 s22, v186
	global_load_lds_dwordx4 v[184:185], off
	s_mov_b32 m0, s22
	s_add_i32 s22, s21, 0xe000
	v_add_u32_e32 v186, s22, v154
	v_lshl_add_u64 v[184:185], v[182:183], 0, s[56:57]
	v_readfirstlane_b32 s22, v186
	global_load_lds_dwordx4 v[184:185], off
	v_lshl_add_u64 v[184:185], v[182:183], 0, s[58:59]
	s_mov_b32 m0, s22
	s_add_i32 s22, s21, 0xf000
	global_load_lds_dwordx4 v[184:185], off
	v_add_u32_e32 v184, s22, v154
	v_lshl_add_u64 v[182:183], v[182:183], 0, s[86:87]
	v_readfirstlane_b32 s22, v184
	s_mov_b32 m0, s22
	s_add_i32 s22, s21, 0x10000
	v_add_u32_e32 v186, s22, v154
	global_load_lds_dwordx4 v[182:183], off
	v_lshl_add_u64 v[182:183], v[138:139], 0, v[134:135]
	v_readfirstlane_b32 s22, v186
	v_lshl_add_u64 v[184:185], v[182:183], 0, s[74:75]
	s_mov_b32 m0, s22
	s_add_i32 s21, s21, 0x11000
	global_load_lds_dwordx4 v[184:185], off
	v_add_u32_e32 v184, s21, v154
	v_lshl_add_u64 v[182:183], v[182:183], 0, s[56:57]
	v_readfirstlane_b32 s21, v184
	s_mov_b32 m0, s21
	s_nop 0
	global_load_lds_dwordx4 v[182:183], off
	ds_read_b128 v[182:185], v190 offset:3072
	ds_read_b128 v[186:189], v190 offset:2048
	s_waitcnt lgkmcnt(0)
	v_mfma_f32_16x16x32_bf16 v[126:129], v[146:149], v[174:177], v[126:129]
	v_mfma_f32_16x16x32_bf16 v[122:125], v[150:153], v[174:177], v[122:125]
	v_mfma_f32_16x16x32_bf16 v[118:121], v[166:169], v[174:177], v[118:121]
	v_mfma_f32_16x16x32_bf16 v[114:117], v[170:173], v[174:177], v[114:117]
	v_mfma_f32_16x16x32_bf16 v[110:113], v[146:149], v[178:181], v[110:113]
	v_mfma_f32_16x16x32_bf16 v[106:109], v[150:153], v[178:181], v[106:109]
	v_mfma_f32_16x16x32_bf16 v[102:105], v[166:169], v[178:181], v[102:105]
	v_mfma_f32_16x16x32_bf16 v[98:101], v[170:173], v[178:181], v[98:101]
	ds_read_b128 v[174:177], v190 offset:5120
	ds_read_b128 v[178:181], v190 offset:4096
	v_mfma_f32_16x16x32_bf16 v[94:97], v[146:149], v[186:189], v[94:97]
	v_mfma_f32_16x16x32_bf16 v[90:93], v[150:153], v[186:189], v[90:93]
	v_mfma_f32_16x16x32_bf16 v[86:89], v[166:169], v[186:189], v[86:89]
	v_mfma_f32_16x16x32_bf16 v[82:85], v[170:173], v[186:189], v[82:85]
	v_mfma_f32_16x16x32_bf16 v[78:81], v[146:149], v[182:185], v[78:81]
	v_mfma_f32_16x16x32_bf16 v[74:77], v[150:153], v[182:185], v[74:77]
	v_mfma_f32_16x16x32_bf16 v[70:73], v[166:169], v[182:185], v[70:73]
	v_mfma_f32_16x16x32_bf16 v[66:69], v[170:173], v[182:185], v[66:69]
	ds_read_b128 v[182:185], v190 offset:7168
	ds_read_b128 v[186:189], v190 offset:6144
	s_waitcnt lgkmcnt(0)
	v_mfma_f32_16x16x32_bf16 v[62:65], v[146:149], v[178:181], v[62:65]
	v_mfma_f32_16x16x32_bf16 v[58:61], v[150:153], v[178:181], v[58:61]
	v_mfma_f32_16x16x32_bf16 v[54:57], v[166:169], v[178:181], v[54:57]
	v_mfma_f32_16x16x32_bf16 v[50:53], v[170:173], v[178:181], v[50:53]
	v_mfma_f32_16x16x32_bf16 v[46:49], v[146:149], v[174:177], v[46:49]
	v_mfma_f32_16x16x32_bf16 v[42:45], v[150:153], v[174:177], v[42:45]
	v_mfma_f32_16x16x32_bf16 v[38:41], v[166:169], v[174:177], v[38:41]
	v_mfma_f32_16x16x32_bf16 v[34:37], v[170:173], v[174:177], v[34:37]
	v_mfma_f32_16x16x32_bf16 v[30:33], v[146:149], v[186:189], v[30:33]
	v_mfma_f32_16x16x32_bf16 v[26:29], v[150:153], v[186:189], v[26:29]
	v_mfma_f32_16x16x32_bf16 v[22:25], v[166:169], v[186:189], v[22:25]
	v_mfma_f32_16x16x32_bf16 v[18:21], v[170:173], v[186:189], v[18:21]
	v_mfma_f32_16x16x32_bf16 v[14:17], v[146:149], v[182:185], v[14:17]
	v_mfma_f32_16x16x32_bf16 v[10:13], v[150:153], v[182:185], v[10:13]
	v_mfma_f32_16x16x32_bf16 v[6:9], v[166:169], v[182:185], v[6:9]
	v_mfma_f32_16x16x32_bf16 v[2:5], v[170:173], v[182:185], v[2:5]
	s_addk_i32 s5, 0x6000
	s_add_i32 s11, s11, 1
	s_add_i32 s12, s12, 1
	v_lshl_add_u64 v[136:137], v[136:137], 0, 64
	v_lshl_add_u64 v[136:137], v[136:137], 0, 64
	s_cmp_eq_u32 s5, 0x204000
	v_lshl_add_u64 v[138:139], v[138:139], 0, 64
	v_lshl_add_u64 v[138:139], v[138:139], 0, 64
	s_cbranch_scc0 .LBB0_1998
	s_waitcnt vmcnt(6)
	s_waitcnt lgkmcnt(0)
	s_barrier
; #define MFMA(a, b, c) __builtin_amdgcn_mfma_f32_16x16x32_bf16((a), (b), (c), 0, 0, 0)
; template <int EPI, int MF>
; __device__ __forceinline__ void gemm_part(const u16* __restrict__ A, int lda, const u16* __restrict__ Bt, int K, int ntn, GemmEpi ep, char* smem,
;                                           int mbase, int mrows) {
;     ...
;     for (int kt = 0; kt < nk; ++kt) {
;       if (kt + 1 < nk) {
;         if (MF == 8) asm volatile("s_waitcnt vmcnt(6)" ::: "memory");
;         else asm volatile("s_waitcnt vmcnt(3)" ::: "memory");
;       } else asm volatile("s_waitcnt vmcnt(0)" ::: "memory");
;       asm volatile("s_waitcnt lgkmcnt(0)" ::: "memory");
;       __builtin_amdgcn_s_barrier();
;       const u16* a_ = sbase + (kt % 3) * STG;
;       const u16* b_ = a_ + BM * 32;
;       bf16x8 bfr[4], afc[2], afn[2];
;       const u16* ap_ = a_ + (wr * (16 * MF) + fr) * 32 + fq * 8;
; #pragma unroll
;       for (int n = 0; n < 4; ++n) bfr[n] = rd_std(b_ + (wc * 64 + n * 16 + fr) * 32 + fq * 8);
;       afc[0] = rd_std(ap_); afc[1] = rd_std(ap_ + 16 * 32);
;       __builtin_amdgcn_sched_barrier(0);
;       if (kt + 2 < nk) GEMM_ISSUE(kt + 2);
;       __builtin_amdgcn_sched_barrier(0);
; #pragma unroll
;       for (int mh = 0; mh < MF / 2; ++mh) {
;         if (mh + 1 < MF / 2) {
;           afn[0] = rd_std(ap_ + ((mh + 1) * 2) * 16 * 32);
;           afn[1] = rd_std(ap_ + ((mh + 1) * 2 + 1) * 16 * 32);
;         }
;         __builtin_amdgcn_sched_barrier(0);
; #pragma unroll
;         for (int m = 0; m < 2; ++m)
; #pragma unroll
;           for (int n = 0; n < 4; ++n) acc[mh * 2 + m][n] = MFMA(bfr[n], afc[m], acc[mh * 2 + m][n]);
;         __builtin_amdgcn_sched_barrier(0);
;         afc[0] = afn[0]; afc[1] = afn[1];
;       }
;     }
;     ...
;     __syncthreads();
	ds_read_b128 v[136:139], v165
	ds_read_b128 v[146:149], v165 offset:1024
	ds_read_b128 v[150:153], v165 offset:2048
	ds_read_b128 v[166:169], v165 offset:3072
	ds_read_b128 v[170:173], v162 offset:49152
	ds_read_b128 v[174:177], v162 offset:50176
	s_mul_hi_u32 s11, s11, 0xaaaaaaab
	s_lshr_b32 s11, s11, 1
	s_mul_i32 s11, s11, 0x12000
	s_sub_i32 s5, s5, s11
	s_add_i32 s5, s5, 0
	s_addk_i32 s5, 0x6000
	ds_read_b128 v[178:181], v162 offset:52224
	ds_read_b128 v[182:185], v162 offset:51200
	s_waitcnt lgkmcnt(0)
	v_mfma_f32_16x16x32_bf16 v[126:129], v[136:139], v[170:173], v[126:129]
	v_mfma_f32_16x16x32_bf16 v[122:125], v[146:149], v[170:173], v[122:125]
	v_mfma_f32_16x16x32_bf16 v[118:121], v[150:153], v[170:173], v[118:121]
	v_mfma_f32_16x16x32_bf16 v[114:117], v[166:169], v[170:173], v[114:117]
	v_mfma_f32_16x16x32_bf16 v[110:113], v[136:139], v[174:177], v[110:113]
	v_mfma_f32_16x16x32_bf16 v[106:109], v[146:149], v[174:177], v[106:109]
	v_mfma_f32_16x16x32_bf16 v[102:105], v[150:153], v[174:177], v[102:105]
	v_mfma_f32_16x16x32_bf16 v[98:101], v[166:169], v[174:177], v[98:101]
	ds_read_b128 v[170:173], v162 offset:54272
	ds_read_b128 v[174:177], v162 offset:53248
	v_mfma_f32_16x16x32_bf16 v[94:97], v[136:139], v[182:185], v[94:97]
	v_mfma_f32_16x16x32_bf16 v[90:93], v[146:149], v[182:185], v[90:93]
	v_mfma_f32_16x16x32_bf16 v[86:89], v[150:153], v[182:185], v[86:89]
	v_mfma_f32_16x16x32_bf16 v[82:85], v[166:169], v[182:185], v[82:85]
	v_mfma_f32_16x16x32_bf16 v[78:81], v[136:139], v[178:181], v[78:81]
	v_mfma_f32_16x16x32_bf16 v[74:77], v[146:149], v[178:181], v[74:77]
	v_mfma_f32_16x16x32_bf16 v[70:73], v[150:153], v[178:181], v[70:73]
	v_mfma_f32_16x16x32_bf16 v[66:69], v[166:169], v[178:181], v[66:69]
	ds_read_b128 v[178:181], v162 offset:56320
	ds_read_b128 v[182:185], v162 offset:55296
	s_waitcnt lgkmcnt(0)
	v_mfma_f32_16x16x32_bf16 v[62:65], v[136:139], v[174:177], v[62:65]
	v_mfma_f32_16x16x32_bf16 v[58:61], v[146:149], v[174:177], v[58:61]
	v_mfma_f32_16x16x32_bf16 v[54:57], v[150:153], v[174:177], v[54:57]
	v_mfma_f32_16x16x32_bf16 v[50:53], v[166:169], v[174:177], v[50:53]
	v_mfma_f32_16x16x32_bf16 v[46:49], v[136:139], v[170:173], v[46:49]
	v_mfma_f32_16x16x32_bf16 v[42:45], v[146:149], v[170:173], v[42:45]
	v_mfma_f32_16x16x32_bf16 v[38:41], v[150:153], v[170:173], v[38:41]
	v_mfma_f32_16x16x32_bf16 v[34:37], v[166:169], v[170:173], v[34:37]
	v_mfma_f32_16x16x32_bf16 v[30:33], v[136:139], v[182:185], v[30:33]
	v_mfma_f32_16x16x32_bf16 v[26:29], v[146:149], v[182:185], v[26:29]
	v_mfma_f32_16x16x32_bf16 v[22:25], v[150:153], v[182:185], v[22:25]
	v_mfma_f32_16x16x32_bf16 v[18:21], v[166:169], v[182:185], v[18:21]
	v_mfma_f32_16x16x32_bf16 v[14:17], v[136:139], v[178:181], v[14:17]
	v_mfma_f32_16x16x32_bf16 v[10:13], v[146:149], v[178:181], v[10:13]
	v_mfma_f32_16x16x32_bf16 v[6:9], v[150:153], v[178:181], v[6:9]
	v_mfma_f32_16x16x32_bf16 v[2:5], v[166:169], v[178:181], v[2:5]
	v_lshl_add_u32 v136, v155, 1, s5
	s_waitcnt vmcnt(0)
	v_add3_u32 v166, v136, v158, v159
	s_waitcnt lgkmcnt(0)
	s_barrier
	ds_read_b128 v[136:139], v166 offset:16384
	ds_read_b128 v[146:149], v166 offset:17408
	ds_read_b128 v[150:153], v166 offset:18432
	ds_read_b128 v[166:169], v166 offset:19456
	ds_read_b128 v[170:173], v162
	ds_read_b128 v[174:177], v162 offset:1024
	ds_read_b128 v[178:181], v162 offset:3072
	ds_read_b128 v[182:185], v162 offset:2048
	s_waitcnt lgkmcnt(0)
	v_mfma_f32_16x16x32_bf16 v[126:129], v[136:139], v[170:173], v[126:129]
	v_mfma_f32_16x16x32_bf16 v[122:125], v[146:149], v[170:173], v[122:125]
	v_mfma_f32_16x16x32_bf16 v[118:121], v[150:153], v[170:173], v[118:121]
	v_mfma_f32_16x16x32_bf16 v[114:117], v[166:169], v[170:173], v[114:117]
	v_mfma_f32_16x16x32_bf16 v[110:113], v[136:139], v[174:177], v[110:113]
	v_mfma_f32_16x16x32_bf16 v[106:109], v[146:149], v[174:177], v[106:109]
	v_mfma_f32_16x16x32_bf16 v[102:105], v[150:153], v[174:177], v[102:105]
	v_mfma_f32_16x16x32_bf16 v[98:101], v[166:169], v[174:177], v[98:101]
	ds_read_b128 v[170:173], v162 offset:5120
	ds_read_b128 v[174:177], v162 offset:4096
	v_mfma_f32_16x16x32_bf16 v[94:97], v[136:139], v[182:185], v[94:97]
	v_mfma_f32_16x16x32_bf16 v[90:93], v[146:149], v[182:185], v[90:93]
	v_mfma_f32_16x16x32_bf16 v[86:89], v[150:153], v[182:185], v[86:89]
	v_mfma_f32_16x16x32_bf16 v[82:85], v[166:169], v[182:185], v[82:85]
	v_mfma_f32_16x16x32_bf16 v[78:81], v[136:139], v[178:181], v[78:81]
	v_mfma_f32_16x16x32_bf16 v[74:77], v[146:149], v[178:181], v[74:77]
	v_mfma_f32_16x16x32_bf16 v[70:73], v[150:153], v[178:181], v[70:73]
	v_mfma_f32_16x16x32_bf16 v[66:69], v[166:169], v[178:181], v[66:69]
	ds_read_b128 v[178:181], v162 offset:7168
	ds_read_b128 v[182:185], v162 offset:6144
	s_waitcnt lgkmcnt(0)
	v_mfma_f32_16x16x32_bf16 v[62:65], v[136:139], v[174:177], v[62:65]
	v_mfma_f32_16x16x32_bf16 v[58:61], v[146:149], v[174:177], v[58:61]
	v_mfma_f32_16x16x32_bf16 v[54:57], v[150:153], v[174:177], v[54:57]
	v_mfma_f32_16x16x32_bf16 v[50:53], v[166:169], v[174:177], v[50:53]
	v_mfma_f32_16x16x32_bf16 v[46:49], v[136:139], v[170:173], v[46:49]
	v_mfma_f32_16x16x32_bf16 v[42:45], v[146:149], v[170:173], v[42:45]
	v_mfma_f32_16x16x32_bf16 v[38:41], v[150:153], v[170:173], v[38:41]
	v_mfma_f32_16x16x32_bf16 v[34:37], v[166:169], v[170:173], v[34:37]
	v_mfma_f32_16x16x32_bf16 v[30:33], v[136:139], v[182:185], v[30:33]
	v_mfma_f32_16x16x32_bf16 v[26:29], v[146:149], v[182:185], v[26:29]
	v_mfma_f32_16x16x32_bf16 v[22:25], v[150:153], v[182:185], v[22:25]
	v_mfma_f32_16x16x32_bf16 v[18:21], v[166:169], v[182:185], v[18:21]
	v_mfma_f32_16x16x32_bf16 v[14:17], v[136:139], v[178:181], v[14:17]
	v_mfma_f32_16x16x32_bf16 v[10:13], v[146:149], v[178:181], v[10:13]
	v_mfma_f32_16x16x32_bf16 v[6:9], v[150:153], v[178:181], v[6:9]
	v_mfma_f32_16x16x32_bf16 v[2:5], v[166:169], v[178:181], v[2:5]
	v_add_u32_e32 v138, s4, v156
	s_waitcnt vmcnt(0)
	s_barrier
; template <int EPI, int MF>
; __device__ __forceinline__ void gemm_part(const u16* __restrict__ A, int lda, const u16* __restrict__ Bt, int K, int ntn, GemmEpi ep, char* smem,
;                                           int mbase, int mrows) {
;     ...
;       } else if (EPI == EPI_RESID) {
;         const float* rp = (row < MP) ? ep.res0 + (size_t)row * DM : ep.res1 + (size_t)(row - MP) * DM;
;         float ssq = 0.f;
; #pragma unroll
;         for (int n = 0; n < 4; ++n) {
;           const int col = cb + n * 16;
;           const float4 r = *(const float4*)(rp + col);
;           float4 v;
;           v.x = r.x + ep.scale * acc[m][n][0]; v.y = r.y + ep.scale * acc[m][n][1];
;           v.z = r.z + ep.scale * acc[m][n][2]; v.w = r.w + ep.scale * acc[m][n][3];
;           *(float4*)(ep.outf + (size_t)row * DM + col) = v;
;           if (ep.xcopy) {
;             bf16x4 o;
;             o[0] = (short)f2bf(v.x); o[1] = (short)f2bf(v.y); o[2] = (short)f2bf(v.z); o[3] = (short)f2bf(v.w);
;             *(bf16x4*)(ep.xcopy + (size_t)row * DM + col) = o;
;           }
;           ssq += v.x * v.x + v.y * v.y + v.z * v.z + v.w * v.w;
;         }
	s_mov_b32 s4, 0xffff
	v_cmp_lt_i32_e32 vcc, s4, v138
	s_and_saveexec_b64 s[4:5], vcc
	s_xor_b64 s[4:5], exec, s[4:5]
	v_add_u32_e32 v136, 0xffff0000, v138
	v_mov_b32_e32 v137, v0
	v_lshlrev_b64 v[136:137], 12, v[136:137]
	v_lshl_add_u64 v[136:137], s[72:73], 0, v[136:137]
	v_mov_b32_e32 v139, v0
	s_andn2_saveexec_b64 s[4:5], s[4:5]
	v_ashrrev_i32_e32 v139, 31, v138
	v_lshlrev_b64 v[136:137], 12, v[138:139]
	v_lshl_add_u64 v[136:137], s[26:27], 0, v[136:137]
	s_or_b64 exec, exec, s[4:5]
	v_lshlrev_b64 v[146:147], 12, v[138:139]
	v_or_b32_e32 v170, s10, v157
	v_lshl_add_u64 v[150:151], s[26:27], 0, v[146:147]
	v_lshlrev_b64 v[146:147], 11, v[138:139]
	v_lshl_add_u64 v[148:149], s[14:15], 0, v[146:147]
	v_lshlrev_b32_e32 v146, 2, v170
	v_mov_b32_e32 v147, v0
	v_lshl_add_u64 v[152:153], v[136:137], 0, v[146:147]
	global_load_dwordx4 v[166:169], v[152:153], off
	global_load_dwordx4 v[172:175], v[152:153], off offset:64
	global_load_dwordx4 v[176:179], v[152:153], off offset:128
	global_load_dwordx4 v[180:183], v[152:153], off offset:192
	v_cndmask_b32_e64 v136, 0, 1, s[2:3]
	v_lshl_add_u64 v[150:151], v[150:151], 0, v[146:147]
	v_cmp_ne_u32_e64 s[10:11], 1, v136
	s_andn2_b64 vcc, exec, s[2:3]
	v_lshlrev_b32_e32 v136, 1, v170
	s_waitcnt vmcnt(0)
	v_pk_fma_f32 v[126:127], v[126:127], 0.5, v[166:167] op_sel_hi:[1,0,1]
	v_pk_fma_f32 v[128:129], v[128:129], 0.5, v[168:169] op_sel_hi:[1,0,1]
	global_store_dwordx4 v[150:151], v[126:129], off
	s_cbranch_vccnz .LBB0_2005
	v_mov_b32_e32 v137, v0
	v_cvt_pk_bf16_f32 v166, v126, v127
	v_cvt_pk_bf16_f32 v167, v128, v129
	v_lshl_add_u64 v[168:169], v[148:149], 0, v[136:137]
	v_lshlrev_b32_e32 v184, 1, v168
	v_bfi_b32 v184, s100, v184, v168
	v_lshrrev_b32_e32 v185, 5, v168
	v_bfi_b32 v184, 64, v185, v184
	v_mov_b32_e32 v185, v169
	global_store_dwordx2 v[184:185], v[166:167], off
.LBB0_2005:
	s_nop 0
	s_and_b64 vcc, exec, s[10:11]
	s_nop 0
	v_pk_fma_f32 v[122:123], v[122:123], 0.5, v[172:173] op_sel_hi:[1,0,1]
	v_pk_fma_f32 v[124:125], v[124:125], 0.5, v[174:175] op_sel_hi:[1,0,1]
	global_store_dwordx4 v[150:151], v[122:125], off offset:64
	s_cbranch_vccnz .LBB0_2007
	v_mov_b32_e32 v137, v0
	v_cvt_pk_bf16_f32 v166, v122, v123
	v_cvt_pk_bf16_f32 v167, v124, v125
	v_lshl_add_u64 v[168:169], v[148:149], 0, v[136:137]
	v_lshlrev_b32_e32 v184, 1, v168
	v_bfi_b32 v184, s100, v184, v168
	v_lshrrev_b32_e32 v185, 5, v168
	v_bfi_b32 v184, 64, v185, v184
	v_mov_b32_e32 v185, v169
	global_store_dwordx2 v[184:185], v[166:167], off offset:32
.LBB0_2007:
	s_nop 0
	s_and_b64 vcc, exec, s[10:11]
	s_nop 0
	v_pk_fma_f32 v[118:119], v[118:119], 0.5, v[176:177] op_sel_hi:[1,0,1]
	v_pk_fma_f32 v[120:121], v[120:121], 0.5, v[178:179] op_sel_hi:[1,0,1]
	global_store_dwordx4 v[150:151], v[118:121], off offset:128
	s_cbranch_vccnz .LBB0_2009
	v_mov_b32_e32 v137, v0
	v_cvt_pk_bf16_f32 v166, v118, v119
	v_cvt_pk_bf16_f32 v167, v120, v121
	v_lshl_add_u64 v[168:169], v[148:149], 0, v[136:137]
	v_lshlrev_b32_e32 v184, 1, v168
	v_bfi_b32 v184, s100, v184, v168
	v_lshrrev_b32_e32 v185, 5, v168
	v_bfi_b32 v184, 64, v185, v184
	v_mov_b32_e32 v185, v169
	global_store_dwordx2 v[184:185], v[166:167], off offset:128
.LBB0_2009:
	s_nop 0
	s_and_b64 vcc, exec, s[10:11]
	s_nop 0
	v_pk_fma_f32 v[114:115], v[114:115], 0.5, v[180:181] op_sel_hi:[1,0,1]
	v_pk_fma_f32 v[116:117], v[116:117], 0.5, v[182:183] op_sel_hi:[1,0,1]
	global_store_dwordx4 v[150:151], v[114:117], off offset:192
	s_cbranch_vccnz .LBB0_2011
	v_mov_b32_e32 v137, v0
	v_cvt_pk_bf16_f32 v150, v114, v115
	v_cvt_pk_bf16_f32 v151, v116, v117
	v_lshl_add_u64 v[148:149], v[148:149], 0, v[136:137]
	v_lshlrev_b32_e32 v184, 1, v148
	v_bfi_b32 v184, s100, v184, v148
	v_lshrrev_b32_e32 v185, 5, v148
	v_bfi_b32 v184, 64, v185, v184
	v_mov_b32_e32 v185, v149
	global_store_dwordx2 v[184:185], v[150:151], off offset:160

; template <int EPI, int MF>
; __device__ __forceinline__ void gemm_part(const u16* __restrict__ A, int lda, const u16* __restrict__ Bt, int K, int ntn, GemmEpi ep, char* smem,
;                                           int mbase, int mrows) {
;     ...
;       } else if (EPI == EPI_RESID) {
;         const float* rp = (row < MP) ? ep.res0 + (size_t)row * DM : ep.res1 + (size_t)(row - MP) * DM;
;         float ssq = 0.f;
; #pragma unroll
;         for (int n = 0; n < 4; ++n) {
;           const int col = cb + n * 16;
;           const float4 r = *(const float4*)(rp + col);
;           float4 v;
;           v.x = r.x + ep.scale * acc[m][n][0]; v.y = r.y + ep.scale * acc[m][n][1];
;           v.z = r.z + ep.scale * acc[m][n][2]; v.w = r.w + ep.scale * acc[m][n][3];
;           *(float4*)(ep.outf + (size_t)row * DM + col) = v;
;           if (ep.xcopy) {
;             bf16x4 o;
;             o[0] = (short)f2bf(v.x); o[1] = (short)f2bf(v.y); o[2] = (short)f2bf(v.z); o[3] = (short)f2bf(v.w);
;             *(bf16x4*)(ep.xcopy + (size_t)row * DM + col) = o;
;           }
;           ssq += v.x * v.x + v.y * v.y + v.z * v.z + v.w * v.w;
;         }
.LBB0_2015:
	s_waitcnt lgkmcnt(0)
	v_or_b32_e32 v114, 16, v138
	s_mov_b32 s4, 0xffff
	v_cmp_lt_i32_e32 vcc, s4, v114
	s_and_saveexec_b64 s[4:5], vcc
	s_xor_b64 s[4:5], exec, s[4:5]
	v_add_u32_e32 v116, 0xffff0010, v138
	v_mov_b32_e32 v117, v0
	v_lshlrev_b64 v[116:117], 12, v[116:117]
	v_lshl_add_u64 v[116:117], s[72:73], 0, v[116:117]
	v_mov_b32_e32 v115, v0
	s_andn2_saveexec_b64 s[4:5], s[4:5]
	v_ashrrev_i32_e32 v115, 31, v114
	v_lshlrev_b64 v[116:117], 12, v[114:115]
	v_lshl_add_u64 v[116:117], s[26:27], 0, v[116:117]
	s_or_b64 exec, exec, s[4:5]
	v_mov_b32_e32 v147, v0
	v_lshl_add_u64 v[120:121], v[116:117], 0, v[146:147]
	global_load_dwordx4 v[122:125], v[120:121], off
	global_load_dwordx4 v[172:175], v[120:121], off offset:64
	global_load_dwordx4 v[176:179], v[120:121], off offset:128
	global_load_dwordx4 v[180:183], v[120:121], off offset:192
	v_lshlrev_b64 v[116:117], 12, v[114:115]
	v_lshlrev_b64 v[118:119], 11, v[114:115]
	v_lshl_add_u64 v[126:127], s[26:27], 0, v[116:117]
	v_lshl_add_u64 v[116:117], s[14:15], 0, v[118:119]
	v_lshl_add_u64 v[118:119], v[126:127], 0, v[146:147]
	s_and_b64 vcc, exec, s[10:11]
	s_waitcnt vmcnt(0)
	v_pk_fma_f32 v[110:111], v[110:111], 0.5, v[122:123] op_sel_hi:[1,0,1]
	v_pk_fma_f32 v[112:113], v[112:113], 0.5, v[124:125] op_sel_hi:[1,0,1]
	global_store_dwordx4 v[118:119], v[110:113], off
	s_cbranch_vccnz .LBB0_2021
	v_mov_b32_e32 v137, v0
	v_cvt_pk_bf16_f32 v122, v110, v111
	v_cvt_pk_bf16_f32 v123, v112, v113
	v_lshl_add_u64 v[124:125], v[116:117], 0, v[136:137]
	v_lshlrev_b32_e32 v184, 1, v124
	v_bfi_b32 v184, s100, v184, v124
	v_lshrrev_b32_e32 v185, 5, v124
	v_bfi_b32 v184, 64, v185, v184
	v_mov_b32_e32 v185, v125
	global_store_dwordx2 v[184:185], v[122:123], off
.LBB0_2021:
	s_nop 0
	s_and_b64 vcc, exec, s[10:11]
	s_nop 0
	v_pk_fma_f32 v[106:107], v[106:107], 0.5, v[172:173] op_sel_hi:[1,0,1]
	v_pk_fma_f32 v[108:109], v[108:109], 0.5, v[174:175] op_sel_hi:[1,0,1]
	global_store_dwordx4 v[118:119], v[106:109], off offset:64
	s_cbranch_vccnz .LBB0_2023
	v_mov_b32_e32 v137, v0
	v_cvt_pk_bf16_f32 v122, v106, v107
	v_cvt_pk_bf16_f32 v123, v108, v109
	v_lshl_add_u64 v[124:125], v[116:117], 0, v[136:137]
	v_lshlrev_b32_e32 v184, 1, v124
	v_bfi_b32 v184, s100, v184, v124
	v_lshrrev_b32_e32 v185, 5, v124
	v_bfi_b32 v184, 64, v185, v184
	v_mov_b32_e32 v185, v125
	global_store_dwordx2 v[184:185], v[122:123], off offset:32
.LBB0_2023:
	s_nop 0
	s_and_b64 vcc, exec, s[10:11]
	s_nop 0
	v_pk_fma_f32 v[102:103], v[102:103], 0.5, v[176:177] op_sel_hi:[1,0,1]
	v_pk_fma_f32 v[104:105], v[104:105], 0.5, v[178:179] op_sel_hi:[1,0,1]
	global_store_dwordx4 v[118:119], v[102:105], off offset:128
	s_cbranch_vccnz .LBB0_2025
	v_mov_b32_e32 v137, v0
	v_cvt_pk_bf16_f32 v122, v102, v103
	v_cvt_pk_bf16_f32 v123, v104, v105
	v_lshl_add_u64 v[124:125], v[116:117], 0, v[136:137]
	v_lshlrev_b32_e32 v184, 1, v124
	v_bfi_b32 v184, s100, v184, v124
	v_lshrrev_b32_e32 v185, 5, v124
	v_bfi_b32 v184, 64, v185, v184
	v_mov_b32_e32 v185, v125
	global_store_dwordx2 v[184:185], v[122:123], off offset:128
.LBB0_2025:
	s_nop 0
	s_and_b64 vcc, exec, s[10:11]
	s_nop 0
	v_pk_fma_f32 v[98:99], v[98:99], 0.5, v[180:181] op_sel_hi:[1,0,1]
	v_pk_fma_f32 v[100:101], v[100:101], 0.5, v[182:183] op_sel_hi:[1,0,1]
	global_store_dwordx4 v[118:119], v[98:101], off offset:192
	s_cbranch_vccnz .LBB0_2027
	v_mov_b32_e32 v137, v0
	v_cvt_pk_bf16_f32 v118, v98, v99
	v_cvt_pk_bf16_f32 v119, v100, v101
	v_lshl_add_u64 v[116:117], v[116:117], 0, v[136:137]
	v_lshlrev_b32_e32 v184, 1, v116
	v_bfi_b32 v184, s100, v184, v116
	v_lshrrev_b32_e32 v185, 5, v116
	v_bfi_b32 v184, 64, v185, v184
	v_mov_b32_e32 v185, v117
	global_store_dwordx2 v[184:185], v[118:119], off offset:160

; template <int EPI, int MF>
; __device__ __forceinline__ void gemm_part(const u16* __restrict__ A, int lda, const u16* __restrict__ Bt, int K, int ntn, GemmEpi ep, char* smem,
;                                           int mbase, int mrows) {
;     ...
;       } else if (EPI == EPI_RESID) {
;         const float* rp = (row < MP) ? ep.res0 + (size_t)row * DM : ep.res1 + (size_t)(row - MP) * DM;
;         float ssq = 0.f;
; #pragma unroll
;         for (int n = 0; n < 4; ++n) {
;           const int col = cb + n * 16;
;           const float4 r = *(const float4*)(rp + col);
;           float4 v;
;           v.x = r.x + ep.scale * acc[m][n][0]; v.y = r.y + ep.scale * acc[m][n][1];
;           v.z = r.z + ep.scale * acc[m][n][2]; v.w = r.w + ep.scale * acc[m][n][3];
;           *(float4*)(ep.outf + (size_t)row * DM + col) = v;
;           if (ep.xcopy) {
;             bf16x4 o;
;             o[0] = (short)f2bf(v.x); o[1] = (short)f2bf(v.y); o[2] = (short)f2bf(v.z); o[3] = (short)f2bf(v.w);
;             *(bf16x4*)(ep.xcopy + (size_t)row * DM + col) = o;
;           }
;           ssq += v.x * v.x + v.y * v.y + v.z * v.z + v.w * v.w;
;         }
.LBB0_2031:
	s_waitcnt lgkmcnt(0)
	v_or_b32_e32 v98, 32, v138
	s_mov_b32 s4, 0xffff
	v_cmp_lt_i32_e32 vcc, s4, v98
	s_and_saveexec_b64 s[4:5], vcc
	s_xor_b64 s[4:5], exec, s[4:5]
	v_add_u32_e32 v100, 0xffff0020, v138
	v_mov_b32_e32 v101, v0
	v_lshlrev_b64 v[100:101], 12, v[100:101]
	v_lshl_add_u64 v[100:101], s[72:73], 0, v[100:101]
	v_mov_b32_e32 v99, v0
	s_andn2_saveexec_b64 s[4:5], s[4:5]
	v_ashrrev_i32_e32 v99, 31, v98
	v_lshlrev_b64 v[100:101], 12, v[98:99]
	v_lshl_add_u64 v[100:101], s[26:27], 0, v[100:101]
	s_or_b64 exec, exec, s[4:5]
	v_mov_b32_e32 v147, v0
	v_lshl_add_u64 v[104:105], v[100:101], 0, v[146:147]
	global_load_dwordx4 v[106:109], v[104:105], off
	global_load_dwordx4 v[172:175], v[104:105], off offset:64
	global_load_dwordx4 v[176:179], v[104:105], off offset:128
	global_load_dwordx4 v[180:183], v[104:105], off offset:192
	v_lshlrev_b64 v[100:101], 12, v[98:99]
	v_lshlrev_b64 v[102:103], 11, v[98:99]
	v_lshl_add_u64 v[110:111], s[26:27], 0, v[100:101]
	v_lshl_add_u64 v[100:101], s[14:15], 0, v[102:103]
	v_lshl_add_u64 v[102:103], v[110:111], 0, v[146:147]
	s_and_b64 vcc, exec, s[10:11]
	s_waitcnt vmcnt(0)
	v_pk_fma_f32 v[94:95], v[94:95], 0.5, v[106:107] op_sel_hi:[1,0,1]
	v_pk_fma_f32 v[96:97], v[96:97], 0.5, v[108:109] op_sel_hi:[1,0,1]
	global_store_dwordx4 v[102:103], v[94:97], off
	s_cbranch_vccnz .LBB0_2037
	v_mov_b32_e32 v137, v0
	v_cvt_pk_bf16_f32 v106, v94, v95
	v_cvt_pk_bf16_f32 v107, v96, v97
	v_lshl_add_u64 v[108:109], v[100:101], 0, v[136:137]
	v_lshlrev_b32_e32 v184, 1, v108
	v_bfi_b32 v184, s100, v184, v108
	v_lshrrev_b32_e32 v185, 5, v108
	v_bfi_b32 v184, 64, v185, v184
	v_mov_b32_e32 v185, v109
	global_store_dwordx2 v[184:185], v[106:107], off
.LBB0_2037:
	s_nop 0
	s_and_b64 vcc, exec, s[10:11]
	s_nop 0
	v_pk_fma_f32 v[90:91], v[90:91], 0.5, v[172:173] op_sel_hi:[1,0,1]
	v_pk_fma_f32 v[92:93], v[92:93], 0.5, v[174:175] op_sel_hi:[1,0,1]
	global_store_dwordx4 v[102:103], v[90:93], off offset:64
	s_cbranch_vccnz .LBB0_2039
	v_mov_b32_e32 v137, v0
	v_cvt_pk_bf16_f32 v106, v90, v91
	v_cvt_pk_bf16_f32 v107, v92, v93
	v_lshl_add_u64 v[108:109], v[100:101], 0, v[136:137]
	v_lshlrev_b32_e32 v184, 1, v108
	v_bfi_b32 v184, s100, v184, v108
	v_lshrrev_b32_e32 v185, 5, v108
	v_bfi_b32 v184, 64, v185, v184
	v_mov_b32_e32 v185, v109
	global_store_dwordx2 v[184:185], v[106:107], off offset:32
.LBB0_2039:
	s_nop 0
	s_and_b64 vcc, exec, s[10:11]
	s_nop 0
	v_pk_fma_f32 v[86:87], v[86:87], 0.5, v[176:177] op_sel_hi:[1,0,1]
	v_pk_fma_f32 v[88:89], v[88:89], 0.5, v[178:179] op_sel_hi:[1,0,1]
	global_store_dwordx4 v[102:103], v[86:89], off offset:128
	s_cbranch_vccnz .LBB0_2041
	v_mov_b32_e32 v137, v0
	v_cvt_pk_bf16_f32 v106, v86, v87
	v_cvt_pk_bf16_f32 v107, v88, v89
	v_lshl_add_u64 v[108:109], v[100:101], 0, v[136:137]
	v_lshlrev_b32_e32 v184, 1, v108
	v_bfi_b32 v184, s100, v184, v108
	v_lshrrev_b32_e32 v185, 5, v108
	v_bfi_b32 v184, 64, v185, v184
	v_mov_b32_e32 v185, v109
	global_store_dwordx2 v[184:185], v[106:107], off offset:128
.LBB0_2041:
	s_nop 0
	s_and_b64 vcc, exec, s[10:11]
	s_nop 0
	v_pk_fma_f32 v[82:83], v[82:83], 0.5, v[180:181] op_sel_hi:[1,0,1]
	v_pk_fma_f32 v[84:85], v[84:85], 0.5, v[182:183] op_sel_hi:[1,0,1]
	global_store_dwordx4 v[102:103], v[82:85], off offset:192
	s_cbranch_vccnz .LBB0_2043
	v_mov_b32_e32 v137, v0
	v_cvt_pk_bf16_f32 v102, v82, v83
	v_cvt_pk_bf16_f32 v103, v84, v85
	v_lshl_add_u64 v[100:101], v[100:101], 0, v[136:137]
	v_lshlrev_b32_e32 v184, 1, v100
	v_bfi_b32 v184, s100, v184, v100
	v_lshrrev_b32_e32 v185, 5, v100
	v_bfi_b32 v184, 64, v185, v184
	v_mov_b32_e32 v185, v101
	global_store_dwordx2 v[184:185], v[102:103], off offset:160

; template <int EPI, int MF>
; __device__ __forceinline__ void gemm_part(const u16* __restrict__ A, int lda, const u16* __restrict__ Bt, int K, int ntn, GemmEpi ep, char* smem,
;                                           int mbase, int mrows) {
;     ...
;       } else if (EPI == EPI_RESID) {
;         const float* rp = (row < MP) ? ep.res0 + (size_t)row * DM : ep.res1 + (size_t)(row - MP) * DM;
;         float ssq = 0.f;
; #pragma unroll
;         for (int n = 0; n < 4; ++n) {
;           const int col = cb + n * 16;
;           const float4 r = *(const float4*)(rp + col);
;           float4 v;
;           v.x = r.x + ep.scale * acc[m][n][0]; v.y = r.y + ep.scale * acc[m][n][1];
;           v.z = r.z + ep.scale * acc[m][n][2]; v.w = r.w + ep.scale * acc[m][n][3];
;           *(float4*)(ep.outf + (size_t)row * DM + col) = v;
;           if (ep.xcopy) {
;             bf16x4 o;
;             o[0] = (short)f2bf(v.x); o[1] = (short)f2bf(v.y); o[2] = (short)f2bf(v.z); o[3] = (short)f2bf(v.w);
;             *(bf16x4*)(ep.xcopy + (size_t)row * DM + col) = o;
;           }
;           ssq += v.x * v.x + v.y * v.y + v.z * v.z + v.w * v.w;
;         }
.LBB0_2047:
	s_waitcnt lgkmcnt(0)
	v_or_b32_e32 v82, 48, v138
	s_mov_b32 s4, 0xffff
	v_cmp_lt_i32_e32 vcc, s4, v82
	s_and_saveexec_b64 s[4:5], vcc
	s_xor_b64 s[4:5], exec, s[4:5]
	v_add_u32_e32 v84, 0xffff0030, v138
	v_mov_b32_e32 v85, v0
	v_lshlrev_b64 v[84:85], 12, v[84:85]
	v_lshl_add_u64 v[84:85], s[72:73], 0, v[84:85]
	v_mov_b32_e32 v83, v0
	s_andn2_saveexec_b64 s[4:5], s[4:5]
	v_ashrrev_i32_e32 v83, 31, v82
	v_lshlrev_b64 v[84:85], 12, v[82:83]
	v_lshl_add_u64 v[84:85], s[26:27], 0, v[84:85]
	s_or_b64 exec, exec, s[4:5]
	v_mov_b32_e32 v147, v0
	v_lshl_add_u64 v[88:89], v[84:85], 0, v[146:147]
	global_load_dwordx4 v[90:93], v[88:89], off
	global_load_dwordx4 v[172:175], v[88:89], off offset:64
	global_load_dwordx4 v[176:179], v[88:89], off offset:128
	global_load_dwordx4 v[180:183], v[88:89], off offset:192
	v_lshlrev_b64 v[84:85], 12, v[82:83]
	v_lshlrev_b64 v[86:87], 11, v[82:83]
	v_lshl_add_u64 v[94:95], s[26:27], 0, v[84:85]
	v_lshl_add_u64 v[84:85], s[14:15], 0, v[86:87]
	v_lshl_add_u64 v[86:87], v[94:95], 0, v[146:147]
	s_and_b64 vcc, exec, s[10:11]
	s_waitcnt vmcnt(0)
	v_pk_fma_f32 v[78:79], v[78:79], 0.5, v[90:91] op_sel_hi:[1,0,1]
	v_pk_fma_f32 v[80:81], v[80:81], 0.5, v[92:93] op_sel_hi:[1,0,1]
	global_store_dwordx4 v[86:87], v[78:81], off
	s_cbranch_vccnz .LBB0_2053
	v_mov_b32_e32 v137, v0
	v_cvt_pk_bf16_f32 v90, v78, v79
	v_cvt_pk_bf16_f32 v91, v80, v81
	v_lshl_add_u64 v[92:93], v[84:85], 0, v[136:137]
	v_lshlrev_b32_e32 v184, 1, v92
	v_bfi_b32 v184, s100, v184, v92
	v_lshrrev_b32_e32 v185, 5, v92
	v_bfi_b32 v184, 64, v185, v184
	v_mov_b32_e32 v185, v93
	global_store_dwordx2 v[184:185], v[90:91], off
.LBB0_2053:
	s_nop 0
	s_and_b64 vcc, exec, s[10:11]
	s_nop 0
	v_pk_fma_f32 v[74:75], v[74:75], 0.5, v[172:173] op_sel_hi:[1,0,1]
	v_pk_fma_f32 v[76:77], v[76:77], 0.5, v[174:175] op_sel_hi:[1,0,1]
	global_store_dwordx4 v[86:87], v[74:77], off offset:64
	s_cbranch_vccnz .LBB0_2055
	v_mov_b32_e32 v137, v0
	v_cvt_pk_bf16_f32 v90, v74, v75
	v_cvt_pk_bf16_f32 v91, v76, v77
	v_lshl_add_u64 v[92:93], v[84:85], 0, v[136:137]
	v_lshlrev_b32_e32 v184, 1, v92
	v_bfi_b32 v184, s100, v184, v92
	v_lshrrev_b32_e32 v185, 5, v92
	v_bfi_b32 v184, 64, v185, v184
	v_mov_b32_e32 v185, v93
	global_store_dwordx2 v[184:185], v[90:91], off offset:32
.LBB0_2055:
	s_nop 0
	s_and_b64 vcc, exec, s[10:11]
	s_nop 0
	v_pk_fma_f32 v[70:71], v[70:71], 0.5, v[176:177] op_sel_hi:[1,0,1]
	v_pk_fma_f32 v[72:73], v[72:73], 0.5, v[178:179] op_sel_hi:[1,0,1]
	global_store_dwordx4 v[86:87], v[70:73], off offset:128
	s_cbranch_vccnz .LBB0_2057
	v_mov_b32_e32 v137, v0
	v_cvt_pk_bf16_f32 v90, v70, v71
	v_cvt_pk_bf16_f32 v91, v72, v73
	v_lshl_add_u64 v[92:93], v[84:85], 0, v[136:137]
	v_lshlrev_b32_e32 v184, 1, v92
	v_bfi_b32 v184, s100, v184, v92
	v_lshrrev_b32_e32 v185, 5, v92
	v_bfi_b32 v184, 64, v185, v184
	v_mov_b32_e32 v185, v93
	global_store_dwordx2 v[184:185], v[90:91], off offset:128
.LBB0_2057:
	s_nop 0
	s_and_b64 vcc, exec, s[10:11]
	s_nop 0
	v_pk_fma_f32 v[66:67], v[66:67], 0.5, v[180:181] op_sel_hi:[1,0,1]
	v_pk_fma_f32 v[68:69], v[68:69], 0.5, v[182:183] op_sel_hi:[1,0,1]
	global_store_dwordx4 v[86:87], v[66:69], off offset:192
	s_cbranch_vccnz .LBB0_2059
	v_mov_b32_e32 v137, v0
	v_cvt_pk_bf16_f32 v86, v66, v67
	v_cvt_pk_bf16_f32 v87, v68, v69
	v_lshl_add_u64 v[84:85], v[84:85], 0, v[136:137]
	v_lshlrev_b32_e32 v184, 1, v84
	v_bfi_b32 v184, s100, v184, v84
	v_lshrrev_b32_e32 v185, 5, v84
	v_bfi_b32 v184, 64, v185, v184
	v_mov_b32_e32 v185, v85
	global_store_dwordx2 v[184:185], v[86:87], off offset:160

; template <int EPI, int MF>
; __device__ __forceinline__ void gemm_part(const u16* __restrict__ A, int lda, const u16* __restrict__ Bt, int K, int ntn, GemmEpi ep, char* smem,
;                                           int mbase, int mrows) {
;     ...
;       } else if (EPI == EPI_RESID) {
;         const float* rp = (row < MP) ? ep.res0 + (size_t)row * DM : ep.res1 + (size_t)(row - MP) * DM;
;         float ssq = 0.f;
; #pragma unroll
;         for (int n = 0; n < 4; ++n) {
;           const int col = cb + n * 16;
;           const float4 r = *(const float4*)(rp + col);
;           float4 v;
;           v.x = r.x + ep.scale * acc[m][n][0]; v.y = r.y + ep.scale * acc[m][n][1];
;           v.z = r.z + ep.scale * acc[m][n][2]; v.w = r.w + ep.scale * acc[m][n][3];
;           *(float4*)(ep.outf + (size_t)row * DM + col) = v;
;           if (ep.xcopy) {
;             bf16x4 o;
;             o[0] = (short)f2bf(v.x); o[1] = (short)f2bf(v.y); o[2] = (short)f2bf(v.z); o[3] = (short)f2bf(v.w);
;             *(bf16x4*)(ep.xcopy + (size_t)row * DM + col) = o;
;           }
;           ssq += v.x * v.x + v.y * v.y + v.z * v.z + v.w * v.w;
;         }
.LBB0_2063:
	s_waitcnt lgkmcnt(0)
	v_or_b32_e32 v66, 64, v138
	s_mov_b32 s4, 0xffff
	v_cmp_lt_i32_e32 vcc, s4, v66
	s_and_saveexec_b64 s[4:5], vcc
	s_xor_b64 s[4:5], exec, s[4:5]
	v_add_u32_e32 v68, 0xffff0040, v138
	v_mov_b32_e32 v69, v0
	v_lshlrev_b64 v[68:69], 12, v[68:69]
	v_lshl_add_u64 v[68:69], s[72:73], 0, v[68:69]
	v_mov_b32_e32 v67, v0
	s_andn2_saveexec_b64 s[4:5], s[4:5]
	v_ashrrev_i32_e32 v67, 31, v66
	v_lshlrev_b64 v[68:69], 12, v[66:67]
	v_lshl_add_u64 v[68:69], s[26:27], 0, v[68:69]
	s_or_b64 exec, exec, s[4:5]
	v_mov_b32_e32 v147, v0
	v_lshl_add_u64 v[72:73], v[68:69], 0, v[146:147]
	global_load_dwordx4 v[74:77], v[72:73], off
	global_load_dwordx4 v[172:175], v[72:73], off offset:64
	global_load_dwordx4 v[176:179], v[72:73], off offset:128
	global_load_dwordx4 v[180:183], v[72:73], off offset:192
	v_lshlrev_b64 v[68:69], 12, v[66:67]
	v_lshlrev_b64 v[70:71], 11, v[66:67]
	v_lshl_add_u64 v[78:79], s[26:27], 0, v[68:69]
	v_lshl_add_u64 v[68:69], s[14:15], 0, v[70:71]
	v_lshl_add_u64 v[70:71], v[78:79], 0, v[146:147]
	s_and_b64 vcc, exec, s[10:11]
	s_waitcnt vmcnt(0)
	v_pk_fma_f32 v[62:63], v[62:63], 0.5, v[74:75] op_sel_hi:[1,0,1]
	v_pk_fma_f32 v[64:65], v[64:65], 0.5, v[76:77] op_sel_hi:[1,0,1]
	global_store_dwordx4 v[70:71], v[62:65], off
	s_cbranch_vccnz .LBB0_2069
	v_mov_b32_e32 v137, v0
	v_cvt_pk_bf16_f32 v74, v62, v63
	v_cvt_pk_bf16_f32 v75, v64, v65
	v_lshl_add_u64 v[76:77], v[68:69], 0, v[136:137]
	v_lshlrev_b32_e32 v184, 1, v76
	v_bfi_b32 v184, s100, v184, v76
	v_lshrrev_b32_e32 v185, 5, v76
	v_bfi_b32 v184, 64, v185, v184
	v_mov_b32_e32 v185, v77
	global_store_dwordx2 v[184:185], v[74:75], off
.LBB0_2069:
	s_nop 0
	s_and_b64 vcc, exec, s[10:11]
	s_nop 0
	v_pk_fma_f32 v[58:59], v[58:59], 0.5, v[172:173] op_sel_hi:[1,0,1]
	v_pk_fma_f32 v[60:61], v[60:61], 0.5, v[174:175] op_sel_hi:[1,0,1]
	global_store_dwordx4 v[70:71], v[58:61], off offset:64
	s_cbranch_vccnz .LBB0_2071
	v_mov_b32_e32 v137, v0
	v_cvt_pk_bf16_f32 v74, v58, v59
	v_cvt_pk_bf16_f32 v75, v60, v61
	v_lshl_add_u64 v[76:77], v[68:69], 0, v[136:137]
	v_lshlrev_b32_e32 v184, 1, v76
	v_bfi_b32 v184, s100, v184, v76
	v_lshrrev_b32_e32 v185, 5, v76
	v_bfi_b32 v184, 64, v185, v184
	v_mov_b32_e32 v185, v77
	global_store_dwordx2 v[184:185], v[74:75], off offset:32
.LBB0_2071:
	s_nop 0
	s_and_b64 vcc, exec, s[10:11]
	s_nop 0
	v_pk_fma_f32 v[54:55], v[54:55], 0.5, v[176:177] op_sel_hi:[1,0,1]
	v_pk_fma_f32 v[56:57], v[56:57], 0.5, v[178:179] op_sel_hi:[1,0,1]
	global_store_dwordx4 v[70:71], v[54:57], off offset:128
	s_cbranch_vccnz .LBB0_2073
	v_mov_b32_e32 v137, v0
	v_cvt_pk_bf16_f32 v74, v54, v55
	v_cvt_pk_bf16_f32 v75, v56, v57
	v_lshl_add_u64 v[76:77], v[68:69], 0, v[136:137]
	v_lshlrev_b32_e32 v184, 1, v76
	v_bfi_b32 v184, s100, v184, v76
	v_lshrrev_b32_e32 v185, 5, v76
	v_bfi_b32 v184, 64, v185, v184
	v_mov_b32_e32 v185, v77
	global_store_dwordx2 v[184:185], v[74:75], off offset:128
.LBB0_2073:
	s_nop 0
	s_and_b64 vcc, exec, s[10:11]
	s_nop 0
	v_pk_fma_f32 v[50:51], v[50:51], 0.5, v[180:181] op_sel_hi:[1,0,1]
	v_pk_fma_f32 v[52:53], v[52:53], 0.5, v[182:183] op_sel_hi:[1,0,1]
	global_store_dwordx4 v[70:71], v[50:53], off offset:192
	s_cbranch_vccnz .LBB0_2075
	v_mov_b32_e32 v137, v0
	v_cvt_pk_bf16_f32 v70, v50, v51
	v_cvt_pk_bf16_f32 v71, v52, v53
	v_lshl_add_u64 v[68:69], v[68:69], 0, v[136:137]
	v_lshlrev_b32_e32 v184, 1, v68
	v_bfi_b32 v184, s100, v184, v68
	v_lshrrev_b32_e32 v185, 5, v68
	v_bfi_b32 v184, 64, v185, v184
	v_mov_b32_e32 v185, v69
	global_store_dwordx2 v[184:185], v[70:71], off offset:160

; template <int EPI, int MF>
; __device__ __forceinline__ void gemm_part(const u16* __restrict__ A, int lda, const u16* __restrict__ Bt, int K, int ntn, GemmEpi ep, char* smem,
;                                           int mbase, int mrows) {
;     ...
;       } else if (EPI == EPI_RESID) {
;         const float* rp = (row < MP) ? ep.res0 + (size_t)row * DM : ep.res1 + (size_t)(row - MP) * DM;
;         float ssq = 0.f;
; #pragma unroll
;         for (int n = 0; n < 4; ++n) {
;           const int col = cb + n * 16;
;           const float4 r = *(const float4*)(rp + col);
;           float4 v;
;           v.x = r.x + ep.scale * acc[m][n][0]; v.y = r.y + ep.scale * acc[m][n][1];
;           v.z = r.z + ep.scale * acc[m][n][2]; v.w = r.w + ep.scale * acc[m][n][3];
;           *(float4*)(ep.outf + (size_t)row * DM + col) = v;
;           if (ep.xcopy) {
;             bf16x4 o;
;             o[0] = (short)f2bf(v.x); o[1] = (short)f2bf(v.y); o[2] = (short)f2bf(v.z); o[3] = (short)f2bf(v.w);
;             *(bf16x4*)(ep.xcopy + (size_t)row * DM + col) = o;
;           }
;           ssq += v.x * v.x + v.y * v.y + v.z * v.z + v.w * v.w;
;         }
.LBB0_2079:
	s_waitcnt lgkmcnt(0)
	v_or_b32_e32 v50, 0x50, v138
	s_mov_b32 s4, 0xffff
	v_cmp_lt_i32_e32 vcc, s4, v50
	s_and_saveexec_b64 s[4:5], vcc
	s_xor_b64 s[4:5], exec, s[4:5]
	v_add_u32_e32 v52, 0xffff0050, v138
	v_mov_b32_e32 v53, v0
	v_lshlrev_b64 v[52:53], 12, v[52:53]
	v_lshl_add_u64 v[52:53], s[72:73], 0, v[52:53]
	v_mov_b32_e32 v51, v0
	s_andn2_saveexec_b64 s[4:5], s[4:5]
	v_ashrrev_i32_e32 v51, 31, v50
	v_lshlrev_b64 v[52:53], 12, v[50:51]
	v_lshl_add_u64 v[52:53], s[26:27], 0, v[52:53]
	s_or_b64 exec, exec, s[4:5]
	v_mov_b32_e32 v147, v0
	v_lshl_add_u64 v[56:57], v[52:53], 0, v[146:147]
	global_load_dwordx4 v[58:61], v[56:57], off
	global_load_dwordx4 v[172:175], v[56:57], off offset:64
	global_load_dwordx4 v[176:179], v[56:57], off offset:128
	global_load_dwordx4 v[180:183], v[56:57], off offset:192
	v_lshlrev_b64 v[52:53], 12, v[50:51]
	v_lshlrev_b64 v[54:55], 11, v[50:51]
	v_lshl_add_u64 v[62:63], s[26:27], 0, v[52:53]
	v_lshl_add_u64 v[52:53], s[14:15], 0, v[54:55]
	v_lshl_add_u64 v[54:55], v[62:63], 0, v[146:147]
	s_and_b64 vcc, exec, s[10:11]
	s_waitcnt vmcnt(0)
	v_pk_fma_f32 v[46:47], v[46:47], 0.5, v[58:59] op_sel_hi:[1,0,1]
	v_pk_fma_f32 v[48:49], v[48:49], 0.5, v[60:61] op_sel_hi:[1,0,1]
	global_store_dwordx4 v[54:55], v[46:49], off
	s_cbranch_vccnz .LBB0_2085
	v_mov_b32_e32 v137, v0
	v_cvt_pk_bf16_f32 v58, v46, v47
	v_cvt_pk_bf16_f32 v59, v48, v49
	v_lshl_add_u64 v[60:61], v[52:53], 0, v[136:137]
	v_lshlrev_b32_e32 v184, 1, v60
	v_bfi_b32 v184, s100, v184, v60
	v_lshrrev_b32_e32 v185, 5, v60
	v_bfi_b32 v184, 64, v185, v184
	v_mov_b32_e32 v185, v61
	global_store_dwordx2 v[184:185], v[58:59], off
.LBB0_2085:
	s_nop 0
	s_and_b64 vcc, exec, s[10:11]
	s_nop 0
	v_pk_fma_f32 v[42:43], v[42:43], 0.5, v[172:173] op_sel_hi:[1,0,1]
	v_pk_fma_f32 v[44:45], v[44:45], 0.5, v[174:175] op_sel_hi:[1,0,1]
	global_store_dwordx4 v[54:55], v[42:45], off offset:64
	s_cbranch_vccnz .LBB0_2087
	v_mov_b32_e32 v137, v0
	v_cvt_pk_bf16_f32 v58, v42, v43
	v_cvt_pk_bf16_f32 v59, v44, v45
	v_lshl_add_u64 v[60:61], v[52:53], 0, v[136:137]
	v_lshlrev_b32_e32 v184, 1, v60
	v_bfi_b32 v184, s100, v184, v60
	v_lshrrev_b32_e32 v185, 5, v60
	v_bfi_b32 v184, 64, v185, v184
	v_mov_b32_e32 v185, v61
	global_store_dwordx2 v[184:185], v[58:59], off offset:32
.LBB0_2087:
	s_nop 0
	s_and_b64 vcc, exec, s[10:11]
	s_nop 0
	v_pk_fma_f32 v[38:39], v[38:39], 0.5, v[176:177] op_sel_hi:[1,0,1]
	v_pk_fma_f32 v[40:41], v[40:41], 0.5, v[178:179] op_sel_hi:[1,0,1]
	global_store_dwordx4 v[54:55], v[38:41], off offset:128
	s_cbranch_vccnz .LBB0_2089
	v_mov_b32_e32 v137, v0
	v_cvt_pk_bf16_f32 v58, v38, v39
	v_cvt_pk_bf16_f32 v59, v40, v41
	v_lshl_add_u64 v[60:61], v[52:53], 0, v[136:137]
	v_lshlrev_b32_e32 v184, 1, v60
	v_bfi_b32 v184, s100, v184, v60
	v_lshrrev_b32_e32 v185, 5, v60
	v_bfi_b32 v184, 64, v185, v184
	v_mov_b32_e32 v185, v61
	global_store_dwordx2 v[184:185], v[58:59], off offset:128
.LBB0_2089:
	s_nop 0
	s_and_b64 vcc, exec, s[10:11]
	s_nop 0
	v_pk_fma_f32 v[34:35], v[34:35], 0.5, v[180:181] op_sel_hi:[1,0,1]
	v_pk_fma_f32 v[36:37], v[36:37], 0.5, v[182:183] op_sel_hi:[1,0,1]
	global_store_dwordx4 v[54:55], v[34:37], off offset:192
	s_cbranch_vccnz .LBB0_2091
	v_mov_b32_e32 v137, v0
	v_cvt_pk_bf16_f32 v54, v34, v35
	v_cvt_pk_bf16_f32 v55, v36, v37
	v_lshl_add_u64 v[52:53], v[52:53], 0, v[136:137]
	v_lshlrev_b32_e32 v184, 1, v52
	v_bfi_b32 v184, s100, v184, v52
	v_lshrrev_b32_e32 v185, 5, v52
	v_bfi_b32 v184, 64, v185, v184
	v_mov_b32_e32 v185, v53
	global_store_dwordx2 v[184:185], v[54:55], off offset:160

; template <int EPI, int MF>
; __device__ __forceinline__ void gemm_part(const u16* __restrict__ A, int lda, const u16* __restrict__ Bt, int K, int ntn, GemmEpi ep, char* smem,
;                                           int mbase, int mrows) {
;     ...
;       } else if (EPI == EPI_RESID) {
;         const float* rp = (row < MP) ? ep.res0 + (size_t)row * DM : ep.res1 + (size_t)(row - MP) * DM;
;         float ssq = 0.f;
; #pragma unroll
;         for (int n = 0; n < 4; ++n) {
;           const int col = cb + n * 16;
;           const float4 r = *(const float4*)(rp + col);
;           float4 v;
;           v.x = r.x + ep.scale * acc[m][n][0]; v.y = r.y + ep.scale * acc[m][n][1];
;           v.z = r.z + ep.scale * acc[m][n][2]; v.w = r.w + ep.scale * acc[m][n][3];
;           *(float4*)(ep.outf + (size_t)row * DM + col) = v;
;           if (ep.xcopy) {
;             bf16x4 o;
;             o[0] = (short)f2bf(v.x); o[1] = (short)f2bf(v.y); o[2] = (short)f2bf(v.z); o[3] = (short)f2bf(v.w);
;             *(bf16x4*)(ep.xcopy + (size_t)row * DM + col) = o;
;           }
;           ssq += v.x * v.x + v.y * v.y + v.z * v.z + v.w * v.w;
;         }
.LBB0_2095:
	s_waitcnt lgkmcnt(0)
	v_or_b32_e32 v34, 0x60, v138
	s_mov_b32 s4, 0xffff
	v_cmp_lt_i32_e32 vcc, s4, v34
	s_and_saveexec_b64 s[4:5], vcc
	s_xor_b64 s[4:5], exec, s[4:5]
	v_add_u32_e32 v36, 0xffff0060, v138
	v_mov_b32_e32 v37, v0
	v_lshlrev_b64 v[36:37], 12, v[36:37]
	v_lshl_add_u64 v[36:37], s[72:73], 0, v[36:37]
	v_mov_b32_e32 v35, v0
	s_andn2_saveexec_b64 s[4:5], s[4:5]
	v_ashrrev_i32_e32 v35, 31, v34
	v_lshlrev_b64 v[36:37], 12, v[34:35]
	v_lshl_add_u64 v[36:37], s[26:27], 0, v[36:37]
	s_or_b64 exec, exec, s[4:5]
	v_mov_b32_e32 v147, v0
	v_lshl_add_u64 v[40:41], v[36:37], 0, v[146:147]
	global_load_dwordx4 v[42:45], v[40:41], off
	global_load_dwordx4 v[172:175], v[40:41], off offset:64
	global_load_dwordx4 v[176:179], v[40:41], off offset:128
	global_load_dwordx4 v[180:183], v[40:41], off offset:192
	v_lshlrev_b64 v[36:37], 12, v[34:35]
	v_lshlrev_b64 v[38:39], 11, v[34:35]
	v_lshl_add_u64 v[46:47], s[26:27], 0, v[36:37]
	v_lshl_add_u64 v[36:37], s[14:15], 0, v[38:39]
	v_lshl_add_u64 v[38:39], v[46:47], 0, v[146:147]
	s_and_b64 vcc, exec, s[10:11]
	s_waitcnt vmcnt(0)
	v_pk_fma_f32 v[30:31], v[30:31], 0.5, v[42:43] op_sel_hi:[1,0,1]
	v_pk_fma_f32 v[32:33], v[32:33], 0.5, v[44:45] op_sel_hi:[1,0,1]
	global_store_dwordx4 v[38:39], v[30:33], off
	s_cbranch_vccnz .LBB0_2101
	v_mov_b32_e32 v137, v0
	v_cvt_pk_bf16_f32 v42, v30, v31
	v_cvt_pk_bf16_f32 v43, v32, v33
	v_lshl_add_u64 v[44:45], v[36:37], 0, v[136:137]
	v_lshlrev_b32_e32 v184, 1, v44
	v_bfi_b32 v184, s100, v184, v44
	v_lshrrev_b32_e32 v185, 5, v44
	v_bfi_b32 v184, 64, v185, v184
	v_mov_b32_e32 v185, v45
	global_store_dwordx2 v[184:185], v[42:43], off
.LBB0_2101:
	s_nop 0
	s_and_b64 vcc, exec, s[10:11]
	s_nop 0
	v_pk_fma_f32 v[26:27], v[26:27], 0.5, v[172:173] op_sel_hi:[1,0,1]
	v_pk_fma_f32 v[28:29], v[28:29], 0.5, v[174:175] op_sel_hi:[1,0,1]
	global_store_dwordx4 v[38:39], v[26:29], off offset:64
	s_cbranch_vccnz .LBB0_2103
	v_mov_b32_e32 v137, v0
	v_cvt_pk_bf16_f32 v42, v26, v27
	v_cvt_pk_bf16_f32 v43, v28, v29
	v_lshl_add_u64 v[44:45], v[36:37], 0, v[136:137]
	v_lshlrev_b32_e32 v184, 1, v44
	v_bfi_b32 v184, s100, v184, v44
	v_lshrrev_b32_e32 v185, 5, v44
	v_bfi_b32 v184, 64, v185, v184
	v_mov_b32_e32 v185, v45
	global_store_dwordx2 v[184:185], v[42:43], off offset:32
.LBB0_2103:
	s_nop 0
	s_and_b64 vcc, exec, s[10:11]
	s_nop 0
	v_pk_fma_f32 v[22:23], v[22:23], 0.5, v[176:177] op_sel_hi:[1,0,1]
	v_pk_fma_f32 v[24:25], v[24:25], 0.5, v[178:179] op_sel_hi:[1,0,1]
	global_store_dwordx4 v[38:39], v[22:25], off offset:128
	s_cbranch_vccnz .LBB0_2105
	v_mov_b32_e32 v137, v0
	v_cvt_pk_bf16_f32 v42, v22, v23
	v_cvt_pk_bf16_f32 v43, v24, v25
	v_lshl_add_u64 v[44:45], v[36:37], 0, v[136:137]
	v_lshlrev_b32_e32 v184, 1, v44
	v_bfi_b32 v184, s100, v184, v44
	v_lshrrev_b32_e32 v185, 5, v44
	v_bfi_b32 v184, 64, v185, v184
	v_mov_b32_e32 v185, v45
	global_store_dwordx2 v[184:185], v[42:43], off offset:128
.LBB0_2105:
	s_nop 0
	s_and_b64 vcc, exec, s[10:11]
	s_nop 0
	v_pk_fma_f32 v[18:19], v[18:19], 0.5, v[180:181] op_sel_hi:[1,0,1]
	v_pk_fma_f32 v[20:21], v[20:21], 0.5, v[182:183] op_sel_hi:[1,0,1]
	global_store_dwordx4 v[38:39], v[18:21], off offset:192
	s_cbranch_vccnz .LBB0_2107
	v_mov_b32_e32 v137, v0
	v_cvt_pk_bf16_f32 v38, v18, v19
	v_cvt_pk_bf16_f32 v39, v20, v21
	v_lshl_add_u64 v[36:37], v[36:37], 0, v[136:137]
	v_lshlrev_b32_e32 v184, 1, v36
	v_bfi_b32 v184, s100, v184, v36
	v_lshrrev_b32_e32 v185, 5, v36
	v_bfi_b32 v184, 64, v185, v184
	v_mov_b32_e32 v185, v37
	global_store_dwordx2 v[184:185], v[38:39], off offset:160

; template <int EPI, int MF>
; __device__ __forceinline__ void gemm_part(const u16* __restrict__ A, int lda, const u16* __restrict__ Bt, int K, int ntn, GemmEpi ep, char* smem,
;                                           int mbase, int mrows) {
;     ...
;       } else if (EPI == EPI_RESID) {
;         const float* rp = (row < MP) ? ep.res0 + (size_t)row * DM : ep.res1 + (size_t)(row - MP) * DM;
;         float ssq = 0.f;
; #pragma unroll
;         for (int n = 0; n < 4; ++n) {
;           const int col = cb + n * 16;
;           const float4 r = *(const float4*)(rp + col);
;           float4 v;
;           v.x = r.x + ep.scale * acc[m][n][0]; v.y = r.y + ep.scale * acc[m][n][1];
;           v.z = r.z + ep.scale * acc[m][n][2]; v.w = r.w + ep.scale * acc[m][n][3];
;           *(float4*)(ep.outf + (size_t)row * DM + col) = v;
;           if (ep.xcopy) {
;             bf16x4 o;
;             o[0] = (short)f2bf(v.x); o[1] = (short)f2bf(v.y); o[2] = (short)f2bf(v.z); o[3] = (short)f2bf(v.w);
;             *(bf16x4*)(ep.xcopy + (size_t)row * DM + col) = o;
;           }
;           ssq += v.x * v.x + v.y * v.y + v.z * v.z + v.w * v.w;
;         }
.LBB0_2111:
	s_waitcnt lgkmcnt(0)
	v_or_b32_e32 v18, 0x70, v138
	s_mov_b32 s4, 0xffff
	v_cmp_lt_i32_e32 vcc, s4, v18
	s_and_saveexec_b64 s[4:5], vcc
	s_xor_b64 s[4:5], exec, s[4:5]
	v_add_u32_e32 v20, 0xffff0070, v138
	v_mov_b32_e32 v21, v0
	v_lshlrev_b64 v[20:21], 12, v[20:21]
	v_lshl_add_u64 v[20:21], s[72:73], 0, v[20:21]
	v_mov_b32_e32 v19, v0
	s_andn2_saveexec_b64 s[4:5], s[4:5]
	v_ashrrev_i32_e32 v19, 31, v18
	v_lshlrev_b64 v[20:21], 12, v[18:19]
	v_lshl_add_u64 v[20:21], s[26:27], 0, v[20:21]
	s_or_b64 exec, exec, s[4:5]
	v_mov_b32_e32 v147, v0
	v_lshl_add_u64 v[24:25], v[20:21], 0, v[146:147]
	global_load_dwordx4 v[26:29], v[24:25], off
	global_load_dwordx4 v[172:175], v[24:25], off offset:64
	global_load_dwordx4 v[176:179], v[24:25], off offset:128
	global_load_dwordx4 v[180:183], v[24:25], off offset:192
	v_lshlrev_b64 v[20:21], 12, v[18:19]
	v_lshlrev_b64 v[22:23], 11, v[18:19]
	v_lshl_add_u64 v[30:31], s[26:27], 0, v[20:21]
	v_lshl_add_u64 v[20:21], s[14:15], 0, v[22:23]
	v_lshl_add_u64 v[22:23], v[30:31], 0, v[146:147]
	s_and_b64 vcc, exec, s[10:11]
	s_waitcnt vmcnt(0)
	v_pk_fma_f32 v[14:15], v[14:15], 0.5, v[26:27] op_sel_hi:[1,0,1]
	v_pk_fma_f32 v[16:17], v[16:17], 0.5, v[28:29] op_sel_hi:[1,0,1]
	global_store_dwordx4 v[22:23], v[14:17], off
	s_cbranch_vccnz .LBB0_2117
	v_mov_b32_e32 v137, v0
	v_cvt_pk_bf16_f32 v26, v14, v15
	v_cvt_pk_bf16_f32 v27, v16, v17
	v_lshl_add_u64 v[28:29], v[20:21], 0, v[136:137]
	v_lshlrev_b32_e32 v184, 1, v28
	v_bfi_b32 v184, s100, v184, v28
	v_lshrrev_b32_e32 v185, 5, v28
	v_bfi_b32 v184, 64, v185, v184
	v_mov_b32_e32 v185, v29
	global_store_dwordx2 v[184:185], v[26:27], off
.LBB0_2117:
	s_nop 0
	s_and_b64 vcc, exec, s[10:11]
	s_nop 0
	v_pk_fma_f32 v[10:11], v[10:11], 0.5, v[172:173] op_sel_hi:[1,0,1]
	v_pk_fma_f32 v[12:13], v[12:13], 0.5, v[174:175] op_sel_hi:[1,0,1]
	global_store_dwordx4 v[22:23], v[10:13], off offset:64
	s_cbranch_vccnz .LBB0_2119
	v_mov_b32_e32 v137, v0
	v_cvt_pk_bf16_f32 v26, v10, v11
	v_cvt_pk_bf16_f32 v27, v12, v13
	v_lshl_add_u64 v[28:29], v[20:21], 0, v[136:137]
	v_lshlrev_b32_e32 v184, 1, v28
	v_bfi_b32 v184, s100, v184, v28
	v_lshrrev_b32_e32 v185, 5, v28
	v_bfi_b32 v184, 64, v185, v184
	v_mov_b32_e32 v185, v29
	global_store_dwordx2 v[184:185], v[26:27], off offset:32
.LBB0_2119:
	s_nop 0
	s_and_b64 vcc, exec, s[10:11]
	s_nop 0
	v_pk_fma_f32 v[6:7], v[6:7], 0.5, v[176:177] op_sel_hi:[1,0,1]
	v_pk_fma_f32 v[8:9], v[8:9], 0.5, v[178:179] op_sel_hi:[1,0,1]
	global_store_dwordx4 v[22:23], v[6:9], off offset:128
	s_cbranch_vccnz .LBB0_2121
	v_mov_b32_e32 v137, v0
	v_cvt_pk_bf16_f32 v26, v6, v7
	v_cvt_pk_bf16_f32 v27, v8, v9
	v_lshl_add_u64 v[28:29], v[20:21], 0, v[136:137]
	v_lshlrev_b32_e32 v184, 1, v28
	v_bfi_b32 v184, s100, v184, v28
	v_lshrrev_b32_e32 v185, 5, v28
	v_bfi_b32 v184, 64, v185, v184
	v_mov_b32_e32 v185, v29
	global_store_dwordx2 v[184:185], v[26:27], off offset:128
.LBB0_2121:
	s_nop 0
	s_and_b64 vcc, exec, s[10:11]
	s_nop 0
	v_pk_fma_f32 v[2:3], v[2:3], 0.5, v[180:181] op_sel_hi:[1,0,1]
	v_pk_fma_f32 v[4:5], v[4:5], 0.5, v[182:183] op_sel_hi:[1,0,1]
	global_store_dwordx4 v[22:23], v[2:5], off offset:192
	s_cbranch_vccnz .LBB0_2123
	v_mov_b32_e32 v137, v0
	v_cvt_pk_bf16_f32 v22, v2, v3
	v_cvt_pk_bf16_f32 v23, v4, v5
	v_lshl_add_u64 v[20:21], v[20:21], 0, v[136:137]
	v_lshlrev_b32_e32 v184, 1, v20
	v_bfi_b32 v184, s100, v184, v20
	v_lshrrev_b32_e32 v185, 5, v20
	v_bfi_b32 v184, 64, v185, v184
	v_mov_b32_e32 v185, v21
	global_store_dwordx2 v[184:185], v[22:23], off offset:160

; template <int EPI, int MF>
; __device__ __forceinline__ void gemm_part(const u16* __restrict__ A, int lda, const u16* __restrict__ Bt, int K, int ntn, GemmEpi ep, char* smem,
;                                           int mbase, int mrows) {
;     ...
;   for (int q = xcd; q * nbx < total; q += (MF == 2) ? 1 : 8) {
;     const int L = q * nbx + li;
;     if (L >= total) continue;
;     const int g = L / (8 * ntn), rr = L % (8 * ntn);
;     const int rows = min(8, ntm - 8 * g);
;     const int tm = 8 * g + rr % rows, tn = rr / rows;
;     const int row0 = mbase + tm * BM, col0 = tn * 128;
;     f32x4 acc[MF][4];
; #pragma unroll
;     for (int m = 0; m < MF; ++m)
; #pragma unroll
;       for (int n = 0; n < 4; ++n) acc[m][n] = (f32x4){0.f, 0.f, 0.f, 0.f};
;     const u16* gA = A + (size_t)(row0 + (tid >> 2)) * lda + (tid & 3) * 8;
;     const u16* gB = Bt + (size_t)(col0 + (tid >> 2)) * K + (tid & 3) * 8;
;     ...
;     GEMM_ISSUE(0);
;     GEMM_ISSUE(1);
;     for (int kt = 0; kt < nk; ++kt) {
;       if (kt + 1 < nk) {
;         if (MF == 8) asm volatile("s_waitcnt vmcnt(6)" ::: "memory");
;         else asm volatile("s_waitcnt vmcnt(3)" ::: "memory");
;       } else asm volatile("s_waitcnt vmcnt(0)" ::: "memory");
;       asm volatile("s_waitcnt lgkmcnt(0)" ::: "memory");
;       __builtin_amdgcn_s_barrier();
;       const u16* a_ = sbase + (kt % 3) * STG;
;       const u16* b_ = a_ + BM * 32;
;       bf16x8 bfr[4], afc[2], afn[2];
;       const u16* ap_ = a_ + (wr * (16 * MF) + fr) * 32 + fq * 8;
; #pragma unroll
;       for (int n = 0; n < 4; ++n) bfr[n] = rd_std(b_ + (wc * 64 + n * 16 + fr) * 32 + fq * 8);
;       afc[0] = rd_std(ap_); afc[1] = rd_std(ap_ + 16 * 32);
;       __builtin_amdgcn_sched_barrier(0);
;       if (kt + 2 < nk) GEMM_ISSUE(kt + 2);
;       __builtin_amdgcn_sched_barrier(0);
; #pragma unroll
;       for (int mh = 0; mh < MF / 2; ++mh) {
;         if (mh + 1 < MF / 2) {
;           afn[0] = rd_std(ap_ + ((mh + 1) * 2) * 16 * 32);
;           afn[1] = rd_std(ap_ + ((mh + 1) * 2 + 1) * 16 * 32);
;         }
;         __builtin_amdgcn_sched_barrier(0);
; #pragma unroll
;         for (int m = 0; m < 2; ++m)
; #pragma unroll
;           for (int n = 0; n < 4; ++n) acc[mh * 2 + m][n] = MFMA(bfr[n], afc[m], acc[mh * 2 + m][n]);
;         __builtin_amdgcn_sched_barrier(0);
;         afc[0] = afn[0]; afc[1] = afn[1];
.LBB0_2129:
	s_add_i32 s4, s4, s64
	s_cmp_gt_i32 s4, 63
	s_cbranch_scc1 .LBB0_2128
	s_ashr_i32 s5, s4, 31
	s_lshr_b32 s5, s5, 26
	s_add_i32 s5, s4, s5
	s_and_b32 s10, s5, 0xffc0
	s_sub_i32 s4, s4, s10
	s_bfe_i32 s10, s4, 0x80000
	s_bfe_u32 s10, s10, 0x3000c
	s_add_i32 s10, s4, s10
	s_bfe_i32 s11, s10, 0x80000
	s_and_b32 s10, s10, 0xf8
	s_sub_i32 s4, s4, s10
	s_sext_i32_i8 s4, s4
	s_lshl_b32 s5, s5, 3
	s_sext_i32_i16 s11, s11
	s_and_b32 s5, s5, 0xfffffe00
	s_lshl_b32 s4, s4, 6
	s_add_i32 s4, s5, s4
	s_lshl_b32 s5, s11, 4
	s_add_i32 s4, s4, 0x10000
	s_and_b32 s10, s5, 0xffffff80
	v_add_u32_e32 v8, s4, v1
	v_add_u32_e32 v9, s10, v1
	v_readfirstlane_b32 s5, v52
	v_add_u32_e32 v6, 0x1000, v52
	s_waitcnt lgkmcnt(0)
	v_mad_i64_i32 v[2:3], s[12:13], v8, s33, v[34:35]
	v_bfe_u32 v12, v140, 2, 1
	v_mul_u32_u24_e32 v12, 0x15c0, v12
	v_sub_u32_e32 v12, 0, v12
	v_ashrrev_i32_e32 v13, 31, v12
	v_lshl_add_u64 v[2:3], v[2:3], 0, v[12:13]
	v_mad_i64_i32 v[4:5], s[12:13], v9, s33, v[36:37]
	v_lshl_add_u64 v[4:5], v[4:5], 0, v[12:13]
	s_mov_b32 m0, s5
	v_readfirstlane_b32 s5, v6
	v_add_u32_e32 v10, 0x2000, v52
	global_load_lds_dwordx4 v[2:3], off
	s_mov_b32 m0, s5
	s_mov_b64 s[12:13], 0x58000
	v_readfirstlane_b32 s5, v10
	global_load_lds_dwordx4 v[4:5], off
	v_lshl_add_u64 v[6:7], v[4:5], 0, s[12:13]
	s_mov_b32 m0, s5
	v_lshl_add_u64 v[2:3], v[2:3], 0, 64
	v_lshl_add_u64 v[2:3], v[2:3], 0, 64
	global_load_lds_dwordx4 v[6:7], off
	v_add_u32_e32 v6, 0x3000, v52
	s_mov_b64 s[12:13], 0x58040
	v_readfirstlane_b32 s5, v6
	v_add_u32_e32 v6, 0x4000, v52
	s_mov_b32 m0, s5
	v_readfirstlane_b32 s5, v6
	global_load_lds_dwordx4 v[2:3], off
	v_lshl_add_u64 v[2:3], v[4:5], 0, 64
	v_lshl_add_u64 v[2:3], v[2:3], 0, 64
	s_mov_b32 m0, s5
	s_mov_b32 s11, 3
	global_load_lds_dwordx4 v[2:3], off
	v_lshl_add_u64 v[2:3], v[4:5], 0, s[12:13]
	v_lshl_add_u64 v[2:3], v[2:3], 0, 64
	v_add_u32_e32 v4, 0x5000, v52
	s_mov_b32 s19, 0
	v_readfirstlane_b32 s5, v4
	s_mov_b32 m0, s5
	s_mov_b32 s5, 0
	global_load_lds_dwordx4 v[2:3], off
	v_mov_b64_e32 v[2:3], s[16:17]
	v_mad_i64_i32 v[40:41], s[12:13], v9, s33, v[2:3]
	v_lshl_add_u64 v[40:41], v[40:41], 0, v[12:13]
	v_lshl_add_u64 v[40:41], v[40:41], 0, 64
	v_lshl_add_u64 v[40:41], v[40:41], 0, 64
	v_mov_b64_e32 v[2:3], s[46:47]
	v_mad_i64_i32 v[42:43], s[12:13], v8, s33, v[2:3]
	v_lshl_add_u64 v[42:43], v[42:43], 0, v[12:13]
	v_lshl_add_u64 v[42:43], v[42:43], 0, 64
	v_lshl_add_u64 v[42:43], v[42:43], 0, 64
	v_mov_b32_e32 v2, 0
	s_mov_b32 s12, 1
	s_mov_b32 s13, 2
	v_mov_b32_e32 v3, v2
	v_mov_b32_e32 v4, v2
	v_mov_b32_e32 v5, v2
	v_mov_b32_e32 v6, v2
	v_mov_b32_e32 v7, v2
	v_mov_b32_e32 v8, v2
	v_mov_b32_e32 v9, v2
	v_mov_b32_e32 v10, v2
	v_mov_b32_e32 v11, v2
	v_mov_b32_e32 v12, v2
	v_mov_b32_e32 v13, v2
	v_mov_b32_e32 v14, v2
	v_mov_b32_e32 v15, v2
	v_mov_b32_e32 v16, v2
	v_mov_b32_e32 v17, v2
	v_mov_b32_e32 v18, v2
	v_mov_b32_e32 v19, v2
	v_mov_b32_e32 v20, v2
	v_mov_b32_e32 v21, v2
	v_mov_b32_e32 v22, v2
	v_mov_b32_e32 v23, v2
	v_mov_b32_e32 v24, v2
	v_mov_b32_e32 v25, v2
	v_mov_b32_e32 v26, v2
	v_mov_b32_e32 v27, v2
	v_mov_b32_e32 v28, v2
	v_mov_b32_e32 v29, v2
	v_mov_b32_e32 v30, v2
	v_mov_b32_e32 v31, v2
	v_mov_b32_e32 v32, v2
	v_mov_b32_e32 v33, v2
	s_waitcnt vmcnt(0)
.LBB0_2131:
	s_mul_hi_u32 s21, s19, 0xaaaaaaab
	s_lshr_b32 s21, s21, 1
	s_mul_i32 s21, s21, 0x9000
	s_mul_hi_u32 s20, s12, 0xaaaaaaab
	v_subrev_u32_e32 v44, s21, v60
	v_add_u32_e32 v97, s5, v58
	s_lshr_b32 s20, s20, 1
	s_waitcnt vmcnt(3)
	v_add_u32_e32 v74, v97, v44
	s_mul_i32 s20, s20, 0x9000
	v_subrev_u32_e32 v78, s21, v61
	s_waitcnt lgkmcnt(0)
	s_barrier
	ds_read_b128 v[44:47], v74 offset:4096
	ds_read_b128 v[48:51], v74 offset:5120
	ds_read_b128 v[70:73], v74 offset:6144
	ds_read_b128 v[74:77], v74 offset:7168
	v_subrev_u32_e32 v92, s20, v60
	v_subrev_u32_e32 v93, s20, v62
	s_mul_hi_u32 s20, s11, 0xaaaaaaab
	v_add_u32_e32 v82, v97, v78
	s_lshr_b32 s20, s20, 1
	ds_read_b128 v[78:81], v82
	ds_read_b128 v[82:85], v82 offset:1024
	s_mul_i32 s20, s20, 0x9000
	v_subrev_u32_e32 v94, s20, v63
	v_subrev_u32_e32 v95, s20, v64
	v_subrev_u32_e32 v96, s20, v65
	s_mul_hi_u32 s20, s13, 0xaaaaaaab
	s_lshr_b32 s20, s20, 1
	s_mul_i32 s20, s20, 0x9000
	v_subrev_u32_e32 v90, s20, v66
	v_subrev_u32_e32 v98, s20, v67
	v_subrev_u32_e32 v99, s20, v68
	s_add_i32 s20, s5, 0
	v_add_u32_e32 v90, s20, v90
	v_lshl_add_u64 v[86:87], v[42:43], 0, v[38:39]
	v_readfirstlane_b32 s21, v90
	v_lshl_add_u64 v[88:89], v[86:87], 0, s[74:75]
	s_mov_b32 m0, s21
	v_add_u32_e32 v98, s20, v98
	global_load_lds_dwordx4 v[88:89], off
	v_lshl_add_u64 v[88:89], v[40:41], 0, v[38:39]
	v_readfirstlane_b32 s21, v98
	v_add_u32_e32 v98, s20, v99
	v_lshl_add_u64 v[90:91], v[88:89], 0, s[74:75]
	s_mov_b32 m0, s21
	v_readfirstlane_b32 s21, v98
	global_load_lds_dwordx4 v[90:91], off
	v_lshl_add_u64 v[90:91], v[88:89], 0, s[56:57]
	s_mov_b32 m0, s21
	s_add_i32 s19, s19, 2
	global_load_lds_dwordx4 v[90:91], off
	s_waitcnt lgkmcnt(0)
	v_mfma_f32_16x16x32_bf16 v[30:33], v[44:47], v[78:81], v[30:33]
	v_mfma_f32_16x16x32_bf16 v[26:29], v[48:51], v[78:81], v[26:29]
	v_mfma_f32_16x16x32_bf16 v[22:25], v[70:73], v[78:81], v[22:25]
	v_mfma_f32_16x16x32_bf16 v[18:21], v[74:77], v[78:81], v[18:21]
	v_mfma_f32_16x16x32_bf16 v[14:17], v[44:47], v[82:85], v[14:17]
	v_mfma_f32_16x16x32_bf16 v[10:13], v[48:51], v[82:85], v[10:13]
	v_mfma_f32_16x16x32_bf16 v[6:9], v[70:73], v[82:85], v[6:9]
	v_mfma_f32_16x16x32_bf16 v[2:5], v[74:77], v[82:85], v[2:5]
	s_waitcnt vmcnt(3)
	v_add_u32_e32 v74, v97, v92
	s_waitcnt lgkmcnt(0)
	s_barrier
; #define MFMA(a, b, c) __builtin_amdgcn_mfma_f32_16x16x32_bf16((a), (b), (c), 0, 0, 0)
; template <int EPI, int MF>
; __device__ __forceinline__ void gemm_part(const u16* __restrict__ A, int lda, const u16* __restrict__ Bt, int K, int ntn, GemmEpi ep, char* smem,
;                                           int mbase, int mrows) {
;     ...
;     for (int kt = 0; kt < nk; ++kt) {
;       if (kt + 1 < nk) {
;         if (MF == 8) asm volatile("s_waitcnt vmcnt(6)" ::: "memory");
;         else asm volatile("s_waitcnt vmcnt(3)" ::: "memory");
;       } else asm volatile("s_waitcnt vmcnt(0)" ::: "memory");
;       asm volatile("s_waitcnt lgkmcnt(0)" ::: "memory");
;       __builtin_amdgcn_s_barrier();
;       const u16* a_ = sbase + (kt % 3) * STG;
;       const u16* b_ = a_ + BM * 32;
;       bf16x8 bfr[4], afc[2], afn[2];
;       const u16* ap_ = a_ + (wr * (16 * MF) + fr) * 32 + fq * 8;
; #pragma unroll
;       for (int n = 0; n < 4; ++n) bfr[n] = rd_std(b_ + (wc * 64 + n * 16 + fr) * 32 + fq * 8);
;       afc[0] = rd_std(ap_); afc[1] = rd_std(ap_ + 16 * 32);
;       __builtin_amdgcn_sched_barrier(0);
;       if (kt + 2 < nk) GEMM_ISSUE(kt + 2);
;       __builtin_amdgcn_sched_barrier(0);
; #pragma unroll
;       for (int mh = 0; mh < MF / 2; ++mh) {
;         if (mh + 1 < MF / 2) {
;           afn[0] = rd_std(ap_ + ((mh + 1) * 2) * 16 * 32);
;           afn[1] = rd_std(ap_ + ((mh + 1) * 2 + 1) * 16 * 32);
;         }
;         __builtin_amdgcn_sched_barrier(0);
; #pragma unroll
;         for (int m = 0; m < 2; ++m)
; #pragma unroll
;           for (int n = 0; n < 4; ++n) acc[mh * 2 + m][n] = MFMA(bfr[n], afc[m], acc[mh * 2 + m][n]);
;         __builtin_amdgcn_sched_barrier(0);
;         afc[0] = afn[0]; afc[1] = afn[1];
;       }
;     ...
;       } else if (EPI == EPI_RESID) {
;         const float* rp = (row < MP) ? ep.res0 + (size_t)row * DM : ep.res1 + (size_t)(row - MP) * DM;
;         float ssq = 0.f;
; #pragma unroll
;         for (int n = 0; n < 4; ++n) {
;           const int col = cb + n * 16;
;           const float4 r = *(const float4*)(rp + col);
;           float4 v;
;           v.x = r.x + ep.scale * acc[m][n][0]; v.y = r.y + ep.scale * acc[m][n][1];
;           v.z = r.z + ep.scale * acc[m][n][2]; v.w = r.w + ep.scale * acc[m][n][3];
;           *(float4*)(ep.outf + (size_t)row * DM + col) = v;
;           if (ep.xcopy) {
;             bf16x4 o;
	ds_read_b128 v[44:47], v74 offset:16384
	ds_read_b128 v[48:51], v74 offset:17408
	ds_read_b128 v[70:73], v74 offset:18432
	ds_read_b128 v[74:77], v74 offset:19456
	v_add_u32_e32 v82, v97, v93
	ds_read_b128 v[78:81], v82
	ds_read_b128 v[82:85], v82 offset:1024
	v_add_u32_e32 v90, s20, v96
	v_lshl_add_u64 v[86:87], v[86:87], 0, s[52:53]
	v_lshl_add_u64 v[86:87], v[86:87], 0, 64
	v_readfirstlane_b32 s21, v90
	v_add_u32_e32 v90, s20, v95
	s_mov_b32 m0, s21
	v_readfirstlane_b32 s21, v90
	global_load_lds_dwordx4 v[86:87], off
	v_lshl_add_u64 v[86:87], v[88:89], 0, s[52:53]
	v_lshl_add_u64 v[86:87], v[86:87], 0, 64
	s_mov_b32 m0, s21
	s_nop 0
	global_load_lds_dwordx4 v[86:87], off
	v_lshl_add_u64 v[86:87], v[88:89], 0, s[0:1]
	v_lshl_add_u64 v[86:87], v[86:87], 0, 64
	v_add_u32_e32 v88, s20, v94
	s_nop 0
	v_readfirstlane_b32 s20, v88
	s_mov_b32 m0, s20
	s_nop 0
	global_load_lds_dwordx4 v[86:87], off
	s_waitcnt lgkmcnt(0)
	v_mfma_f32_16x16x32_bf16 v[30:33], v[44:47], v[78:81], v[30:33]
	v_mfma_f32_16x16x32_bf16 v[26:29], v[48:51], v[78:81], v[26:29]
	v_mfma_f32_16x16x32_bf16 v[22:25], v[70:73], v[78:81], v[22:25]
	v_mfma_f32_16x16x32_bf16 v[18:21], v[74:77], v[78:81], v[18:21]
	v_mfma_f32_16x16x32_bf16 v[14:17], v[44:47], v[82:85], v[14:17]
	v_mfma_f32_16x16x32_bf16 v[10:13], v[48:51], v[82:85], v[10:13]
	v_mfma_f32_16x16x32_bf16 v[6:9], v[70:73], v[82:85], v[6:9]
	v_mfma_f32_16x16x32_bf16 v[2:5], v[74:77], v[82:85], v[2:5]
	s_addk_i32 s5, 0x6000
	s_add_i32 s12, s12, 2
	s_add_i32 s11, s11, 2
	s_add_i32 s13, s13, 2
	v_lshl_add_u64 v[40:41], v[40:41], 0, s[74:75]
	v_lshl_add_u64 v[40:41], v[40:41], 0, s[74:75]
	s_cmp_eq_u32 s5, 0x102000
	v_lshl_add_u64 v[42:43], v[42:43], 0, s[74:75]
	v_lshl_add_u64 v[42:43], v[42:43], 0, s[74:75]
	s_cbranch_scc0 .LBB0_2131
	s_waitcnt vmcnt(3)
	s_waitcnt lgkmcnt(0)
	s_barrier
	ds_read_b128 v[40:43], v69 offset:28672
	ds_read_b128 v[44:47], v69 offset:29696
	ds_read_b128 v[48:51], v69 offset:30720
	ds_read_b128 v[70:73], v69 offset:31744
	ds_read_b128 v[74:77], v59 offset:24576
	ds_read_b128 v[78:81], v59 offset:25600
	s_mul_hi_u32 s11, s12, 0xaaaaaaab
	s_lshr_b32 s11, s11, 1
	s_mul_i32 s11, s11, 0x9000
	s_sub_i32 s5, s5, s11
	s_add_i32 s5, s5, 0
	s_addk_i32 s5, 0x3000
	s_waitcnt lgkmcnt(0)
	v_mfma_f32_16x16x32_bf16 v[30:33], v[40:43], v[74:77], v[30:33]
	v_mfma_f32_16x16x32_bf16 v[26:29], v[44:47], v[74:77], v[26:29]
	v_mfma_f32_16x16x32_bf16 v[22:25], v[48:51], v[74:77], v[22:25]
	v_mfma_f32_16x16x32_bf16 v[18:21], v[70:73], v[74:77], v[18:21]
	v_mfma_f32_16x16x32_bf16 v[14:17], v[40:43], v[78:81], v[14:17]
	v_mfma_f32_16x16x32_bf16 v[10:13], v[44:47], v[78:81], v[10:13]
	v_mfma_f32_16x16x32_bf16 v[6:9], v[48:51], v[78:81], v[6:9]
	v_mfma_f32_16x16x32_bf16 v[2:5], v[70:73], v[78:81], v[2:5]
	v_lshl_add_u32 v40, v54, 1, s5
	s_waitcnt vmcnt(0)
	v_add3_u32 v70, v40, v57, v53
	s_waitcnt lgkmcnt(0)
	s_barrier
	ds_read_b128 v[40:43], v70 offset:4096
	ds_read_b128 v[44:47], v70 offset:5120
	ds_read_b128 v[48:51], v70 offset:6144
	ds_read_b128 v[70:73], v70 offset:7168
	ds_read_b128 v[74:77], v59
	ds_read_b128 v[78:81], v59 offset:1024
	s_waitcnt lgkmcnt(0)
	v_mfma_f32_16x16x32_bf16 v[30:33], v[40:43], v[74:77], v[30:33]
	v_mfma_f32_16x16x32_bf16 v[26:29], v[44:47], v[74:77], v[26:29]
	v_mfma_f32_16x16x32_bf16 v[22:25], v[48:51], v[74:77], v[22:25]
	v_mfma_f32_16x16x32_bf16 v[18:21], v[70:73], v[74:77], v[18:21]
	v_mfma_f32_16x16x32_bf16 v[14:17], v[40:43], v[78:81], v[14:17]
	v_mfma_f32_16x16x32_bf16 v[10:13], v[44:47], v[78:81], v[10:13]
	v_mfma_f32_16x16x32_bf16 v[6:9], v[48:51], v[78:81], v[6:9]
	v_mfma_f32_16x16x32_bf16 v[2:5], v[70:73], v[78:81], v[2:5]
	v_add_u32_e32 v42, s4, v55
	s_waitcnt vmcnt(0)
	s_barrier
	s_mov_b32 s4, 0xffff
	v_cmp_lt_i32_e32 vcc, s4, v42
	s_and_saveexec_b64 s[4:5], vcc
	s_xor_b64 s[4:5], exec, s[4:5]
	v_add_u32_e32 v40, 0xffff0000, v42
	v_mov_b32_e32 v41, v0
	v_lshlrev_b64 v[40:41], 12, v[40:41]
	v_lshl_add_u64 v[46:47], s[72:73], 0, v[40:41]
	v_mov_b32_e32 v43, v0
	s_andn2_saveexec_b64 s[4:5], s[4:5]
	v_ashrrev_i32_e32 v43, 31, v42
	v_lshlrev_b64 v[40:41], 12, v[42:43]
	v_lshl_add_u64 v[46:47], s[26:27], 0, v[40:41]
	s_or_b64 exec, exec, s[4:5]
	v_or_b32_e32 v40, s10, v56
	v_lshlrev_b64 v[44:45], 12, v[42:43]
	v_lshl_add_u64 v[50:51], s[26:27], 0, v[44:45]
	v_lshlrev_b64 v[44:45], 11, v[42:43]
	v_ashrrev_i32_e32 v41, 31, v40
	v_lshl_add_u64 v[74:75], s[14:15], 0, v[44:45]
	v_lshlrev_b64 v[44:45], 2, v[40:41]
	v_lshl_add_u64 v[48:49], v[46:47], 0, v[44:45]
	global_load_dwordx4 v[70:73], v[48:49], off
	v_lshl_add_u64 v[46:47], v[50:51], 0, v[44:45]
	v_cndmask_b32_e64 v50, 0, 1, s[2:3]
	v_cmp_ne_u32_e64 s[10:11], 1, v50
	s_andn2_b64 vcc, exec, s[2:3]
	v_lshl_add_u64 v[50:51], v[40:41], 1, v[74:75]
	s_waitcnt vmcnt(0)
	v_pk_fma_f32 v[30:31], v[30:31], 0.5, v[70:71] op_sel_hi:[1,0,1]
	v_pk_fma_f32 v[32:33], v[32:33], 0.5, v[72:73] op_sel_hi:[1,0,1]
	global_store_dwordx4 v[46:47], v[30:33], off
	s_cbranch_vccnz .LBB0_2138
	v_cvt_pk_bf16_f32 v70, v30, v31
	v_cvt_pk_bf16_f32 v71, v32, v33
	v_lshlrev_b32_e32 v84, 1, v50
	v_bfi_b32 v84, s100, v84, v50
	v_lshrrev_b32_e32 v85, 5, v50
	v_bfi_b32 v84, 64, v85, v84
	v_mov_b32_e32 v85, v51
	global_store_dwordx2 v[84:85], v[70:71], off
.LBB0_2138:
	global_load_dwordx4 v[70:73], v[48:49], off offset:64
	s_and_b64 vcc, exec, s[10:11]
	s_waitcnt vmcnt(0)
	v_pk_fma_f32 v[26:27], v[26:27], 0.5, v[70:71] op_sel_hi:[1,0,1]
	v_pk_fma_f32 v[28:29], v[28:29], 0.5, v[72:73] op_sel_hi:[1,0,1]
	global_store_dwordx4 v[46:47], v[26:29], off offset:64
	s_cbranch_vccnz .LBB0_2140
	v_cvt_pk_bf16_f32 v70, v26, v27
	v_cvt_pk_bf16_f32 v71, v28, v29
	v_lshlrev_b32_e32 v84, 1, v50
	v_bfi_b32 v84, s100, v84, v50
	v_lshrrev_b32_e32 v85, 5, v50
	v_bfi_b32 v84, 64, v85, v84
	v_mov_b32_e32 v85, v51
	global_store_dwordx2 v[84:85], v[70:71], off offset:32
.LBB0_2140:
	global_load_dwordx4 v[70:73], v[48:49], off offset:128
	s_and_b64 vcc, exec, s[10:11]
	s_waitcnt vmcnt(0)
	v_pk_fma_f32 v[22:23], v[22:23], 0.5, v[70:71] op_sel_hi:[1,0,1]
	v_pk_fma_f32 v[24:25], v[24:25], 0.5, v[72:73] op_sel_hi:[1,0,1]
	global_store_dwordx4 v[46:47], v[22:25], off offset:128
	s_cbranch_vccnz .LBB0_2142
	v_cvt_pk_bf16_f32 v70, v22, v23
	v_cvt_pk_bf16_f32 v71, v24, v25
	v_lshlrev_b32_e32 v84, 1, v50
	v_bfi_b32 v84, s100, v84, v50
	v_lshrrev_b32_e32 v85, 5, v50
	v_bfi_b32 v84, 64, v85, v84
	v_mov_b32_e32 v85, v51
	global_store_dwordx2 v[84:85], v[70:71], off offset:128
.LBB0_2142:
	global_load_dwordx4 v[70:73], v[48:49], off offset:192
	s_and_b64 vcc, exec, s[10:11]
	s_waitcnt vmcnt(0)
	v_pk_fma_f32 v[18:19], v[18:19], 0.5, v[70:71] op_sel_hi:[1,0,1]
	v_pk_fma_f32 v[20:21], v[20:21], 0.5, v[72:73] op_sel_hi:[1,0,1]
	global_store_dwordx4 v[46:47], v[18:21], off offset:192
	s_cbranch_vccnz .LBB0_2144
	v_cvt_pk_bf16_f32 v46, v18, v19
	v_cvt_pk_bf16_f32 v47, v20, v21
	v_lshlrev_b32_e32 v84, 1, v50
	v_bfi_b32 v84, s100, v84, v50
	v_lshrrev_b32_e32 v85, 5, v50
	v_bfi_b32 v84, 64, v85, v84
	v_mov_b32_e32 v85, v51
	global_store_dwordx2 v[84:85], v[46:47], off offset:160

; template <int EPI, int MF>
; __device__ __forceinline__ void gemm_part(const u16* __restrict__ A, int lda, const u16* __restrict__ Bt, int K, int ntn, GemmEpi ep, char* smem,
;                                           int mbase, int mrows) {
;     ...
;       } else if (EPI == EPI_RESID) {
;         const float* rp = (row < MP) ? ep.res0 + (size_t)row * DM : ep.res1 + (size_t)(row - MP) * DM;
;         float ssq = 0.f;
; #pragma unroll
;         for (int n = 0; n < 4; ++n) {
;           const int col = cb + n * 16;
;           const float4 r = *(const float4*)(rp + col);
;           float4 v;
;           v.x = r.x + ep.scale * acc[m][n][0]; v.y = r.y + ep.scale * acc[m][n][1];
;           v.z = r.z + ep.scale * acc[m][n][2]; v.w = r.w + ep.scale * acc[m][n][3];
;           *(float4*)(ep.outf + (size_t)row * DM + col) = v;
;           if (ep.xcopy) {
;             bf16x4 o;
;             o[0] = (short)f2bf(v.x); o[1] = (short)f2bf(v.y); o[2] = (short)f2bf(v.z); o[3] = (short)f2bf(v.w);
;             *(bf16x4*)(ep.xcopy + (size_t)row * DM + col) = o;
;           }
;           ssq += v.x * v.x + v.y * v.y + v.z * v.z + v.w * v.w;
;         }
.LBB0_2148:
	s_waitcnt lgkmcnt(0)
	v_or_b32_e32 v18, 16, v42
	s_mov_b32 s4, 0xffff
	v_cmp_lt_i32_e32 vcc, s4, v18
	s_and_saveexec_b64 s[4:5], vcc
	s_xor_b64 s[4:5], exec, s[4:5]
	v_add_u32_e32 v20, 0xffff0010, v42
	v_mov_b32_e32 v21, v0
	v_lshlrev_b64 v[20:21], 12, v[20:21]
	v_lshl_add_u64 v[20:21], s[72:73], 0, v[20:21]
	v_mov_b32_e32 v19, v0
	s_andn2_saveexec_b64 s[4:5], s[4:5]
	v_ashrrev_i32_e32 v19, 31, v18
	v_lshlrev_b64 v[20:21], 12, v[18:19]
	v_lshl_add_u64 v[20:21], s[26:27], 0, v[20:21]
	s_or_b64 exec, exec, s[4:5]
	v_lshl_add_u64 v[20:21], v[20:21], 0, v[44:45]
	global_load_dwordx4 v[26:29], v[20:21], off
	v_lshlrev_b64 v[22:23], 12, v[18:19]
	v_lshlrev_b64 v[24:25], 11, v[18:19]
	v_lshl_add_u64 v[22:23], s[26:27], 0, v[22:23]
	v_lshl_add_u64 v[30:31], s[14:15], 0, v[24:25]
	s_and_b64 vcc, exec, s[10:11]
	v_lshl_add_u64 v[24:25], v[22:23], 0, v[44:45]
	v_lshl_add_u64 v[22:23], v[40:41], 1, v[30:31]
	s_waitcnt vmcnt(0)
	v_pk_fma_f32 v[14:15], v[14:15], 0.5, v[26:27] op_sel_hi:[1,0,1]
	v_pk_fma_f32 v[16:17], v[16:17], 0.5, v[28:29] op_sel_hi:[1,0,1]
	global_store_dwordx4 v[24:25], v[14:17], off
	s_cbranch_vccnz .LBB0_2154
	v_cvt_pk_bf16_f32 v26, v14, v15
	v_cvt_pk_bf16_f32 v27, v16, v17
	v_lshlrev_b32_e32 v84, 1, v22
	v_bfi_b32 v84, s100, v84, v22
	v_lshrrev_b32_e32 v85, 5, v22
	v_bfi_b32 v84, 64, v85, v84
	v_mov_b32_e32 v85, v23
	global_store_dwordx2 v[84:85], v[26:27], off
.LBB0_2154:
	global_load_dwordx4 v[26:29], v[20:21], off offset:64
	s_and_b64 vcc, exec, s[10:11]
	s_waitcnt vmcnt(0)
	v_pk_fma_f32 v[10:11], v[10:11], 0.5, v[26:27] op_sel_hi:[1,0,1]
	v_pk_fma_f32 v[12:13], v[12:13], 0.5, v[28:29] op_sel_hi:[1,0,1]
	global_store_dwordx4 v[24:25], v[10:13], off offset:64
	s_cbranch_vccnz .LBB0_2156
	v_cvt_pk_bf16_f32 v26, v10, v11
	v_cvt_pk_bf16_f32 v27, v12, v13
	v_lshlrev_b32_e32 v84, 1, v22
	v_bfi_b32 v84, s100, v84, v22
	v_lshrrev_b32_e32 v85, 5, v22
	v_bfi_b32 v84, 64, v85, v84
	v_mov_b32_e32 v85, v23
	global_store_dwordx2 v[84:85], v[26:27], off offset:32
.LBB0_2156:
	global_load_dwordx4 v[26:29], v[20:21], off offset:128
	s_and_b64 vcc, exec, s[10:11]
	s_waitcnt vmcnt(0)
	v_pk_fma_f32 v[6:7], v[6:7], 0.5, v[26:27] op_sel_hi:[1,0,1]
	v_pk_fma_f32 v[8:9], v[8:9], 0.5, v[28:29] op_sel_hi:[1,0,1]
	global_store_dwordx4 v[24:25], v[6:9], off offset:128
	s_cbranch_vccnz .LBB0_2158
	v_cvt_pk_bf16_f32 v26, v6, v7
	v_cvt_pk_bf16_f32 v27, v8, v9
	v_lshlrev_b32_e32 v84, 1, v22
	v_bfi_b32 v84, s100, v84, v22
	v_lshrrev_b32_e32 v85, 5, v22
	v_bfi_b32 v84, 64, v85, v84
	v_mov_b32_e32 v85, v23
	global_store_dwordx2 v[84:85], v[26:27], off offset:128
.LBB0_2158:
	global_load_dwordx4 v[26:29], v[20:21], off offset:192
	s_and_b64 vcc, exec, s[10:11]
	s_waitcnt vmcnt(0)
	v_pk_fma_f32 v[2:3], v[2:3], 0.5, v[26:27] op_sel_hi:[1,0,1]
	v_pk_fma_f32 v[4:5], v[4:5], 0.5, v[28:29] op_sel_hi:[1,0,1]
	global_store_dwordx4 v[24:25], v[2:5], off offset:192
	s_cbranch_vccnz .LBB0_2160
	v_cvt_pk_bf16_f32 v20, v2, v3
	v_cvt_pk_bf16_f32 v21, v4, v5
	v_lshlrev_b32_e32 v84, 1, v22
	v_bfi_b32 v84, s100, v84, v22
	v_lshrrev_b32_e32 v85, 5, v22
	v_bfi_b32 v84, 64, v85, v84
	v_mov_b32_e32 v85, v23
	global_store_dwordx2 v[84:85], v[20:21], off offset:160
